# hyena order-1 epilogue (both layers) de-serialised: per 4 q all 32 conv/gate loads issued together, one vmcnt wait per group instead of ~6 dependent round trips per q
# speedup vs baseline: 1.0492x; 1.0051x over previous
.LBB0_538:
	v_mov_b32_e32 v20, v46
	v_mov_b32_e32 v21, v48
	v_mov_b32_e32 v22, v51
	v_mov_b32_e32 v23, v53
	v_pk_add_f32 v[88:89], v[20:21], 0 op_sel_hi:[1,0]
	v_pk_mul_f32 v[20:21], v[20:21], s[58:59] op_sel_hi:[1,0]
	v_xor_b32_e32 v91, 0x80000000, v46
	v_mov_b32_e32 v90, v48
	v_pk_add_f32 v[92:93], v[50:51], 0 neg_lo:[1,1] neg_hi:[1,1]
	v_mov_b32_e32 v24, v50
	v_mov_b32_e32 v25, v52
	v_pk_fma_f32 v[20:21], v[90:91], s[46:47], v[20:21] op_sel_hi:[1,0,1] neg_lo:[0,0,1] neg_hi:[0,0,1]
	v_pk_add_f32 v[90:91], v[22:23], 0 op_sel_hi:[1,0]
	v_pk_mul_f32 v[22:23], v[22:23], s[62:63] op_sel_hi:[1,0]
	v_mov_b32_e32 v92, v53
	v_mov_b32_e32 v26, v55
	v_mov_b32_e32 v27, v57
	v_pk_fma_f32 v[22:23], v[92:93], s[60:61], v[22:23] op_sel_hi:[1,0,1] neg_lo:[0,0,1] neg_hi:[0,0,1]
	v_pk_add_f32 v[92:93], v[24:25], 0 op_sel_hi:[1,0]
	v_pk_mul_f32 v[24:25], v[24:25], s[66:67] op_sel_hi:[1,0]
	v_xor_b32_e32 v95, 0x80000000, v50
	v_mov_b32_e32 v94, v52
	v_pk_add_f32 v[96:97], v[54:55], 0 neg_lo:[1,1] neg_hi:[1,1]
	v_mov_b32_e32 v64, v54
	v_mov_b32_e32 v65, v56
	v_pk_fma_f32 v[24:25], v[94:95], s[64:65], v[24:25] op_sel_hi:[1,0,1] neg_lo:[0,0,1] neg_hi:[0,0,1]
	v_pk_add_f32 v[94:95], v[26:27], 0 op_sel_hi:[1,0]
	v_pk_mul_f32 v[26:27], v[26:27], s[70:71] op_sel_hi:[1,0]
	v_mov_b32_e32 v96, v57
	v_mov_b32_e32 v66, v59
	v_mov_b32_e32 v67, v61
	v_pk_fma_f32 v[26:27], v[96:97], s[70:71], v[26:27] op_sel_hi:[1,0,1] neg_lo:[0,0,1] neg_hi:[0,0,1]
	v_pk_add_f32 v[96:97], v[64:65], 0 op_sel_hi:[1,0]
	v_pk_mul_f32 v[64:65], v[64:65], s[64:65] op_sel_hi:[1,0]
	v_xor_b32_e32 v99, 0x80000000, v54
	v_mov_b32_e32 v98, v56
	v_pk_add_f32 v[100:101], v[58:59], 0 neg_lo:[1,1] neg_hi:[1,1]
	v_mov_b32_e32 v2, v32
	v_mov_b32_e32 v3, v34
	v_mov_b32_e32 v4, v33
	v_mov_b32_e32 v5, v35
	v_mov_b32_e32 v18, v47
	v_mov_b32_e32 v19, v49
	v_mov_b32_e32 v68, v58
	v_mov_b32_e32 v69, v60
	v_pk_fma_f32 v[64:65], v[98:99], s[66:67], v[64:65] op_sel_hi:[1,0,1] neg_lo:[0,0,1] neg_hi:[0,0,1]
	v_pk_add_f32 v[98:99], v[66:67], 0 op_sel_hi:[1,0]
	v_pk_mul_f32 v[66:67], v[66:67], s[60:61] op_sel_hi:[1,0]
	v_mov_b32_e32 v100, v61
	v_pk_add_f32 v[70:71], v[2:3], 0 op_sel_hi:[1,0]
	v_pk_add_f32 v[72:73], v[4:5], 0 op_sel_hi:[1,0]
	v_pk_add_f32 v[74:75], v[32:33], 0 neg_lo:[1,1] neg_hi:[1,1]
	v_pk_add_f32 v[18:19], v[18:19], 0 op_sel_hi:[1,0]
	v_pk_fma_f32 v[66:67], v[100:101], s[62:63], v[66:67] op_sel_hi:[1,0,1] neg_lo:[0,0,1] neg_hi:[0,0,1]
	v_pk_add_f32 v[100:101], v[68:69], 0 op_sel_hi:[1,0]
	v_pk_mul_f32 v[68:69], v[68:69], s[46:47] op_sel_hi:[1,0]
	v_xor_b32_e32 v103, 0x80000000, v58
	v_mov_b32_e32 v102, v60
	v_mov_b32_e32 v74, v35
	v_pk_fma_f32 v[68:69], v[102:103], s[58:59], v[68:69] op_sel_hi:[1,0,1] neg_lo:[0,0,1] neg_hi:[0,0,1]
	v_pk_add_f32 v[102:103], v[18:19], v[70:71]
	v_pk_add_f32 v[18:19], v[70:71], v[18:19] neg_lo:[0,1] neg_hi:[0,1]
	v_pk_add_f32 v[70:71], v[88:89], v[72:73]
	v_pk_add_f32 v[72:73], v[72:73], v[88:89] neg_lo:[0,1] neg_hi:[0,1]
	v_mov_b32_e32 v6, v37
	v_mov_b32_e32 v7, v31
	v_pk_mul_f32 v[74:75], v[74:75], s[58:59] op_sel_hi:[1,0]
	v_xor_b32_e32 v89, 0x80000000, v72
	v_mov_b32_e32 v88, v73
	v_pk_fma_f32 v[4:5], v[4:5], s[46:47], v[74:75] op_sel_hi:[1,0,1]
	v_pk_add_f32 v[74:75], v[6:7], 0 op_sel_hi:[1,0]
	v_pk_add_f32 v[76:77], v[36:37], 0 neg_lo:[1,1] neg_hi:[1,1]
	v_pk_mul_f32 v[88:89], v[88:89], s[62:63] op_sel_hi:[1,0]
	v_mov_b32_e32 v76, v31
	v_pk_fma_f32 v[72:73], v[72:73], s[60:61], v[88:89] op_sel_hi:[1,0,1]
	v_pk_add_f32 v[88:89], v[90:91], v[74:75]
	v_pk_add_f32 v[74:75], v[74:75], v[90:91] neg_lo:[0,1] neg_hi:[0,1]
	v_mov_b32_e32 v8, v36
	v_mov_b32_e32 v9, v30
	v_pk_mul_f32 v[76:77], v[76:77], s[62:63] op_sel_hi:[1,0]
	v_xor_b32_e32 v91, 0x80000000, v74
	v_mov_b32_e32 v90, v75
	v_pk_fma_f32 v[6:7], v[6:7], s[60:61], v[76:77] op_sel_hi:[1,0,1]
	v_pk_add_f32 v[76:77], v[8:9], 0 op_sel_hi:[1,0]
	v_pk_mul_f32 v[90:91], v[90:91], s[70:71] op_sel_hi:[1,0]
	v_xor_b32_e32 v79, 0x80000000, v36
	v_mov_b32_e32 v78, v30
	v_pk_add_f32 v[80:81], v[38:39], 0 neg_lo:[1,1] neg_hi:[1,1]
	v_pk_fma_f32 v[74:75], v[74:75], s[70:71], v[90:91] op_sel_hi:[1,0,1]
	v_pk_add_f32 v[90:91], v[92:93], v[76:77]
	v_pk_add_f32 v[76:77], v[76:77], v[92:93] neg_lo:[0,1] neg_hi:[0,1]
	v_mov_b32_e32 v10, v39
	v_mov_b32_e32 v11, v41
	v_pk_mul_f32 v[78:79], v[78:79], s[66:67] op_sel_hi:[1,0]
	v_mov_b32_e32 v80, v41
	v_xor_b32_e32 v93, 0x80000000, v76
	v_mov_b32_e32 v92, v77
	v_mov_b32_e32 v12, v38
	v_mov_b32_e32 v13, v40
	v_pk_fma_f32 v[8:9], v[8:9], s[64:65], v[78:79] op_sel_hi:[1,0,1]
	v_pk_add_f32 v[78:79], v[10:11], 0 op_sel_hi:[1,0]
	v_pk_mul_f32 v[80:81], v[80:81], s[70:71] op_sel_hi:[1,0]
	v_pk_mul_f32 v[92:93], v[92:93], s[60:61] op_sel_hi:[1,0]
	v_pk_fma_f32 v[10:11], v[10:11], s[70:71], v[80:81] op_sel_hi:[1,0,1]
	v_pk_add_f32 v[80:81], v[12:13], 0 op_sel_hi:[1,0]
	v_xor_b32_e32 v83, 0x80000000, v38
	v_mov_b32_e32 v82, v40
	v_pk_fma_f32 v[76:77], v[76:77], s[62:63], v[92:93] op_sel_hi:[1,0,1]
	v_pk_add_f32 v[92:93], v[94:95], v[78:79]
	v_pk_add_f32 v[78:79], v[78:79], v[94:95] neg_lo:[0,1] neg_hi:[0,1]
	v_mov_b32_e32 v14, v43
	v_mov_b32_e32 v15, v45
	v_pk_mul_f32 v[82:83], v[82:83], s[64:65] op_sel_hi:[1,0]
	v_pk_add_f32 v[84:85], v[42:43], 0 neg_lo:[1,1] neg_hi:[1,1]
	v_xor_b32_e32 v95, 0x80000000, v78
	v_mov_b32_e32 v94, v79
	v_pk_add_f32 v[78:79], v[96:97], v[80:81]
	v_pk_add_f32 v[80:81], v[80:81], v[96:97] neg_lo:[0,1] neg_hi:[0,1]
	v_pk_fma_f32 v[12:13], v[12:13], s[66:67], v[82:83] op_sel_hi:[1,0,1]
	v_pk_add_f32 v[82:83], v[14:15], 0 op_sel_hi:[1,0]
	v_mov_b32_e32 v84, v45
	v_pk_mul_f32 v[96:97], v[80:81], s[62:63] op_sel_hi:[1,0]
	v_xor_b32_e32 v105, 0x80000000, v80
	v_mov_b32_e32 v104, v81
	v_mov_b32_e32 v16, v42
	v_mov_b32_e32 v17, v44
	v_pk_mul_f32 v[84:85], v[84:85], s[60:61] op_sel_hi:[1,0]
	v_xor_b32_e32 v87, 0x80000000, v42
	v_mov_b32_e32 v86, v44
	v_pk_fma_f32 v[80:81], v[104:105], s[60:61], v[96:97] op_sel_hi:[1,0,1] neg_lo:[0,0,1] neg_hi:[0,0,1]
	v_pk_add_f32 v[96:97], v[98:99], v[82:83]
	v_pk_add_f32 v[82:83], v[82:83], v[98:99] neg_lo:[0,1] neg_hi:[0,1]
	v_pk_fma_f32 v[14:15], v[14:15], s[62:63], v[84:85] op_sel_hi:[1,0,1]
	v_pk_add_f32 v[84:85], v[16:17], 0 op_sel_hi:[1,0]
	v_pk_mul_f32 v[86:87], v[86:87], s[46:47] op_sel_hi:[1,0]
	v_pk_mul_f32 v[98:99], v[82:83], s[70:71] op_sel_hi:[1,0]
	v_xor_b32_e32 v105, 0x80000000, v82
	v_mov_b32_e32 v104, v83
	v_pk_fma_f32 v[16:17], v[16:17], s[58:59], v[86:87] op_sel_hi:[1,0,1]
	v_pk_add_f32 v[86:87], v[46:47], 0 neg_lo:[1,1] neg_hi:[1,1]
	v_pk_fma_f32 v[82:83], v[104:105], s[70:71], v[98:99] op_sel_hi:[1,0,1] neg_lo:[0,0,1] neg_hi:[0,0,1]
	v_pk_add_f32 v[98:99], v[100:101], v[84:85]
	v_pk_add_f32 v[84:85], v[84:85], v[100:101] neg_lo:[0,1] neg_hi:[0,1]
	v_mov_b32_e32 v86, v49
	v_pk_mul_f32 v[100:101], v[84:85], s[60:61] op_sel_hi:[1,0]
	v_xor_b32_e32 v105, 0x80000000, v84
	v_mov_b32_e32 v104, v85
	v_pk_fma_f32 v[84:85], v[104:105], s[62:63], v[100:101] op_sel_hi:[1,0,1] neg_lo:[0,0,1] neg_hi:[0,0,1]
	v_pk_add_f32 v[100:101], v[86:87], v[2:3]
	v_pk_add_f32 v[2:3], v[2:3], v[86:87] neg_lo:[0,1] neg_hi:[0,1]
	v_pk_add_f32 v[86:87], v[20:21], v[4:5]
	v_pk_add_f32 v[4:5], v[4:5], v[20:21] neg_lo:[0,1] neg_hi:[0,1]
	v_mov_b32_e32 v63, v146
	v_xor_b32_e32 v21, 0x80000000, v4
	v_mov_b32_e32 v20, v5
	v_pk_mul_f32 v[20:21], v[20:21], s[62:63] op_sel_hi:[1,0]
	s_nop 0
	v_pk_fma_f32 v[4:5], v[4:5], s[60:61], v[20:21] op_sel_hi:[1,0,1]
	v_pk_add_f32 v[20:21], v[22:23], v[6:7]
	v_pk_add_f32 v[6:7], v[6:7], v[22:23] neg_lo:[0,1] neg_hi:[0,1]
	s_barrier
	v_xor_b32_e32 v23, 0x80000000, v6
	v_mov_b32_e32 v22, v7
	v_pk_mul_f32 v[22:23], v[22:23], s[70:71] op_sel_hi:[1,0]
	s_nop 0
	v_pk_fma_f32 v[6:7], v[6:7], s[70:71], v[22:23] op_sel_hi:[1,0,1]
	v_pk_add_f32 v[22:23], v[24:25], v[8:9]
	v_pk_add_f32 v[8:9], v[8:9], v[24:25] neg_lo:[0,1] neg_hi:[0,1]
	s_add_i32 s19, 16, 0x11000
	v_xor_b32_e32 v25, 0x80000000, v8
	v_mov_b32_e32 v24, v9
	v_pk_mul_f32 v[24:25], v[24:25], s[60:61] op_sel_hi:[1,0]
	s_add_i32 s18, 16, 0x12000
	v_pk_fma_f32 v[8:9], v[8:9], s[62:63], v[24:25] op_sel_hi:[1,0,1]
	v_pk_add_f32 v[24:25], v[26:27], v[10:11]
	v_pk_add_f32 v[10:11], v[10:11], v[26:27] neg_lo:[0,1] neg_hi:[0,1]
	s_add_i32 s17, 16, 0x13000
	v_xor_b32_e32 v27, 0x80000000, v10
	v_mov_b32_e32 v26, v11
	v_pk_add_f32 v[10:11], v[64:65], v[12:13]
	v_pk_add_f32 v[12:13], v[12:13], v[64:65] neg_lo:[0,1] neg_hi:[0,1]
	s_add_i32 s13, 16, 0x14000
	v_pk_mul_f32 v[64:65], v[12:13], s[62:63] op_sel_hi:[1,0]
	v_xor_b32_e32 v105, 0x80000000, v12
	v_mov_b32_e32 v104, v13
	v_pk_fma_f32 v[12:13], v[104:105], s[60:61], v[64:65] op_sel_hi:[1,0,1] neg_lo:[0,0,1] neg_hi:[0,0,1]
	v_pk_add_f32 v[64:65], v[66:67], v[14:15]
	v_pk_add_f32 v[14:15], v[14:15], v[66:67] neg_lo:[0,1] neg_hi:[0,1]
	s_add_i32 s12, 16, 0x15000
	v_pk_mul_f32 v[66:67], v[14:15], s[70:71] op_sel_hi:[1,0]
	v_xor_b32_e32 v105, 0x80000000, v14
	v_mov_b32_e32 v104, v15
	v_pk_fma_f32 v[14:15], v[104:105], s[70:71], v[66:67] op_sel_hi:[1,0,1] neg_lo:[0,0,1] neg_hi:[0,0,1]
	v_pk_add_f32 v[66:67], v[68:69], v[16:17]
	v_pk_add_f32 v[16:17], v[16:17], v[68:69] neg_lo:[0,1] neg_hi:[0,1]
	s_add_i32 s11, 16, 0x16000
	v_pk_mul_f32 v[68:69], v[16:17], s[60:61] op_sel_hi:[1,0]
	v_xor_b32_e32 v105, 0x80000000, v16
	v_mov_b32_e32 v104, v17
	v_pk_fma_f32 v[16:17], v[104:105], s[62:63], v[68:69] op_sel_hi:[1,0,1] neg_lo:[0,0,1] neg_hi:[0,0,1]
	v_pk_add_f32 v[68:69], v[92:93], v[102:103]
	v_pk_add_f32 v[92:93], v[102:103], v[92:93] neg_lo:[0,1] neg_hi:[0,1]
	v_pk_add_f32 v[102:103], v[78:79], v[70:71]
	v_pk_add_f32 v[70:71], v[70:71], v[78:79] neg_lo:[0,1] neg_hi:[0,1]
	s_add_i32 s10, 16, 0x17000
	v_xor_b32_e32 v79, 0x80000000, v70
	v_mov_b32_e32 v78, v71
	v_pk_mul_f32 v[78:79], v[78:79], s[70:71] op_sel_hi:[1,0]
	s_add_i32 s9, 16, 0x18000
	v_pk_fma_f32 v[70:71], v[70:71], s[70:71], v[78:79] op_sel_hi:[1,0,1]
	v_pk_add_f32 v[78:79], v[96:97], v[88:89]
	v_pk_add_f32 v[88:89], v[88:89], v[96:97] neg_lo:[0,1] neg_hi:[0,1]
	s_add_i32 s8, 16, 0x19000
	v_xor_b32_e32 v97, 0x80000000, v88
	v_mov_b32_e32 v96, v89
	v_pk_add_f32 v[88:89], v[98:99], v[90:91]
	v_pk_add_f32 v[90:91], v[90:91], v[98:99] neg_lo:[0,1] neg_hi:[0,1]
	s_add_i32 s7, 16, 0x1a000
	v_pk_mul_f32 v[98:99], v[90:91], s[70:71] op_sel_hi:[1,0]
	v_xor_b32_e32 v105, 0x80000000, v90
	v_mov_b32_e32 v104, v91
	v_pk_fma_f32 v[90:91], v[104:105], s[70:71], v[98:99] op_sel_hi:[1,0,1] neg_lo:[0,0,1] neg_hi:[0,0,1]
	v_pk_add_f32 v[98:99], v[94:95], v[18:19]
	v_pk_add_f32 v[18:19], v[18:19], v[94:95] neg_lo:[0,1] neg_hi:[0,1]
	v_pk_add_f32 v[94:95], v[80:81], v[72:73]
	v_pk_add_f32 v[72:73], v[72:73], v[80:81] neg_lo:[0,1] neg_hi:[0,1]
	s_add_i32 s6, 16, 0x1b000
	v_xor_b32_e32 v81, 0x80000000, v72
	v_mov_b32_e32 v80, v73
	v_pk_mul_f32 v[80:81], v[80:81], s[70:71] op_sel_hi:[1,0]
	s_add_i32 s5, 16, 0x1c000
	v_pk_fma_f32 v[72:73], v[72:73], s[70:71], v[80:81] op_sel_hi:[1,0,1]
	v_pk_add_f32 v[80:81], v[82:83], v[74:75]
	v_pk_add_f32 v[74:75], v[74:75], v[82:83] neg_lo:[0,1] neg_hi:[0,1]
	s_add_i32 s4, 16, 0x1d000
	v_xor_b32_e32 v83, 0x80000000, v74
	v_mov_b32_e32 v82, v75
	v_pk_add_f32 v[74:75], v[84:85], v[76:77]
	v_pk_add_f32 v[76:77], v[76:77], v[84:85] neg_lo:[0,1] neg_hi:[0,1]
	v_pk_add_f32 v[106:107], v[18:19], v[82:83]
	v_pk_mul_f32 v[84:85], v[76:77], s[70:71] op_sel_hi:[1,0]
	v_xor_b32_e32 v105, 0x80000000, v76
	v_mov_b32_e32 v104, v77
	v_pk_fma_f32 v[76:77], v[104:105], s[70:71], v[84:85] op_sel_hi:[1,0,1] neg_lo:[0,0,1] neg_hi:[0,0,1]
	v_pk_add_f32 v[84:85], v[24:25], v[100:101]
	v_pk_add_f32 v[24:25], v[100:101], v[24:25] neg_lo:[0,1] neg_hi:[0,1]
	v_pk_add_f32 v[100:101], v[10:11], v[86:87]
	v_pk_add_f32 v[10:11], v[86:87], v[10:11] neg_lo:[0,1] neg_hi:[0,1]
	v_pk_add_f32 v[18:19], v[18:19], v[82:83] neg_lo:[0,1] neg_hi:[0,1]
	v_xor_b32_e32 v87, 0x80000000, v10
	v_mov_b32_e32 v86, v11
	v_pk_mul_f32 v[86:87], v[86:87], s[70:71] op_sel_hi:[1,0]
	v_pk_add_f32 v[82:83], v[76:77], v[72:73]
	v_pk_fma_f32 v[10:11], v[10:11], s[70:71], v[86:87] op_sel_hi:[1,0,1]
	v_pk_add_f32 v[86:87], v[64:65], v[20:21]
	v_pk_add_f32 v[20:21], v[20:21], v[64:65] neg_lo:[0,1] neg_hi:[0,1]
	v_pk_add_f32 v[72:73], v[72:73], v[76:77] neg_lo:[0,1] neg_hi:[0,1]
	v_xor_b32_e32 v65, 0x80000000, v20
	v_mov_b32_e32 v64, v21
	v_pk_add_f32 v[20:21], v[66:67], v[22:23]
	v_pk_add_f32 v[22:23], v[22:23], v[66:67] neg_lo:[0,1] neg_hi:[0,1]
	v_xor_b32_e32 v77, 0x80000000, v72
	v_pk_mul_f32 v[66:67], v[22:23], s[70:71] op_sel_hi:[1,0]
	v_xor_b32_e32 v105, 0x80000000, v22
	v_mov_b32_e32 v104, v23
	v_pk_fma_f32 v[22:23], v[104:105], s[70:71], v[66:67] op_sel_hi:[1,0,1] neg_lo:[0,0,1] neg_hi:[0,0,1]
	v_pk_add_f32 v[66:67], v[2:3], v[26:27]
	v_pk_add_f32 v[2:3], v[2:3], v[26:27] neg_lo:[0,1] neg_hi:[0,1]
	v_pk_add_f32 v[26:27], v[12:13], v[4:5]
	v_pk_add_f32 v[4:5], v[4:5], v[12:13] neg_lo:[0,1] neg_hi:[0,1]
	v_mov_b32_e32 v76, v73
	v_xor_b32_e32 v13, 0x80000000, v4
	v_mov_b32_e32 v12, v5
	v_pk_mul_f32 v[12:13], v[12:13], s[70:71] op_sel_hi:[1,0]
	v_pk_add_f32 v[72:73], v[84:85], v[86:87]
	v_pk_fma_f32 v[4:5], v[4:5], s[70:71], v[12:13] op_sel_hi:[1,0,1]
	v_pk_add_f32 v[12:13], v[14:15], v[6:7]
	v_pk_add_f32 v[6:7], v[6:7], v[14:15] neg_lo:[0,1] neg_hi:[0,1]
	v_pk_add_f32 v[84:85], v[84:85], v[86:87] neg_lo:[0,1] neg_hi:[0,1]
	v_xor_b32_e32 v15, 0x80000000, v6
	v_mov_b32_e32 v14, v7
	v_pk_add_f32 v[6:7], v[16:17], v[8:9]
	v_pk_add_f32 v[8:9], v[8:9], v[16:17] neg_lo:[0,1] neg_hi:[0,1]
	v_pk_add_f32 v[86:87], v[20:21], v[100:101]
	v_pk_mul_f32 v[16:17], v[8:9], s[70:71] op_sel_hi:[1,0]
	v_xor_b32_e32 v105, 0x80000000, v8
	v_mov_b32_e32 v104, v9
	v_pk_fma_f32 v[8:9], v[104:105], s[70:71], v[16:17] op_sel_hi:[1,0,1] neg_lo:[0,0,1] neg_hi:[0,0,1]
	v_pk_add_f32 v[104:105], v[92:93], v[96:97]
	v_pk_add_f32 v[92:93], v[92:93], v[96:97] neg_lo:[0,1] neg_hi:[0,1]
	v_pk_add_f32 v[96:97], v[90:91], v[70:71]
	v_pk_add_f32 v[70:71], v[70:71], v[90:91] neg_lo:[0,1] neg_hi:[0,1]
	v_pk_add_f32 v[16:17], v[78:79], v[68:69]
	v_pk_add_f32 v[68:69], v[68:69], v[78:79] neg_lo:[0,1] neg_hi:[0,1]
	v_pk_add_f32 v[78:79], v[88:89], v[102:103]
	v_pk_add_f32 v[88:89], v[102:103], v[88:89] neg_lo:[0,1] neg_hi:[0,1]
	v_xor_b32_e32 v91, 0x80000000, v70
	v_mov_b32_e32 v90, v71
	v_pk_add_f32 v[70:71], v[98:99], v[80:81]
	v_pk_add_f32 v[98:99], v[98:99], v[80:81] neg_lo:[0,1] neg_hi:[0,1]
	v_pk_add_f32 v[80:81], v[74:75], v[94:95]
	v_pk_add_f32 v[74:75], v[94:95], v[74:75] neg_lo:[0,1] neg_hi:[0,1]
	v_pk_add_f32 v[20:21], v[100:101], v[20:21] neg_lo:[0,1] neg_hi:[0,1]
	v_pk_add_f32 v[108:109], v[24:25], v[64:65]
	v_pk_add_f32 v[24:25], v[24:25], v[64:65] neg_lo:[0,1] neg_hi:[0,1]
	v_pk_add_f32 v[64:65], v[22:23], v[10:11]
	v_pk_add_f32 v[10:11], v[10:11], v[22:23] neg_lo:[0,1] neg_hi:[0,1]
	v_pk_add_f32 v[114:115], v[6:7], v[26:27]
	v_pk_add_f32 v[6:7], v[26:27], v[6:7] neg_lo:[0,1] neg_hi:[0,1]
	v_xor_b32_e32 v103, 0x80000000, v88
	v_mov_b32_e32 v102, v89
	v_xor_b32_e32 v95, 0x80000000, v74
	v_mov_b32_e32 v94, v75
	v_xor_b32_e32 v101, 0x80000000, v20
	v_mov_b32_e32 v100, v21
	v_xor_b32_e32 v111, 0x80000000, v10
	v_mov_b32_e32 v110, v11
	v_xor_b32_e32 v27, 0x80000000, v6
	v_mov_b32_e32 v26, v7
	v_pk_add_f32 v[6:7], v[2:3], v[14:15]
	v_pk_add_f32 v[116:117], v[2:3], v[14:15] neg_lo:[0,1] neg_hi:[0,1]
	v_pk_add_f32 v[2:3], v[4:5], v[8:9] neg_lo:[0,1] neg_hi:[0,1]
	v_pk_add_f32 v[112:113], v[66:67], v[12:13]
	v_pk_add_f32 v[66:67], v[66:67], v[12:13] neg_lo:[0,1] neg_hi:[0,1]
	v_pk_add_f32 v[118:119], v[8:9], v[4:5]
	v_xor_b32_e32 v121, 0x80000000, v2
	v_mov_b32_e32 v120, v3
	v_pk_add_f32 v[2:3], v[78:79], v[16:17]
	v_pk_add_f32 v[88:89], v[16:17], v[78:79] neg_lo:[0,1] neg_hi:[0,1]
	v_pk_add_f32 v[122:123], v[68:69], v[102:103]
	v_pk_add_f32 v[20:21], v[68:69], v[102:103] neg_lo:[0,1] neg_hi:[0,1]
	v_pk_add_f32 v[78:79], v[104:105], v[96:97]
	v_pk_add_f32 v[74:75], v[104:105], v[96:97] neg_lo:[0,1] neg_hi:[0,1]
	v_pk_add_f32 v[96:97], v[92:93], v[90:91]
	v_pk_add_f32 v[8:9], v[92:93], v[90:91] neg_lo:[0,1] neg_hi:[0,1]
	v_pk_add_f32 v[102:103], v[98:99], v[94:95]
	v_pk_add_f32 v[12:13], v[98:99], v[94:95] neg_lo:[0,1] neg_hi:[0,1]
	v_pk_add_f32 v[98:99], v[18:19], v[76:77]
	v_pk_add_f32 v[4:5], v[18:19], v[76:77] neg_lo:[0,1] neg_hi:[0,1]
	v_pk_add_f32 v[18:19], v[72:73], v[86:87]
	v_pk_add_f32 v[92:93], v[72:73], v[86:87] neg_lo:[0,1] neg_hi:[0,1]
	v_pk_add_f32 v[86:87], v[84:85], v[100:101]
	v_pk_add_f32 v[22:23], v[84:85], v[100:101] neg_lo:[0,1] neg_hi:[0,1]
	v_pk_add_f32 v[100:101], v[24:25], v[110:111]
	v_pk_add_f32 v[10:11], v[24:25], v[110:111] neg_lo:[0,1] neg_hi:[0,1]
	v_mov_b32_e32 v24, v63
	v_pk_add_f32 v[84:85], v[108:109], v[64:65]
	v_cvt_f32_i32_e32 v24, v24
	v_pk_add_f32 v[76:77], v[108:109], v[64:65] neg_lo:[0,1] neg_hi:[0,1]
	v_pk_add_f32 v[104:105], v[66:67], v[26:27]
	v_pk_add_f32 v[14:15], v[66:67], v[26:27] neg_lo:[0,1] neg_hi:[0,1]
	v_mul_f32_e32 v25, 0x38800000, v24
	v_cos_f32_e32 v24, v25
	v_sin_f32_e32 v25, v25
	v_xor_b32_e32 v95, 0x80000000, v18
	v_mov_b32_e32 v94, v19
	v_add_f32_e32 v62, v24, v24
	v_pk_mul_f32 v[26:27], v[24:25], v[24:25]
	v_mul_f32_e32 v62, v25, v62
	v_xor_b32_e32 v72, 0x80000000, v25
	v_mov_b32_e32 v73, v24
	v_mov_b32_e32 v108, v25
	v_pk_add_f32 v[26:27], v[26:27], v[26:27] op_sel:[0,1] op_sel_hi:[0,1] neg_lo:[0,1] neg_hi:[0,1]
	v_pk_mul_f32 v[72:73], v[72:73], v[62:63] op_sel_hi:[1,0]
	v_pk_mul_f32 v[94:95], v[94:95], v[108:109] op_sel_hi:[1,0]
	v_pk_add_f32 v[16:17], v[70:71], v[80:81]
	v_pk_fma_f32 v[72:73], v[24:25], v[26:27], v[72:73]
	v_pk_fma_f32 v[18:19], v[18:19], v[24:25], v[94:95] op_sel_hi:[1,0,1]
	v_pk_mul_f32 v[24:25], v[62:63], s[48:49] op_sel_hi:[0,1]
	v_pk_fma_f32 v[94:95], v[26:27], s[40:41], v[24:25]
	v_xor_b32_e32 v25, 0x80000000, v16
	v_mov_b32_e32 v24, v17
	v_pk_mul_f32 v[24:25], v[24:25], v[94:95] op_sel:[0,1]
	v_pk_add_f32 v[64:65], v[112:113], v[114:115]
	v_pk_fma_f32 v[24:25], v[16:17], v[94:95], v[24:25] op_sel_hi:[1,0,1]
	v_xor_b32_e32 v16, 0x80000000, v73
	v_mov_b32_e32 v17, v72
	v_pk_mul_f32 v[16:17], v[62:63], v[16:17] op_sel_hi:[0,1]
	v_pk_fma_f32 v[108:109], v[26:27], v[72:73], v[16:17]
	v_xor_b32_e32 v17, 0x80000000, v64
	v_mov_b32_e32 v16, v65
	v_pk_mul_f32 v[16:17], v[16:17], v[72:73] op_sel:[0,1]
	v_pk_add_f32 v[90:91], v[106:107], v[82:83]
	v_pk_fma_f32 v[16:17], v[64:65], v[72:73], v[16:17] op_sel_hi:[1,0,1]
	v_xor_b32_e32 v64, 0x80000000, v95
	v_mov_b32_e32 v65, v94
	v_pk_mul_f32 v[64:65], v[62:63], v[64:65] op_sel_hi:[0,1]
	v_pk_fma_f32 v[94:95], v[26:27], v[94:95], v[64:65]
	v_xor_b32_e32 v65, 0x80000000, v78
	v_mov_b32_e32 v64, v79
	v_pk_mul_f32 v[64:65], v[64:65], v[94:95] op_sel:[0,1]
	v_pk_add_f32 v[66:67], v[6:7], v[118:119]
	v_pk_fma_f32 v[72:73], v[78:79], v[94:95], v[64:65] op_sel_hi:[1,0,1]
	v_xor_b32_e32 v64, 0x80000000, v109
	v_mov_b32_e32 v65, v108
	v_pk_mul_f32 v[64:65], v[62:63], v[64:65] op_sel_hi:[0,1]
	v_pk_fma_f32 v[110:111], v[26:27], v[108:109], v[64:65]
	v_xor_b32_e32 v65, 0x80000000, v84
	v_mov_b32_e32 v64, v85
	v_xor_b32_e32 v78, 0x80000000, v95
	v_mov_b32_e32 v79, v94
	v_pk_mul_f32 v[64:65], v[64:65], v[108:109] op_sel:[0,1]
	v_pk_mul_f32 v[78:79], v[62:63], v[78:79] op_sel_hi:[0,1]
	v_pk_fma_f32 v[64:65], v[84:85], v[108:109], v[64:65] op_sel_hi:[1,0,1]
	v_pk_fma_f32 v[84:85], v[26:27], v[94:95], v[78:79]
	v_xor_b32_e32 v79, 0x80000000, v90
	v_mov_b32_e32 v78, v91
	v_pk_mul_f32 v[78:79], v[78:79], v[84:85] op_sel:[0,1]
	v_pk_add_f32 v[68:69], v[106:107], v[82:83] neg_lo:[0,1] neg_hi:[0,1]
	v_pk_fma_f32 v[78:79], v[90:91], v[84:85], v[78:79] op_sel_hi:[1,0,1]
	v_xor_b32_e32 v90, 0x80000000, v111
	v_mov_b32_e32 v91, v110
	v_pk_mul_f32 v[90:91], v[62:63], v[90:91] op_sel_hi:[0,1]
	v_pk_fma_f32 v[94:95], v[26:27], v[110:111], v[90:91]
	v_xor_b32_e32 v91, 0x80000000, v66
	v_mov_b32_e32 v90, v67
	v_pk_mul_f32 v[90:91], v[90:91], v[110:111] op_sel:[0,1]
	v_pk_add_f32 v[106:107], v[116:117], v[120:121]
	v_pk_fma_f32 v[66:67], v[66:67], v[110:111], v[90:91] op_sel_hi:[1,0,1]
	v_xor_b32_e32 v90, 0x80000000, v85
	v_mov_b32_e32 v91, v84
	v_pk_mul_f32 v[90:91], v[62:63], v[90:91] op_sel_hi:[0,1]
	v_pk_fma_f32 v[108:109], v[26:27], v[84:85], v[90:91]
	v_xor_b32_e32 v85, 0x80000000, v122
	v_mov_b32_e32 v84, v123
	v_pk_mul_f32 v[84:85], v[84:85], v[108:109] op_sel:[0,1]
	v_pk_add_f32 v[80:81], v[70:71], v[80:81] neg_lo:[0,1] neg_hi:[0,1]
	v_pk_fma_f32 v[90:91], v[122:123], v[108:109], v[84:85] op_sel_hi:[1,0,1]
	v_xor_b32_e32 v84, 0x80000000, v95
	v_mov_b32_e32 v85, v94
	v_pk_mul_f32 v[84:85], v[62:63], v[84:85] op_sel_hi:[0,1]
	v_pk_fma_f32 v[110:111], v[26:27], v[94:95], v[84:85]
	v_xor_b32_e32 v85, 0x80000000, v86
	v_mov_b32_e32 v84, v87
	v_pk_mul_f32 v[84:85], v[84:85], v[94:95] op_sel:[0,1]
	v_pk_add_f32 v[82:83], v[112:113], v[114:115] neg_lo:[0,1] neg_hi:[0,1]
	v_pk_fma_f32 v[84:85], v[86:87], v[94:95], v[84:85] op_sel_hi:[1,0,1]
	v_xor_b32_e32 v86, 0x80000000, v109
	v_mov_b32_e32 v87, v108
	v_pk_mul_f32 v[86:87], v[62:63], v[86:87] op_sel_hi:[0,1]
	v_pk_fma_f32 v[108:109], v[26:27], v[108:109], v[86:87]
	v_xor_b32_e32 v87, 0x80000000, v102
	v_mov_b32_e32 v86, v103
	v_pk_mul_f32 v[86:87], v[86:87], v[108:109] op_sel:[0,1]
	v_pk_add_f32 v[70:71], v[6:7], v[118:119] neg_lo:[0,1] neg_hi:[0,1]
	v_pk_fma_f32 v[94:95], v[102:103], v[108:109], v[86:87] op_sel_hi:[1,0,1]
	v_xor_b32_e32 v86, 0x80000000, v111
	v_mov_b32_e32 v87, v110
	v_pk_mul_f32 v[86:87], v[62:63], v[86:87] op_sel_hi:[0,1]
	v_pk_fma_f32 v[102:103], v[26:27], v[110:111], v[86:87]
	v_xor_b32_e32 v87, 0x80000000, v104
	v_mov_b32_e32 v86, v105
	v_pk_mul_f32 v[86:87], v[86:87], v[110:111] op_sel:[0,1]
	v_pk_add_f32 v[6:7], v[116:117], v[120:121] neg_lo:[0,1] neg_hi:[0,1]
	v_pk_fma_f32 v[86:87], v[104:105], v[110:111], v[86:87] op_sel_hi:[1,0,1]
	v_xor_b32_e32 v104, 0x80000000, v109
	v_mov_b32_e32 v105, v108
	v_pk_mul_f32 v[104:105], v[62:63], v[104:105] op_sel_hi:[0,1]
	v_pk_fma_f32 v[104:105], v[26:27], v[108:109], v[104:105]
	v_xor_b32_e32 v109, 0x80000000, v96
	v_mov_b32_e32 v108, v97
	v_pk_mul_f32 v[108:109], v[108:109], v[104:105] op_sel:[0,1]
	v_xor_b32_e32 v111, 0x80000000, v100
	v_pk_fma_f32 v[96:97], v[96:97], v[104:105], v[108:109] op_sel_hi:[1,0,1]
	v_xor_b32_e32 v108, 0x80000000, v103
	v_mov_b32_e32 v109, v102
	v_mov_b32_e32 v110, v101
	v_pk_mul_f32 v[108:109], v[62:63], v[108:109] op_sel_hi:[0,1]
	v_pk_mul_f32 v[110:111], v[110:111], v[102:103] op_sel:[0,1]
	v_pk_fma_f32 v[108:109], v[26:27], v[102:103], v[108:109]
	v_pk_fma_f32 v[100:101], v[100:101], v[102:103], v[110:111] op_sel_hi:[1,0,1]
	v_xor_b32_e32 v102, 0x80000000, v105
	v_mov_b32_e32 v103, v104
	v_pk_mul_f32 v[102:103], v[62:63], v[102:103] op_sel_hi:[0,1]
	v_pk_fma_f32 v[102:103], v[26:27], v[104:105], v[102:103]
	v_xor_b32_e32 v105, 0x80000000, v98
	v_mov_b32_e32 v104, v99
	v_pk_mul_f32 v[104:105], v[104:105], v[102:103] op_sel:[0,1]
	v_xor_b32_e32 v111, 0x80000000, v106
	v_pk_fma_f32 v[98:99], v[98:99], v[102:103], v[104:105] op_sel_hi:[1,0,1]
	v_xor_b32_e32 v104, 0x80000000, v109
	v_mov_b32_e32 v105, v108
	v_mov_b32_e32 v110, v107
	v_pk_mul_f32 v[104:105], v[62:63], v[104:105] op_sel_hi:[0,1]
	v_pk_mul_f32 v[110:111], v[110:111], v[108:109] op_sel:[0,1]
	v_pk_fma_f32 v[104:105], v[26:27], v[108:109], v[104:105]
	v_pk_fma_f32 v[106:107], v[106:107], v[108:109], v[110:111] op_sel_hi:[1,0,1]
	v_xor_b32_e32 v108, 0x80000000, v103
	v_mov_b32_e32 v109, v102
	v_pk_mul_f32 v[108:109], v[62:63], v[108:109] op_sel_hi:[0,1]
	v_pk_fma_f32 v[102:103], v[26:27], v[102:103], v[108:109]
	v_xor_b32_e32 v109, 0x80000000, v88
	v_mov_b32_e32 v108, v89
	v_pk_mul_f32 v[108:109], v[108:109], v[102:103] op_sel:[0,1]
	v_xor_b32_e32 v111, 0x80000000, v92
	v_pk_fma_f32 v[88:89], v[88:89], v[102:103], v[108:109] op_sel_hi:[1,0,1]
	v_xor_b32_e32 v108, 0x80000000, v105
	v_mov_b32_e32 v109, v104
	v_mov_b32_e32 v110, v93
	v_pk_mul_f32 v[108:109], v[62:63], v[108:109] op_sel_hi:[0,1]
	v_pk_mul_f32 v[110:111], v[110:111], v[104:105] op_sel:[0,1]
	v_pk_fma_f32 v[108:109], v[26:27], v[104:105], v[108:109]
	v_pk_fma_f32 v[92:93], v[92:93], v[104:105], v[110:111] op_sel_hi:[1,0,1]
	v_xor_b32_e32 v104, 0x80000000, v103
	v_mov_b32_e32 v105, v102
	v_pk_mul_f32 v[104:105], v[62:63], v[104:105] op_sel_hi:[0,1]
	v_pk_fma_f32 v[102:103], v[26:27], v[102:103], v[104:105]
	v_xor_b32_e32 v105, 0x80000000, v80
	v_mov_b32_e32 v104, v81
	v_pk_mul_f32 v[104:105], v[104:105], v[102:103] op_sel:[0,1]
	v_xor_b32_e32 v111, 0x80000000, v82
	v_pk_fma_f32 v[80:81], v[80:81], v[102:103], v[104:105] op_sel_hi:[1,0,1]
	v_xor_b32_e32 v104, 0x80000000, v109
	v_mov_b32_e32 v105, v108
	v_mov_b32_e32 v110, v83
	v_pk_mul_f32 v[104:105], v[62:63], v[104:105] op_sel_hi:[0,1]
	v_pk_mul_f32 v[110:111], v[110:111], v[108:109] op_sel:[0,1]
	v_pk_fma_f32 v[104:105], v[26:27], v[108:109], v[104:105]
	v_pk_fma_f32 v[82:83], v[82:83], v[108:109], v[110:111] op_sel_hi:[1,0,1]
	v_xor_b32_e32 v108, 0x80000000, v103
	v_mov_b32_e32 v109, v102
	v_pk_mul_f32 v[108:109], v[62:63], v[108:109] op_sel_hi:[0,1]
	v_pk_fma_f32 v[102:103], v[26:27], v[102:103], v[108:109]
	v_xor_b32_e32 v109, 0x80000000, v74
	v_mov_b32_e32 v108, v75
	v_pk_mul_f32 v[108:109], v[108:109], v[102:103] op_sel:[0,1]
	v_xor_b32_e32 v111, 0x80000000, v76
	v_pk_fma_f32 v[74:75], v[74:75], v[102:103], v[108:109] op_sel_hi:[1,0,1]
	v_xor_b32_e32 v108, 0x80000000, v105
	v_mov_b32_e32 v109, v104
	v_mov_b32_e32 v110, v77
	v_pk_mul_f32 v[108:109], v[62:63], v[108:109] op_sel_hi:[0,1]
	v_pk_mul_f32 v[110:111], v[110:111], v[104:105] op_sel:[0,1]
	v_pk_fma_f32 v[108:109], v[26:27], v[104:105], v[108:109]
	v_pk_fma_f32 v[76:77], v[76:77], v[104:105], v[110:111] op_sel_hi:[1,0,1]
	v_xor_b32_e32 v104, 0x80000000, v103
	v_mov_b32_e32 v105, v102
	v_pk_mul_f32 v[104:105], v[62:63], v[104:105] op_sel_hi:[0,1]
	v_pk_fma_f32 v[102:103], v[26:27], v[102:103], v[104:105]
	v_xor_b32_e32 v105, 0x80000000, v68
	v_mov_b32_e32 v104, v69
	v_pk_mul_f32 v[104:105], v[104:105], v[102:103] op_sel:[0,1]
	v_xor_b32_e32 v111, 0x80000000, v70
	v_pk_fma_f32 v[68:69], v[68:69], v[102:103], v[104:105] op_sel_hi:[1,0,1]
	v_xor_b32_e32 v104, 0x80000000, v109
	v_mov_b32_e32 v105, v108
	v_mov_b32_e32 v110, v71
	v_pk_mul_f32 v[104:105], v[62:63], v[104:105] op_sel_hi:[0,1]
	v_pk_mul_f32 v[110:111], v[110:111], v[108:109] op_sel:[0,1]
	v_pk_fma_f32 v[104:105], v[26:27], v[108:109], v[104:105]
	v_pk_fma_f32 v[70:71], v[70:71], v[108:109], v[110:111] op_sel_hi:[1,0,1]
	v_xor_b32_e32 v108, 0x80000000, v103
	v_mov_b32_e32 v109, v102
	v_pk_mul_f32 v[108:109], v[62:63], v[108:109] op_sel_hi:[0,1]
	v_pk_fma_f32 v[102:103], v[26:27], v[102:103], v[108:109]
	v_xor_b32_e32 v109, 0x80000000, v20
	v_mov_b32_e32 v108, v21
	v_pk_mul_f32 v[108:109], v[108:109], v[102:103] op_sel:[0,1]
	v_xor_b32_e32 v111, 0x80000000, v22
	v_pk_fma_f32 v[20:21], v[20:21], v[102:103], v[108:109] op_sel_hi:[1,0,1]
	v_xor_b32_e32 v108, 0x80000000, v105
	v_mov_b32_e32 v109, v104
	v_mov_b32_e32 v110, v23
	v_pk_mul_f32 v[108:109], v[62:63], v[108:109] op_sel_hi:[0,1]
	v_pk_mul_f32 v[110:111], v[110:111], v[104:105] op_sel:[0,1]
	v_pk_fma_f32 v[108:109], v[26:27], v[104:105], v[108:109]
	v_pk_fma_f32 v[22:23], v[22:23], v[104:105], v[110:111] op_sel_hi:[1,0,1]
	v_xor_b32_e32 v104, 0x80000000, v103
	v_mov_b32_e32 v105, v102
	v_pk_mul_f32 v[104:105], v[62:63], v[104:105] op_sel_hi:[0,1]
	v_pk_fma_f32 v[102:103], v[26:27], v[102:103], v[104:105]
	v_xor_b32_e32 v105, 0x80000000, v12
	v_mov_b32_e32 v104, v13
	v_pk_mul_f32 v[104:105], v[104:105], v[102:103] op_sel:[0,1]
	v_xor_b32_e32 v111, 0x80000000, v14
	v_pk_fma_f32 v[12:13], v[12:13], v[102:103], v[104:105] op_sel_hi:[1,0,1]
	v_xor_b32_e32 v104, 0x80000000, v109
	v_mov_b32_e32 v105, v108
	v_mov_b32_e32 v110, v15
	v_pk_mul_f32 v[104:105], v[62:63], v[104:105] op_sel_hi:[0,1]
	v_pk_mul_f32 v[110:111], v[110:111], v[108:109] op_sel:[0,1]
	v_pk_fma_f32 v[104:105], v[26:27], v[108:109], v[104:105]
	v_pk_fma_f32 v[14:15], v[14:15], v[108:109], v[110:111] op_sel_hi:[1,0,1]
	v_xor_b32_e32 v108, 0x80000000, v103
	v_mov_b32_e32 v109, v102
	v_pk_mul_f32 v[108:109], v[62:63], v[108:109] op_sel_hi:[0,1]
	v_pk_fma_f32 v[102:103], v[26:27], v[102:103], v[108:109]
	v_xor_b32_e32 v109, 0x80000000, v8
	v_mov_b32_e32 v108, v9
	v_pk_mul_f32 v[108:109], v[108:109], v[102:103] op_sel:[0,1]
	v_xor_b32_e32 v111, 0x80000000, v10
	v_pk_fma_f32 v[8:9], v[8:9], v[102:103], v[108:109] op_sel_hi:[1,0,1]
	v_xor_b32_e32 v108, 0x80000000, v105
	v_mov_b32_e32 v109, v104
	v_mov_b32_e32 v110, v11
	v_pk_mul_f32 v[108:109], v[62:63], v[108:109] op_sel_hi:[0,1]
	v_pk_mul_f32 v[110:111], v[110:111], v[104:105] op_sel:[0,1]
	v_pk_fma_f32 v[108:109], v[26:27], v[104:105], v[108:109]
	v_pk_fma_f32 v[10:11], v[10:11], v[104:105], v[110:111] op_sel_hi:[1,0,1]
	v_xor_b32_e32 v104, 0x80000000, v103
	v_mov_b32_e32 v105, v102
	v_pk_mul_f32 v[104:105], v[62:63], v[104:105] op_sel_hi:[0,1]
	v_pk_fma_f32 v[26:27], v[26:27], v[102:103], v[104:105]
	v_xor_b32_e32 v103, 0x80000000, v4
	v_mov_b32_e32 v102, v5
	v_pk_mul_f32 v[102:103], v[102:103], v[26:27] op_sel:[0,1]
	s_add_i32 s1, 16, 0x1e000
	v_pk_fma_f32 v[4:5], v[4:5], v[26:27], v[102:103] op_sel_hi:[1,0,1]
	v_xor_b32_e32 v27, 0x80000000, v6
	v_mov_b32_e32 v26, v7
	v_pk_mul_f32 v[26:27], v[26:27], v[108:109] op_sel:[0,1]
	s_add_i32 s0, 16, 0x1f000
	v_pk_fma_f32 v[6:7], v[6:7], v[108:109], v[26:27] op_sel_hi:[1,0,1]
	v_lshrrev_b32_e32 v26, 5, v63
	v_bitop3_b32 v26, v26, v63, 15 bitop3:0x6c
	v_lshlrev_b32_e32 v26, 3, v26
	v_bfe_u32 v27, v63, 5, 4
	v_add_u32_e32 v62, 16, v26
	ds_write_b64 v62, v[2:3]
	v_bitop3_b32 v2, v27, v63, 16 bitop3:0x36
	v_lshlrev_b32_e32 v2, 3, v2
	v_add_u32_e32 v3, 16, v2
	ds_write_b64 v3, v[88:89] offset:4096
	ds_write_b64 v62, v[90:91] offset:8192
	ds_write_b64 v3, v[20:21] offset:12288
	ds_write_b64 v62, v[72:73] offset:16384
	ds_write_b64 v3, v[74:75] offset:20480
	ds_write_b64 v62, v[96:97] offset:24576
	ds_write_b64 v3, v[8:9] offset:28672
	ds_write_b64 v62, v[24:25] offset:32768
	ds_write_b64 v3, v[80:81] offset:36864
	ds_write_b64 v62, v[94:95] offset:40960
	ds_write_b64 v3, v[12:13] offset:45056
	ds_write_b64 v62, v[78:79] offset:49152
	ds_write_b64 v3, v[68:69] offset:53248
	ds_write_b64 v62, v[98:99] offset:57344
	ds_write_b64 v3, v[4:5] offset:61440
	v_add_u32_e32 v3, s47, v26
	ds_write_b64 v3, v[18:19]
	v_add_u32_e32 v3, s19, v2
	ds_write_b64 v3, v[92:93]
	v_add_u32_e32 v3, s18, v26
	ds_write_b64 v3, v[84:85]
	v_add_u32_e32 v3, s17, v2
	ds_write_b64 v3, v[22:23]
	v_add_u32_e32 v3, s13, v26
	ds_write_b64 v3, v[64:65]
	v_add_u32_e32 v3, s12, v2
	ds_write_b64 v3, v[76:77]
	v_add_u32_e32 v3, s11, v26
	ds_write_b64 v3, v[100:101]
	v_add_u32_e32 v3, s10, v2
	ds_write_b64 v3, v[10:11]
	v_add_u32_e32 v3, s9, v26
	ds_write_b64 v3, v[16:17]
	v_add_u32_e32 v3, s8, v2
	ds_write_b64 v3, v[82:83]
	v_add_u32_e32 v3, s7, v26
	ds_write_b64 v3, v[86:87]
	v_add_u32_e32 v3, s6, v2
	ds_write_b64 v3, v[14:15]
	v_add_u32_e32 v3, s5, v26
	ds_write_b64 v3, v[66:67]
	v_add_u32_e32 v3, s4, v2
	ds_write_b64 v3, v[70:71]
	v_add_u32_e32 v3, s1, v26
	v_add_u32_e32 v2, s0, v2
	v_mov_b32_e32 v21, v146
	ds_write_b64 v3, v[106:107]
	ds_write_b64 v2, v[6:7]
	s_waitcnt lgkmcnt(0)
	s_barrier
	s_lshl_b32 s44, s16, 14
	v_lshlrev_b32_e32 v2, 5, v21
	v_and_b32_e32 v4, 0xfffffe00, v2
	v_and_b32_e32 v20, 15, v21
	v_and_or_b32 v2, v21, 16, v4
	v_bitop3_b32 v4, v4, 16, v21 bitop3:0x34
	v_bitop3_b32 v72, v21, 8, 15 bitop3:0x6c
	v_lshl_add_u32 v26, v2, 3, 16
	v_lshlrev_b32_e32 v5, 3, v20
	v_lshl_add_u32 v126, v4, 3, 16
	v_lshlrev_b32_e32 v74, 3, v72
	v_add_u32_e32 v27, v26, v5
	v_add_u32_e32 v96, v126, v5
	v_add_u32_e32 v111, v26, v74
	v_add_u32_e32 v112, v126, v74
	ds_read_b64 v[2:3], v27
	ds_read_b64 v[4:5], v96
	v_bitop3_b32 v6, v21, 1, 15 bitop3:0x6c
	ds_read_b64 v[72:73], v111 offset:2048
	ds_read_b64 v[74:75], v112 offset:2048
	v_bitop3_b32 v76, v21, 9, 15 bitop3:0x6c
	v_lshlrev_b32_e32 v8, 3, v6
	v_lshlrev_b32_e32 v78, 3, v76
	v_add_u32_e32 v97, v26, v8
	v_add_u32_e32 v113, v26, v78
	ds_read_b64 v[6:7], v97 offset:256
	ds_read_b64 v[76:77], v113 offset:2304
	v_add_u32_e32 v98, v126, v8
	v_add_u32_e32 v114, v126, v78
	ds_read_b64 v[8:9], v98 offset:256
	ds_read_b64 v[78:79], v114 offset:2304
	s_waitcnt lgkmcnt(5)
	v_pk_add_f32 v[136:137], v[2:3], v[72:73]
	v_pk_add_f32 v[2:3], v[2:3], v[72:73] neg_lo:[0,1] neg_hi:[0,1]
	s_waitcnt lgkmcnt(4)
	v_pk_add_f32 v[72:73], v[4:5], v[74:75]
	v_pk_add_f32 v[4:5], v[4:5], v[74:75] neg_lo:[0,1] neg_hi:[0,1]
	v_bitop3_b32 v10, v21, 2, 15 bitop3:0x6c
	v_bitop3_b32 v80, v21, 10, 15 bitop3:0x6c
	v_xor_b32_e32 v75, 0x80000000, v4
	v_mov_b32_e32 v74, v5
	v_lshlrev_b32_e32 v12, 3, v10
	v_lshlrev_b32_e32 v82, 3, v80
	v_pk_mul_f32 v[74:75], v[74:75], s[58:59] op_sel_hi:[1,0]
	v_add_u32_e32 v99, v26, v12
	v_add_u32_e32 v115, v26, v82
	v_pk_fma_f32 v[4:5], v[4:5], s[46:47], v[74:75] op_sel_hi:[1,0,1]
	s_waitcnt lgkmcnt(2)
	v_pk_add_f32 v[74:75], v[6:7], v[76:77]
	v_pk_add_f32 v[6:7], v[6:7], v[76:77] neg_lo:[0,1] neg_hi:[0,1]
	ds_read_b64 v[10:11], v99 offset:512
	ds_read_b64 v[80:81], v115 offset:2560
	v_xor_b32_e32 v77, 0x80000000, v6
	v_mov_b32_e32 v76, v7
	v_pk_mul_f32 v[76:77], v[76:77], s[62:63] op_sel_hi:[1,0]
	v_add_u32_e32 v100, v126, v12
	v_bitop3_b32 v14, v21, 3, 15 bitop3:0x6c
	v_add_u32_e32 v116, v126, v82
	v_bitop3_b32 v84, v21, 11, 15 bitop3:0x6c
	v_pk_fma_f32 v[6:7], v[6:7], s[60:61], v[76:77] op_sel_hi:[1,0,1]
	s_waitcnt lgkmcnt(2)
	v_pk_add_f32 v[76:77], v[8:9], v[78:79]
	v_pk_add_f32 v[8:9], v[8:9], v[78:79] neg_lo:[0,1] neg_hi:[0,1]
	ds_read_b64 v[12:13], v100 offset:512
	v_lshlrev_b32_e32 v16, 3, v14
	ds_read_b64 v[82:83], v116 offset:2560
	v_lshlrev_b32_e32 v86, 3, v84
	v_xor_b32_e32 v79, 0x80000000, v8
	v_mov_b32_e32 v78, v9
	v_add_u32_e32 v101, v26, v16
	v_add_u32_e32 v102, v126, v16
	v_add_u32_e32 v117, v26, v86
	v_add_u32_e32 v118, v126, v86
	v_pk_mul_f32 v[78:79], v[78:79], s[66:67] op_sel_hi:[1,0]
	ds_read_b64 v[14:15], v101 offset:768
	ds_read_b64 v[16:17], v102 offset:768
	ds_read_b64 v[84:85], v117 offset:2816
	ds_read_b64 v[86:87], v118 offset:2816
	v_pk_fma_f32 v[8:9], v[8:9], s[64:65], v[78:79] op_sel_hi:[1,0,1]
	s_waitcnt lgkmcnt(6)
	v_pk_add_f32 v[78:79], v[10:11], v[80:81]
	v_pk_add_f32 v[10:11], v[10:11], v[80:81] neg_lo:[0,1] neg_hi:[0,1]
	v_bitop3_b32 v18, v21, 4, 15 bitop3:0x6c
	v_xor_b32_e32 v81, 0x80000000, v10
	v_mov_b32_e32 v80, v11
	v_pk_mul_f32 v[80:81], v[80:81], s[70:71] op_sel_hi:[1,0]
	v_bitop3_b32 v88, v21, 12, 15 bitop3:0x6c
	v_pk_fma_f32 v[10:11], v[10:11], s[70:71], v[80:81] op_sel_hi:[1,0,1]
	s_waitcnt lgkmcnt(4)
	v_pk_add_f32 v[80:81], v[12:13], v[82:83]
	v_pk_add_f32 v[12:13], v[12:13], v[82:83] neg_lo:[0,1] neg_hi:[0,1]
	v_lshlrev_b32_e32 v22, 3, v18
	v_xor_b32_e32 v83, 0x80000000, v12
	v_mov_b32_e32 v82, v13
	v_lshlrev_b32_e32 v90, 3, v88
	v_pk_mul_f32 v[82:83], v[82:83], s[64:65] op_sel_hi:[1,0]
	v_add_u32_e32 v103, v26, v22
	v_add_u32_e32 v119, v26, v90
	v_pk_fma_f32 v[12:13], v[12:13], s[66:67], v[82:83] op_sel_hi:[1,0,1]
	s_waitcnt lgkmcnt(1)
	v_pk_add_f32 v[82:83], v[14:15], v[84:85]
	v_pk_add_f32 v[14:15], v[14:15], v[84:85] neg_lo:[0,1] neg_hi:[0,1]
	ds_read_b64 v[18:19], v103 offset:1024
	v_add_u32_e32 v104, v126, v22
	v_bitop3_b32 v24, v21, 5, 15 bitop3:0x6c
	ds_read_b64 v[88:89], v119 offset:3072
	v_add_u32_e32 v120, v126, v90
	v_bitop3_b32 v92, v21, 13, 15 bitop3:0x6c
	v_xor_b32_e32 v85, 0x80000000, v14
	v_mov_b32_e32 v84, v15
	ds_read_b64 v[22:23], v104 offset:1024
	v_lshlrev_b32_e32 v62, 3, v24
	ds_read_b64 v[90:91], v120 offset:3072
	v_lshlrev_b32_e32 v94, 3, v92
	v_pk_mul_f32 v[84:85], v[84:85], s[60:61] op_sel_hi:[1,0]
	v_add_u32_e32 v105, v26, v62
	v_add_u32_e32 v121, v26, v94
	v_pk_fma_f32 v[14:15], v[14:15], s[62:63], v[84:85] op_sel_hi:[1,0,1]
	s_waitcnt lgkmcnt(4)
	v_pk_add_f32 v[84:85], v[16:17], v[86:87]
	v_pk_add_f32 v[16:17], v[16:17], v[86:87] neg_lo:[0,1] neg_hi:[0,1]
	ds_read_b64 v[24:25], v105 offset:1280
	ds_read_b64 v[92:93], v121 offset:3328
	v_xor_b32_e32 v87, 0x80000000, v16
	v_mov_b32_e32 v86, v17
	v_add_u32_e32 v106, v126, v62
	v_bitop3_b32 v64, v21, 6, 15 bitop3:0x6c
	v_add_u32_e32 v122, v126, v94
	v_bitop3_b32 v123, v21, 14, 15 bitop3:0x6c
	v_pk_mul_f32 v[86:87], v[86:87], s[46:47] op_sel_hi:[1,0]
	ds_read_b64 v[62:63], v106 offset:1280
	v_lshlrev_b32_e32 v66, 3, v64
	ds_read_b64 v[94:95], v122 offset:3328
	v_lshlrev_b32_e32 v124, 3, v123
	v_pk_fma_f32 v[16:17], v[16:17], s[58:59], v[86:87] op_sel_hi:[1,0,1]
	s_waitcnt lgkmcnt(6)
	v_pk_add_f32 v[86:87], v[18:19], v[88:89]
	v_pk_add_f32 v[18:19], v[18:19], v[88:89] neg_lo:[0,1] neg_hi:[0,1]
	v_add_u32_e32 v107, v26, v66
	v_add_u32_e32 v123, v26, v124
	v_xor_b32_e32 v89, 0x80000000, v18
	v_mov_b32_e32 v88, v19
	s_waitcnt lgkmcnt(4)
	v_pk_add_f32 v[18:19], v[22:23], v[90:91]
	v_pk_add_f32 v[22:23], v[22:23], v[90:91] neg_lo:[0,1] neg_hi:[0,1]
	ds_read_b64 v[64:65], v107 offset:1536
	ds_read_b64 v[128:129], v123 offset:3584
	v_pk_mul_f32 v[90:91], v[22:23], s[58:59] op_sel_hi:[1,0]
	v_xor_b32_e32 v139, 0x80000000, v22
	v_mov_b32_e32 v138, v23
	v_add_u32_e32 v108, v126, v66
	v_bitop3_b32 v68, v21, 7, 15 bitop3:0x6c
	v_add_u32_e32 v124, v126, v124
	v_bitop3_b32 v21, v21, 15, v21 bitop3:0xc
	v_pk_fma_f32 v[22:23], v[138:139], s[46:47], v[90:91] op_sel_hi:[1,0,1] neg_lo:[0,0,1] neg_hi:[0,0,1]
	s_waitcnt lgkmcnt(4)
	v_pk_add_f32 v[90:91], v[24:25], v[92:93]
	v_pk_add_f32 v[24:25], v[24:25], v[92:93] neg_lo:[0,1] neg_hi:[0,1]
	ds_read_b64 v[66:67], v108 offset:1536
	v_lshlrev_b32_e32 v70, 3, v68
	ds_read_b64 v[130:131], v124 offset:3584
	v_lshlrev_b32_e32 v21, 3, v21
	v_pk_mul_f32 v[92:93], v[24:25], s[62:63] op_sel_hi:[1,0]
	v_xor_b32_e32 v139, 0x80000000, v24
	v_mov_b32_e32 v138, v25
	v_add_u32_e32 v109, v26, v70
	v_add_u32_e32 v125, v26, v21
	v_pk_fma_f32 v[24:25], v[138:139], s[60:61], v[92:93] op_sel_hi:[1,0,1] neg_lo:[0,0,1] neg_hi:[0,0,1]
	s_waitcnt lgkmcnt(4)
	v_pk_add_f32 v[92:93], v[62:63], v[94:95]
	v_pk_add_f32 v[62:63], v[62:63], v[94:95] neg_lo:[0,1] neg_hi:[0,1]
	ds_read_b64 v[68:69], v109 offset:1792
	v_add_u32_e32 v110, v126, v70
	ds_read_b64 v[132:133], v125 offset:3840
	v_add_u32_e32 v126, v126, v21
	v_pk_mul_f32 v[94:95], v[62:63], s[66:67] op_sel_hi:[1,0]
	v_xor_b32_e32 v139, 0x80000000, v62
	v_mov_b32_e32 v138, v63
	ds_read_b64 v[70:71], v110 offset:1792
	ds_read_b64 v[134:135], v126 offset:3840
	v_pk_fma_f32 v[62:63], v[138:139], s[64:65], v[94:95] op_sel_hi:[1,0,1] neg_lo:[0,0,1] neg_hi:[0,0,1]
	s_waitcnt lgkmcnt(6)
	v_pk_add_f32 v[94:95], v[64:65], v[128:129]
	v_pk_add_f32 v[64:65], v[64:65], v[128:129] neg_lo:[0,1] neg_hi:[0,1]
	v_lshl_add_u64 v[0:1], s[44:45], 2, v[28:29]
	v_pk_mul_f32 v[128:129], v[64:65], s[70:71] op_sel_hi:[1,0]
	v_xor_b32_e32 v139, 0x80000000, v64
	v_mov_b32_e32 v138, v65
	v_pk_fma_f32 v[64:65], v[138:139], s[70:71], v[128:129] op_sel_hi:[1,0,1] neg_lo:[0,0,1] neg_hi:[0,0,1]
	s_waitcnt lgkmcnt(4)
	v_pk_add_f32 v[128:129], v[66:67], v[130:131]
	v_pk_add_f32 v[66:67], v[66:67], v[130:131] neg_lo:[0,1] neg_hi:[0,1]
	v_cvt_f32_i32_e32 v20, v20
	v_pk_mul_f32 v[130:131], v[66:67], s[64:65] op_sel_hi:[1,0]
	v_xor_b32_e32 v139, 0x80000000, v66
	v_mov_b32_e32 v138, v67
	v_pk_fma_f32 v[66:67], v[138:139], s[66:67], v[130:131] op_sel_hi:[1,0,1] neg_lo:[0,0,1] neg_hi:[0,0,1]
	s_waitcnt lgkmcnt(2)
	v_pk_add_f32 v[130:131], v[68:69], v[132:133]
	v_pk_add_f32 v[68:69], v[68:69], v[132:133] neg_lo:[0,1] neg_hi:[0,1]
	v_mul_f32_e32 v21, 0x3b000000, v20
	v_pk_mul_f32 v[132:133], v[68:69], s[60:61] op_sel_hi:[1,0]
	v_xor_b32_e32 v139, 0x80000000, v68
	v_mov_b32_e32 v138, v69
	v_pk_fma_f32 v[68:69], v[138:139], s[62:63], v[132:133] op_sel_hi:[1,0,1] neg_lo:[0,0,1] neg_hi:[0,0,1]
	s_waitcnt lgkmcnt(0)
	v_pk_add_f32 v[132:133], v[70:71], v[134:135]
	v_pk_add_f32 v[70:71], v[70:71], v[134:135] neg_lo:[0,1] neg_hi:[0,1]
	v_cos_f32_e32 v20, v21
	v_pk_mul_f32 v[134:135], v[70:71], s[46:47] op_sel_hi:[1,0]
	v_xor_b32_e32 v139, 0x80000000, v70
	v_mov_b32_e32 v138, v71
	v_pk_fma_f32 v[70:71], v[138:139], s[58:59], v[134:135] op_sel_hi:[1,0,1] neg_lo:[0,0,1] neg_hi:[0,0,1]
	v_pk_add_f32 v[134:135], v[136:137], v[86:87]
	v_pk_add_f32 v[86:87], v[136:137], v[86:87] neg_lo:[0,1] neg_hi:[0,1]
	v_pk_add_f32 v[136:137], v[72:73], v[18:19]
	v_pk_add_f32 v[18:19], v[72:73], v[18:19] neg_lo:[0,1] neg_hi:[0,1]
	v_sin_f32_e32 v21, v21
	v_xor_b32_e32 v73, 0x80000000, v18
	v_mov_b32_e32 v72, v19
	v_pk_mul_f32 v[72:73], v[72:73], s[62:63] op_sel_hi:[1,0]
	v_add_f32_e32 v26, v20, v20
	v_pk_fma_f32 v[18:19], v[18:19], s[60:61], v[72:73] op_sel_hi:[1,0,1]
	v_pk_add_f32 v[72:73], v[74:75], v[90:91]
	v_pk_add_f32 v[74:75], v[74:75], v[90:91] neg_lo:[0,1] neg_hi:[0,1]
	v_mul_f32_e32 v26, v21, v26
	v_xor_b32_e32 v91, 0x80000000, v74
	v_mov_b32_e32 v90, v75
	v_pk_mul_f32 v[90:91], v[90:91], s[70:71] op_sel_hi:[1,0]
	s_lshl_b32 s44, s16, 9
	v_pk_fma_f32 v[74:75], v[74:75], s[70:71], v[90:91] op_sel_hi:[1,0,1]
	v_pk_add_f32 v[90:91], v[76:77], v[92:93]
	v_pk_add_f32 v[76:77], v[76:77], v[92:93] neg_lo:[0,1] neg_hi:[0,1]
	s_mov_b64 s[28:29], -1
	v_xor_b32_e32 v93, 0x80000000, v76
	v_mov_b32_e32 v92, v77
	v_pk_mul_f32 v[92:93], v[92:93], s[60:61] op_sel_hi:[1,0]
	s_nop 0
	v_pk_fma_f32 v[76:77], v[76:77], s[62:63], v[92:93] op_sel_hi:[1,0,1]
	v_pk_add_f32 v[92:93], v[78:79], v[94:95]
	v_pk_add_f32 v[78:79], v[78:79], v[94:95] neg_lo:[0,1] neg_hi:[0,1]
	s_nop 0
	v_xor_b32_e32 v95, 0x80000000, v78
	v_mov_b32_e32 v94, v79
	v_pk_add_f32 v[78:79], v[80:81], v[128:129]
	v_pk_add_f32 v[80:81], v[80:81], v[128:129] neg_lo:[0,1] neg_hi:[0,1]
	s_nop 0
	v_pk_mul_f32 v[128:129], v[80:81], s[62:63] op_sel_hi:[1,0]
	v_xor_b32_e32 v139, 0x80000000, v80
	v_mov_b32_e32 v138, v81
	v_pk_fma_f32 v[80:81], v[138:139], s[60:61], v[128:129] op_sel_hi:[1,0,1] neg_lo:[0,0,1] neg_hi:[0,0,1]
	v_pk_add_f32 v[128:129], v[82:83], v[130:131]
	v_pk_add_f32 v[82:83], v[82:83], v[130:131] neg_lo:[0,1] neg_hi:[0,1]
	s_nop 0
	v_pk_mul_f32 v[130:131], v[82:83], s[70:71] op_sel_hi:[1,0]
	v_xor_b32_e32 v139, 0x80000000, v82
	v_mov_b32_e32 v138, v83
	v_pk_fma_f32 v[82:83], v[138:139], s[70:71], v[130:131] op_sel_hi:[1,0,1] neg_lo:[0,0,1] neg_hi:[0,0,1]
	v_pk_add_f32 v[130:131], v[84:85], v[132:133]
	v_pk_add_f32 v[84:85], v[84:85], v[132:133] neg_lo:[0,1] neg_hi:[0,1]
	s_nop 0
	v_pk_mul_f32 v[132:133], v[84:85], s[60:61] op_sel_hi:[1,0]
	v_xor_b32_e32 v139, 0x80000000, v84
	v_mov_b32_e32 v138, v85
	v_pk_fma_f32 v[84:85], v[138:139], s[62:63], v[132:133] op_sel_hi:[1,0,1] neg_lo:[0,0,1] neg_hi:[0,0,1]
	v_pk_add_f32 v[132:133], v[2:3], v[88:89]
	v_pk_add_f32 v[2:3], v[2:3], v[88:89] neg_lo:[0,1] neg_hi:[0,1]
	v_pk_add_f32 v[88:89], v[4:5], v[22:23]
	v_pk_add_f32 v[4:5], v[4:5], v[22:23] neg_lo:[0,1] neg_hi:[0,1]
	s_nop 0
	v_xor_b32_e32 v23, 0x80000000, v4
	v_mov_b32_e32 v22, v5
	v_pk_mul_f32 v[22:23], v[22:23], s[62:63] op_sel_hi:[1,0]
	s_nop 0
	v_pk_fma_f32 v[4:5], v[4:5], s[60:61], v[22:23] op_sel_hi:[1,0,1]
	v_pk_add_f32 v[22:23], v[6:7], v[24:25]
	v_pk_add_f32 v[6:7], v[6:7], v[24:25] neg_lo:[0,1] neg_hi:[0,1]
	s_nop 0
	v_xor_b32_e32 v25, 0x80000000, v6
	v_mov_b32_e32 v24, v7
	v_pk_mul_f32 v[24:25], v[24:25], s[70:71] op_sel_hi:[1,0]
	s_nop 0
	v_pk_fma_f32 v[6:7], v[6:7], s[70:71], v[24:25] op_sel_hi:[1,0,1]
	v_pk_add_f32 v[24:25], v[8:9], v[62:63]
	v_pk_add_f32 v[8:9], v[8:9], v[62:63] neg_lo:[0,1] neg_hi:[0,1]
	s_nop 0
	v_xor_b32_e32 v63, 0x80000000, v8
	v_mov_b32_e32 v62, v9
	v_pk_mul_f32 v[62:63], v[62:63], s[60:61] op_sel_hi:[1,0]
	s_nop 0
	v_pk_fma_f32 v[8:9], v[8:9], s[62:63], v[62:63] op_sel_hi:[1,0,1]
	v_pk_add_f32 v[62:63], v[10:11], v[64:65]
	v_pk_add_f32 v[10:11], v[10:11], v[64:65] neg_lo:[0,1] neg_hi:[0,1]
	s_nop 0
	v_xor_b32_e32 v65, 0x80000000, v10
	v_mov_b32_e32 v64, v11
	v_pk_add_f32 v[10:11], v[12:13], v[66:67]
	v_pk_add_f32 v[12:13], v[12:13], v[66:67] neg_lo:[0,1] neg_hi:[0,1]
	s_nop 0
	v_pk_mul_f32 v[66:67], v[12:13], s[62:63] op_sel_hi:[1,0]
	v_xor_b32_e32 v139, 0x80000000, v12
	v_mov_b32_e32 v138, v13
	v_pk_fma_f32 v[12:13], v[138:139], s[60:61], v[66:67] op_sel_hi:[1,0,1] neg_lo:[0,0,1] neg_hi:[0,0,1]
	v_pk_add_f32 v[66:67], v[14:15], v[68:69]
	v_pk_add_f32 v[14:15], v[14:15], v[68:69] neg_lo:[0,1] neg_hi:[0,1]
	s_nop 0
	v_pk_mul_f32 v[68:69], v[14:15], s[70:71] op_sel_hi:[1,0]
	v_xor_b32_e32 v139, 0x80000000, v14
	v_mov_b32_e32 v138, v15
	v_pk_fma_f32 v[14:15], v[138:139], s[70:71], v[68:69] op_sel_hi:[1,0,1] neg_lo:[0,0,1] neg_hi:[0,0,1]
	v_pk_add_f32 v[68:69], v[16:17], v[70:71]
	v_pk_add_f32 v[16:17], v[16:17], v[70:71] neg_lo:[0,1] neg_hi:[0,1]
	s_nop 0
	v_pk_mul_f32 v[70:71], v[16:17], s[60:61] op_sel_hi:[1,0]
	v_xor_b32_e32 v139, 0x80000000, v16
	v_mov_b32_e32 v138, v17
	v_pk_fma_f32 v[16:17], v[138:139], s[62:63], v[70:71] op_sel_hi:[1,0,1] neg_lo:[0,0,1] neg_hi:[0,0,1]
	v_pk_add_f32 v[70:71], v[134:135], v[92:93]
	v_pk_add_f32 v[92:93], v[134:135], v[92:93] neg_lo:[0,1] neg_hi:[0,1]
	v_pk_add_f32 v[134:135], v[136:137], v[78:79]
	v_pk_add_f32 v[78:79], v[136:137], v[78:79] neg_lo:[0,1] neg_hi:[0,1]
	s_nop 0
	v_xor_b32_e32 v137, 0x80000000, v78
	v_mov_b32_e32 v136, v79
	v_pk_mul_f32 v[136:137], v[136:137], s[70:71] op_sel_hi:[1,0]
	s_nop 0
	v_pk_fma_f32 v[78:79], v[78:79], s[70:71], v[136:137] op_sel_hi:[1,0,1]
	v_pk_add_f32 v[136:137], v[72:73], v[128:129]
	v_pk_add_f32 v[72:73], v[72:73], v[128:129] neg_lo:[0,1] neg_hi:[0,1]
	s_nop 0
	v_xor_b32_e32 v129, 0x80000000, v72
	v_mov_b32_e32 v128, v73
	v_pk_add_f32 v[72:73], v[90:91], v[130:131]
	v_pk_add_f32 v[90:91], v[90:91], v[130:131] neg_lo:[0,1] neg_hi:[0,1]
	s_nop 0
	v_pk_mul_f32 v[130:131], v[90:91], s[70:71] op_sel_hi:[1,0]
	v_xor_b32_e32 v139, 0x80000000, v90
	v_mov_b32_e32 v138, v91
	v_pk_fma_f32 v[90:91], v[138:139], s[70:71], v[130:131] op_sel_hi:[1,0,1] neg_lo:[0,0,1] neg_hi:[0,0,1]
	v_pk_add_f32 v[130:131], v[86:87], v[94:95]
	v_pk_add_f32 v[86:87], v[86:87], v[94:95] neg_lo:[0,1] neg_hi:[0,1]
	v_pk_add_f32 v[94:95], v[18:19], v[80:81]
	v_pk_add_f32 v[18:19], v[18:19], v[80:81] neg_lo:[0,1] neg_hi:[0,1]
	s_nop 0
	v_xor_b32_e32 v81, 0x80000000, v18
	v_mov_b32_e32 v80, v19
	v_pk_mul_f32 v[80:81], v[80:81], s[70:71] op_sel_hi:[1,0]
	s_nop 0
	v_pk_fma_f32 v[18:19], v[18:19], s[70:71], v[80:81] op_sel_hi:[1,0,1]
	v_pk_add_f32 v[80:81], v[74:75], v[82:83]
	v_pk_add_f32 v[74:75], v[74:75], v[82:83] neg_lo:[0,1] neg_hi:[0,1]
	s_nop 0
	v_xor_b32_e32 v83, 0x80000000, v74
	v_mov_b32_e32 v82, v75
	v_pk_add_f32 v[74:75], v[76:77], v[84:85]
	v_pk_add_f32 v[76:77], v[76:77], v[84:85] neg_lo:[0,1] neg_hi:[0,1]
	s_nop 0
	v_pk_mul_f32 v[84:85], v[76:77], s[70:71] op_sel_hi:[1,0]
	v_xor_b32_e32 v139, 0x80000000, v76
	v_mov_b32_e32 v138, v77
	v_pk_fma_f32 v[76:77], v[138:139], s[70:71], v[84:85] op_sel_hi:[1,0,1] neg_lo:[0,0,1] neg_hi:[0,0,1]
	v_pk_add_f32 v[84:85], v[132:133], v[62:63]
	v_pk_add_f32 v[62:63], v[132:133], v[62:63] neg_lo:[0,1] neg_hi:[0,1]
	v_pk_add_f32 v[132:133], v[88:89], v[10:11]
	v_pk_add_f32 v[10:11], v[88:89], v[10:11] neg_lo:[0,1] neg_hi:[0,1]
	s_nop 0
	v_xor_b32_e32 v89, 0x80000000, v10
	v_mov_b32_e32 v88, v11
	v_pk_mul_f32 v[88:89], v[88:89], s[70:71] op_sel_hi:[1,0]
	s_nop 0
	v_pk_fma_f32 v[10:11], v[10:11], s[70:71], v[88:89] op_sel_hi:[1,0,1]
	v_pk_add_f32 v[88:89], v[22:23], v[66:67]
	v_pk_add_f32 v[22:23], v[22:23], v[66:67] neg_lo:[0,1] neg_hi:[0,1]
	s_nop 0
	v_xor_b32_e32 v67, 0x80000000, v22
	v_mov_b32_e32 v66, v23
	v_pk_add_f32 v[22:23], v[24:25], v[68:69]
	v_pk_add_f32 v[24:25], v[24:25], v[68:69] neg_lo:[0,1] neg_hi:[0,1]
	s_nop 0
	v_pk_mul_f32 v[68:69], v[24:25], s[70:71] op_sel_hi:[1,0]
	v_xor_b32_e32 v139, 0x80000000, v24
	v_mov_b32_e32 v138, v25
	v_pk_fma_f32 v[24:25], v[138:139], s[70:71], v[68:69] op_sel_hi:[1,0,1] neg_lo:[0,0,1] neg_hi:[0,0,1]
	v_pk_add_f32 v[68:69], v[2:3], v[64:65]
	v_pk_add_f32 v[2:3], v[2:3], v[64:65] neg_lo:[0,1] neg_hi:[0,1]
	v_pk_add_f32 v[64:65], v[4:5], v[12:13]
	v_pk_add_f32 v[4:5], v[4:5], v[12:13] neg_lo:[0,1] neg_hi:[0,1]
	s_nop 0
	v_xor_b32_e32 v13, 0x80000000, v4
	v_mov_b32_e32 v12, v5
	v_pk_mul_f32 v[12:13], v[12:13], s[70:71] op_sel_hi:[1,0]
	s_nop 0
	v_pk_fma_f32 v[4:5], v[4:5], s[70:71], v[12:13] op_sel_hi:[1,0,1]
	v_pk_add_f32 v[12:13], v[6:7], v[14:15]
	v_pk_add_f32 v[6:7], v[6:7], v[14:15] neg_lo:[0,1] neg_hi:[0,1]
	v_pk_add_f32 v[140:141], v[68:69], v[12:13]
	v_xor_b32_e32 v15, 0x80000000, v6
	v_mov_b32_e32 v14, v7
	v_pk_add_f32 v[6:7], v[8:9], v[16:17]
	v_pk_add_f32 v[8:9], v[8:9], v[16:17] neg_lo:[0,1] neg_hi:[0,1]
	v_pk_add_f32 v[142:143], v[64:65], v[6:7]
	v_pk_mul_f32 v[16:17], v[8:9], s[70:71] op_sel_hi:[1,0]
	v_xor_b32_e32 v139, 0x80000000, v8
	v_mov_b32_e32 v138, v9
	v_pk_fma_f32 v[8:9], v[138:139], s[70:71], v[16:17] op_sel_hi:[1,0,1] neg_lo:[0,0,1] neg_hi:[0,0,1]
	v_pk_add_f32 v[16:17], v[70:71], v[136:137]
	v_pk_add_f32 v[70:71], v[70:71], v[136:137] neg_lo:[0,1] neg_hi:[0,1]
	v_pk_add_f32 v[136:137], v[134:135], v[72:73]
	v_pk_add_f32 v[72:73], v[134:135], v[72:73] neg_lo:[0,1] neg_hi:[0,1]
	v_pk_add_f32 v[138:139], v[84:85], v[88:89] neg_lo:[0,1] neg_hi:[0,1]
	v_xor_b32_e32 v135, 0x80000000, v72
	v_mov_b32_e32 v134, v73
	v_pk_add_f32 v[72:73], v[92:93], v[128:129]
	v_pk_add_f32 v[92:93], v[92:93], v[128:129] neg_lo:[0,1] neg_hi:[0,1]
	v_pk_add_f32 v[128:129], v[78:79], v[90:91]
	v_pk_add_f32 v[78:79], v[78:79], v[90:91] neg_lo:[0,1] neg_hi:[0,1]
	v_pk_add_f32 v[6:7], v[64:65], v[6:7] neg_lo:[0,1] neg_hi:[0,1]
	v_xor_b32_e32 v91, 0x80000000, v78
	v_mov_b32_e32 v90, v79
	v_pk_add_f32 v[78:79], v[130:131], v[80:81]
	v_pk_add_f32 v[130:131], v[130:131], v[80:81] neg_lo:[0,1] neg_hi:[0,1]
	v_pk_add_f32 v[80:81], v[94:95], v[74:75]
	v_pk_add_f32 v[74:75], v[94:95], v[74:75] neg_lo:[0,1] neg_hi:[0,1]
	v_xor_b32_e32 v149, 0x80000000, v6
	v_xor_b32_e32 v95, 0x80000000, v74
	v_mov_b32_e32 v94, v75
	v_pk_add_f32 v[74:75], v[86:87], v[82:83]
	v_pk_add_f32 v[82:83], v[86:87], v[82:83] neg_lo:[0,1] neg_hi:[0,1]
	v_pk_add_f32 v[86:87], v[18:19], v[76:77]
	v_pk_add_f32 v[18:19], v[18:19], v[76:77] neg_lo:[0,1] neg_hi:[0,1]
	v_mov_b32_e32 v148, v7
	v_xor_b32_e32 v77, 0x80000000, v18
	v_mov_b32_e32 v76, v19
	v_pk_add_f32 v[18:19], v[84:85], v[88:89]
	v_pk_add_f32 v[88:89], v[132:133], v[22:23]
	v_pk_add_f32 v[22:23], v[132:133], v[22:23] neg_lo:[0,1] neg_hi:[0,1]
	v_pk_add_f32 v[6:7], v[2:3], v[14:15]
	v_xor_b32_e32 v133, 0x80000000, v22
	v_mov_b32_e32 v132, v23
	v_pk_add_f32 v[22:23], v[62:63], v[66:67]
	v_pk_add_f32 v[62:63], v[62:63], v[66:67] neg_lo:[0,1] neg_hi:[0,1]
	v_pk_add_f32 v[66:67], v[10:11], v[24:25]
	v_pk_add_f32 v[10:11], v[10:11], v[24:25] neg_lo:[0,1] neg_hi:[0,1]
	v_pk_add_f32 v[150:151], v[2:3], v[14:15] neg_lo:[0,1] neg_hi:[0,1]
	v_xor_b32_e32 v25, 0x80000000, v10
	v_mov_b32_e32 v24, v11
	v_pk_add_f32 v[2:3], v[4:5], v[8:9] neg_lo:[0,1] neg_hi:[0,1]
	v_pk_add_f32 v[68:69], v[68:69], v[12:13] neg_lo:[0,1] neg_hi:[0,1]
	v_pk_add_f32 v[156:157], v[4:5], v[8:9]
	v_xor_b32_e32 v159, 0x80000000, v2
	v_mov_b32_e32 v158, v3
	v_pk_add_f32 v[2:3], v[16:17], v[136:137]
	v_pk_add_f32 v[84:85], v[16:17], v[136:137] neg_lo:[0,1] neg_hi:[0,1]
	v_pk_add_f32 v[136:137], v[70:71], v[134:135]
	v_pk_add_f32 v[16:17], v[70:71], v[134:135] neg_lo:[0,1] neg_hi:[0,1]
	v_pk_add_f32 v[134:135], v[72:73], v[128:129]
	v_pk_add_f32 v[70:71], v[72:73], v[128:129] neg_lo:[0,1] neg_hi:[0,1]
	v_pk_add_f32 v[128:129], v[92:93], v[90:91]
	v_pk_add_f32 v[8:9], v[92:93], v[90:91] neg_lo:[0,1] neg_hi:[0,1]
	v_pk_add_f32 v[72:73], v[78:79], v[80:81]
	v_pk_add_f32 v[80:81], v[78:79], v[80:81] neg_lo:[0,1] neg_hi:[0,1]
	v_pk_add_f32 v[92:93], v[130:131], v[94:95]
	v_pk_add_f32 v[12:13], v[130:131], v[94:95] neg_lo:[0,1] neg_hi:[0,1]
	v_pk_add_f32 v[78:79], v[74:75], v[86:87]
	v_pk_add_f32 v[64:65], v[74:75], v[86:87] neg_lo:[0,1] neg_hi:[0,1]
	v_pk_add_f32 v[130:131], v[82:83], v[76:77]
	v_pk_add_f32 v[4:5], v[82:83], v[76:77] neg_lo:[0,1] neg_hi:[0,1]
	v_pk_add_f32 v[76:77], v[18:19], v[88:89]
	v_pk_add_f32 v[88:89], v[18:19], v[88:89] neg_lo:[0,1] neg_hi:[0,1]
	v_pk_add_f32 v[86:87], v[138:139], v[132:133]
	v_pk_add_f32 v[18:19], v[138:139], v[132:133] neg_lo:[0,1] neg_hi:[0,1]
	v_pk_add_f32 v[132:133], v[62:63], v[24:25]
	v_pk_add_f32 v[10:11], v[62:63], v[24:25] neg_lo:[0,1] neg_hi:[0,1]
	v_pk_mul_f32 v[24:25], v[20:21], v[20:21]
	v_xor_b32_e32 v62, 0x80000000, v21
	v_mov_b32_e32 v63, v20
	v_pk_add_f32 v[24:25], v[24:25], v[24:25] op_sel:[0,1] op_sel_hi:[0,1] neg_lo:[0,1] neg_hi:[0,1]
	v_pk_mul_f32 v[62:63], v[62:63], v[26:27] op_sel_hi:[1,0]
	v_pk_add_f32 v[90:91], v[22:23], v[66:67]
	v_pk_add_f32 v[74:75], v[22:23], v[66:67] neg_lo:[0,1] neg_hi:[0,1]
	v_pk_add_f32 v[22:23], v[140:141], v[142:143]
	v_pk_add_f32 v[82:83], v[140:141], v[142:143] neg_lo:[0,1] neg_hi:[0,1]
	v_pk_add_f32 v[138:139], v[68:69], v[148:149]
	v_pk_add_f32 v[14:15], v[68:69], v[148:149] neg_lo:[0,1] neg_hi:[0,1]
	v_pk_fma_f32 v[68:69], v[20:21], v[24:25], v[62:63]
	v_xor_b32_e32 v63, 0x80000000, v76
	v_mov_b32_e32 v62, v77
	v_mov_b32_e32 v142, v21
	v_pk_mul_f32 v[62:63], v[142:143], v[62:63] op_sel_hi:[0,1]
	v_pk_fma_f32 v[20:21], v[20:21], v[76:77], v[62:63] op_sel_hi:[0,1,1]
	v_pk_mul_f32 v[62:63], v[26:27], s[48:49] op_sel_hi:[0,1]
	v_pk_fma_f32 v[76:77], v[24:25], s[40:41], v[62:63]
	v_xor_b32_e32 v63, 0x80000000, v72
	v_mov_b32_e32 v62, v73
	v_pk_mul_f32 v[62:63], v[76:77], v[62:63] op_sel:[1,0]
	v_pk_add_f32 v[94:95], v[6:7], v[156:157]
	v_pk_fma_f32 v[62:63], v[72:73], v[76:77], v[62:63] op_sel_hi:[1,0,1]
	v_xor_b32_e32 v72, 0x80000000, v69
	v_mov_b32_e32 v73, v68
	v_pk_mul_f32 v[72:73], v[26:27], v[72:73] op_sel_hi:[0,1]
	v_pk_fma_f32 v[142:143], v[24:25], v[68:69], v[72:73]
	v_xor_b32_e32 v73, 0x80000000, v22
	v_mov_b32_e32 v72, v23
	v_pk_mul_f32 v[72:73], v[68:69], v[72:73] op_sel:[1,0]
	v_pk_add_f32 v[140:141], v[150:151], v[158:159]
	v_pk_fma_f32 v[22:23], v[68:69], v[22:23], v[72:73] op_sel_hi:[0,1,1]
	v_xor_b32_e32 v68, 0x80000000, v77
	v_mov_b32_e32 v69, v76
	v_pk_mul_f32 v[68:69], v[26:27], v[68:69] op_sel_hi:[0,1]
	v_pk_fma_f32 v[76:77], v[24:25], v[76:77], v[68:69]
	v_xor_b32_e32 v69, 0x80000000, v134
	v_mov_b32_e32 v68, v135
	v_pk_mul_f32 v[68:69], v[68:69], v[76:77] op_sel:[0,1]
	v_pk_add_f32 v[66:67], v[6:7], v[156:157] neg_lo:[0,1] neg_hi:[0,1]
	v_pk_fma_f32 v[72:73], v[134:135], v[76:77], v[68:69] op_sel_hi:[1,0,1]
	v_xor_b32_e32 v68, 0x80000000, v143
	v_mov_b32_e32 v69, v142
	v_pk_mul_f32 v[68:69], v[26:27], v[68:69] op_sel_hi:[0,1]
	v_pk_fma_f32 v[134:135], v[24:25], v[142:143], v[68:69]
	v_xor_b32_e32 v69, 0x80000000, v90
	v_mov_b32_e32 v68, v91
	v_pk_mul_f32 v[68:69], v[142:143], v[68:69] op_sel:[1,0]
	v_pk_add_f32 v[6:7], v[150:151], v[158:159] neg_lo:[0,1] neg_hi:[0,1]
	v_pk_fma_f32 v[68:69], v[90:91], v[142:143], v[68:69] op_sel_hi:[1,0,1]
	v_xor_b32_e32 v90, 0x80000000, v77
	v_mov_b32_e32 v91, v76
	v_pk_mul_f32 v[90:91], v[26:27], v[90:91] op_sel_hi:[0,1]
	v_pk_fma_f32 v[90:91], v[24:25], v[76:77], v[90:91]
	v_xor_b32_e32 v77, 0x80000000, v78
	v_mov_b32_e32 v76, v79
	v_pk_mul_f32 v[76:77], v[76:77], v[90:91] op_sel:[0,1]
	s_nop 0
	v_pk_fma_f32 v[78:79], v[78:79], v[90:91], v[76:77] op_sel_hi:[1,0,1]
	v_xor_b32_e32 v76, 0x80000000, v135
	v_mov_b32_e32 v77, v134
	v_pk_mul_f32 v[76:77], v[26:27], v[76:77] op_sel_hi:[0,1]
	v_pk_fma_f32 v[142:143], v[24:25], v[134:135], v[76:77]
	v_xor_b32_e32 v77, 0x80000000, v94
	v_mov_b32_e32 v76, v95
	v_pk_mul_f32 v[76:77], v[134:135], v[76:77] op_sel:[1,0]
	s_nop 0
	v_pk_fma_f32 v[76:77], v[94:95], v[134:135], v[76:77] op_sel_hi:[1,0,1]
	v_xor_b32_e32 v94, 0x80000000, v91
	v_mov_b32_e32 v95, v90
	v_pk_mul_f32 v[94:95], v[26:27], v[94:95] op_sel_hi:[0,1]
	v_pk_fma_f32 v[94:95], v[24:25], v[90:91], v[94:95]
	v_xor_b32_e32 v91, 0x80000000, v136
	v_mov_b32_e32 v90, v137
	v_pk_mul_f32 v[90:91], v[90:91], v[94:95] op_sel:[0,1]
	v_xor_b32_e32 v134, 0x80000000, v143
	v_pk_fma_f32 v[90:91], v[136:137], v[94:95], v[90:91] op_sel_hi:[1,0,1]
	v_xor_b32_e32 v137, 0x80000000, v86
	v_mov_b32_e32 v136, v87
	v_pk_mul_f32 v[136:137], v[136:137], v[142:143] op_sel:[0,1]
	v_mov_b32_e32 v135, v142
	v_pk_fma_f32 v[86:87], v[86:87], v[142:143], v[136:137] op_sel_hi:[1,0,1]
	v_xor_b32_e32 v136, 0x80000000, v95
	v_mov_b32_e32 v137, v94
	v_pk_mul_f32 v[136:137], v[26:27], v[136:137] op_sel_hi:[0,1]
	v_pk_mul_f32 v[134:135], v[26:27], v[134:135] op_sel_hi:[0,1]
	v_pk_fma_f32 v[136:137], v[24:25], v[94:95], v[136:137]
	v_xor_b32_e32 v95, 0x80000000, v92
	v_mov_b32_e32 v94, v93
	v_pk_fma_f32 v[134:135], v[24:25], v[142:143], v[134:135]
	v_pk_mul_f32 v[94:95], v[94:95], v[136:137] op_sel:[0,1]
	s_nop 0
	v_pk_fma_f32 v[94:95], v[92:93], v[136:137], v[94:95] op_sel_hi:[1,0,1]
	v_xor_b32_e32 v92, 0x80000000, v135
	v_mov_b32_e32 v93, v134
	v_pk_mul_f32 v[92:93], v[26:27], v[92:93] op_sel_hi:[0,1]
	v_pk_fma_f32 v[142:143], v[24:25], v[134:135], v[92:93]
	v_xor_b32_e32 v93, 0x80000000, v138
	v_mov_b32_e32 v92, v139
	v_pk_mul_f32 v[92:93], v[92:93], v[134:135] op_sel:[0,1]
	s_nop 0
	v_pk_fma_f32 v[92:93], v[138:139], v[134:135], v[92:93] op_sel_hi:[1,0,1]
	v_xor_b32_e32 v134, 0x80000000, v137
	v_mov_b32_e32 v135, v136
	v_pk_mul_f32 v[134:135], v[26:27], v[134:135] op_sel_hi:[0,1]
	v_xor_b32_e32 v139, 0x80000000, v132
	v_mov_b32_e32 v138, v133
	v_pk_fma_f32 v[134:135], v[24:25], v[136:137], v[134:135]
	v_xor_b32_e32 v137, 0x80000000, v128
	v_mov_b32_e32 v136, v129
	v_pk_mul_f32 v[138:139], v[138:139], v[142:143] op_sel:[0,1]
	v_pk_mul_f32 v[136:137], v[136:137], v[134:135] op_sel:[0,1]
	v_pk_fma_f32 v[132:133], v[132:133], v[142:143], v[138:139] op_sel_hi:[1,0,1]
	v_xor_b32_e32 v138, 0x80000000, v135
	v_mov_b32_e32 v139, v134
	v_pk_fma_f32 v[128:129], v[128:129], v[134:135], v[136:137] op_sel_hi:[1,0,1]
	v_xor_b32_e32 v136, 0x80000000, v143
	v_mov_b32_e32 v137, v142
	v_pk_mul_f32 v[138:139], v[26:27], v[138:139] op_sel_hi:[0,1]
	v_pk_mul_f32 v[136:137], v[26:27], v[136:137] op_sel_hi:[0,1]
	v_pk_fma_f32 v[134:135], v[24:25], v[134:135], v[138:139]
	v_xor_b32_e32 v139, 0x80000000, v130
	v_mov_b32_e32 v138, v131
	v_pk_fma_f32 v[136:137], v[24:25], v[142:143], v[136:137]
	v_pk_mul_f32 v[138:139], v[138:139], v[134:135] op_sel:[0,1]
	v_xor_b32_e32 v143, 0x80000000, v140
	v_pk_fma_f32 v[130:131], v[130:131], v[134:135], v[138:139] op_sel_hi:[1,0,1]
	v_xor_b32_e32 v138, 0x80000000, v137
	v_mov_b32_e32 v139, v136
	v_mov_b32_e32 v142, v141
	v_pk_mul_f32 v[138:139], v[26:27], v[138:139] op_sel_hi:[0,1]
	v_pk_mul_f32 v[142:143], v[142:143], v[136:137] op_sel:[0,1]
	v_pk_fma_f32 v[138:139], v[24:25], v[136:137], v[138:139]
	v_pk_fma_f32 v[136:137], v[140:141], v[136:137], v[142:143] op_sel_hi:[1,0,1]
	v_xor_b32_e32 v140, 0x80000000, v135
	v_mov_b32_e32 v141, v134
	v_pk_mul_f32 v[140:141], v[26:27], v[140:141] op_sel_hi:[0,1]
	v_pk_fma_f32 v[134:135], v[24:25], v[134:135], v[140:141]
	v_xor_b32_e32 v141, 0x80000000, v84
	v_mov_b32_e32 v140, v85
	v_pk_mul_f32 v[140:141], v[140:141], v[134:135] op_sel:[0,1]
	v_xor_b32_e32 v143, 0x80000000, v88
	v_pk_fma_f32 v[84:85], v[84:85], v[134:135], v[140:141] op_sel_hi:[1,0,1]
	v_xor_b32_e32 v140, 0x80000000, v139
	v_mov_b32_e32 v141, v138
	v_mov_b32_e32 v142, v89
	v_pk_mul_f32 v[140:141], v[26:27], v[140:141] op_sel_hi:[0,1]
	v_pk_mul_f32 v[142:143], v[142:143], v[138:139] op_sel:[0,1]
	v_pk_fma_f32 v[140:141], v[24:25], v[138:139], v[140:141]
	v_pk_fma_f32 v[88:89], v[88:89], v[138:139], v[142:143] op_sel_hi:[1,0,1]
	v_xor_b32_e32 v138, 0x80000000, v135
	v_mov_b32_e32 v139, v134
	v_pk_mul_f32 v[138:139], v[26:27], v[138:139] op_sel_hi:[0,1]
	v_pk_fma_f32 v[134:135], v[24:25], v[134:135], v[138:139]
	v_xor_b32_e32 v139, 0x80000000, v80
	v_mov_b32_e32 v138, v81
	v_pk_mul_f32 v[138:139], v[138:139], v[134:135] op_sel:[0,1]
	v_xor_b32_e32 v143, 0x80000000, v82
	v_pk_fma_f32 v[80:81], v[80:81], v[134:135], v[138:139] op_sel_hi:[1,0,1]
	v_xor_b32_e32 v138, 0x80000000, v141
	v_mov_b32_e32 v139, v140
	v_mov_b32_e32 v142, v83
	v_pk_mul_f32 v[138:139], v[26:27], v[138:139] op_sel_hi:[0,1]
	v_pk_mul_f32 v[142:143], v[142:143], v[140:141] op_sel:[0,1]
	v_pk_fma_f32 v[138:139], v[24:25], v[140:141], v[138:139]
	v_pk_fma_f32 v[82:83], v[82:83], v[140:141], v[142:143] op_sel_hi:[1,0,1]
	v_xor_b32_e32 v140, 0x80000000, v135
	v_mov_b32_e32 v141, v134
	v_pk_mul_f32 v[140:141], v[26:27], v[140:141] op_sel_hi:[0,1]
	v_pk_fma_f32 v[134:135], v[24:25], v[134:135], v[140:141]
	v_xor_b32_e32 v141, 0x80000000, v70
	v_mov_b32_e32 v140, v71
	v_pk_mul_f32 v[140:141], v[140:141], v[134:135] op_sel:[0,1]
	v_xor_b32_e32 v143, 0x80000000, v74
	v_pk_fma_f32 v[70:71], v[70:71], v[134:135], v[140:141] op_sel_hi:[1,0,1]
	v_xor_b32_e32 v140, 0x80000000, v139
	v_mov_b32_e32 v141, v138
	v_mov_b32_e32 v142, v75
	v_pk_mul_f32 v[140:141], v[26:27], v[140:141] op_sel_hi:[0,1]
	v_pk_mul_f32 v[142:143], v[142:143], v[138:139] op_sel:[0,1]
	v_pk_fma_f32 v[140:141], v[24:25], v[138:139], v[140:141]
	v_pk_fma_f32 v[74:75], v[74:75], v[138:139], v[142:143] op_sel_hi:[1,0,1]
	v_xor_b32_e32 v138, 0x80000000, v135
	v_mov_b32_e32 v139, v134
	v_pk_mul_f32 v[138:139], v[26:27], v[138:139] op_sel_hi:[0,1]
	v_pk_fma_f32 v[134:135], v[24:25], v[134:135], v[138:139]
	v_xor_b32_e32 v139, 0x80000000, v64
	v_mov_b32_e32 v138, v65
	v_pk_mul_f32 v[138:139], v[138:139], v[134:135] op_sel:[0,1]
	v_xor_b32_e32 v143, 0x80000000, v66
	v_pk_fma_f32 v[64:65], v[64:65], v[134:135], v[138:139] op_sel_hi:[1,0,1]
	v_xor_b32_e32 v138, 0x80000000, v141
	v_mov_b32_e32 v139, v140
	v_mov_b32_e32 v142, v67
	v_pk_mul_f32 v[138:139], v[26:27], v[138:139] op_sel_hi:[0,1]
	v_pk_mul_f32 v[142:143], v[142:143], v[140:141] op_sel:[0,1]
	v_pk_fma_f32 v[138:139], v[24:25], v[140:141], v[138:139]
	v_pk_fma_f32 v[66:67], v[66:67], v[140:141], v[142:143] op_sel_hi:[1,0,1]
	v_xor_b32_e32 v140, 0x80000000, v135
	v_mov_b32_e32 v141, v134
	v_pk_mul_f32 v[140:141], v[26:27], v[140:141] op_sel_hi:[0,1]
	v_pk_fma_f32 v[134:135], v[24:25], v[134:135], v[140:141]
	v_xor_b32_e32 v141, 0x80000000, v16
	v_mov_b32_e32 v140, v17
	v_pk_mul_f32 v[140:141], v[140:141], v[134:135] op_sel:[0,1]
	v_xor_b32_e32 v143, 0x80000000, v18
	v_pk_fma_f32 v[16:17], v[16:17], v[134:135], v[140:141] op_sel_hi:[1,0,1]
	v_xor_b32_e32 v140, 0x80000000, v139
	v_mov_b32_e32 v141, v138
	v_mov_b32_e32 v142, v19
	v_pk_mul_f32 v[140:141], v[26:27], v[140:141] op_sel_hi:[0,1]
	v_pk_mul_f32 v[142:143], v[142:143], v[138:139] op_sel:[0,1]
	v_pk_fma_f32 v[140:141], v[24:25], v[138:139], v[140:141]
	v_pk_fma_f32 v[18:19], v[18:19], v[138:139], v[142:143] op_sel_hi:[1,0,1]
	v_xor_b32_e32 v138, 0x80000000, v135
	v_mov_b32_e32 v139, v134
	v_pk_mul_f32 v[138:139], v[26:27], v[138:139] op_sel_hi:[0,1]
	v_pk_fma_f32 v[134:135], v[24:25], v[134:135], v[138:139]
	v_xor_b32_e32 v139, 0x80000000, v12
	v_mov_b32_e32 v138, v13
	v_pk_mul_f32 v[138:139], v[138:139], v[134:135] op_sel:[0,1]
	v_xor_b32_e32 v143, 0x80000000, v14
	v_pk_fma_f32 v[12:13], v[12:13], v[134:135], v[138:139] op_sel_hi:[1,0,1]
	v_xor_b32_e32 v138, 0x80000000, v141
	v_mov_b32_e32 v139, v140
	v_mov_b32_e32 v142, v15
	v_pk_mul_f32 v[138:139], v[26:27], v[138:139] op_sel_hi:[0,1]
	v_pk_mul_f32 v[142:143], v[142:143], v[140:141] op_sel:[0,1]
	v_pk_fma_f32 v[138:139], v[24:25], v[140:141], v[138:139]
	v_pk_fma_f32 v[14:15], v[14:15], v[140:141], v[142:143] op_sel_hi:[1,0,1]
	v_xor_b32_e32 v140, 0x80000000, v135
	v_mov_b32_e32 v141, v134
	v_pk_mul_f32 v[140:141], v[26:27], v[140:141] op_sel_hi:[0,1]
	v_pk_fma_f32 v[134:135], v[24:25], v[134:135], v[140:141]
	v_xor_b32_e32 v141, 0x80000000, v8
	v_mov_b32_e32 v140, v9
	v_pk_mul_f32 v[140:141], v[140:141], v[134:135] op_sel:[0,1]
	v_xor_b32_e32 v143, 0x80000000, v10
	v_pk_fma_f32 v[8:9], v[8:9], v[134:135], v[140:141] op_sel_hi:[1,0,1]
	v_xor_b32_e32 v140, 0x80000000, v139
	v_mov_b32_e32 v141, v138
	v_mov_b32_e32 v142, v11
	v_pk_mul_f32 v[140:141], v[26:27], v[140:141] op_sel_hi:[0,1]
	v_pk_mul_f32 v[142:143], v[142:143], v[138:139] op_sel:[0,1]
	v_pk_fma_f32 v[140:141], v[24:25], v[138:139], v[140:141]
	v_pk_fma_f32 v[10:11], v[10:11], v[138:139], v[142:143] op_sel_hi:[1,0,1]
	v_xor_b32_e32 v138, 0x80000000, v135
	v_mov_b32_e32 v139, v134
	v_pk_mul_f32 v[138:139], v[26:27], v[138:139] op_sel_hi:[0,1]
	v_pk_fma_f32 v[24:25], v[24:25], v[134:135], v[138:139]
	v_xor_b32_e32 v135, 0x80000000, v4
	v_mov_b32_e32 v134, v5
	v_pk_mul_f32 v[134:135], v[134:135], v[24:25] op_sel:[0,1]
	s_nop 0
	v_pk_fma_f32 v[4:5], v[4:5], v[24:25], v[134:135] op_sel_hi:[1,0,1]
	v_xor_b32_e32 v25, 0x80000000, v6
	v_mov_b32_e32 v24, v7
	v_pk_mul_f32 v[24:25], v[24:25], v[140:141] op_sel:[0,1]
	s_nop 0
	v_pk_fma_f32 v[6:7], v[6:7], v[140:141], v[24:25] op_sel_hi:[1,0,1]
	ds_write_b64 v27, v[2:3]
	ds_write_b64 v96, v[84:85]
	ds_write_b64 v97, v[90:91] offset:256
	ds_write_b64 v98, v[16:17] offset:256
	ds_write_b64 v99, v[72:73] offset:512
	ds_write_b64 v100, v[70:71] offset:512
	ds_write_b64 v101, v[128:129] offset:768
	ds_write_b64 v102, v[8:9] offset:768
	ds_write_b64 v103, v[62:63] offset:1024
	ds_write_b64 v104, v[80:81] offset:1024
	ds_write_b64 v105, v[94:95] offset:1280
	ds_write_b64 v106, v[12:13] offset:1280
	ds_write_b64 v107, v[78:79] offset:1536
	ds_write_b64 v108, v[64:65] offset:1536
	ds_write_b64 v109, v[130:131] offset:1792
	ds_write_b64 v110, v[4:5] offset:1792
	ds_write_b64 v111, v[20:21] offset:2048
	ds_write_b64 v112, v[88:89] offset:2048
	ds_write_b64 v113, v[86:87] offset:2304
	ds_write_b64 v114, v[18:19] offset:2304
	ds_write_b64 v115, v[68:69] offset:2560
	ds_write_b64 v116, v[74:75] offset:2560
	ds_write_b64 v117, v[132:133] offset:2816
	ds_write_b64 v118, v[10:11] offset:2816
	ds_write_b64 v119, v[22:23] offset:3072
	ds_write_b64 v120, v[82:83] offset:3072
	ds_write_b64 v121, v[92:93] offset:3328
	ds_write_b64 v122, v[14:15] offset:3328
	ds_write_b64 v123, v[76:77] offset:3584
	ds_write_b64 v124, v[66:67] offset:3584
	ds_write_b64 v125, v[136:137] offset:3840
	ds_write_b64 v126, v[6:7] offset:3840
	v_mov_b32_e32 v2, v146
	s_waitcnt lgkmcnt(0)
	s_barrier
	s_nop 0
	v_lshlrev_b32_e32 v3, 4, v2
	v_lshrrev_b32_e32 v4, 1, v2
	v_bfe_u32 v2, v2, 1, 4
	v_bitop3_b32 v5, v4, v3, 16 bitop3:0x6c
	v_lshl_add_u32 v5, v5, 3, 16
	v_lshlrev_b32_e32 v2, 3, v2
	v_add_u32_e32 v6, v5, v2
	ds_read_b64 v[12:13], v6
	v_bitop3_b32 v6, v4, 1, 15 bitop3:0x6c
	v_lshlrev_b32_e32 v8, 3, v6
	v_add_u32_e32 v6, v5, v8
	ds_read_b64 v[14:15], v6
	v_bitop3_b32 v6, v4, 2, 15 bitop3:0x6c
	v_lshlrev_b32_e32 v9, 3, v6
	v_add_u32_e32 v6, v5, v9
	ds_read_b64 v[16:17], v6
	v_bitop3_b32 v6, v4, 3, 15 bitop3:0x6c
	v_lshlrev_b32_e32 v10, 3, v6
	v_add_u32_e32 v6, v5, v10
	ds_read_b64 v[18:19], v6
	v_bitop3_b32 v6, v4, 4, 15 bitop3:0x6c
	v_lshlrev_b32_e32 v11, 3, v6
	v_add_u32_e32 v6, v5, v11
	ds_read_b64 v[20:21], v6
	v_bitop3_b32 v6, v4, 5, 15 bitop3:0x6c
	v_lshlrev_b32_e32 v82, 3, v6
	v_add_u32_e32 v6, v5, v82
	ds_read_b64 v[22:23], v6
	v_bitop3_b32 v6, v4, 6, 15 bitop3:0x6c
	v_lshlrev_b32_e32 v83, 3, v6
	v_add_u32_e32 v6, v5, v83
	ds_read_b64 v[24:25], v6
	v_bitop3_b32 v6, v4, 7, 15 bitop3:0x6c
	v_lshlrev_b32_e32 v84, 3, v6
	v_add_u32_e32 v6, v5, v84
	ds_read_b64 v[26:27], v6
	v_bitop3_b32 v6, v4, 8, 15 bitop3:0x6c
	v_lshlrev_b32_e32 v85, 3, v6
	v_add_u32_e32 v6, v5, v85
	ds_read_b64 v[62:63], v6
	v_bitop3_b32 v6, v4, 9, 15 bitop3:0x6c
	v_lshlrev_b32_e32 v86, 3, v6
	v_add_u32_e32 v6, v5, v86
	ds_read_b64 v[64:65], v6
	v_bitop3_b32 v6, v4, 10, 15 bitop3:0x6c
	v_lshlrev_b32_e32 v87, 3, v6
	v_add_u32_e32 v6, v5, v87
	ds_read_b64 v[66:67], v6
	v_bitop3_b32 v6, v4, 11, 15 bitop3:0x6c
	v_lshlrev_b32_e32 v88, 3, v6
	v_add_u32_e32 v6, v5, v88
	ds_read_b64 v[68:69], v6
	v_bitop3_b32 v6, v4, 12, 15 bitop3:0x6c
	v_lshlrev_b32_e32 v89, 3, v6
	v_add_u32_e32 v6, v5, v89
	ds_read_b64 v[70:71], v6
	v_bitop3_b32 v6, v4, 13, 15 bitop3:0x6c
	v_lshlrev_b32_e32 v90, 3, v6
	v_add_u32_e32 v6, v5, v90
	ds_read_b64 v[72:73], v6
	v_bitop3_b32 v6, v4, 14, 15 bitop3:0x6c
	v_lshlrev_b32_e32 v91, 3, v6
	v_add_u32_e32 v6, v5, v91
	v_add_u32_e32 v3, 0x2000, v3
	ds_read_b64 v[74:75], v6
	v_bitop3_b32 v6, v4, 15, v4 bitop3:0xc
	v_bitop3_b32 v3, v3, v4, 16 bitop3:0x78
	v_lshlrev_b32_e32 v106, 3, v6
	v_lshl_add_u32 v107, v3, 3, 16
	v_add_u32_e32 v5, v5, v106
	v_add_u32_e32 v2, v107, v2
	ds_read_b64 v[76:77], v5
	ds_read_b64 v[6:7], v2
	v_add_u32_e32 v2, v107, v8
	ds_read_b64 v[78:79], v2
	v_add_u32_e32 v2, v107, v9
	ds_read_b64 v[8:9], v2
	v_add_u32_e32 v2, v107, v10
	ds_read_b64 v[80:81], v2
	v_add_u32_e32 v2, v107, v11
	ds_read_b64 v[10:11], v2
	v_add_u32_e32 v2, v107, v82
	v_add_u32_e32 v82, v107, v84
	v_add_u32_e32 v84, v107, v85
	ds_read_b64 v[4:5], v2
	ds_read_b64 v[92:93], v84
	v_add_u32_e32 v2, v107, v83
	v_add_u32_e32 v84, v107, v86
	ds_read_b64 v[2:3], v2
	ds_read_b64 v[82:83], v82
	ds_read_b64 v[94:95], v84
	v_add_u32_e32 v84, v107, v87
	ds_read_b64 v[96:97], v84
	v_add_u32_e32 v84, v107, v88
	ds_read_b64 v[98:99], v84
	v_add_u32_e32 v84, v107, v89
	ds_read_b64 v[100:101], v84
	v_add_u32_e32 v84, v107, v90
	ds_read_b64 v[102:103], v84
	v_add_u32_e32 v84, v107, v91
	ds_read_b64 v[104:105], v84
	v_add_u32_e32 v84, v107, v106
	ds_read_b64 v[106:107], v84
	s_waitcnt lgkmcnt(14)
	v_pk_add_f32 v[84:85], v[12:13], v[62:63]
	v_pk_add_f32 v[12:13], v[12:13], v[62:63] neg_lo:[0,1] neg_hi:[0,1]
	v_pk_add_f32 v[62:63], v[14:15], v[64:65]
	v_pk_add_f32 v[14:15], v[14:15], v[64:65] neg_lo:[0,1] neg_hi:[0,1]
	s_nop 0
	v_xor_b32_e32 v65, 0x80000000, v14
	v_mov_b32_e32 v64, v15
	v_pk_mul_f32 v[64:65], v[64:65], s[62:63] op_sel_hi:[1,0]
	s_nop 0
	v_pk_fma_f32 v[14:15], v[14:15], s[60:61], v[64:65] op_sel_hi:[1,0,1]
	v_pk_add_f32 v[64:65], v[16:17], v[66:67]
	v_pk_add_f32 v[16:17], v[16:17], v[66:67] neg_lo:[0,1] neg_hi:[0,1]
	s_nop 0
	v_xor_b32_e32 v67, 0x80000000, v16
	v_mov_b32_e32 v66, v17
	v_pk_mul_f32 v[66:67], v[66:67], s[70:71] op_sel_hi:[1,0]
	s_nop 0
	v_pk_fma_f32 v[16:17], v[16:17], s[70:71], v[66:67] op_sel_hi:[1,0,1]
	v_pk_add_f32 v[66:67], v[18:19], v[68:69]
	v_pk_add_f32 v[18:19], v[18:19], v[68:69] neg_lo:[0,1] neg_hi:[0,1]
	s_nop 0
	v_xor_b32_e32 v69, 0x80000000, v18
	v_mov_b32_e32 v68, v19
	v_pk_mul_f32 v[68:69], v[68:69], s[60:61] op_sel_hi:[1,0]
	s_nop 0
	v_pk_fma_f32 v[18:19], v[18:19], s[62:63], v[68:69] op_sel_hi:[1,0,1]
	v_pk_add_f32 v[68:69], v[20:21], v[70:71]
	v_pk_add_f32 v[20:21], v[20:21], v[70:71] neg_lo:[0,1] neg_hi:[0,1]
	s_nop 0
	v_xor_b32_e32 v71, 0x80000000, v20
	v_mov_b32_e32 v70, v21
	v_pk_add_f32 v[20:21], v[22:23], v[72:73]
	v_pk_add_f32 v[22:23], v[22:23], v[72:73] neg_lo:[0,1] neg_hi:[0,1]
	s_nop 0
	v_pk_mul_f32 v[72:73], v[22:23], s[62:63] op_sel_hi:[1,0]
	v_xor_b32_e32 v87, 0x80000000, v22
	v_mov_b32_e32 v86, v23
	v_pk_fma_f32 v[22:23], v[86:87], s[60:61], v[72:73] op_sel_hi:[1,0,1] neg_lo:[0,0,1] neg_hi:[0,0,1]
	v_pk_add_f32 v[72:73], v[24:25], v[74:75]
	v_pk_add_f32 v[24:25], v[24:25], v[74:75] neg_lo:[0,1] neg_hi:[0,1]
	s_nop 0
	v_pk_mul_f32 v[74:75], v[24:25], s[70:71] op_sel_hi:[1,0]
	v_xor_b32_e32 v87, 0x80000000, v24
	v_mov_b32_e32 v86, v25
	v_pk_fma_f32 v[24:25], v[86:87], s[70:71], v[74:75] op_sel_hi:[1,0,1] neg_lo:[0,0,1] neg_hi:[0,0,1]
	v_pk_add_f32 v[74:75], v[26:27], v[76:77]
	v_pk_add_f32 v[26:27], v[26:27], v[76:77] neg_lo:[0,1] neg_hi:[0,1]
	s_nop 0
	v_pk_mul_f32 v[76:77], v[26:27], s[60:61] op_sel_hi:[1,0]
	v_xor_b32_e32 v87, 0x80000000, v26
	v_mov_b32_e32 v86, v27
	v_pk_fma_f32 v[26:27], v[86:87], s[62:63], v[76:77] op_sel_hi:[1,0,1] neg_lo:[0,0,1] neg_hi:[0,0,1]
	v_pk_add_f32 v[76:77], v[84:85], v[68:69]
	v_pk_add_f32 v[68:69], v[84:85], v[68:69] neg_lo:[0,1] neg_hi:[0,1]
	v_pk_add_f32 v[84:85], v[62:63], v[20:21]
	v_pk_add_f32 v[20:21], v[62:63], v[20:21] neg_lo:[0,1] neg_hi:[0,1]
	s_nop 0
	v_xor_b32_e32 v63, 0x80000000, v20
	v_mov_b32_e32 v62, v21
	v_pk_mul_f32 v[62:63], v[62:63], s[70:71] op_sel_hi:[1,0]
	s_nop 0
	v_pk_fma_f32 v[20:21], v[20:21], s[70:71], v[62:63] op_sel_hi:[1,0,1]
	v_pk_add_f32 v[62:63], v[64:65], v[72:73]
	v_pk_add_f32 v[64:65], v[64:65], v[72:73] neg_lo:[0,1] neg_hi:[0,1]
	s_nop 0
	v_xor_b32_e32 v73, 0x80000000, v64
	v_mov_b32_e32 v72, v65
	v_pk_add_f32 v[64:65], v[66:67], v[74:75]
	v_pk_add_f32 v[66:67], v[66:67], v[74:75] neg_lo:[0,1] neg_hi:[0,1]
	s_nop 0
	v_pk_mul_f32 v[74:75], v[66:67], s[70:71] op_sel_hi:[1,0]
	v_xor_b32_e32 v87, 0x80000000, v66
	v_mov_b32_e32 v86, v67
	v_pk_fma_f32 v[66:67], v[86:87], s[70:71], v[74:75] op_sel_hi:[1,0,1] neg_lo:[0,0,1] neg_hi:[0,0,1]
	v_pk_add_f32 v[74:75], v[12:13], v[70:71]
	v_pk_add_f32 v[12:13], v[12:13], v[70:71] neg_lo:[0,1] neg_hi:[0,1]
	v_pk_add_f32 v[70:71], v[14:15], v[22:23]
	v_pk_add_f32 v[14:15], v[14:15], v[22:23] neg_lo:[0,1] neg_hi:[0,1]
	s_nop 0
	v_xor_b32_e32 v23, 0x80000000, v14
	v_mov_b32_e32 v22, v15
	v_pk_mul_f32 v[22:23], v[22:23], s[70:71] op_sel_hi:[1,0]
	s_nop 0
	v_pk_fma_f32 v[14:15], v[14:15], s[70:71], v[22:23] op_sel_hi:[1,0,1]
	v_pk_add_f32 v[22:23], v[16:17], v[24:25]
	v_pk_add_f32 v[16:17], v[16:17], v[24:25] neg_lo:[0,1] neg_hi:[0,1]
	s_nop 0
	v_xor_b32_e32 v25, 0x80000000, v16
	v_mov_b32_e32 v24, v17
	v_pk_add_f32 v[16:17], v[18:19], v[26:27]
	v_pk_add_f32 v[18:19], v[18:19], v[26:27] neg_lo:[0,1] neg_hi:[0,1]
	v_pk_add_f32 v[108:109], v[12:13], v[24:25]
	v_pk_mul_f32 v[26:27], v[18:19], s[70:71] op_sel_hi:[1,0]
	v_xor_b32_e32 v87, 0x80000000, v18
	v_mov_b32_e32 v86, v19
	v_pk_fma_f32 v[18:19], v[86:87], s[70:71], v[26:27] op_sel_hi:[1,0,1] neg_lo:[0,0,1] neg_hi:[0,0,1]
	v_pk_add_f32 v[26:27], v[76:77], v[62:63]
	v_pk_add_f32 v[62:63], v[76:77], v[62:63] neg_lo:[0,1] neg_hi:[0,1]
	v_pk_add_f32 v[76:77], v[84:85], v[64:65]
	v_pk_add_f32 v[64:65], v[84:85], v[64:65] neg_lo:[0,1] neg_hi:[0,1]
	v_pk_add_f32 v[110:111], v[12:13], v[24:25] neg_lo:[0,1] neg_hi:[0,1]
	v_xor_b32_e32 v85, 0x80000000, v64
	v_mov_b32_e32 v84, v65
	v_pk_add_f32 v[64:65], v[68:69], v[72:73]
	v_pk_add_f32 v[68:69], v[68:69], v[72:73] neg_lo:[0,1] neg_hi:[0,1]
	v_pk_add_f32 v[72:73], v[20:21], v[66:67]
	v_pk_add_f32 v[20:21], v[20:21], v[66:67] neg_lo:[0,1] neg_hi:[0,1]
	v_pk_add_f32 v[12:13], v[14:15], v[18:19] neg_lo:[0,1] neg_hi:[0,1]
	v_xor_b32_e32 v67, 0x80000000, v20
	v_mov_b32_e32 v66, v21
	v_pk_add_f32 v[112:113], v[14:15], v[18:19]
	v_xor_b32_e32 v115, 0x80000000, v12
	v_mov_b32_e32 v114, v13
	v_pk_add_f32 v[12:13], v[26:27], v[76:77]
	v_pk_add_f32 v[14:15], v[26:27], v[76:77] neg_lo:[0,1] neg_hi:[0,1]
	v_pk_add_f32 v[24:25], v[68:69], v[66:67]
	v_pk_add_f32 v[26:27], v[68:69], v[66:67] neg_lo:[0,1] neg_hi:[0,1]
	s_waitcnt lgkmcnt(6)
	v_pk_add_f32 v[66:67], v[78:79], v[94:95] neg_lo:[0,1] neg_hi:[0,1]
	v_pk_add_f32 v[86:87], v[74:75], v[22:23]
	v_xor_b32_e32 v77, 0x80000000, v66
	v_mov_b32_e32 v76, v67
	v_pk_mul_f32 v[76:77], v[76:77], s[62:63] op_sel_hi:[1,0]
	v_pk_add_f32 v[74:75], v[74:75], v[22:23] neg_lo:[0,1] neg_hi:[0,1]
	v_pk_fma_f32 v[66:67], v[66:67], s[60:61], v[76:77] op_sel_hi:[1,0,1]
	s_waitcnt lgkmcnt(5)
	v_pk_add_f32 v[76:77], v[8:9], v[96:97]
	v_pk_add_f32 v[8:9], v[8:9], v[96:97] neg_lo:[0,1] neg_hi:[0,1]
	v_pk_add_f32 v[20:21], v[64:65], v[72:73]
	v_pk_add_f32 v[22:23], v[64:65], v[72:73] neg_lo:[0,1] neg_hi:[0,1]
	v_pk_add_f32 v[64:65], v[78:79], v[94:95]
	v_xor_b32_e32 v79, 0x80000000, v8
	v_mov_b32_e32 v78, v9
	v_pk_mul_f32 v[78:79], v[78:79], s[70:71] op_sel_hi:[1,0]
	v_pk_add_f32 v[88:89], v[70:71], v[16:17]
	v_pk_add_f32 v[16:17], v[70:71], v[16:17] neg_lo:[0,1] neg_hi:[0,1]
	v_pk_fma_f32 v[8:9], v[8:9], s[70:71], v[78:79] op_sel_hi:[1,0,1]
	s_waitcnt lgkmcnt(4)
	v_pk_add_f32 v[78:79], v[80:81], v[98:99]
	v_pk_add_f32 v[80:81], v[80:81], v[98:99] neg_lo:[0,1] neg_hi:[0,1]
	v_xor_b32_e32 v91, 0x80000000, v16
	v_mov_b32_e32 v90, v17
	v_pk_add_f32 v[16:17], v[62:63], v[84:85]
	v_pk_add_f32 v[18:19], v[62:63], v[84:85] neg_lo:[0,1] neg_hi:[0,1]
	v_pk_add_f32 v[62:63], v[6:7], v[92:93]
	v_pk_add_f32 v[6:7], v[6:7], v[92:93] neg_lo:[0,1] neg_hi:[0,1]
	v_xor_b32_e32 v93, 0x80000000, v80
	v_mov_b32_e32 v92, v81
	v_pk_mul_f32 v[92:93], v[92:93], s[60:61] op_sel_hi:[1,0]
	v_pk_add_f32 v[68:69], v[86:87], v[88:89]
	v_pk_fma_f32 v[80:81], v[80:81], s[62:63], v[92:93] op_sel_hi:[1,0,1]
	s_waitcnt lgkmcnt(3)
	v_pk_add_f32 v[92:93], v[10:11], v[100:101]
	v_pk_add_f32 v[10:11], v[10:11], v[100:101] neg_lo:[0,1] neg_hi:[0,1]
	v_pk_add_f32 v[70:71], v[86:87], v[88:89] neg_lo:[0,1] neg_hi:[0,1]
	v_xor_b32_e32 v95, 0x80000000, v10
	v_mov_b32_e32 v94, v11
	s_waitcnt lgkmcnt(2)
	v_pk_add_f32 v[10:11], v[4:5], v[102:103]
	v_pk_add_f32 v[4:5], v[4:5], v[102:103] neg_lo:[0,1] neg_hi:[0,1]
	v_pk_add_f32 v[84:85], v[108:109], v[112:113]
	v_pk_mul_f32 v[96:97], v[4:5], s[62:63] op_sel_hi:[1,0]
	v_xor_b32_e32 v99, 0x80000000, v4
	v_mov_b32_e32 v98, v5
	v_pk_fma_f32 v[4:5], v[98:99], s[60:61], v[96:97] op_sel_hi:[1,0,1] neg_lo:[0,0,1] neg_hi:[0,0,1]
	s_waitcnt lgkmcnt(1)
	v_pk_add_f32 v[96:97], v[2:3], v[104:105]
	v_pk_add_f32 v[2:3], v[2:3], v[104:105] neg_lo:[0,1] neg_hi:[0,1]
	v_pk_add_f32 v[86:87], v[108:109], v[112:113] neg_lo:[0,1] neg_hi:[0,1]
	v_pk_mul_f32 v[98:99], v[2:3], s[70:71] op_sel_hi:[1,0]
	v_xor_b32_e32 v101, 0x80000000, v2
	v_mov_b32_e32 v100, v3
	v_pk_fma_f32 v[2:3], v[100:101], s[70:71], v[98:99] op_sel_hi:[1,0,1] neg_lo:[0,0,1] neg_hi:[0,0,1]
	s_waitcnt lgkmcnt(0)
	v_pk_add_f32 v[98:99], v[82:83], v[106:107]
	v_pk_add_f32 v[82:83], v[82:83], v[106:107] neg_lo:[0,1] neg_hi:[0,1]
	v_pk_add_f32 v[72:73], v[74:75], v[90:91]
	v_pk_mul_f32 v[100:101], v[82:83], s[60:61] op_sel_hi:[1,0]
	v_xor_b32_e32 v103, 0x80000000, v82
	v_mov_b32_e32 v102, v83
	v_pk_fma_f32 v[82:83], v[102:103], s[62:63], v[100:101] op_sel_hi:[1,0,1] neg_lo:[0,0,1] neg_hi:[0,0,1]
	v_pk_add_f32 v[100:101], v[62:63], v[92:93]
	v_pk_add_f32 v[62:63], v[62:63], v[92:93] neg_lo:[0,1] neg_hi:[0,1]
	v_pk_add_f32 v[92:93], v[64:65], v[10:11]
	v_pk_add_f32 v[10:11], v[64:65], v[10:11] neg_lo:[0,1] neg_hi:[0,1]
	v_pk_add_f32 v[74:75], v[74:75], v[90:91] neg_lo:[0,1] neg_hi:[0,1]
	v_xor_b32_e32 v65, 0x80000000, v10
	v_mov_b32_e32 v64, v11
	v_pk_mul_f32 v[64:65], v[64:65], s[70:71] op_sel_hi:[1,0]
	v_pk_add_f32 v[88:89], v[110:111], v[114:115]
	v_pk_fma_f32 v[10:11], v[10:11], s[70:71], v[64:65] op_sel_hi:[1,0,1]
	v_pk_add_f32 v[64:65], v[76:77], v[96:97]
	v_pk_add_f32 v[76:77], v[76:77], v[96:97] neg_lo:[0,1] neg_hi:[0,1]
	v_pk_add_f32 v[90:91], v[110:111], v[114:115] neg_lo:[0,1] neg_hi:[0,1]
	v_xor_b32_e32 v97, 0x80000000, v76
	v_mov_b32_e32 v96, v77
	v_pk_add_f32 v[76:77], v[78:79], v[98:99]
	v_pk_add_f32 v[78:79], v[78:79], v[98:99] neg_lo:[0,1] neg_hi:[0,1]
	s_nop 0
	v_pk_mul_f32 v[98:99], v[78:79], s[70:71] op_sel_hi:[1,0]
	v_xor_b32_e32 v103, 0x80000000, v78
	v_mov_b32_e32 v102, v79
	v_pk_fma_f32 v[78:79], v[102:103], s[70:71], v[98:99] op_sel_hi:[1,0,1] neg_lo:[0,0,1] neg_hi:[0,0,1]
	v_pk_add_f32 v[98:99], v[6:7], v[94:95]
	v_pk_add_f32 v[6:7], v[6:7], v[94:95] neg_lo:[0,1] neg_hi:[0,1]
	v_pk_add_f32 v[94:95], v[66:67], v[4:5]
	v_pk_add_f32 v[4:5], v[66:67], v[4:5] neg_lo:[0,1] neg_hi:[0,1]
	s_nop 0
	v_xor_b32_e32 v67, 0x80000000, v4
	v_mov_b32_e32 v66, v5
	v_pk_mul_f32 v[66:67], v[66:67], s[70:71] op_sel_hi:[1,0]
	s_nop 0
	v_pk_fma_f32 v[4:5], v[4:5], s[70:71], v[66:67] op_sel_hi:[1,0,1]
	v_pk_add_f32 v[66:67], v[8:9], v[2:3]
	v_pk_add_f32 v[2:3], v[8:9], v[2:3] neg_lo:[0,1] neg_hi:[0,1]
	v_pk_add_f32 v[106:107], v[98:99], v[66:67] neg_lo:[0,1] neg_hi:[0,1]
	v_xor_b32_e32 v9, 0x80000000, v2
	v_mov_b32_e32 v8, v3
	v_pk_add_f32 v[2:3], v[80:81], v[82:83]
	v_pk_add_f32 v[80:81], v[80:81], v[82:83] neg_lo:[0,1] neg_hi:[0,1]
	v_pk_add_f32 v[108:109], v[94:95], v[2:3]
	v_pk_mul_f32 v[82:83], v[80:81], s[70:71] op_sel_hi:[1,0]
	v_xor_b32_e32 v103, 0x80000000, v80
	v_mov_b32_e32 v102, v81
	v_pk_fma_f32 v[80:81], v[102:103], s[70:71], v[82:83] op_sel_hi:[1,0,1] neg_lo:[0,0,1] neg_hi:[0,0,1]
	v_pk_add_f32 v[82:83], v[100:101], v[64:65]
	v_pk_add_f32 v[64:65], v[100:101], v[64:65] neg_lo:[0,1] neg_hi:[0,1]
	v_pk_add_f32 v[100:101], v[92:93], v[76:77]
	v_pk_add_f32 v[76:77], v[92:93], v[76:77] neg_lo:[0,1] neg_hi:[0,1]
	v_pk_add_f32 v[102:103], v[10:11], v[78:79]
	v_xor_b32_e32 v93, 0x80000000, v76
	v_mov_b32_e32 v92, v77
	v_pk_add_f32 v[76:77], v[62:63], v[96:97]
	v_pk_add_f32 v[10:11], v[10:11], v[78:79] neg_lo:[0,1] neg_hi:[0,1]
	v_pk_add_f32 v[2:3], v[94:95], v[2:3] neg_lo:[0,1] neg_hi:[0,1]
	v_pk_add_f32 v[62:63], v[62:63], v[96:97] neg_lo:[0,1] neg_hi:[0,1]
	v_xor_b32_e32 v105, 0x80000000, v10
	v_mov_b32_e32 v104, v11
	v_pk_add_f32 v[10:11], v[98:99], v[66:67]
	v_xor_b32_e32 v111, 0x80000000, v2
	v_mov_b32_e32 v110, v3
	v_pk_add_f32 v[112:113], v[6:7], v[8:9]
	v_pk_add_f32 v[114:115], v[6:7], v[8:9] neg_lo:[0,1] neg_hi:[0,1]
	v_pk_add_f32 v[6:7], v[4:5], v[80:81]
	v_pk_add_f32 v[2:3], v[4:5], v[80:81] neg_lo:[0,1] neg_hi:[0,1]
	v_pk_add_f32 v[98:99], v[82:83], v[100:101]
	v_pk_add_f32 v[96:97], v[82:83], v[100:101] neg_lo:[0,1] neg_hi:[0,1]
	v_pk_add_f32 v[82:83], v[76:77], v[102:103]
	v_pk_add_f32 v[80:81], v[76:77], v[102:103] neg_lo:[0,1] neg_hi:[0,1]
	global_load_dwordx4 v[100:103], v[0:1], off
	v_pk_add_f32 v[78:79], v[62:63], v[104:105]
	v_pk_add_f32 v[76:77], v[62:63], v[104:105] neg_lo:[0,1] neg_hi:[0,1]
	v_xor_b32_e32 v5, 0x80000000, v2
	v_mov_b32_e32 v4, v3
	v_pk_add_f32 v[62:63], v[106:107], v[110:111]
	v_pk_add_f32 v[2:3], v[106:107], v[110:111] neg_lo:[0,1] neg_hi:[0,1]
	v_xor_b32_e32 v106, 0x80000000, v13
	v_mov_b32_e32 v107, v12
	v_pk_add_f32 v[94:95], v[64:65], v[92:93]
	v_pk_add_f32 v[92:93], v[64:65], v[92:93] neg_lo:[0,1] neg_hi:[0,1]
	v_pk_add_f32 v[66:67], v[10:11], v[108:109]
	v_pk_add_f32 v[64:65], v[10:11], v[108:109] neg_lo:[0,1] neg_hi:[0,1]
	v_pk_add_f32 v[10:11], v[112:113], v[6:7]
	v_pk_add_f32 v[8:9], v[112:113], v[6:7] neg_lo:[0,1] neg_hi:[0,1]
	v_pk_add_f32 v[6:7], v[114:115], v[4:5]
	v_pk_add_f32 v[4:5], v[114:115], v[4:5] neg_lo:[0,1] neg_hi:[0,1]
	s_waitcnt vmcnt(0)
	v_cvt_f32_f16_e32 v104, v100
	v_cvt_f32_f16_sdwa v100, v100 dst_sel:DWORD dst_unused:UNUSED_PAD src0_sel:WORD_1
	v_mul_f32_e32 v104, 0x38800000, v104
	v_mul_f32_e32 v100, 0x38800000, v100
	v_pk_mul_f32 v[106:107], v[106:107], v[100:101] op_sel_hi:[1,0]
	v_cvt_f32_f16_e32 v100, v101
	v_cvt_f32_f16_sdwa v101, v101 dst_sel:DWORD dst_unused:UNUSED_PAD src0_sel:WORD_1
	v_pk_fma_f32 v[12:13], v[12:13], v[104:105], v[106:107] op_sel_hi:[1,0,1]
	v_xor_b32_e32 v106, 0x80000000, v15
	v_mov_b32_e32 v107, v14
	v_mul_f32_e32 v104, 0x38800000, v101
	v_mul_f32_e32 v100, 0x38800000, v100
	v_pk_mul_f32 v[104:105], v[106:107], v[104:105] op_sel_hi:[1,0]
	v_xor_b32_e32 v106, 0x80000000, v21
	v_pk_fma_f32 v[14:15], v[14:15], v[100:101], v[104:105] op_sel_hi:[1,0,1]
	v_cvt_f32_f16_sdwa v101, v102 dst_sel:DWORD dst_unused:UNUSED_PAD src0_sel:WORD_1
	v_cvt_f32_f16_e32 v100, v102
	v_xor_b32_e32 v104, 0x80000000, v17
	v_mov_b32_e32 v105, v16
	v_mul_f32_e32 v102, 0x38800000, v101
	v_mul_f32_e32 v100, 0x38800000, v100
	v_pk_mul_f32 v[104:105], v[104:105], v[102:103] op_sel_hi:[1,0]
	v_mov_b32_e32 v107, v20
	v_pk_fma_f32 v[16:17], v[16:17], v[100:101], v[104:105] op_sel_hi:[1,0,1]
	v_cvt_f32_f16_sdwa v101, v103 dst_sel:DWORD dst_unused:UNUSED_PAD src0_sel:WORD_1
	v_cvt_f32_f16_e32 v100, v103
	v_xor_b32_e32 v104, 0x80000000, v19
	v_mov_b32_e32 v105, v18
	v_mul_f32_e32 v102, 0x38800000, v101
	v_mul_f32_e32 v100, 0x38800000, v100
	v_pk_mul_f32 v[102:103], v[104:105], v[102:103] op_sel_hi:[1,0]
	s_nop 0
	v_pk_fma_f32 v[18:19], v[18:19], v[100:101], v[102:103] op_sel_hi:[1,0,1]
	global_load_dwordx4 v[100:103], v[0:1], off offset:16
	s_waitcnt vmcnt(0)
	v_cvt_f32_f16_e32 v104, v100
	v_cvt_f32_f16_sdwa v100, v100 dst_sel:DWORD dst_unused:UNUSED_PAD src0_sel:WORD_1
	v_mul_f32_e32 v104, 0x38800000, v104
	v_mul_f32_e32 v100, 0x38800000, v100
	v_pk_mul_f32 v[106:107], v[106:107], v[100:101] op_sel_hi:[1,0]
	v_cvt_f32_f16_e32 v100, v101
	v_cvt_f32_f16_sdwa v101, v101 dst_sel:DWORD dst_unused:UNUSED_PAD src0_sel:WORD_1
	v_pk_fma_f32 v[20:21], v[20:21], v[104:105], v[106:107] op_sel_hi:[1,0,1]
	v_xor_b32_e32 v106, 0x80000000, v23
	v_mov_b32_e32 v107, v22
	v_mul_f32_e32 v104, 0x38800000, v101
	v_mul_f32_e32 v100, 0x38800000, v100
	v_pk_mul_f32 v[104:105], v[106:107], v[104:105] op_sel_hi:[1,0]
	v_xor_b32_e32 v106, 0x80000000, v69
	v_pk_fma_f32 v[22:23], v[22:23], v[100:101], v[104:105] op_sel_hi:[1,0,1]
	v_cvt_f32_f16_sdwa v101, v102 dst_sel:DWORD dst_unused:UNUSED_PAD src0_sel:WORD_1
	v_cvt_f32_f16_e32 v100, v102
	v_xor_b32_e32 v104, 0x80000000, v25
	v_mov_b32_e32 v105, v24
	v_mul_f32_e32 v102, 0x38800000, v101
	v_mul_f32_e32 v100, 0x38800000, v100
	v_pk_mul_f32 v[104:105], v[104:105], v[102:103] op_sel_hi:[1,0]
	v_mov_b32_e32 v107, v68
	v_pk_fma_f32 v[24:25], v[24:25], v[100:101], v[104:105] op_sel_hi:[1,0,1]
	v_cvt_f32_f16_sdwa v101, v103 dst_sel:DWORD dst_unused:UNUSED_PAD src0_sel:WORD_1
	v_cvt_f32_f16_e32 v100, v103
	v_xor_b32_e32 v104, 0x80000000, v27
	v_mov_b32_e32 v105, v26
	v_mul_f32_e32 v102, 0x38800000, v101
	v_mul_f32_e32 v100, 0x38800000, v100
	v_pk_mul_f32 v[102:103], v[104:105], v[102:103] op_sel_hi:[1,0]
	s_nop 0
	v_pk_fma_f32 v[26:27], v[26:27], v[100:101], v[102:103] op_sel_hi:[1,0,1]
	global_load_dwordx4 v[100:103], v[0:1], off offset:32
	s_waitcnt vmcnt(0)
	v_cvt_f32_f16_e32 v104, v100
	v_cvt_f32_f16_sdwa v100, v100 dst_sel:DWORD dst_unused:UNUSED_PAD src0_sel:WORD_1
	v_mul_f32_e32 v104, 0x38800000, v104
	v_mul_f32_e32 v100, 0x38800000, v100
	v_pk_mul_f32 v[106:107], v[106:107], v[100:101] op_sel_hi:[1,0]
	v_cvt_f32_f16_e32 v100, v101
	v_cvt_f32_f16_sdwa v101, v101 dst_sel:DWORD dst_unused:UNUSED_PAD src0_sel:WORD_1
	v_pk_fma_f32 v[68:69], v[68:69], v[104:105], v[106:107] op_sel_hi:[1,0,1]
	v_xor_b32_e32 v106, 0x80000000, v71
	v_mov_b32_e32 v107, v70
	v_mul_f32_e32 v104, 0x38800000, v101
	v_mul_f32_e32 v100, 0x38800000, v100
	v_pk_mul_f32 v[104:105], v[106:107], v[104:105] op_sel_hi:[1,0]
	v_xor_b32_e32 v106, 0x80000000, v85
	v_pk_fma_f32 v[70:71], v[70:71], v[100:101], v[104:105] op_sel_hi:[1,0,1]
	v_cvt_f32_f16_sdwa v101, v102 dst_sel:DWORD dst_unused:UNUSED_PAD src0_sel:WORD_1
	v_cvt_f32_f16_e32 v100, v102
	v_xor_b32_e32 v104, 0x80000000, v73
	v_mov_b32_e32 v105, v72
	v_mul_f32_e32 v102, 0x38800000, v101
	v_mul_f32_e32 v100, 0x38800000, v100
	v_pk_mul_f32 v[104:105], v[104:105], v[102:103] op_sel_hi:[1,0]
	v_mov_b32_e32 v107, v84
	v_pk_fma_f32 v[72:73], v[72:73], v[100:101], v[104:105] op_sel_hi:[1,0,1]
	v_cvt_f32_f16_sdwa v101, v103 dst_sel:DWORD dst_unused:UNUSED_PAD src0_sel:WORD_1
	v_cvt_f32_f16_e32 v100, v103
	v_xor_b32_e32 v104, 0x80000000, v75
	v_mov_b32_e32 v105, v74
	v_mul_f32_e32 v102, 0x38800000, v101
	v_mul_f32_e32 v100, 0x38800000, v100
	v_pk_mul_f32 v[102:103], v[104:105], v[102:103] op_sel_hi:[1,0]
	s_nop 0
	v_pk_fma_f32 v[74:75], v[74:75], v[100:101], v[102:103] op_sel_hi:[1,0,1]
	global_load_dwordx4 v[100:103], v[0:1], off offset:48
	s_waitcnt vmcnt(0)
	v_cvt_f32_f16_e32 v104, v100
	v_cvt_f32_f16_sdwa v100, v100 dst_sel:DWORD dst_unused:UNUSED_PAD src0_sel:WORD_1
	v_mul_f32_e32 v104, 0x38800000, v104
	v_mul_f32_e32 v100, 0x38800000, v100
	v_pk_mul_f32 v[106:107], v[106:107], v[100:101] op_sel_hi:[1,0]
	v_cvt_f32_f16_e32 v100, v101
	v_cvt_f32_f16_sdwa v101, v101 dst_sel:DWORD dst_unused:UNUSED_PAD src0_sel:WORD_1
	v_pk_fma_f32 v[84:85], v[84:85], v[104:105], v[106:107] op_sel_hi:[1,0,1]
	v_xor_b32_e32 v106, 0x80000000, v87
	v_mov_b32_e32 v107, v86
	v_mul_f32_e32 v104, 0x38800000, v101
	v_mul_f32_e32 v100, 0x38800000, v100
	v_pk_mul_f32 v[104:105], v[106:107], v[104:105] op_sel_hi:[1,0]
	v_xor_b32_e32 v106, 0x80000000, v99
	v_pk_fma_f32 v[86:87], v[86:87], v[100:101], v[104:105] op_sel_hi:[1,0,1]
	v_cvt_f32_f16_sdwa v101, v102 dst_sel:DWORD dst_unused:UNUSED_PAD src0_sel:WORD_1
	v_cvt_f32_f16_e32 v100, v102
	v_xor_b32_e32 v104, 0x80000000, v89
	v_mov_b32_e32 v105, v88
	v_mul_f32_e32 v102, 0x38800000, v101
	v_mul_f32_e32 v100, 0x38800000, v100
	v_pk_mul_f32 v[104:105], v[104:105], v[102:103] op_sel_hi:[1,0]
	v_mov_b32_e32 v107, v98
	v_pk_fma_f32 v[88:89], v[88:89], v[100:101], v[104:105] op_sel_hi:[1,0,1]
	v_cvt_f32_f16_sdwa v101, v103 dst_sel:DWORD dst_unused:UNUSED_PAD src0_sel:WORD_1
	v_cvt_f32_f16_e32 v100, v103
	v_xor_b32_e32 v104, 0x80000000, v91
	v_mov_b32_e32 v105, v90
	v_mul_f32_e32 v102, 0x38800000, v101
	v_mul_f32_e32 v100, 0x38800000, v100
	v_pk_mul_f32 v[102:103], v[104:105], v[102:103] op_sel_hi:[1,0]
	s_nop 0
	v_pk_fma_f32 v[90:91], v[90:91], v[100:101], v[102:103] op_sel_hi:[1,0,1]
	global_load_dwordx4 v[100:103], v[0:1], off offset:64
	s_waitcnt vmcnt(0)
	v_cvt_f32_f16_e32 v104, v100
	v_cvt_f32_f16_sdwa v100, v100 dst_sel:DWORD dst_unused:UNUSED_PAD src0_sel:WORD_1
	v_mul_f32_e32 v104, 0x38800000, v104
	v_mul_f32_e32 v100, 0x38800000, v100
	v_pk_mul_f32 v[106:107], v[106:107], v[100:101] op_sel_hi:[1,0]
	v_cvt_f32_f16_e32 v100, v101
	v_cvt_f32_f16_sdwa v101, v101 dst_sel:DWORD dst_unused:UNUSED_PAD src0_sel:WORD_1
	v_pk_fma_f32 v[98:99], v[98:99], v[104:105], v[106:107] op_sel_hi:[1,0,1]
	v_xor_b32_e32 v106, 0x80000000, v97
	v_mov_b32_e32 v107, v96
	v_mul_f32_e32 v104, 0x38800000, v101
	v_mul_f32_e32 v100, 0x38800000, v100
	v_pk_mul_f32 v[104:105], v[106:107], v[104:105] op_sel_hi:[1,0]
	v_xor_b32_e32 v106, 0x80000000, v83
	v_pk_fma_f32 v[96:97], v[96:97], v[100:101], v[104:105] op_sel_hi:[1,0,1]
	v_cvt_f32_f16_sdwa v101, v102 dst_sel:DWORD dst_unused:UNUSED_PAD src0_sel:WORD_1
	v_cvt_f32_f16_e32 v100, v102
	v_xor_b32_e32 v104, 0x80000000, v95
	v_mov_b32_e32 v105, v94
	v_mul_f32_e32 v102, 0x38800000, v101
	v_mul_f32_e32 v100, 0x38800000, v100
	v_pk_mul_f32 v[104:105], v[104:105], v[102:103] op_sel_hi:[1,0]
	v_mov_b32_e32 v107, v82
	v_pk_fma_f32 v[94:95], v[94:95], v[100:101], v[104:105] op_sel_hi:[1,0,1]
	v_cvt_f32_f16_sdwa v101, v103 dst_sel:DWORD dst_unused:UNUSED_PAD src0_sel:WORD_1
	v_cvt_f32_f16_e32 v100, v103
	v_xor_b32_e32 v104, 0x80000000, v93
	v_mov_b32_e32 v105, v92
	v_mul_f32_e32 v102, 0x38800000, v101
	v_mul_f32_e32 v100, 0x38800000, v100
	v_pk_mul_f32 v[102:103], v[104:105], v[102:103] op_sel_hi:[1,0]
	s_nop 0
	v_pk_fma_f32 v[92:93], v[92:93], v[100:101], v[102:103] op_sel_hi:[1,0,1]
	global_load_dwordx4 v[100:103], v[0:1], off offset:80
	s_waitcnt vmcnt(0)
	v_cvt_f32_f16_e32 v104, v100
	v_cvt_f32_f16_sdwa v100, v100 dst_sel:DWORD dst_unused:UNUSED_PAD src0_sel:WORD_1
	v_mul_f32_e32 v104, 0x38800000, v104
	v_mul_f32_e32 v100, 0x38800000, v100
	v_pk_mul_f32 v[106:107], v[106:107], v[100:101] op_sel_hi:[1,0]
	v_cvt_f32_f16_e32 v100, v101
	v_cvt_f32_f16_sdwa v101, v101 dst_sel:DWORD dst_unused:UNUSED_PAD src0_sel:WORD_1
	v_pk_fma_f32 v[82:83], v[82:83], v[104:105], v[106:107] op_sel_hi:[1,0,1]
	v_xor_b32_e32 v106, 0x80000000, v81
	v_mov_b32_e32 v107, v80
	v_mul_f32_e32 v104, 0x38800000, v101
	v_mul_f32_e32 v100, 0x38800000, v100
	v_pk_mul_f32 v[104:105], v[106:107], v[104:105] op_sel_hi:[1,0]
	v_xor_b32_e32 v106, 0x80000000, v67
	v_pk_fma_f32 v[80:81], v[80:81], v[100:101], v[104:105] op_sel_hi:[1,0,1]
	v_cvt_f32_f16_sdwa v101, v102 dst_sel:DWORD dst_unused:UNUSED_PAD src0_sel:WORD_1
	v_cvt_f32_f16_e32 v100, v102
	v_xor_b32_e32 v104, 0x80000000, v79
	v_mov_b32_e32 v105, v78
	v_mul_f32_e32 v102, 0x38800000, v101
	v_mul_f32_e32 v100, 0x38800000, v100
	v_pk_mul_f32 v[104:105], v[104:105], v[102:103] op_sel_hi:[1,0]
	v_mov_b32_e32 v107, v66
	v_pk_fma_f32 v[78:79], v[78:79], v[100:101], v[104:105] op_sel_hi:[1,0,1]
	v_cvt_f32_f16_sdwa v101, v103 dst_sel:DWORD dst_unused:UNUSED_PAD src0_sel:WORD_1
	v_cvt_f32_f16_e32 v100, v103
	v_xor_b32_e32 v104, 0x80000000, v77
	v_mov_b32_e32 v105, v76
	v_mul_f32_e32 v102, 0x38800000, v101
	v_mul_f32_e32 v100, 0x38800000, v100
	v_pk_mul_f32 v[102:103], v[104:105], v[102:103] op_sel_hi:[1,0]
	s_nop 0
	v_pk_fma_f32 v[76:77], v[76:77], v[100:101], v[102:103] op_sel_hi:[1,0,1]
	global_load_dwordx4 v[100:103], v[0:1], off offset:96
	s_waitcnt vmcnt(0)
	v_cvt_f32_f16_e32 v104, v100
	v_cvt_f32_f16_sdwa v100, v100 dst_sel:DWORD dst_unused:UNUSED_PAD src0_sel:WORD_1
	v_mul_f32_e32 v104, 0x38800000, v104
	v_mul_f32_e32 v100, 0x38800000, v100
	v_pk_mul_f32 v[106:107], v[106:107], v[100:101] op_sel_hi:[1,0]
	v_cvt_f32_f16_e32 v100, v101
	v_cvt_f32_f16_sdwa v101, v101 dst_sel:DWORD dst_unused:UNUSED_PAD src0_sel:WORD_1
	v_pk_fma_f32 v[66:67], v[66:67], v[104:105], v[106:107] op_sel_hi:[1,0,1]
	v_xor_b32_e32 v106, 0x80000000, v65
	v_mov_b32_e32 v107, v64
	v_mul_f32_e32 v104, 0x38800000, v101
	v_mul_f32_e32 v100, 0x38800000, v100
	v_pk_mul_f32 v[104:105], v[106:107], v[104:105] op_sel_hi:[1,0]
	s_nop 0
	v_pk_fma_f32 v[64:65], v[64:65], v[100:101], v[104:105] op_sel_hi:[1,0,1]
	v_cvt_f32_f16_sdwa v101, v102 dst_sel:DWORD dst_unused:UNUSED_PAD src0_sel:WORD_1
	v_cvt_f32_f16_e32 v100, v102
	v_xor_b32_e32 v104, 0x80000000, v63
	v_mov_b32_e32 v105, v62
	v_mul_f32_e32 v102, 0x38800000, v101
	v_mul_f32_e32 v100, 0x38800000, v100
	v_pk_mul_f32 v[104:105], v[104:105], v[102:103] op_sel_hi:[1,0]
	s_nop 0
	v_pk_fma_f32 v[62:63], v[62:63], v[100:101], v[104:105] op_sel_hi:[1,0,1]
	v_cvt_f32_f16_sdwa v101, v103 dst_sel:DWORD dst_unused:UNUSED_PAD src0_sel:WORD_1
	v_cvt_f32_f16_e32 v100, v103
	v_xor_b32_e32 v104, 0x80000000, v3
	v_mov_b32_e32 v105, v2
	v_mul_f32_e32 v102, 0x38800000, v101
	v_mul_f32_e32 v100, 0x38800000, v100
	v_pk_mul_f32 v[102:103], v[104:105], v[102:103] op_sel_hi:[1,0]
	v_xor_b32_e32 v104, 0x80000000, v11
	v_pk_fma_f32 v[100:101], v[2:3], v[100:101], v[102:103] op_sel_hi:[1,0,1]
	global_load_dwordx4 v[0:3], v[0:1], off offset:112
	v_mov_b32_e32 v105, v10
	s_waitcnt vmcnt(0)
	v_cvt_f32_f16_e32 v102, v0
	v_cvt_f32_f16_sdwa v0, v0 dst_sel:DWORD dst_unused:UNUSED_PAD src0_sel:WORD_1
	v_mul_f32_e32 v102, 0x38800000, v102
	v_mul_f32_e32 v0, 0x38800000, v0
	v_pk_mul_f32 v[104:105], v[104:105], v[0:1] op_sel_hi:[1,0]
	v_cvt_f32_f16_e32 v0, v1
	v_cvt_f32_f16_sdwa v1, v1 dst_sel:DWORD dst_unused:UNUSED_PAD src0_sel:WORD_1
	v_pk_fma_f32 v[10:11], v[10:11], v[102:103], v[104:105] op_sel_hi:[1,0,1]
	v_xor_b32_e32 v104, 0x80000000, v9
	v_mov_b32_e32 v105, v8
	v_mul_f32_e32 v102, 0x38800000, v1
	v_mul_f32_e32 v0, 0x38800000, v0
	v_pk_mul_f32 v[102:103], v[104:105], v[102:103] op_sel_hi:[1,0]
	s_nop 0
	v_pk_fma_f32 v[0:1], v[8:9], v[0:1], v[102:103] op_sel_hi:[1,0,1]
	v_cvt_f32_f16_e32 v8, v2
	v_cvt_f32_f16_sdwa v2, v2 dst_sel:DWORD dst_unused:UNUSED_PAD src0_sel:WORD_1
	v_xor_b32_e32 v102, 0x80000000, v7
	v_mov_b32_e32 v103, v6
	v_mul_f32_e32 v8, 0x38800000, v8
	v_mul_f32_e32 v2, 0x38800000, v2
	v_pk_mul_f32 v[102:103], v[102:103], v[2:3] op_sel_hi:[1,0]
	v_cvt_f32_f16_e32 v2, v3
	v_cvt_f32_f16_sdwa v3, v3 dst_sel:DWORD dst_unused:UNUSED_PAD src0_sel:WORD_1
	v_pk_fma_f32 v[6:7], v[6:7], v[8:9], v[102:103] op_sel_hi:[1,0,1]
	v_xor_b32_e32 v102, 0x80000000, v5
	v_mov_b32_e32 v103, v4
	v_mul_f32_e32 v8, 0x38800000, v3
	v_mul_f32_e32 v2, 0x38800000, v2
	v_pk_mul_f32 v[8:9], v[102:103], v[8:9] op_sel_hi:[1,0]
	v_mov_b32_e32 v102, v146
	v_pk_fma_f32 v[2:3], v[4:5], v[2:3], v[8:9] op_sel_hi:[1,0,1]
	v_pk_add_f32 v[4:5], v[12:13], v[14:15]
	v_pk_add_f32 v[8:9], v[12:13], v[14:15] neg_lo:[0,1] neg_hi:[0,1]
	v_pk_add_f32 v[12:13], v[16:17], v[18:19]
	v_pk_add_f32 v[14:15], v[16:17], v[18:19] neg_lo:[0,1] neg_hi:[0,1]
	v_pk_add_f32 v[16:17], v[20:21], v[22:23]
	v_pk_add_f32 v[18:19], v[20:21], v[22:23] neg_lo:[0,1] neg_hi:[0,1]
	v_pk_add_f32 v[20:21], v[24:25], v[26:27]
	v_pk_add_f32 v[22:23], v[24:25], v[26:27] neg_lo:[0,1] neg_hi:[0,1]
	v_pk_add_f32 v[24:25], v[68:69], v[70:71]
	v_pk_add_f32 v[26:27], v[68:69], v[70:71] neg_lo:[0,1] neg_hi:[0,1]
	v_pk_add_f32 v[68:69], v[72:73], v[74:75]
	v_pk_add_f32 v[70:71], v[72:73], v[74:75] neg_lo:[0,1] neg_hi:[0,1]
	v_pk_add_f32 v[72:73], v[84:85], v[86:87]
	v_pk_add_f32 v[74:75], v[84:85], v[86:87] neg_lo:[0,1] neg_hi:[0,1]
	v_pk_add_f32 v[84:85], v[88:89], v[90:91]
	v_pk_add_f32 v[86:87], v[88:89], v[90:91] neg_lo:[0,1] neg_hi:[0,1]
	v_pk_add_f32 v[88:89], v[4:5], v[12:13]
	v_pk_add_f32 v[4:5], v[4:5], v[12:13] neg_lo:[0,1] neg_hi:[0,1]
	v_xor_b32_e32 v12, 0x80000000, v15
	v_mov_b32_e32 v13, v14
	v_pk_add_f32 v[14:15], v[8:9], v[12:13]
	v_pk_add_f32 v[8:9], v[8:9], v[12:13] neg_lo:[0,1] neg_hi:[0,1]
	v_pk_add_f32 v[12:13], v[16:17], v[20:21]
	v_pk_add_f32 v[16:17], v[16:17], v[20:21] neg_lo:[0,1] neg_hi:[0,1]
	v_xor_b32_e32 v20, 0x80000000, v23
	v_mov_b32_e32 v21, v22
	v_pk_add_f32 v[22:23], v[18:19], v[20:21]
	v_pk_add_f32 v[18:19], v[18:19], v[20:21] neg_lo:[0,1] neg_hi:[0,1]
	v_pk_add_f32 v[20:21], v[24:25], v[68:69]
	v_pk_add_f32 v[24:25], v[24:25], v[68:69] neg_lo:[0,1] neg_hi:[0,1]
	v_xor_b32_e32 v68, 0x80000000, v71
	v_mov_b32_e32 v69, v70
	v_pk_add_f32 v[70:71], v[26:27], v[68:69]
	v_pk_add_f32 v[26:27], v[26:27], v[68:69] neg_lo:[0,1] neg_hi:[0,1]
	v_pk_add_f32 v[68:69], v[72:73], v[84:85]
	v_pk_add_f32 v[72:73], v[72:73], v[84:85] neg_lo:[0,1] neg_hi:[0,1]
	v_xor_b32_e32 v84, 0x80000000, v87
	v_mov_b32_e32 v85, v86
	v_pk_add_f32 v[86:87], v[74:75], v[84:85]
	v_pk_add_f32 v[74:75], v[74:75], v[84:85] neg_lo:[0,1] neg_hi:[0,1]
	v_pk_add_f32 v[84:85], v[88:89], v[12:13]
	v_pk_add_f32 v[12:13], v[88:89], v[12:13] neg_lo:[0,1] neg_hi:[0,1]
	v_xor_b32_e32 v88, 0x80000000, v23
	v_mov_b32_e32 v89, v22
	v_pk_mul_f32 v[88:89], v[88:89], s[70:71] op_sel_hi:[1,0]
	v_xor_b32_e32 v90, 0x80000000, v19
	v_pk_fma_f32 v[22:23], v[22:23], s[70:71], v[88:89] op_sel_hi:[1,0,1]
	v_mov_b32_e32 v91, v18
	v_pk_add_f32 v[88:89], v[14:15], v[22:23]
	v_pk_add_f32 v[14:15], v[14:15], v[22:23] neg_lo:[0,1] neg_hi:[0,1]
	v_xor_b32_e32 v22, 0x80000000, v17
	v_mov_b32_e32 v23, v16
	v_pk_add_f32 v[16:17], v[4:5], v[22:23]
	v_pk_add_f32 v[4:5], v[4:5], v[22:23] neg_lo:[0,1] neg_hi:[0,1]
	v_pk_mul_f32 v[22:23], v[18:19], s[70:71] op_sel_hi:[1,0]
	s_nop 0
	v_pk_fma_f32 v[18:19], v[90:91], s[70:71], v[22:23] op_sel_hi:[1,0,1] neg_lo:[0,0,1] neg_hi:[0,0,1]
	v_xor_b32_e32 v90, 0x80000000, v75
	v_pk_add_f32 v[22:23], v[8:9], v[18:19]
	v_pk_add_f32 v[8:9], v[8:9], v[18:19] neg_lo:[0,1] neg_hi:[0,1]
	v_pk_add_f32 v[18:19], v[20:21], v[68:69]
	v_pk_add_f32 v[20:21], v[20:21], v[68:69] neg_lo:[0,1] neg_hi:[0,1]
	v_xor_b32_e32 v68, 0x80000000, v87
	v_mov_b32_e32 v69, v86
	v_pk_mul_f32 v[68:69], v[68:69], s[70:71] op_sel_hi:[1,0]
	v_mov_b32_e32 v91, v74
	v_pk_fma_f32 v[68:69], v[86:87], s[70:71], v[68:69] op_sel_hi:[1,0,1]
	s_nop 0
	v_pk_add_f32 v[86:87], v[70:71], v[68:69]
	v_pk_add_f32 v[68:69], v[70:71], v[68:69] neg_lo:[0,1] neg_hi:[0,1]
	v_xor_b32_e32 v70, 0x80000000, v73
	v_mov_b32_e32 v71, v72
	v_pk_add_f32 v[72:73], v[24:25], v[70:71]
	v_pk_add_f32 v[24:25], v[24:25], v[70:71] neg_lo:[0,1] neg_hi:[0,1]
	v_pk_mul_f32 v[70:71], v[74:75], s[70:71] op_sel_hi:[1,0]
	s_nop 0
	v_pk_fma_f32 v[70:71], v[90:91], s[70:71], v[70:71] op_sel_hi:[1,0,1] neg_lo:[0,0,1] neg_hi:[0,0,1]
	v_xor_b32_e32 v90, 0x80000000, v69
	v_pk_add_f32 v[74:75], v[26:27], v[70:71]
	v_pk_add_f32 v[26:27], v[26:27], v[70:71] neg_lo:[0,1] neg_hi:[0,1]
	v_pk_add_f32 v[70:71], v[84:85], v[18:19]
	v_pk_add_f32 v[18:19], v[84:85], v[18:19] neg_lo:[0,1] neg_hi:[0,1]
	v_xor_b32_e32 v84, 0x80000000, v87
	v_mov_b32_e32 v85, v86
	v_pk_mul_f32 v[84:85], v[84:85], s[62:63] op_sel_hi:[1,0]
	v_mov_b32_e32 v91, v68
	v_pk_fma_f32 v[84:85], v[86:87], s[60:61], v[84:85] op_sel_hi:[1,0,1]
	s_nop 0
	v_pk_add_f32 v[86:87], v[88:89], v[84:85]
	v_pk_add_f32 v[84:85], v[88:89], v[84:85] neg_lo:[0,1] neg_hi:[0,1]
	v_xor_b32_e32 v88, 0x80000000, v73
	v_mov_b32_e32 v89, v72
	v_pk_mul_f32 v[88:89], v[88:89], s[70:71] op_sel_hi:[1,0]
	s_nop 0
	v_pk_fma_f32 v[72:73], v[72:73], s[70:71], v[88:89] op_sel_hi:[1,0,1]
	s_nop 0
	v_pk_add_f32 v[88:89], v[16:17], v[72:73]
	v_pk_add_f32 v[16:17], v[16:17], v[72:73] neg_lo:[0,1] neg_hi:[0,1]
	v_xor_b32_e32 v72, 0x80000000, v75
	v_mov_b32_e32 v73, v74
	v_pk_mul_f32 v[72:73], v[72:73], s[60:61] op_sel_hi:[1,0]
	s_nop 0
	v_pk_fma_f32 v[72:73], v[74:75], s[62:63], v[72:73] op_sel_hi:[1,0,1]
	s_nop 0
	v_pk_add_f32 v[74:75], v[22:23], v[72:73]
	v_pk_add_f32 v[22:23], v[22:23], v[72:73] neg_lo:[0,1] neg_hi:[0,1]
	v_xor_b32_e32 v72, 0x80000000, v21
	v_mov_b32_e32 v73, v20
	v_pk_add_f32 v[20:21], v[12:13], v[72:73]
	v_pk_add_f32 v[12:13], v[12:13], v[72:73] neg_lo:[0,1] neg_hi:[0,1]
	v_pk_mul_f32 v[72:73], v[68:69], s[62:63] op_sel_hi:[1,0]
	s_nop 0
	v_pk_fma_f32 v[68:69], v[90:91], s[60:61], v[72:73] op_sel_hi:[1,0,1] neg_lo:[0,0,1] neg_hi:[0,0,1]
	v_xor_b32_e32 v90, 0x80000000, v25
	v_pk_add_f32 v[72:73], v[14:15], v[68:69]
	v_pk_add_f32 v[14:15], v[14:15], v[68:69] neg_lo:[0,1] neg_hi:[0,1]
	v_pk_mul_f32 v[68:69], v[24:25], s[70:71] op_sel_hi:[1,0]
	v_mov_b32_e32 v91, v24
	v_pk_fma_f32 v[24:25], v[90:91], s[70:71], v[68:69] op_sel_hi:[1,0,1] neg_lo:[0,0,1] neg_hi:[0,0,1]
	v_xor_b32_e32 v90, 0x80000000, v27
	v_pk_add_f32 v[68:69], v[4:5], v[24:25]
	v_pk_add_f32 v[4:5], v[4:5], v[24:25] neg_lo:[0,1] neg_hi:[0,1]
	v_pk_mul_f32 v[24:25], v[26:27], s[60:61] op_sel_hi:[1,0]
	v_mov_b32_e32 v91, v26
	v_pk_fma_f32 v[24:25], v[90:91], s[62:63], v[24:25] op_sel_hi:[1,0,1] neg_lo:[0,0,1] neg_hi:[0,0,1]
	v_pk_add_f32 v[90:91], v[98:99], v[96:97] neg_lo:[0,1] neg_hi:[0,1]
	v_pk_add_f32 v[26:27], v[8:9], v[24:25]
	v_pk_add_f32 v[8:9], v[8:9], v[24:25] neg_lo:[0,1] neg_hi:[0,1]
	v_pk_add_f32 v[24:25], v[98:99], v[96:97]
	v_pk_add_f32 v[96:97], v[94:95], v[92:93]
	v_pk_add_f32 v[92:93], v[94:95], v[92:93] neg_lo:[0,1] neg_hi:[0,1]
	v_pk_add_f32 v[94:95], v[82:83], v[80:81]
	v_pk_add_f32 v[80:81], v[82:83], v[80:81] neg_lo:[0,1] neg_hi:[0,1]
	v_pk_add_f32 v[82:83], v[78:79], v[76:77]
	v_pk_add_f32 v[76:77], v[78:79], v[76:77] neg_lo:[0,1] neg_hi:[0,1]
	v_pk_add_f32 v[98:99], v[10:11], v[0:1]
	v_pk_add_f32 v[0:1], v[10:11], v[0:1] neg_lo:[0,1] neg_hi:[0,1]
	v_pk_add_f32 v[10:11], v[6:7], v[2:3]
	v_pk_add_f32 v[2:3], v[6:7], v[2:3] neg_lo:[0,1] neg_hi:[0,1]
	v_pk_add_f32 v[6:7], v[24:25], v[96:97]
	v_pk_add_f32 v[24:25], v[24:25], v[96:97] neg_lo:[0,1] neg_hi:[0,1]
	v_xor_b32_e32 v96, 0x80000000, v93
	v_mov_b32_e32 v97, v92
	v_pk_add_f32 v[78:79], v[66:67], v[64:65]
	v_pk_add_f32 v[64:65], v[66:67], v[64:65] neg_lo:[0,1] neg_hi:[0,1]
	v_pk_add_f32 v[66:67], v[62:63], v[100:101]
	v_pk_add_f32 v[62:63], v[62:63], v[100:101] neg_lo:[0,1] neg_hi:[0,1]
	v_pk_add_f32 v[92:93], v[90:91], v[96:97]
	v_pk_add_f32 v[90:91], v[90:91], v[96:97] neg_lo:[0,1] neg_hi:[0,1]
	v_pk_add_f32 v[96:97], v[94:95], v[82:83]
	v_pk_add_f32 v[82:83], v[94:95], v[82:83] neg_lo:[0,1] neg_hi:[0,1]
	v_xor_b32_e32 v94, 0x80000000, v77
	v_mov_b32_e32 v95, v76
	v_pk_add_f32 v[76:77], v[80:81], v[94:95]
	v_pk_add_f32 v[80:81], v[80:81], v[94:95] neg_lo:[0,1] neg_hi:[0,1]
	v_pk_add_f32 v[94:95], v[78:79], v[66:67]
	v_pk_add_f32 v[66:67], v[78:79], v[66:67] neg_lo:[0,1] neg_hi:[0,1]
	v_xor_b32_e32 v78, 0x80000000, v63
	v_mov_b32_e32 v79, v62
	v_pk_add_f32 v[62:63], v[64:65], v[78:79]
	v_pk_add_f32 v[64:65], v[64:65], v[78:79] neg_lo:[0,1] neg_hi:[0,1]
	v_pk_add_f32 v[78:79], v[98:99], v[10:11]
	v_pk_add_f32 v[10:11], v[98:99], v[10:11] neg_lo:[0,1] neg_hi:[0,1]
	v_xor_b32_e32 v98, 0x80000000, v3
	v_mov_b32_e32 v99, v2
	v_pk_add_f32 v[2:3], v[0:1], v[98:99]
	v_pk_add_f32 v[0:1], v[0:1], v[98:99] neg_lo:[0,1] neg_hi:[0,1]
	v_pk_add_f32 v[98:99], v[6:7], v[96:97]
	v_pk_add_f32 v[6:7], v[6:7], v[96:97] neg_lo:[0,1] neg_hi:[0,1]
	v_xor_b32_e32 v96, 0x80000000, v77
	v_mov_b32_e32 v97, v76
	v_pk_mul_f32 v[96:97], v[96:97], s[70:71] op_sel_hi:[1,0]
	v_xor_b32_e32 v100, 0x80000000, v81
	v_pk_fma_f32 v[76:77], v[76:77], s[70:71], v[96:97] op_sel_hi:[1,0,1]
	v_mov_b32_e32 v101, v80
	v_pk_add_f32 v[96:97], v[92:93], v[76:77]
	v_pk_add_f32 v[76:77], v[92:93], v[76:77] neg_lo:[0,1] neg_hi:[0,1]
	v_xor_b32_e32 v92, 0x80000000, v83
	v_mov_b32_e32 v93, v82
	v_pk_add_f32 v[82:83], v[24:25], v[92:93]
	v_pk_add_f32 v[24:25], v[24:25], v[92:93] neg_lo:[0,1] neg_hi:[0,1]
	v_pk_mul_f32 v[92:93], v[80:81], s[70:71] op_sel_hi:[1,0]
	s_nop 0
	v_pk_fma_f32 v[80:81], v[100:101], s[70:71], v[92:93] op_sel_hi:[1,0,1] neg_lo:[0,0,1] neg_hi:[0,0,1]
	v_xor_b32_e32 v100, 0x80000000, v1
	v_pk_add_f32 v[92:93], v[90:91], v[80:81]
	v_pk_add_f32 v[80:81], v[90:91], v[80:81] neg_lo:[0,1] neg_hi:[0,1]
	v_pk_add_f32 v[90:91], v[94:95], v[78:79]
	v_pk_add_f32 v[78:79], v[94:95], v[78:79] neg_lo:[0,1] neg_hi:[0,1]
	v_xor_b32_e32 v94, 0x80000000, v3
	v_mov_b32_e32 v95, v2
	v_pk_mul_f32 v[94:95], v[94:95], s[70:71] op_sel_hi:[1,0]
	v_mov_b32_e32 v101, v0
	v_pk_fma_f32 v[2:3], v[2:3], s[70:71], v[94:95] op_sel_hi:[1,0,1]
	s_nop 0
	v_pk_add_f32 v[94:95], v[62:63], v[2:3]
	v_pk_add_f32 v[2:3], v[62:63], v[2:3] neg_lo:[0,1] neg_hi:[0,1]
	v_xor_b32_e32 v62, 0x80000000, v11
	v_mov_b32_e32 v63, v10
	v_pk_add_f32 v[10:11], v[66:67], v[62:63]
	v_pk_add_f32 v[62:63], v[66:67], v[62:63] neg_lo:[0,1] neg_hi:[0,1]
	v_pk_mul_f32 v[66:67], v[0:1], s[70:71] op_sel_hi:[1,0]
	s_nop 0
	v_pk_fma_f32 v[0:1], v[100:101], s[70:71], v[66:67] op_sel_hi:[1,0,1] neg_lo:[0,0,1] neg_hi:[0,0,1]
	v_xor_b32_e32 v100, 0x80000000, v3
	v_pk_add_f32 v[66:67], v[64:65], v[0:1]
	v_pk_add_f32 v[0:1], v[64:65], v[0:1] neg_lo:[0,1] neg_hi:[0,1]
	v_pk_add_f32 v[64:65], v[98:99], v[90:91]
	v_pk_add_f32 v[90:91], v[98:99], v[90:91] neg_lo:[0,1] neg_hi:[0,1]
	v_xor_b32_e32 v98, 0x80000000, v95
	v_mov_b32_e32 v99, v94
	v_pk_mul_f32 v[98:99], v[98:99], s[62:63] op_sel_hi:[1,0]
	v_mov_b32_e32 v101, v2
	v_pk_fma_f32 v[94:95], v[94:95], s[60:61], v[98:99] op_sel_hi:[1,0,1]
	s_nop 0
	v_pk_add_f32 v[98:99], v[96:97], v[94:95]
	v_pk_add_f32 v[94:95], v[96:97], v[94:95] neg_lo:[0,1] neg_hi:[0,1]
	v_xor_b32_e32 v96, 0x80000000, v11
	v_mov_b32_e32 v97, v10
	v_pk_mul_f32 v[96:97], v[96:97], s[70:71] op_sel_hi:[1,0]
	s_nop 0
	v_pk_fma_f32 v[10:11], v[10:11], s[70:71], v[96:97] op_sel_hi:[1,0,1]
	s_nop 0
	v_pk_add_f32 v[96:97], v[82:83], v[10:11]
	v_pk_add_f32 v[10:11], v[82:83], v[10:11] neg_lo:[0,1] neg_hi:[0,1]
	v_xor_b32_e32 v82, 0x80000000, v67
	v_mov_b32_e32 v83, v66
	v_pk_mul_f32 v[82:83], v[82:83], s[60:61] op_sel_hi:[1,0]
	s_nop 0
	v_pk_fma_f32 v[66:67], v[66:67], s[62:63], v[82:83] op_sel_hi:[1,0,1]
	s_nop 0
	v_pk_add_f32 v[82:83], v[92:93], v[66:67]
	v_pk_add_f32 v[66:67], v[92:93], v[66:67] neg_lo:[0,1] neg_hi:[0,1]
	v_xor_b32_e32 v92, 0x80000000, v79
	v_mov_b32_e32 v93, v78
	v_pk_add_f32 v[78:79], v[6:7], v[92:93]
	v_pk_add_f32 v[6:7], v[6:7], v[92:93] neg_lo:[0,1] neg_hi:[0,1]
	v_pk_mul_f32 v[92:93], v[2:3], s[62:63] op_sel_hi:[1,0]
	s_nop 0
	v_pk_fma_f32 v[2:3], v[100:101], s[60:61], v[92:93] op_sel_hi:[1,0,1] neg_lo:[0,0,1] neg_hi:[0,0,1]
	v_xor_b32_e32 v100, 0x80000000, v63
	v_pk_add_f32 v[92:93], v[76:77], v[2:3]
	v_pk_add_f32 v[2:3], v[76:77], v[2:3] neg_lo:[0,1] neg_hi:[0,1]
	v_pk_mul_f32 v[76:77], v[62:63], s[70:71] op_sel_hi:[1,0]
	v_mov_b32_e32 v101, v62
	v_pk_fma_f32 v[62:63], v[100:101], s[70:71], v[76:77] op_sel_hi:[1,0,1] neg_lo:[0,0,1] neg_hi:[0,0,1]
	v_xor_b32_e32 v100, 0x80000000, v1
	v_pk_add_f32 v[76:77], v[24:25], v[62:63]
	v_pk_add_f32 v[24:25], v[24:25], v[62:63] neg_lo:[0,1] neg_hi:[0,1]
	v_pk_mul_f32 v[62:63], v[0:1], s[60:61] op_sel_hi:[1,0]
	v_mov_b32_e32 v101, v0
	v_pk_fma_f32 v[0:1], v[100:101], s[62:63], v[62:63] op_sel_hi:[1,0,1] neg_lo:[0,0,1] neg_hi:[0,0,1]
	v_bfe_u32 v100, v102, 1, 4
	v_pk_add_f32 v[62:63], v[80:81], v[0:1]
	v_pk_add_f32 v[0:1], v[80:81], v[0:1] neg_lo:[0,1] neg_hi:[0,1]
	v_lshlrev_b32_e32 v80, 4, v102
	v_lshrrev_b32_e32 v81, 1, v102
	v_bitop3_b32 v101, v81, v80, 16 bitop3:0x6c
	v_lshl_add_u32 v101, v101, 3, 16
	v_lshlrev_b32_e32 v100, 3, v100
	v_add_u32_e32 v102, v101, v100
	ds_write_b64 v102, v[70:71]
	v_bitop3_b32 v70, v81, 1, 15 bitop3:0x6c
	v_lshlrev_b32_e32 v70, 3, v70
	v_add_u32_e32 v71, v101, v70
	ds_write_b64 v71, v[86:87]
	v_bitop3_b32 v71, v81, 2, 15 bitop3:0x6c
	v_lshlrev_b32_e32 v71, 3, v71
	v_add_u32_e32 v86, v101, v71
	ds_write_b64 v86, v[88:89]
	v_bitop3_b32 v86, v81, 3, 15 bitop3:0x6c
	v_lshlrev_b32_e32 v86, 3, v86
	v_add_u32_e32 v87, v101, v86
	ds_write_b64 v87, v[74:75]
	v_bitop3_b32 v74, v81, 4, 15 bitop3:0x6c
	v_lshlrev_b32_e32 v74, 3, v74
	v_add_u32_e32 v75, v101, v74
	ds_write_b64 v75, v[20:21]
	v_bitop3_b32 v20, v81, 5, 15 bitop3:0x6c
	v_lshlrev_b32_e32 v20, 3, v20
	v_add_u32_e32 v21, v101, v20
	ds_write_b64 v21, v[72:73]
	v_bitop3_b32 v21, v81, 6, 15 bitop3:0x6c
	v_lshlrev_b32_e32 v21, 3, v21
	v_add_u32_e32 v72, v101, v21
	ds_write_b64 v72, v[68:69]
	v_bitop3_b32 v68, v81, 7, 15 bitop3:0x6c
	v_lshlrev_b32_e32 v68, 3, v68
	v_add_u32_e32 v69, v101, v68
	ds_write_b64 v69, v[26:27]
	v_bitop3_b32 v26, v81, 8, 15 bitop3:0x6c
	v_lshlrev_b32_e32 v26, 3, v26
	v_add_u32_e32 v27, v101, v26
	ds_write_b64 v27, v[18:19]
	v_bitop3_b32 v18, v81, 9, 15 bitop3:0x6c
	v_lshlrev_b32_e32 v18, 3, v18
	v_add_u32_e32 v19, v101, v18
	ds_write_b64 v19, v[84:85]
	v_bitop3_b32 v19, v81, 10, 15 bitop3:0x6c
	v_lshlrev_b32_e32 v19, 3, v19
	v_add_u32_e32 v27, v101, v19
	ds_write_b64 v27, v[16:17]
	v_bitop3_b32 v16, v81, 11, 15 bitop3:0x6c
	v_lshlrev_b32_e32 v16, 3, v16
	v_add_u32_e32 v17, v101, v16
	ds_write_b64 v17, v[22:23]
	v_bitop3_b32 v17, v81, 12, 15 bitop3:0x6c
	v_lshlrev_b32_e32 v17, 3, v17
	v_add_u32_e32 v22, v101, v17
	ds_write_b64 v22, v[12:13]
	v_bitop3_b32 v12, v81, 13, 15 bitop3:0x6c
	v_lshlrev_b32_e32 v12, 3, v12
	v_add_u32_e32 v13, v101, v12
	ds_write_b64 v13, v[14:15]
	v_bitop3_b32 v13, v81, 14, 15 bitop3:0x6c
	v_lshlrev_b32_e32 v13, 3, v13
	v_add_u32_e32 v14, v101, v13
	ds_write_b64 v14, v[4:5]
	v_bitop3_b32 v4, v81, 15, v81 bitop3:0xc
	v_lshlrev_b32_e32 v4, 3, v4
	v_add_u32_e32 v5, v101, v4
	ds_write_b64 v5, v[8:9]
	v_add_u32_e32 v5, 0x2000, v80
	v_bitop3_b32 v5, v5, v81, 16 bitop3:0x78
	v_lshl_add_u32 v5, v5, 3, 16
	v_add_u32_e32 v8, v5, v100
	ds_write_b64 v8, v[64:65]
	v_add_u32_e32 v8, v5, v70
	ds_write_b64 v8, v[98:99]
	v_add_u32_e32 v8, v5, v71
	ds_write_b64 v8, v[96:97]
	v_add_u32_e32 v8, v5, v86
	ds_write_b64 v8, v[82:83]
	v_add_u32_e32 v8, v5, v74
	ds_write_b64 v8, v[78:79]
	v_add_u32_e32 v8, v5, v20
	ds_write_b64 v8, v[92:93]
	v_add_u32_e32 v8, v5, v21
	ds_write_b64 v8, v[76:77]
	v_add_u32_e32 v8, v5, v68
	ds_write_b64 v8, v[62:63]
	v_add_u32_e32 v8, v5, v26
	ds_write_b64 v8, v[90:91]
	v_add_u32_e32 v8, v5, v18
	ds_write_b64 v8, v[94:95]
	v_add_u32_e32 v8, v5, v19
	ds_write_b64 v8, v[10:11]
	v_add_u32_e32 v8, v5, v16
	ds_write_b64 v8, v[66:67]
	v_add_u32_e32 v8, v5, v17
	ds_write_b64 v8, v[6:7]
	v_add_u32_e32 v6, v5, v12
	ds_write_b64 v6, v[2:3]
	v_add_u32_e32 v2, v5, v13
	ds_write_b64 v2, v[24:25]
	v_add_u32_e32 v2, v5, v4
	v_mov_b32_e32 v22, v146
	ds_write_b64 v2, v[0:1]
	s_waitcnt lgkmcnt(0)
	s_barrier
	s_nop 0
	v_lshlrev_b32_e32 v0, 5, v22
	v_and_b32_e32 v2, 0xfffffe00, v0
	v_and_or_b32 v0, v22, 16, v2
	v_bitop3_b32 v2, v2, 16, v22 bitop3:0x34
	v_bitop3_b32 v6, v22, 4, 15 bitop3:0x6c
	v_bitop3_b32 v14, v22, 8, 15 bitop3:0x6c
	v_lshl_add_u32 v23, v0, 3, 16
	v_lshl_add_u32 v65, v2, 3, 16
	v_lshlrev_b32_e32 v6, 3, v6
	v_lshlrev_b32_e32 v14, 3, v14
	v_bitop3_b32 v2, v22, 1, 15 bitop3:0x6c
	v_add_u32_e32 v105, v23, v6
	v_add_u32_e32 v106, v65, v6
	v_bitop3_b32 v6, v22, 5, 15 bitop3:0x6c
	v_add_u32_e32 v113, v23, v14
	v_add_u32_e32 v114, v65, v14
	v_bitop3_b32 v14, v22, 9, 15 bitop3:0x6c
	v_lshlrev_b32_e32 v2, 3, v2
	v_lshlrev_b32_e32 v6, 3, v6
	v_lshlrev_b32_e32 v14, 3, v14
	v_add_u32_e32 v99, v23, v2
	v_add_u32_e32 v100, v65, v2
	v_bitop3_b32 v2, v22, 2, 15 bitop3:0x6c
	v_add_u32_e32 v107, v23, v6
	v_add_u32_e32 v108, v65, v6
	v_bitop3_b32 v6, v22, 6, 15 bitop3:0x6c
	v_add_u32_e32 v115, v23, v14
	v_add_u32_e32 v116, v65, v14
	v_bitop3_b32 v14, v22, 10, 15 bitop3:0x6c
	v_bitop3_b32 v26, v22, 12, 15 bitop3:0x6c
	v_lshlrev_b32_e32 v2, 3, v2
	v_lshlrev_b32_e32 v6, 3, v6
	v_lshlrev_b32_e32 v14, 3, v14
	v_lshlrev_b32_e32 v26, 3, v26
	v_and_b32_e32 v64, 15, v22
	v_add_u32_e32 v101, v23, v2
	v_add_u32_e32 v102, v65, v2
	v_bitop3_b32 v2, v22, 3, 15 bitop3:0x6c
	v_add_u32_e32 v109, v23, v6
	v_add_u32_e32 v110, v65, v6
	v_bitop3_b32 v6, v22, 7, 15 bitop3:0x6c
	v_add_u32_e32 v117, v23, v14
	v_add_u32_e32 v118, v65, v14
	v_bitop3_b32 v14, v22, 11, 15 bitop3:0x6c
	v_add_u32_e32 v121, v23, v26
	v_add_u32_e32 v122, v65, v26
	v_bitop3_b32 v26, v22, 13, 15 bitop3:0x6c
	v_bitop3_b32 v66, v22, 14, 15 bitop3:0x6c
	v_bitop3_b32 v22, v22, 15, v22 bitop3:0xc
	v_lshlrev_b32_e32 v3, 3, v64
	v_lshlrev_b32_e32 v2, 3, v2
	v_lshlrev_b32_e32 v6, 3, v6
	v_lshlrev_b32_e32 v14, 3, v14
	v_lshlrev_b32_e32 v26, 3, v26
	v_lshlrev_b32_e32 v66, 3, v66
	v_lshlrev_b32_e32 v22, 3, v22
	v_add_u32_e32 v67, v23, v3
	v_add_u32_e32 v98, v65, v3
	v_add_u32_e32 v103, v23, v2
	v_add_u32_e32 v104, v65, v2
	v_add_u32_e32 v111, v23, v6
	v_add_u32_e32 v112, v65, v6
	v_add_u32_e32 v119, v23, v14
	v_add_u32_e32 v120, v65, v14
	v_add_u32_e32 v123, v23, v26
	v_add_u32_e32 v124, v65, v26
	v_add_u32_e32 v125, v23, v66
	v_add_u32_e32 v126, v65, v66
	v_add_u32_e32 v127, v23, v22
	v_add_u32_e32 v128, v65, v22
	ds_read_b64 v[0:1], v67
	ds_read_b64 v[12:13], v98
	ds_read_b64 v[74:75], v99 offset:256
	ds_read_b64 v[4:5], v100 offset:256
	ds_read_b64 v[76:77], v101 offset:512
	ds_read_b64 v[10:11], v102 offset:512
	ds_read_b64 v[70:71], v103 offset:768
	ds_read_b64 v[2:3], v104 offset:768
	ds_read_b64 v[62:63], v105 offset:1024
	ds_read_b64 v[20:21], v106 offset:1024
	ds_read_b64 v[90:91], v107 offset:1280
	ds_read_b64 v[8:9], v108 offset:1280
	ds_read_b64 v[84:85], v109 offset:1536
	ds_read_b64 v[16:17], v110 offset:1536
	ds_read_b64 v[82:83], v111 offset:1792
	ds_read_b64 v[6:7], v112 offset:1792
	ds_read_b64 v[24:25], v113 offset:2048
	ds_read_b64 v[78:79], v114 offset:2048
	ds_read_b64 v[96:97], v115 offset:2304
	ds_read_b64 v[18:19], v116 offset:2304
	ds_read_b64 v[86:87], v117 offset:2560
	ds_read_b64 v[72:73], v118 offset:2560
	ds_read_b64 v[130:131], v119 offset:2816
	ds_read_b64 v[14:15], v120 offset:2816
	ds_read_b64 v[80:81], v121 offset:3072
	ds_read_b64 v[92:93], v122 offset:3072
	ds_read_b64 v[132:133], v123 offset:3328
	ds_read_b64 v[26:27], v124 offset:3328
	ds_read_b64 v[94:95], v125 offset:3584
	ds_read_b64 v[88:89], v126 offset:3584
	ds_read_b64 v[134:135], v127 offset:3840
	ds_read_b64 v[22:23], v128 offset:3840
	s_waitcnt lgkmcnt(14)
	v_xor_b32_e32 v138, 0x80000000, v25
	v_cvt_f32_i32_e32 v64, v64
	v_mov_b32_e32 v139, v24
	v_mul_f32_e32 v64, 0x3b000000, v64
	v_cos_f32_e32 v68, v64
	v_sin_f32_e32 v69, v64
	v_add_f32_e32 v66, v68, v68
	v_pk_mul_f32 v[64:65], v[68:69], v[68:69]
	v_mul_f32_e32 v66, v69, v66
	v_xor_b32_e32 v136, 0x80000000, v69
	v_mov_b32_e32 v137, v68
	v_mov_b32_e32 v140, v69
	v_pk_add_f32 v[64:65], v[64:65], v[64:65] op_sel:[0,1] op_sel_hi:[0,1] neg_lo:[0,1] neg_hi:[0,1]
	v_pk_mul_f32 v[136:137], v[136:137], v[66:67] op_sel_hi:[1,0]
	v_pk_mul_f32 v[138:139], v[138:139], v[140:141] op_sel_hi:[1,0]
	v_pk_fma_f32 v[136:137], v[68:69], v[64:65], v[136:137]
	v_pk_fma_f32 v[24:25], v[24:25], v[68:69], v[138:139] op_sel_hi:[1,0,1]
	v_pk_mul_f32 v[68:69], v[66:67], s[48:49] op_sel_hi:[0,1]
	v_pk_fma_f32 v[138:139], v[64:65], s[40:41], v[68:69]
	v_xor_b32_e32 v68, 0x80000000, v63
	v_mov_b32_e32 v69, v62
	v_pk_mul_f32 v[68:69], v[68:69], v[138:139] op_sel:[0,1]
	s_nop 0
	v_pk_fma_f32 v[68:69], v[62:63], v[138:139], v[68:69] op_sel_hi:[1,0,1]
	v_xor_b32_e32 v62, 0x80000000, v137
	v_mov_b32_e32 v63, v136
	v_pk_mul_f32 v[62:63], v[66:67], v[62:63] op_sel_hi:[0,1]
	v_pk_fma_f32 v[140:141], v[64:65], v[136:137], v[62:63]
	s_waitcnt lgkmcnt(7)
	v_xor_b32_e32 v62, 0x80000000, v81
	v_mov_b32_e32 v63, v80
	v_pk_mul_f32 v[62:63], v[62:63], v[136:137] op_sel:[0,1]
	s_nop 0
	v_pk_fma_f32 v[62:63], v[80:81], v[136:137], v[62:63] op_sel_hi:[1,0,1]
	v_xor_b32_e32 v80, 0x80000000, v139
	v_mov_b32_e32 v81, v138
	v_pk_mul_f32 v[80:81], v[66:67], v[80:81] op_sel_hi:[0,1]
	v_pk_fma_f32 v[136:137], v[64:65], v[138:139], v[80:81]
	v_xor_b32_e32 v80, 0x80000000, v77
	v_mov_b32_e32 v81, v76
	v_pk_mul_f32 v[80:81], v[80:81], v[136:137] op_sel:[0,1]
	s_nop 0
	v_pk_fma_f32 v[80:81], v[76:77], v[136:137], v[80:81] op_sel_hi:[1,0,1]
	v_xor_b32_e32 v76, 0x80000000, v141
	v_mov_b32_e32 v77, v140
	v_pk_mul_f32 v[76:77], v[66:67], v[76:77] op_sel_hi:[0,1]
	v_pk_fma_f32 v[138:139], v[64:65], v[140:141], v[76:77]
	v_xor_b32_e32 v76, 0x80000000, v87
	v_mov_b32_e32 v77, v86
	v_pk_mul_f32 v[76:77], v[76:77], v[140:141] op_sel:[0,1]
	s_nop 0
	v_pk_fma_f32 v[76:77], v[86:87], v[140:141], v[76:77] op_sel_hi:[1,0,1]
	v_xor_b32_e32 v86, 0x80000000, v137
	v_mov_b32_e32 v87, v136
	v_pk_mul_f32 v[86:87], v[66:67], v[86:87] op_sel_hi:[0,1]
	v_pk_fma_f32 v[136:137], v[64:65], v[136:137], v[86:87]
	v_xor_b32_e32 v86, 0x80000000, v85
	v_mov_b32_e32 v87, v84
	v_pk_mul_f32 v[86:87], v[86:87], v[136:137] op_sel:[0,1]
	s_nop 0
	v_pk_fma_f32 v[86:87], v[84:85], v[136:137], v[86:87] op_sel_hi:[1,0,1]
	v_xor_b32_e32 v84, 0x80000000, v139
	v_mov_b32_e32 v85, v138
	v_pk_mul_f32 v[84:85], v[66:67], v[84:85] op_sel_hi:[0,1]
	v_pk_fma_f32 v[140:141], v[64:65], v[138:139], v[84:85]
	s_waitcnt lgkmcnt(3)
	v_xor_b32_e32 v84, 0x80000000, v95
	v_mov_b32_e32 v85, v94
	v_pk_mul_f32 v[84:85], v[84:85], v[138:139] op_sel:[0,1]
	s_nop 0
	v_pk_fma_f32 v[84:85], v[94:95], v[138:139], v[84:85] op_sel_hi:[1,0,1]
	v_xor_b32_e32 v94, 0x80000000, v137
	v_mov_b32_e32 v95, v136
	v_pk_mul_f32 v[94:95], v[66:67], v[94:95] op_sel_hi:[0,1]
	v_pk_fma_f32 v[136:137], v[64:65], v[136:137], v[94:95]
	v_xor_b32_e32 v94, 0x80000000, v75
	v_mov_b32_e32 v95, v74
	v_pk_mul_f32 v[94:95], v[94:95], v[136:137] op_sel:[0,1]
	s_nop 0
	v_pk_fma_f32 v[94:95], v[74:75], v[136:137], v[94:95] op_sel_hi:[1,0,1]
	v_xor_b32_e32 v74, 0x80000000, v141
	v_mov_b32_e32 v75, v140
	v_pk_mul_f32 v[74:75], v[66:67], v[74:75] op_sel_hi:[0,1]
	v_pk_fma_f32 v[138:139], v[64:65], v[140:141], v[74:75]
	v_xor_b32_e32 v74, 0x80000000, v97
	v_mov_b32_e32 v75, v96
	v_pk_mul_f32 v[74:75], v[74:75], v[140:141] op_sel:[0,1]
	s_nop 0
	v_pk_fma_f32 v[74:75], v[96:97], v[140:141], v[74:75] op_sel_hi:[1,0,1]
	v_xor_b32_e32 v96, 0x80000000, v137
	v_mov_b32_e32 v97, v136
	v_pk_mul_f32 v[96:97], v[66:67], v[96:97] op_sel_hi:[0,1]
	v_pk_fma_f32 v[136:137], v[64:65], v[136:137], v[96:97]
	v_xor_b32_e32 v96, 0x80000000, v91
	v_mov_b32_e32 v97, v90
	v_pk_mul_f32 v[96:97], v[96:97], v[136:137] op_sel:[0,1]
	s_nop 0
	v_pk_fma_f32 v[96:97], v[90:91], v[136:137], v[96:97] op_sel_hi:[1,0,1]
	v_xor_b32_e32 v90, 0x80000000, v139
	v_mov_b32_e32 v91, v138
	v_pk_mul_f32 v[90:91], v[66:67], v[90:91] op_sel_hi:[0,1]
	v_pk_fma_f32 v[140:141], v[64:65], v[138:139], v[90:91]
	v_xor_b32_e32 v90, 0x80000000, v133
	v_mov_b32_e32 v91, v132
	v_pk_mul_f32 v[90:91], v[90:91], v[138:139] op_sel:[0,1]
	s_nop 0
	v_pk_fma_f32 v[90:91], v[132:133], v[138:139], v[90:91] op_sel_hi:[1,0,1]
	v_xor_b32_e32 v132, 0x80000000, v137
	v_mov_b32_e32 v133, v136
	v_pk_mul_f32 v[132:133], v[66:67], v[132:133] op_sel_hi:[0,1]
	v_xor_b32_e32 v138, 0x80000000, v131
	v_mov_b32_e32 v139, v130
	v_pk_fma_f32 v[132:133], v[64:65], v[136:137], v[132:133]
	v_xor_b32_e32 v136, 0x80000000, v71
	v_mov_b32_e32 v137, v70
	v_pk_mul_f32 v[138:139], v[138:139], v[140:141] op_sel:[0,1]
	v_pk_mul_f32 v[136:137], v[136:137], v[132:133] op_sel:[0,1]
	v_pk_fma_f32 v[130:131], v[130:131], v[140:141], v[138:139] op_sel_hi:[1,0,1]
	v_xor_b32_e32 v138, 0x80000000, v133
	v_mov_b32_e32 v139, v132
	v_pk_fma_f32 v[70:71], v[70:71], v[132:133], v[136:137] op_sel_hi:[1,0,1]
	v_xor_b32_e32 v136, 0x80000000, v141
	v_mov_b32_e32 v137, v140
	v_pk_mul_f32 v[138:139], v[66:67], v[138:139] op_sel_hi:[0,1]
	v_pk_mul_f32 v[136:137], v[66:67], v[136:137] op_sel_hi:[0,1]
	v_pk_fma_f32 v[132:133], v[64:65], v[132:133], v[138:139]
	v_xor_b32_e32 v138, 0x80000000, v83
	v_mov_b32_e32 v139, v82
	v_pk_fma_f32 v[136:137], v[64:65], v[140:141], v[136:137]
	v_pk_mul_f32 v[138:139], v[138:139], v[132:133] op_sel:[0,1]
	s_waitcnt lgkmcnt(1)
	v_xor_b32_e32 v140, 0x80000000, v135
	v_pk_fma_f32 v[82:83], v[82:83], v[132:133], v[138:139] op_sel_hi:[1,0,1]
	v_xor_b32_e32 v138, 0x80000000, v137
	v_mov_b32_e32 v139, v136
	v_mov_b32_e32 v141, v134
	v_pk_mul_f32 v[138:139], v[66:67], v[138:139] op_sel_hi:[0,1]
	v_pk_mul_f32 v[140:141], v[140:141], v[136:137] op_sel:[0,1]
	v_pk_fma_f32 v[138:139], v[64:65], v[136:137], v[138:139]
	v_pk_fma_f32 v[134:135], v[134:135], v[136:137], v[140:141] op_sel_hi:[1,0,1]
	v_xor_b32_e32 v136, 0x80000000, v133
	v_mov_b32_e32 v137, v132
	v_pk_mul_f32 v[136:137], v[66:67], v[136:137] op_sel_hi:[0,1]
	v_pk_fma_f32 v[132:133], v[64:65], v[132:133], v[136:137]
	v_xor_b32_e32 v136, 0x80000000, v13
	v_mov_b32_e32 v137, v12
	v_pk_mul_f32 v[136:137], v[136:137], v[132:133] op_sel:[0,1]
	v_xor_b32_e32 v140, 0x80000000, v79
	v_pk_fma_f32 v[12:13], v[12:13], v[132:133], v[136:137] op_sel_hi:[1,0,1]
	v_xor_b32_e32 v136, 0x80000000, v139
	v_mov_b32_e32 v137, v138
	v_mov_b32_e32 v141, v78
	v_pk_mul_f32 v[136:137], v[66:67], v[136:137] op_sel_hi:[0,1]
	v_pk_mul_f32 v[140:141], v[140:141], v[138:139] op_sel:[0,1]
	v_pk_fma_f32 v[136:137], v[64:65], v[138:139], v[136:137]
	v_pk_fma_f32 v[78:79], v[78:79], v[138:139], v[140:141] op_sel_hi:[1,0,1]
	v_xor_b32_e32 v138, 0x80000000, v133
	v_mov_b32_e32 v139, v132
	v_pk_mul_f32 v[138:139], v[66:67], v[138:139] op_sel_hi:[0,1]
	v_pk_fma_f32 v[132:133], v[64:65], v[132:133], v[138:139]
	v_xor_b32_e32 v138, 0x80000000, v21
	v_mov_b32_e32 v139, v20
	v_pk_mul_f32 v[138:139], v[138:139], v[132:133] op_sel:[0,1]
	v_xor_b32_e32 v140, 0x80000000, v93
	v_pk_fma_f32 v[20:21], v[20:21], v[132:133], v[138:139] op_sel_hi:[1,0,1]
	v_xor_b32_e32 v138, 0x80000000, v137
	v_mov_b32_e32 v139, v136
	v_mov_b32_e32 v141, v92
	v_pk_mul_f32 v[138:139], v[66:67], v[138:139] op_sel_hi:[0,1]
	v_pk_mul_f32 v[140:141], v[140:141], v[136:137] op_sel:[0,1]
	v_pk_fma_f32 v[138:139], v[64:65], v[136:137], v[138:139]
	v_pk_fma_f32 v[92:93], v[92:93], v[136:137], v[140:141] op_sel_hi:[1,0,1]
	v_xor_b32_e32 v136, 0x80000000, v133
	v_mov_b32_e32 v137, v132
	v_pk_mul_f32 v[136:137], v[66:67], v[136:137] op_sel_hi:[0,1]
	v_pk_fma_f32 v[132:133], v[64:65], v[132:133], v[136:137]
	v_xor_b32_e32 v136, 0x80000000, v11
	v_mov_b32_e32 v137, v10
	v_pk_mul_f32 v[136:137], v[136:137], v[132:133] op_sel:[0,1]
	v_xor_b32_e32 v140, 0x80000000, v73
	v_pk_fma_f32 v[10:11], v[10:11], v[132:133], v[136:137] op_sel_hi:[1,0,1]
	v_xor_b32_e32 v136, 0x80000000, v139
	v_mov_b32_e32 v137, v138
	v_mov_b32_e32 v141, v72
	v_pk_mul_f32 v[136:137], v[66:67], v[136:137] op_sel_hi:[0,1]
	v_pk_mul_f32 v[140:141], v[140:141], v[138:139] op_sel:[0,1]
	v_pk_fma_f32 v[136:137], v[64:65], v[138:139], v[136:137]
	v_pk_fma_f32 v[72:73], v[72:73], v[138:139], v[140:141] op_sel_hi:[1,0,1]
	v_xor_b32_e32 v138, 0x80000000, v133
	v_mov_b32_e32 v139, v132
	v_pk_mul_f32 v[138:139], v[66:67], v[138:139] op_sel_hi:[0,1]
	v_pk_fma_f32 v[132:133], v[64:65], v[132:133], v[138:139]
	v_xor_b32_e32 v138, 0x80000000, v17
	v_mov_b32_e32 v139, v16
	v_pk_mul_f32 v[138:139], v[138:139], v[132:133] op_sel:[0,1]
	v_xor_b32_e32 v140, 0x80000000, v89
	v_pk_fma_f32 v[16:17], v[16:17], v[132:133], v[138:139] op_sel_hi:[1,0,1]
	v_xor_b32_e32 v138, 0x80000000, v137
	v_mov_b32_e32 v139, v136
	v_mov_b32_e32 v141, v88
	v_pk_mul_f32 v[138:139], v[66:67], v[138:139] op_sel_hi:[0,1]
	v_pk_mul_f32 v[140:141], v[140:141], v[136:137] op_sel:[0,1]
	v_pk_fma_f32 v[138:139], v[64:65], v[136:137], v[138:139]
	v_pk_fma_f32 v[88:89], v[88:89], v[136:137], v[140:141] op_sel_hi:[1,0,1]
	v_xor_b32_e32 v136, 0x80000000, v133
	v_mov_b32_e32 v137, v132
	v_pk_mul_f32 v[136:137], v[66:67], v[136:137] op_sel_hi:[0,1]
	v_pk_fma_f32 v[132:133], v[64:65], v[132:133], v[136:137]
	v_xor_b32_e32 v136, 0x80000000, v5
	v_mov_b32_e32 v137, v4
	v_pk_mul_f32 v[136:137], v[136:137], v[132:133] op_sel:[0,1]
	v_xor_b32_e32 v140, 0x80000000, v19
	v_pk_fma_f32 v[4:5], v[4:5], v[132:133], v[136:137] op_sel_hi:[1,0,1]
	v_xor_b32_e32 v136, 0x80000000, v139
	v_mov_b32_e32 v137, v138
	v_mov_b32_e32 v141, v18
	v_pk_mul_f32 v[136:137], v[66:67], v[136:137] op_sel_hi:[0,1]
	v_pk_mul_f32 v[140:141], v[140:141], v[138:139] op_sel:[0,1]
	v_pk_fma_f32 v[136:137], v[64:65], v[138:139], v[136:137]
	v_pk_fma_f32 v[18:19], v[18:19], v[138:139], v[140:141] op_sel_hi:[1,0,1]
	v_xor_b32_e32 v138, 0x80000000, v133
	v_mov_b32_e32 v139, v132
	v_pk_mul_f32 v[138:139], v[66:67], v[138:139] op_sel_hi:[0,1]
	v_pk_fma_f32 v[132:133], v[64:65], v[132:133], v[138:139]
	v_xor_b32_e32 v138, 0x80000000, v9
	v_mov_b32_e32 v139, v8
	v_pk_mul_f32 v[138:139], v[138:139], v[132:133] op_sel:[0,1]
	v_xor_b32_e32 v140, 0x80000000, v27
	v_pk_fma_f32 v[8:9], v[8:9], v[132:133], v[138:139] op_sel_hi:[1,0,1]
	v_xor_b32_e32 v138, 0x80000000, v137
	v_mov_b32_e32 v139, v136
	v_mov_b32_e32 v141, v26
	v_pk_mul_f32 v[138:139], v[66:67], v[138:139] op_sel_hi:[0,1]
	v_pk_mul_f32 v[140:141], v[140:141], v[136:137] op_sel:[0,1]
	v_pk_fma_f32 v[138:139], v[64:65], v[136:137], v[138:139]
	v_pk_fma_f32 v[26:27], v[26:27], v[136:137], v[140:141] op_sel_hi:[1,0,1]
	v_xor_b32_e32 v136, 0x80000000, v133
	v_mov_b32_e32 v137, v132
	v_pk_mul_f32 v[136:137], v[66:67], v[136:137] op_sel_hi:[0,1]
	v_pk_fma_f32 v[132:133], v[64:65], v[132:133], v[136:137]
	v_xor_b32_e32 v136, 0x80000000, v3
	v_mov_b32_e32 v137, v2
	v_pk_mul_f32 v[136:137], v[136:137], v[132:133] op_sel:[0,1]
	v_xor_b32_e32 v140, 0x80000000, v15
	v_pk_fma_f32 v[2:3], v[2:3], v[132:133], v[136:137] op_sel_hi:[1,0,1]
	v_xor_b32_e32 v136, 0x80000000, v139
	v_mov_b32_e32 v137, v138
	v_mov_b32_e32 v141, v14
	v_pk_mul_f32 v[136:137], v[66:67], v[136:137] op_sel_hi:[0,1]
	v_pk_mul_f32 v[140:141], v[140:141], v[138:139] op_sel:[0,1]
	v_pk_fma_f32 v[136:137], v[64:65], v[138:139], v[136:137]
	v_pk_fma_f32 v[14:15], v[14:15], v[138:139], v[140:141] op_sel_hi:[1,0,1]
	v_xor_b32_e32 v138, 0x80000000, v133
	v_mov_b32_e32 v139, v132
	v_pk_mul_f32 v[138:139], v[66:67], v[138:139] op_sel_hi:[0,1]
	v_pk_fma_f32 v[64:65], v[64:65], v[132:133], v[138:139]
	v_xor_b32_e32 v132, 0x80000000, v7
	v_mov_b32_e32 v133, v6
	v_pk_mul_f32 v[132:133], v[132:133], v[64:65] op_sel:[0,1]
	s_nop 0
	v_pk_fma_f32 v[6:7], v[6:7], v[64:65], v[132:133] op_sel_hi:[1,0,1]
	s_waitcnt lgkmcnt(0)
	v_xor_b32_e32 v64, 0x80000000, v23
	v_mov_b32_e32 v65, v22
	v_pk_mul_f32 v[64:65], v[64:65], v[136:137] op_sel:[0,1]
	s_nop 0
	v_pk_fma_f32 v[22:23], v[22:23], v[136:137], v[64:65] op_sel_hi:[1,0,1]
	v_pk_add_f32 v[64:65], v[0:1], v[12:13]
	v_pk_add_f32 v[0:1], v[0:1], v[12:13] neg_lo:[0,1] neg_hi:[0,1]
	v_pk_add_f32 v[12:13], v[94:95], v[4:5]
	v_pk_add_f32 v[4:5], v[94:95], v[4:5] neg_lo:[0,1] neg_hi:[0,1]
	v_pk_add_f32 v[94:95], v[80:81], v[10:11]
	v_pk_add_f32 v[10:11], v[80:81], v[10:11] neg_lo:[0,1] neg_hi:[0,1]
	v_pk_add_f32 v[80:81], v[70:71], v[2:3]
	v_pk_add_f32 v[2:3], v[70:71], v[2:3] neg_lo:[0,1] neg_hi:[0,1]
	v_pk_add_f32 v[132:133], v[64:65], v[12:13]
	v_pk_add_f32 v[12:13], v[64:65], v[12:13] neg_lo:[0,1] neg_hi:[0,1]
	v_xor_b32_e32 v64, 0x80000000, v5
	v_mov_b32_e32 v65, v4
	v_pk_add_f32 v[70:71], v[68:69], v[20:21]
	v_pk_add_f32 v[20:21], v[68:69], v[20:21] neg_lo:[0,1] neg_hi:[0,1]
	v_pk_add_f32 v[68:69], v[96:97], v[8:9]
	v_pk_add_f32 v[8:9], v[96:97], v[8:9] neg_lo:[0,1] neg_hi:[0,1]
	v_pk_add_f32 v[4:5], v[0:1], v[64:65]
	v_pk_add_f32 v[0:1], v[0:1], v[64:65] neg_lo:[0,1] neg_hi:[0,1]
	v_pk_add_f32 v[64:65], v[94:95], v[80:81]
	v_pk_add_f32 v[80:81], v[94:95], v[80:81] neg_lo:[0,1] neg_hi:[0,1]
	v_xor_b32_e32 v94, 0x80000000, v3
	v_mov_b32_e32 v95, v2
	v_pk_add_f32 v[96:97], v[86:87], v[16:17]
	v_pk_add_f32 v[16:17], v[86:87], v[16:17] neg_lo:[0,1] neg_hi:[0,1]
	v_pk_add_f32 v[86:87], v[82:83], v[6:7]
	v_pk_add_f32 v[6:7], v[82:83], v[6:7] neg_lo:[0,1] neg_hi:[0,1]
	v_pk_add_f32 v[2:3], v[10:11], v[94:95]
	v_pk_add_f32 v[10:11], v[10:11], v[94:95] neg_lo:[0,1] neg_hi:[0,1]
	v_pk_add_f32 v[94:95], v[70:71], v[68:69]
	v_pk_add_f32 v[68:69], v[70:71], v[68:69] neg_lo:[0,1] neg_hi:[0,1]
	v_xor_b32_e32 v70, 0x80000000, v9
	v_mov_b32_e32 v71, v8
	v_pk_add_f32 v[82:83], v[24:25], v[78:79]
	v_pk_add_f32 v[24:25], v[24:25], v[78:79] neg_lo:[0,1] neg_hi:[0,1]
	v_pk_add_f32 v[78:79], v[74:75], v[18:19]
	v_pk_add_f32 v[18:19], v[74:75], v[18:19] neg_lo:[0,1] neg_hi:[0,1]
	v_pk_add_f32 v[8:9], v[20:21], v[70:71]
	v_pk_add_f32 v[20:21], v[20:21], v[70:71] neg_lo:[0,1] neg_hi:[0,1]
	v_pk_add_f32 v[70:71], v[96:97], v[86:87]
	v_pk_add_f32 v[86:87], v[96:97], v[86:87] neg_lo:[0,1] neg_hi:[0,1]
	v_xor_b32_e32 v96, 0x80000000, v7
	v_mov_b32_e32 v97, v6
	v_pk_add_f32 v[74:75], v[76:77], v[72:73]
	v_pk_add_f32 v[72:73], v[76:77], v[72:73] neg_lo:[0,1] neg_hi:[0,1]
	v_pk_add_f32 v[76:77], v[130:131], v[14:15]
	v_pk_add_f32 v[14:15], v[130:131], v[14:15] neg_lo:[0,1] neg_hi:[0,1]
	v_pk_add_f32 v[6:7], v[16:17], v[96:97]
	v_pk_add_f32 v[16:17], v[16:17], v[96:97] neg_lo:[0,1] neg_hi:[0,1]
	v_pk_add_f32 v[96:97], v[82:83], v[78:79]
	v_pk_add_f32 v[78:79], v[82:83], v[78:79] neg_lo:[0,1] neg_hi:[0,1]
	v_xor_b32_e32 v82, 0x80000000, v19
	v_mov_b32_e32 v83, v18
	v_pk_add_f32 v[130:131], v[62:63], v[92:93]
	v_pk_add_f32 v[62:63], v[62:63], v[92:93] neg_lo:[0,1] neg_hi:[0,1]
	v_pk_add_f32 v[92:93], v[90:91], v[26:27]
	v_pk_add_f32 v[26:27], v[90:91], v[26:27] neg_lo:[0,1] neg_hi:[0,1]
	v_pk_add_f32 v[18:19], v[24:25], v[82:83]
	v_pk_add_f32 v[24:25], v[24:25], v[82:83] neg_lo:[0,1] neg_hi:[0,1]
	v_pk_add_f32 v[82:83], v[74:75], v[76:77]
	v_pk_add_f32 v[74:75], v[74:75], v[76:77] neg_lo:[0,1] neg_hi:[0,1]
	v_xor_b32_e32 v76, 0x80000000, v15
	v_mov_b32_e32 v77, v14
	v_pk_add_f32 v[90:91], v[84:85], v[88:89]
	v_pk_add_f32 v[84:85], v[84:85], v[88:89] neg_lo:[0,1] neg_hi:[0,1]
	v_pk_add_f32 v[88:89], v[134:135], v[22:23]
	v_pk_add_f32 v[22:23], v[134:135], v[22:23] neg_lo:[0,1] neg_hi:[0,1]
	v_pk_add_f32 v[14:15], v[72:73], v[76:77]
	v_pk_add_f32 v[72:73], v[72:73], v[76:77] neg_lo:[0,1] neg_hi:[0,1]
	v_pk_add_f32 v[76:77], v[130:131], v[92:93]
	v_pk_add_f32 v[92:93], v[130:131], v[92:93] neg_lo:[0,1] neg_hi:[0,1]
	v_xor_b32_e32 v130, 0x80000000, v27
	v_mov_b32_e32 v131, v26
	v_pk_add_f32 v[26:27], v[62:63], v[130:131]
	v_pk_add_f32 v[62:63], v[62:63], v[130:131] neg_lo:[0,1] neg_hi:[0,1]
	v_pk_add_f32 v[130:131], v[90:91], v[88:89]
	v_pk_add_f32 v[88:89], v[90:91], v[88:89] neg_lo:[0,1] neg_hi:[0,1]
	v_xor_b32_e32 v90, 0x80000000, v23
	v_mov_b32_e32 v91, v22
	v_pk_add_f32 v[22:23], v[84:85], v[90:91]
	v_pk_add_f32 v[84:85], v[84:85], v[90:91] neg_lo:[0,1] neg_hi:[0,1]
	v_pk_add_f32 v[90:91], v[132:133], v[64:65]
	v_pk_add_f32 v[64:65], v[132:133], v[64:65] neg_lo:[0,1] neg_hi:[0,1]
	v_xor_b32_e32 v132, 0x80000000, v3
	v_mov_b32_e32 v133, v2
	v_pk_mul_f32 v[132:133], v[132:133], s[70:71] op_sel_hi:[1,0]
	v_xor_b32_e32 v134, 0x80000000, v11
	v_pk_fma_f32 v[2:3], v[2:3], s[70:71], v[132:133] op_sel_hi:[1,0,1]
	v_mov_b32_e32 v135, v10
	v_pk_add_f32 v[132:133], v[4:5], v[2:3]
	v_pk_add_f32 v[2:3], v[4:5], v[2:3] neg_lo:[0,1] neg_hi:[0,1]
	v_xor_b32_e32 v4, 0x80000000, v81
	v_mov_b32_e32 v5, v80
	v_pk_add_f32 v[80:81], v[12:13], v[4:5]
	v_pk_add_f32 v[4:5], v[12:13], v[4:5] neg_lo:[0,1] neg_hi:[0,1]
	v_pk_mul_f32 v[12:13], v[10:11], s[70:71] op_sel_hi:[1,0]
	s_nop 0
	v_pk_fma_f32 v[10:11], v[134:135], s[70:71], v[12:13] op_sel_hi:[1,0,1] neg_lo:[0,0,1] neg_hi:[0,0,1]
	v_xor_b32_e32 v134, 0x80000000, v17
	v_pk_add_f32 v[12:13], v[0:1], v[10:11]
	v_pk_add_f32 v[0:1], v[0:1], v[10:11] neg_lo:[0,1] neg_hi:[0,1]
	v_pk_add_f32 v[10:11], v[94:95], v[70:71]
	v_pk_add_f32 v[70:71], v[94:95], v[70:71] neg_lo:[0,1] neg_hi:[0,1]
	v_xor_b32_e32 v94, 0x80000000, v7
	v_mov_b32_e32 v95, v6
	v_pk_mul_f32 v[94:95], v[94:95], s[70:71] op_sel_hi:[1,0]
	v_mov_b32_e32 v135, v16
	v_pk_fma_f32 v[6:7], v[6:7], s[70:71], v[94:95] op_sel_hi:[1,0,1]
	s_nop 0
	v_pk_add_f32 v[94:95], v[8:9], v[6:7]
	v_pk_add_f32 v[6:7], v[8:9], v[6:7] neg_lo:[0,1] neg_hi:[0,1]
	v_xor_b32_e32 v8, 0x80000000, v87
	v_mov_b32_e32 v9, v86
	v_pk_add_f32 v[86:87], v[68:69], v[8:9]
	v_pk_add_f32 v[8:9], v[68:69], v[8:9] neg_lo:[0,1] neg_hi:[0,1]
	v_pk_mul_f32 v[68:69], v[16:17], s[70:71] op_sel_hi:[1,0]
	s_nop 0
	v_pk_fma_f32 v[16:17], v[134:135], s[70:71], v[68:69] op_sel_hi:[1,0,1] neg_lo:[0,0,1] neg_hi:[0,0,1]
	v_xor_b32_e32 v134, 0x80000000, v73
	v_pk_add_f32 v[68:69], v[20:21], v[16:17]
	v_pk_add_f32 v[16:17], v[20:21], v[16:17] neg_lo:[0,1] neg_hi:[0,1]
	v_pk_add_f32 v[20:21], v[96:97], v[82:83]
	v_pk_add_f32 v[82:83], v[96:97], v[82:83] neg_lo:[0,1] neg_hi:[0,1]
	v_xor_b32_e32 v96, 0x80000000, v15
	v_mov_b32_e32 v97, v14
	v_pk_mul_f32 v[96:97], v[96:97], s[70:71] op_sel_hi:[1,0]
	v_mov_b32_e32 v135, v72
	v_pk_fma_f32 v[14:15], v[14:15], s[70:71], v[96:97] op_sel_hi:[1,0,1]
	s_nop 0
	v_pk_add_f32 v[96:97], v[18:19], v[14:15]
	v_pk_add_f32 v[14:15], v[18:19], v[14:15] neg_lo:[0,1] neg_hi:[0,1]
	v_xor_b32_e32 v18, 0x80000000, v75
	v_mov_b32_e32 v19, v74
	v_pk_add_f32 v[74:75], v[78:79], v[18:19]
	v_pk_add_f32 v[18:19], v[78:79], v[18:19] neg_lo:[0,1] neg_hi:[0,1]
	v_pk_mul_f32 v[78:79], v[72:73], s[70:71] op_sel_hi:[1,0]
	s_nop 0
	v_pk_fma_f32 v[72:73], v[134:135], s[70:71], v[78:79] op_sel_hi:[1,0,1] neg_lo:[0,0,1] neg_hi:[0,0,1]
	v_xor_b32_e32 v134, 0x80000000, v85
	v_pk_add_f32 v[78:79], v[24:25], v[72:73]
	v_pk_add_f32 v[24:25], v[24:25], v[72:73] neg_lo:[0,1] neg_hi:[0,1]
	v_pk_add_f32 v[72:73], v[76:77], v[130:131]
	v_pk_add_f32 v[76:77], v[76:77], v[130:131] neg_lo:[0,1] neg_hi:[0,1]
	v_xor_b32_e32 v130, 0x80000000, v23
	v_mov_b32_e32 v131, v22
	v_pk_mul_f32 v[130:131], v[130:131], s[70:71] op_sel_hi:[1,0]
	v_mov_b32_e32 v135, v84
	v_pk_fma_f32 v[22:23], v[22:23], s[70:71], v[130:131] op_sel_hi:[1,0,1]
	s_nop 0
	v_pk_add_f32 v[130:131], v[26:27], v[22:23]
	v_pk_add_f32 v[22:23], v[26:27], v[22:23] neg_lo:[0,1] neg_hi:[0,1]
	v_xor_b32_e32 v26, 0x80000000, v89
	v_mov_b32_e32 v27, v88
	v_pk_add_f32 v[88:89], v[92:93], v[26:27]
	v_pk_add_f32 v[26:27], v[92:93], v[26:27] neg_lo:[0,1] neg_hi:[0,1]
	v_pk_mul_f32 v[92:93], v[84:85], s[70:71] op_sel_hi:[1,0]
	s_nop 0
	v_pk_fma_f32 v[84:85], v[134:135], s[70:71], v[92:93] op_sel_hi:[1,0,1] neg_lo:[0,0,1] neg_hi:[0,0,1]
	v_xor_b32_e32 v134, 0x80000000, v7
	v_pk_add_f32 v[92:93], v[62:63], v[84:85]
	v_pk_add_f32 v[62:63], v[62:63], v[84:85] neg_lo:[0,1] neg_hi:[0,1]
	v_pk_add_f32 v[84:85], v[90:91], v[10:11]
	v_pk_add_f32 v[10:11], v[90:91], v[10:11] neg_lo:[0,1] neg_hi:[0,1]
	v_xor_b32_e32 v90, 0x80000000, v95
	v_mov_b32_e32 v91, v94
	v_pk_mul_f32 v[90:91], v[90:91], s[62:63] op_sel_hi:[1,0]
	v_mov_b32_e32 v135, v6
	v_pk_fma_f32 v[90:91], v[94:95], s[60:61], v[90:91] op_sel_hi:[1,0,1]
	s_nop 0
	v_pk_add_f32 v[94:95], v[132:133], v[90:91]
	v_pk_add_f32 v[90:91], v[132:133], v[90:91] neg_lo:[0,1] neg_hi:[0,1]
	v_xor_b32_e32 v132, 0x80000000, v87
	v_mov_b32_e32 v133, v86
	v_pk_mul_f32 v[132:133], v[132:133], s[70:71] op_sel_hi:[1,0]
	s_nop 0
	v_pk_fma_f32 v[86:87], v[86:87], s[70:71], v[132:133] op_sel_hi:[1,0,1]
	s_nop 0
	v_pk_add_f32 v[132:133], v[80:81], v[86:87]
	v_pk_add_f32 v[80:81], v[80:81], v[86:87] neg_lo:[0,1] neg_hi:[0,1]
	v_xor_b32_e32 v86, 0x80000000, v69
	v_mov_b32_e32 v87, v68
	v_pk_mul_f32 v[86:87], v[86:87], s[60:61] op_sel_hi:[1,0]
	s_nop 0
	v_pk_fma_f32 v[68:69], v[68:69], s[62:63], v[86:87] op_sel_hi:[1,0,1]
	s_nop 0
	v_pk_add_f32 v[86:87], v[12:13], v[68:69]
	v_pk_add_f32 v[12:13], v[12:13], v[68:69] neg_lo:[0,1] neg_hi:[0,1]
	v_xor_b32_e32 v68, 0x80000000, v71
	v_mov_b32_e32 v69, v70
	v_pk_add_f32 v[70:71], v[64:65], v[68:69]
	v_pk_add_f32 v[64:65], v[64:65], v[68:69] neg_lo:[0,1] neg_hi:[0,1]
	v_pk_mul_f32 v[68:69], v[6:7], s[62:63] op_sel_hi:[1,0]
	s_nop 0
	v_pk_fma_f32 v[6:7], v[134:135], s[60:61], v[68:69] op_sel_hi:[1,0,1] neg_lo:[0,0,1] neg_hi:[0,0,1]
	v_xor_b32_e32 v134, 0x80000000, v9
	v_pk_add_f32 v[68:69], v[2:3], v[6:7]
	v_pk_add_f32 v[2:3], v[2:3], v[6:7] neg_lo:[0,1] neg_hi:[0,1]
	v_pk_mul_f32 v[6:7], v[8:9], s[70:71] op_sel_hi:[1,0]
	v_mov_b32_e32 v135, v8
	v_pk_fma_f32 v[6:7], v[134:135], s[70:71], v[6:7] op_sel_hi:[1,0,1] neg_lo:[0,0,1] neg_hi:[0,0,1]
	v_xor_b32_e32 v134, 0x80000000, v17
	v_pk_add_f32 v[8:9], v[4:5], v[6:7]
	v_pk_add_f32 v[4:5], v[4:5], v[6:7] neg_lo:[0,1] neg_hi:[0,1]
	v_pk_mul_f32 v[6:7], v[16:17], s[60:61] op_sel_hi:[1,0]
	v_mov_b32_e32 v135, v16
	v_pk_fma_f32 v[6:7], v[134:135], s[62:63], v[6:7] op_sel_hi:[1,0,1] neg_lo:[0,0,1] neg_hi:[0,0,1]
	v_xor_b32_e32 v134, 0x80000000, v23
	v_pk_add_f32 v[16:17], v[0:1], v[6:7]
	v_pk_add_f32 v[0:1], v[0:1], v[6:7] neg_lo:[0,1] neg_hi:[0,1]
	v_pk_add_f32 v[6:7], v[20:21], v[72:73]
	v_pk_add_f32 v[20:21], v[20:21], v[72:73] neg_lo:[0,1] neg_hi:[0,1]
	v_xor_b32_e32 v72, 0x80000000, v131
	v_mov_b32_e32 v73, v130
	v_pk_mul_f32 v[72:73], v[72:73], s[62:63] op_sel_hi:[1,0]
	v_mov_b32_e32 v135, v22
	v_pk_fma_f32 v[72:73], v[130:131], s[60:61], v[72:73] op_sel_hi:[1,0,1]
	s_nop 0
	v_pk_add_f32 v[130:131], v[96:97], v[72:73]
	v_pk_add_f32 v[72:73], v[96:97], v[72:73] neg_lo:[0,1] neg_hi:[0,1]
	v_xor_b32_e32 v96, 0x80000000, v89
	v_mov_b32_e32 v97, v88
	v_pk_mul_f32 v[96:97], v[96:97], s[70:71] op_sel_hi:[1,0]
	s_nop 0
	v_pk_fma_f32 v[88:89], v[88:89], s[70:71], v[96:97] op_sel_hi:[1,0,1]
	s_nop 0
	v_pk_add_f32 v[96:97], v[74:75], v[88:89]
	v_pk_add_f32 v[74:75], v[74:75], v[88:89] neg_lo:[0,1] neg_hi:[0,1]
	v_xor_b32_e32 v88, 0x80000000, v93
	v_mov_b32_e32 v89, v92
	v_pk_mul_f32 v[88:89], v[88:89], s[60:61] op_sel_hi:[1,0]
	s_nop 0
	v_pk_fma_f32 v[88:89], v[92:93], s[62:63], v[88:89] op_sel_hi:[1,0,1]
	s_nop 0
	v_pk_add_f32 v[92:93], v[78:79], v[88:89]
	v_pk_add_f32 v[78:79], v[78:79], v[88:89] neg_lo:[0,1] neg_hi:[0,1]
	v_xor_b32_e32 v88, 0x80000000, v77
	v_mov_b32_e32 v89, v76
	v_pk_add_f32 v[76:77], v[82:83], v[88:89]
	v_pk_add_f32 v[82:83], v[82:83], v[88:89] neg_lo:[0,1] neg_hi:[0,1]
	v_pk_mul_f32 v[88:89], v[22:23], s[62:63] op_sel_hi:[1,0]
	s_nop 0
	v_pk_fma_f32 v[22:23], v[134:135], s[60:61], v[88:89] op_sel_hi:[1,0,1] neg_lo:[0,0,1] neg_hi:[0,0,1]
	v_xor_b32_e32 v134, 0x80000000, v27
	v_pk_add_f32 v[88:89], v[14:15], v[22:23]
	v_pk_add_f32 v[14:15], v[14:15], v[22:23] neg_lo:[0,1] neg_hi:[0,1]
	v_pk_mul_f32 v[22:23], v[26:27], s[70:71] op_sel_hi:[1,0]
	v_mov_b32_e32 v135, v26
	v_pk_fma_f32 v[22:23], v[134:135], s[70:71], v[22:23] op_sel_hi:[1,0,1] neg_lo:[0,0,1] neg_hi:[0,0,1]
	v_xor_b32_e32 v134, 0x80000000, v63
	v_pk_add_f32 v[26:27], v[18:19], v[22:23]
	v_pk_add_f32 v[18:19], v[18:19], v[22:23] neg_lo:[0,1] neg_hi:[0,1]
	v_pk_mul_f32 v[22:23], v[62:63], s[60:61] op_sel_hi:[1,0]
	v_mov_b32_e32 v135, v62
	v_pk_fma_f32 v[22:23], v[134:135], s[62:63], v[22:23] op_sel_hi:[1,0,1] neg_lo:[0,0,1] neg_hi:[0,0,1]
	v_xor_b32_e32 v134, 0x80000000, v73
	v_pk_add_f32 v[62:63], v[24:25], v[22:23]
	v_pk_add_f32 v[22:23], v[24:25], v[22:23] neg_lo:[0,1] neg_hi:[0,1]
	v_pk_add_f32 v[24:25], v[84:85], v[6:7]
	v_pk_add_f32 v[6:7], v[84:85], v[6:7] neg_lo:[0,1] neg_hi:[0,1]
	v_xor_b32_e32 v84, 0x80000000, v131
	v_mov_b32_e32 v85, v130
	v_pk_mul_f32 v[84:85], v[84:85], s[58:59] op_sel_hi:[1,0]
	v_mov_b32_e32 v135, v72
	v_pk_fma_f32 v[84:85], v[130:131], s[46:47], v[84:85] op_sel_hi:[1,0,1]
	s_nop 0
	v_pk_add_f32 v[130:131], v[94:95], v[84:85]
	v_pk_add_f32 v[84:85], v[94:95], v[84:85] neg_lo:[0,1] neg_hi:[0,1]
	v_xor_b32_e32 v94, 0x80000000, v97
	v_mov_b32_e32 v95, v96
	v_pk_mul_f32 v[94:95], v[94:95], s[62:63] op_sel_hi:[1,0]
	s_nop 0
	v_pk_fma_f32 v[94:95], v[96:97], s[60:61], v[94:95] op_sel_hi:[1,0,1]
	s_nop 0
	v_pk_add_f32 v[96:97], v[132:133], v[94:95]
	v_pk_add_f32 v[94:95], v[132:133], v[94:95] neg_lo:[0,1] neg_hi:[0,1]
	v_xor_b32_e32 v132, 0x80000000, v93
	v_mov_b32_e32 v133, v92
	v_pk_mul_f32 v[132:133], v[132:133], s[66:67] op_sel_hi:[1,0]
	s_nop 0
	v_pk_fma_f32 v[92:93], v[92:93], s[64:65], v[132:133] op_sel_hi:[1,0,1]
	s_nop 0
	v_pk_add_f32 v[132:133], v[86:87], v[92:93]
	v_pk_add_f32 v[86:87], v[86:87], v[92:93] neg_lo:[0,1] neg_hi:[0,1]
	v_xor_b32_e32 v92, 0x80000000, v77
	v_mov_b32_e32 v93, v76
	v_pk_mul_f32 v[92:93], v[92:93], s[70:71] op_sel_hi:[1,0]
	s_nop 0
	v_pk_fma_f32 v[76:77], v[76:77], s[70:71], v[92:93] op_sel_hi:[1,0,1]
	s_nop 0
	v_pk_add_f32 v[92:93], v[70:71], v[76:77]
	v_pk_add_f32 v[70:71], v[70:71], v[76:77] neg_lo:[0,1] neg_hi:[0,1]
	v_xor_b32_e32 v76, 0x80000000, v89
	v_mov_b32_e32 v77, v88
	v_pk_mul_f32 v[76:77], v[76:77], s[64:65] op_sel_hi:[1,0]
	s_nop 0
	v_pk_fma_f32 v[76:77], v[88:89], s[66:67], v[76:77] op_sel_hi:[1,0,1]
	s_nop 0
	v_pk_add_f32 v[88:89], v[68:69], v[76:77]
	v_pk_add_f32 v[68:69], v[68:69], v[76:77] neg_lo:[0,1] neg_hi:[0,1]
	v_xor_b32_e32 v76, 0x80000000, v27
	v_mov_b32_e32 v77, v26
	v_pk_mul_f32 v[76:77], v[76:77], s[60:61] op_sel_hi:[1,0]
	s_nop 0
	v_pk_fma_f32 v[26:27], v[26:27], s[62:63], v[76:77] op_sel_hi:[1,0,1]
	s_nop 0
	v_pk_add_f32 v[76:77], v[8:9], v[26:27]
	v_pk_add_f32 v[8:9], v[8:9], v[26:27] neg_lo:[0,1] neg_hi:[0,1]
	v_xor_b32_e32 v26, 0x80000000, v63
	v_mov_b32_e32 v27, v62
	v_pk_mul_f32 v[26:27], v[26:27], s[46:47] op_sel_hi:[1,0]
	s_nop 0
	v_pk_fma_f32 v[26:27], v[62:63], s[58:59], v[26:27] op_sel_hi:[1,0,1]
	s_nop 0
	v_pk_add_f32 v[62:63], v[16:17], v[26:27]
	v_pk_add_f32 v[16:17], v[16:17], v[26:27] neg_lo:[0,1] neg_hi:[0,1]
	v_xor_b32_e32 v26, 0x80000000, v21
	v_mov_b32_e32 v27, v20
	v_pk_add_f32 v[20:21], v[10:11], v[26:27]
	v_pk_add_f32 v[10:11], v[10:11], v[26:27] neg_lo:[0,1] neg_hi:[0,1]
	v_pk_mul_f32 v[26:27], v[72:73], s[58:59] op_sel_hi:[1,0]
	s_nop 0
	v_pk_fma_f32 v[26:27], v[134:135], s[46:47], v[26:27] op_sel_hi:[1,0,1] neg_lo:[0,0,1] neg_hi:[0,0,1]
	v_xor_b32_e32 v134, 0x80000000, v75
	v_pk_add_f32 v[72:73], v[90:91], v[26:27]
	v_pk_add_f32 v[26:27], v[90:91], v[26:27] neg_lo:[0,1] neg_hi:[0,1]
	v_pk_mul_f32 v[90:91], v[74:75], s[62:63] op_sel_hi:[1,0]
	v_mov_b32_e32 v135, v74
	v_pk_fma_f32 v[74:75], v[134:135], s[60:61], v[90:91] op_sel_hi:[1,0,1] neg_lo:[0,0,1] neg_hi:[0,0,1]
	v_xor_b32_e32 v134, 0x80000000, v79
	v_pk_add_f32 v[90:91], v[80:81], v[74:75]
	v_pk_add_f32 v[74:75], v[80:81], v[74:75] neg_lo:[0,1] neg_hi:[0,1]
	v_pk_mul_f32 v[80:81], v[78:79], s[66:67] op_sel_hi:[1,0]
	v_mov_b32_e32 v135, v78
	v_pk_fma_f32 v[78:79], v[134:135], s[64:65], v[80:81] op_sel_hi:[1,0,1] neg_lo:[0,0,1] neg_hi:[0,0,1]
	v_xor_b32_e32 v134, 0x80000000, v83
	v_pk_add_f32 v[80:81], v[12:13], v[78:79]
	v_pk_add_f32 v[12:13], v[12:13], v[78:79] neg_lo:[0,1] neg_hi:[0,1]
	v_pk_mul_f32 v[78:79], v[82:83], s[70:71] op_sel_hi:[1,0]
	v_mov_b32_e32 v135, v82
	v_pk_fma_f32 v[78:79], v[134:135], s[70:71], v[78:79] op_sel_hi:[1,0,1] neg_lo:[0,0,1] neg_hi:[0,0,1]
	v_xor_b32_e32 v134, 0x80000000, v15
	v_pk_add_f32 v[82:83], v[64:65], v[78:79]
	v_pk_add_f32 v[64:65], v[64:65], v[78:79] neg_lo:[0,1] neg_hi:[0,1]
	v_pk_mul_f32 v[78:79], v[14:15], s[64:65] op_sel_hi:[1,0]
	v_mov_b32_e32 v135, v14
	v_pk_fma_f32 v[14:15], v[134:135], s[66:67], v[78:79] op_sel_hi:[1,0,1] neg_lo:[0,0,1] neg_hi:[0,0,1]
	v_xor_b32_e32 v134, 0x80000000, v19
	v_pk_add_f32 v[78:79], v[2:3], v[14:15]
	v_pk_add_f32 v[2:3], v[2:3], v[14:15] neg_lo:[0,1] neg_hi:[0,1]
	v_pk_mul_f32 v[14:15], v[18:19], s[60:61] op_sel_hi:[1,0]
	v_mov_b32_e32 v135, v18
	v_pk_fma_f32 v[14:15], v[134:135], s[62:63], v[14:15] op_sel_hi:[1,0,1] neg_lo:[0,0,1] neg_hi:[0,0,1]
	v_xor_b32_e32 v134, 0x80000000, v23
	v_pk_add_f32 v[18:19], v[4:5], v[14:15]
	v_pk_add_f32 v[4:5], v[4:5], v[14:15] neg_lo:[0,1] neg_hi:[0,1]
	v_pk_mul_f32 v[14:15], v[22:23], s[46:47] op_sel_hi:[1,0]
	v_mov_b32_e32 v135, v22
	v_pk_fma_f32 v[14:15], v[134:135], s[58:59], v[14:15] op_sel_hi:[1,0,1] neg_lo:[0,0,1] neg_hi:[0,0,1]
	s_nop 0
	v_pk_add_f32 v[22:23], v[0:1], v[14:15]
	v_pk_add_f32 v[0:1], v[0:1], v[14:15] neg_lo:[0,1] neg_hi:[0,1]
	ds_write_b64 v67, v[24:25]
	ds_write_b64 v98, v[130:131]
	ds_write_b64 v99, v[96:97] offset:256
	ds_write_b64 v100, v[132:133] offset:256
	ds_write_b64 v101, v[92:93] offset:512
	ds_write_b64 v102, v[88:89] offset:512
	ds_write_b64 v103, v[76:77] offset:768
	ds_write_b64 v104, v[62:63] offset:768
	ds_write_b64 v105, v[20:21] offset:1024
	ds_write_b64 v106, v[72:73] offset:1024
	ds_write_b64 v107, v[90:91] offset:1280
	ds_write_b64 v108, v[80:81] offset:1280
	ds_write_b64 v109, v[82:83] offset:1536
	ds_write_b64 v110, v[78:79] offset:1536
	ds_write_b64 v111, v[18:19] offset:1792
	ds_write_b64 v112, v[22:23] offset:1792
	ds_write_b64 v113, v[6:7] offset:2048
	ds_write_b64 v114, v[84:85] offset:2048
	ds_write_b64 v115, v[94:95] offset:2304
	ds_write_b64 v116, v[86:87] offset:2304
	ds_write_b64 v117, v[70:71] offset:2560
	ds_write_b64 v118, v[68:69] offset:2560
	ds_write_b64 v119, v[8:9] offset:2816
	ds_write_b64 v120, v[16:17] offset:2816
	ds_write_b64 v121, v[10:11] offset:3072
	ds_write_b64 v122, v[26:27] offset:3072
	ds_write_b64 v123, v[74:75] offset:3328
	ds_write_b64 v124, v[12:13] offset:3328
	ds_write_b64 v125, v[64:65] offset:3584
	ds_write_b64 v126, v[2:3] offset:3584
	ds_write_b64 v127, v[4:5] offset:3840
	ds_write_b64 v128, v[0:1] offset:3840
	v_mov_b32_e32 v74, v146
	s_waitcnt lgkmcnt(0)
	s_barrier
	s_nop 0
	v_lshrrev_b32_e32 v0, 5, v74
	v_bfe_u32 v4, v74, 5, 4
	v_bitop3_b32 v0, v0, v74, 15 bitop3:0x6c
	v_bitop3_b32 v4, v4, v74, 16 bitop3:0x36
	v_lshlrev_b32_e32 v66, 3, v0
	v_lshlrev_b32_e32 v67, 3, v4
	v_add_u32_e32 v5, 16, v66
	v_add_u32_e32 v4, 16, v67
	v_add_u32_e32 v62, s47, v66
	v_add_u32_e32 v70, s9, v66
	ds_read2st64_b64 v[0:3], v5 offset1:16
	ds_read2st64_b64 v[16:19], v4 offset0:8 offset1:24
	ds_read2st64_b64 v[24:27], v5 offset0:32 offset1:48
	ds_read2st64_b64 v[8:11], v4 offset0:40 offset1:56
	ds_read2st64_b64 v[92:95], v5 offset0:64 offset1:80
	ds_read2st64_b64 v[12:15], v4 offset0:72 offset1:88
	ds_read2st64_b64 v[20:23], v5 offset0:96 offset1:112
	ds_read2st64_b64 v[4:7], v4 offset0:104 offset1:120
	ds_read_b64 v[68:69], v62
	ds_read_b64 v[72:73], v70
	v_add_u32_e32 v62, s19, v67
	v_add_u32_e32 v70, s8, v67
	ds_read_b64 v[84:85], v62
	ds_read_b64 v[90:91], v70
	v_add_u32_e32 v62, s18, v66
	v_add_u32_e32 v70, s7, v66
	ds_read_b64 v[96:97], v62
	ds_read_b64 v[100:101], v70
	v_add_u32_e32 v62, s17, v67
	v_add_u32_e32 v70, s6, v67
	ds_read_b64 v[64:65], v62
	ds_read_b64 v[70:71], v70
	v_add_u32_e32 v62, s13, v66
	v_add_u32_e32 v75, s5, v66
	ds_read_b64 v[86:87], v62
	ds_read_b64 v[102:103], v75
	v_add_u32_e32 v62, s12, v67
	v_add_u32_e32 v75, s4, v67
	ds_read_b64 v[80:81], v62
	ds_read_b64 v[88:89], v75
	v_add_u32_e32 v62, s11, v66
	v_add_u32_e32 v66, s1, v66
	ds_read_b64 v[98:99], v62
	ds_read_b64 v[104:105], v66
	v_add_u32_e32 v62, s10, v67
	v_add_u32_e32 v66, s0, v67
	ds_read_b64 v[62:63], v62
	ds_read_b64 v[66:67], v66
	s_waitcnt lgkmcnt(14)
	v_xor_b32_e32 v106, 0x80000000, v69
	v_cvt_f32_i32_e32 v74, v74
	v_mov_b32_e32 v107, v68
	s_lshl_b64 s[0:1], s[44:45], 2
	s_add_u32 s0, s24, s0
	v_mul_f32_e32 v74, 0x38800000, v74
	v_cos_f32_e32 v78, v74
	v_sin_f32_e32 v79, v74
	s_addc_u32 s1, s59, s1
	s_and_b64 vcc, s[14:15], exec
	v_add_f32_e32 v76, v78, v78
	v_pk_mul_f32 v[74:75], v[78:79], v[78:79]
	v_mul_f32_e32 v76, v79, v76
	v_xor_b32_e32 v82, 0x80000000, v79
	v_mov_b32_e32 v83, v78
	v_mov_b32_e32 v108, v79
	v_pk_add_f32 v[74:75], v[74:75], v[74:75] op_sel:[0,1] op_sel_hi:[0,1] neg_lo:[0,1] neg_hi:[0,1]
	v_pk_mul_f32 v[82:83], v[82:83], v[76:77] op_sel_hi:[1,0]
	v_pk_mul_f32 v[106:107], v[106:107], v[108:109] op_sel_hi:[1,0]
	v_pk_fma_f32 v[82:83], v[78:79], v[74:75], v[82:83]
	v_pk_fma_f32 v[68:69], v[68:69], v[78:79], v[106:107] op_sel_hi:[1,0,1]
	v_pk_mul_f32 v[78:79], v[76:77], s[48:49] op_sel_hi:[0,1]
	v_pk_fma_f32 v[106:107], v[74:75], s[40:41], v[78:79]
	v_xor_b32_e32 v78, 0x80000000, v93
	v_mov_b32_e32 v79, v92
	v_pk_mul_f32 v[78:79], v[78:79], v[106:107] op_sel:[0,1]
	v_xor_b32_e32 v108, 0x80000000, v73
	v_pk_fma_f32 v[78:79], v[92:93], v[106:107], v[78:79] op_sel_hi:[1,0,1]
	v_xor_b32_e32 v92, 0x80000000, v83
	v_mov_b32_e32 v93, v82
	v_mov_b32_e32 v109, v72
	v_pk_mul_f32 v[92:93], v[76:77], v[92:93] op_sel_hi:[0,1]
	v_pk_mul_f32 v[108:109], v[108:109], v[82:83] op_sel:[0,1]
	v_pk_fma_f32 v[92:93], v[74:75], v[82:83], v[92:93]
	v_pk_fma_f32 v[72:73], v[72:73], v[82:83], v[108:109] op_sel_hi:[1,0,1]
	v_xor_b32_e32 v82, 0x80000000, v107
	v_mov_b32_e32 v83, v106
	v_pk_mul_f32 v[82:83], v[76:77], v[82:83] op_sel_hi:[0,1]
	v_pk_fma_f32 v[106:107], v[74:75], v[106:107], v[82:83]
	v_xor_b32_e32 v82, 0x80000000, v25
	v_mov_b32_e32 v83, v24
	v_pk_mul_f32 v[82:83], v[82:83], v[106:107] op_sel:[0,1]
	s_nop 0
	v_pk_fma_f32 v[82:83], v[24:25], v[106:107], v[82:83] op_sel_hi:[1,0,1]
	v_xor_b32_e32 v24, 0x80000000, v93
	v_mov_b32_e32 v25, v92
	v_pk_mul_f32 v[24:25], v[76:77], v[24:25] op_sel_hi:[0,1]
	v_pk_fma_f32 v[108:109], v[74:75], v[92:93], v[24:25]
	s_waitcnt lgkmcnt(7)
	v_xor_b32_e32 v24, 0x80000000, v87
	v_mov_b32_e32 v25, v86
	v_pk_mul_f32 v[24:25], v[24:25], v[92:93] op_sel:[0,1]
	s_nop 0
	v_pk_fma_f32 v[24:25], v[86:87], v[92:93], v[24:25] op_sel_hi:[1,0,1]
	v_xor_b32_e32 v86, 0x80000000, v107
	v_mov_b32_e32 v87, v106
	v_pk_mul_f32 v[86:87], v[76:77], v[86:87] op_sel_hi:[0,1]
	v_pk_fma_f32 v[92:93], v[74:75], v[106:107], v[86:87]
	v_xor_b32_e32 v86, 0x80000000, v21
	v_mov_b32_e32 v87, v20
	v_pk_mul_f32 v[86:87], v[86:87], v[92:93] op_sel:[0,1]
	s_nop 0
	v_pk_fma_f32 v[86:87], v[20:21], v[92:93], v[86:87] op_sel_hi:[1,0,1]
	v_xor_b32_e32 v20, 0x80000000, v109
	v_mov_b32_e32 v21, v108
	v_pk_mul_f32 v[20:21], v[76:77], v[20:21] op_sel_hi:[0,1]
	v_pk_fma_f32 v[106:107], v[74:75], v[108:109], v[20:21]
	s_waitcnt lgkmcnt(6)
	v_xor_b32_e32 v20, 0x80000000, v103
	v_mov_b32_e32 v21, v102
	v_pk_mul_f32 v[20:21], v[20:21], v[108:109] op_sel:[0,1]
	s_nop 0
	v_pk_fma_f32 v[20:21], v[102:103], v[108:109], v[20:21] op_sel_hi:[1,0,1]
	v_xor_b32_e32 v102, 0x80000000, v93
	v_mov_b32_e32 v103, v92
	v_pk_mul_f32 v[102:103], v[76:77], v[102:103] op_sel_hi:[0,1]
	v_pk_fma_f32 v[102:103], v[74:75], v[92:93], v[102:103]
	v_xor_b32_e32 v92, 0x80000000, v3
	v_mov_b32_e32 v93, v2
	v_pk_mul_f32 v[92:93], v[92:93], v[102:103] op_sel:[0,1]
	s_nop 0
	v_pk_fma_f32 v[92:93], v[2:3], v[102:103], v[92:93] op_sel_hi:[1,0,1]
	v_xor_b32_e32 v2, 0x80000000, v107
	v_mov_b32_e32 v3, v106
	v_pk_mul_f32 v[2:3], v[76:77], v[2:3] op_sel_hi:[0,1]
	v_pk_fma_f32 v[108:109], v[74:75], v[106:107], v[2:3]
	v_xor_b32_e32 v2, 0x80000000, v97
	v_mov_b32_e32 v3, v96
	v_pk_mul_f32 v[2:3], v[2:3], v[106:107] op_sel:[0,1]
	s_nop 0
	v_pk_fma_f32 v[2:3], v[96:97], v[106:107], v[2:3] op_sel_hi:[1,0,1]
	v_xor_b32_e32 v96, 0x80000000, v103
	v_mov_b32_e32 v97, v102
	v_pk_mul_f32 v[96:97], v[76:77], v[96:97] op_sel_hi:[0,1]
	v_pk_fma_f32 v[102:103], v[74:75], v[102:103], v[96:97]
	v_xor_b32_e32 v96, 0x80000000, v95
	v_mov_b32_e32 v97, v94
	v_pk_mul_f32 v[96:97], v[96:97], v[102:103] op_sel:[0,1]
	s_nop 0
	v_pk_fma_f32 v[96:97], v[94:95], v[102:103], v[96:97] op_sel_hi:[1,0,1]
	v_xor_b32_e32 v94, 0x80000000, v109
	v_mov_b32_e32 v95, v108
	v_pk_mul_f32 v[94:95], v[76:77], v[94:95] op_sel_hi:[0,1]
	v_pk_fma_f32 v[106:107], v[74:75], v[108:109], v[94:95]
	v_xor_b32_e32 v94, 0x80000000, v101
	v_mov_b32_e32 v95, v100
	v_pk_mul_f32 v[94:95], v[94:95], v[108:109] op_sel:[0,1]
	s_nop 0
	v_pk_fma_f32 v[94:95], v[100:101], v[108:109], v[94:95] op_sel_hi:[1,0,1]
	v_xor_b32_e32 v100, 0x80000000, v103
	v_mov_b32_e32 v101, v102
	v_pk_mul_f32 v[100:101], v[76:77], v[100:101] op_sel_hi:[0,1]
	v_pk_fma_f32 v[100:101], v[74:75], v[102:103], v[100:101]
	v_xor_b32_e32 v102, 0x80000000, v27
	v_mov_b32_e32 v103, v26
	v_pk_mul_f32 v[102:103], v[102:103], v[100:101] op_sel:[0,1]
	s_waitcnt lgkmcnt(3)
	v_xor_b32_e32 v108, 0x80000000, v99
	v_pk_fma_f32 v[26:27], v[26:27], v[100:101], v[102:103] op_sel_hi:[1,0,1]
	v_xor_b32_e32 v102, 0x80000000, v107
	v_mov_b32_e32 v103, v106
	v_mov_b32_e32 v109, v98
	v_pk_mul_f32 v[102:103], v[76:77], v[102:103] op_sel_hi:[0,1]
	v_pk_mul_f32 v[108:109], v[108:109], v[106:107] op_sel:[0,1]
	v_pk_fma_f32 v[102:103], v[74:75], v[106:107], v[102:103]
	v_pk_fma_f32 v[98:99], v[98:99], v[106:107], v[108:109] op_sel_hi:[1,0,1]
	v_xor_b32_e32 v106, 0x80000000, v101
	v_mov_b32_e32 v107, v100
	v_pk_mul_f32 v[106:107], v[76:77], v[106:107] op_sel_hi:[0,1]
	v_pk_fma_f32 v[100:101], v[74:75], v[100:101], v[106:107]
	v_xor_b32_e32 v106, 0x80000000, v23
	v_mov_b32_e32 v107, v22
	v_pk_mul_f32 v[106:107], v[106:107], v[100:101] op_sel:[0,1]
	s_waitcnt lgkmcnt(2)
	v_xor_b32_e32 v108, 0x80000000, v105
	v_pk_fma_f32 v[22:23], v[22:23], v[100:101], v[106:107] op_sel_hi:[1,0,1]
	v_xor_b32_e32 v106, 0x80000000, v103
	v_mov_b32_e32 v107, v102
	v_mov_b32_e32 v109, v104
	v_pk_mul_f32 v[106:107], v[76:77], v[106:107] op_sel_hi:[0,1]
	v_pk_mul_f32 v[108:109], v[108:109], v[102:103] op_sel:[0,1]
	v_pk_fma_f32 v[106:107], v[74:75], v[102:103], v[106:107]
	v_pk_fma_f32 v[102:103], v[104:105], v[102:103], v[108:109] op_sel_hi:[1,0,1]
	v_xor_b32_e32 v104, 0x80000000, v101
	v_mov_b32_e32 v105, v100
	v_pk_mul_f32 v[104:105], v[76:77], v[104:105] op_sel_hi:[0,1]
	v_pk_fma_f32 v[100:101], v[74:75], v[100:101], v[104:105]
	v_xor_b32_e32 v104, 0x80000000, v17
	v_mov_b32_e32 v105, v16
	v_pk_mul_f32 v[104:105], v[104:105], v[100:101] op_sel:[0,1]
	v_xor_b32_e32 v108, 0x80000000, v85
	v_pk_fma_f32 v[16:17], v[16:17], v[100:101], v[104:105] op_sel_hi:[1,0,1]
	v_xor_b32_e32 v104, 0x80000000, v107
	v_mov_b32_e32 v105, v106
	v_mov_b32_e32 v109, v84
	v_pk_mul_f32 v[104:105], v[76:77], v[104:105] op_sel_hi:[0,1]
	v_pk_mul_f32 v[108:109], v[108:109], v[106:107] op_sel:[0,1]
	v_pk_fma_f32 v[104:105], v[74:75], v[106:107], v[104:105]
	v_pk_fma_f32 v[84:85], v[84:85], v[106:107], v[108:109] op_sel_hi:[1,0,1]
	v_xor_b32_e32 v106, 0x80000000, v101
	v_mov_b32_e32 v107, v100
	v_pk_mul_f32 v[106:107], v[76:77], v[106:107] op_sel_hi:[0,1]
	v_pk_fma_f32 v[100:101], v[74:75], v[100:101], v[106:107]
	v_xor_b32_e32 v106, 0x80000000, v13
	v_mov_b32_e32 v107, v12
	v_pk_mul_f32 v[106:107], v[106:107], v[100:101] op_sel:[0,1]
	v_xor_b32_e32 v108, 0x80000000, v91
	v_pk_fma_f32 v[12:13], v[12:13], v[100:101], v[106:107] op_sel_hi:[1,0,1]
	v_xor_b32_e32 v106, 0x80000000, v105
	v_mov_b32_e32 v107, v104
	v_mov_b32_e32 v109, v90
	v_pk_mul_f32 v[106:107], v[76:77], v[106:107] op_sel_hi:[0,1]
	v_pk_mul_f32 v[108:109], v[108:109], v[104:105] op_sel:[0,1]
	v_pk_fma_f32 v[106:107], v[74:75], v[104:105], v[106:107]
	v_pk_fma_f32 v[90:91], v[90:91], v[104:105], v[108:109] op_sel_hi:[1,0,1]
	v_xor_b32_e32 v104, 0x80000000, v101
	v_mov_b32_e32 v105, v100
	v_pk_mul_f32 v[104:105], v[76:77], v[104:105] op_sel_hi:[0,1]
	v_pk_fma_f32 v[100:101], v[74:75], v[100:101], v[104:105]
	v_xor_b32_e32 v104, 0x80000000, v9
	v_mov_b32_e32 v105, v8
	v_pk_mul_f32 v[104:105], v[104:105], v[100:101] op_sel:[0,1]
	v_xor_b32_e32 v108, 0x80000000, v81
	v_pk_fma_f32 v[8:9], v[8:9], v[100:101], v[104:105] op_sel_hi:[1,0,1]
	v_xor_b32_e32 v104, 0x80000000, v107
	v_mov_b32_e32 v105, v106
	v_mov_b32_e32 v109, v80
	v_pk_mul_f32 v[104:105], v[76:77], v[104:105] op_sel_hi:[0,1]
	v_pk_mul_f32 v[108:109], v[108:109], v[106:107] op_sel:[0,1]
	v_pk_fma_f32 v[104:105], v[74:75], v[106:107], v[104:105]
	v_pk_fma_f32 v[80:81], v[80:81], v[106:107], v[108:109] op_sel_hi:[1,0,1]
	v_xor_b32_e32 v106, 0x80000000, v101
	v_mov_b32_e32 v107, v100
	v_pk_mul_f32 v[106:107], v[76:77], v[106:107] op_sel_hi:[0,1]
	v_pk_fma_f32 v[100:101], v[74:75], v[100:101], v[106:107]
	v_xor_b32_e32 v106, 0x80000000, v5
	v_mov_b32_e32 v107, v4
	v_pk_mul_f32 v[106:107], v[106:107], v[100:101] op_sel:[0,1]
	v_xor_b32_e32 v108, 0x80000000, v89
	v_pk_fma_f32 v[4:5], v[4:5], v[100:101], v[106:107] op_sel_hi:[1,0,1]
	v_xor_b32_e32 v106, 0x80000000, v105
	v_mov_b32_e32 v107, v104
	v_mov_b32_e32 v109, v88
	v_pk_mul_f32 v[106:107], v[76:77], v[106:107] op_sel_hi:[0,1]
	v_pk_mul_f32 v[108:109], v[108:109], v[104:105] op_sel:[0,1]
	v_pk_fma_f32 v[106:107], v[74:75], v[104:105], v[106:107]
	v_pk_fma_f32 v[88:89], v[88:89], v[104:105], v[108:109] op_sel_hi:[1,0,1]
	v_xor_b32_e32 v104, 0x80000000, v101
	v_mov_b32_e32 v105, v100
	v_pk_mul_f32 v[104:105], v[76:77], v[104:105] op_sel_hi:[0,1]
	v_pk_fma_f32 v[100:101], v[74:75], v[100:101], v[104:105]
	v_xor_b32_e32 v104, 0x80000000, v19
	v_mov_b32_e32 v105, v18
	v_pk_mul_f32 v[104:105], v[104:105], v[100:101] op_sel:[0,1]
	v_xor_b32_e32 v108, 0x80000000, v65
	v_pk_fma_f32 v[18:19], v[18:19], v[100:101], v[104:105] op_sel_hi:[1,0,1]
	v_xor_b32_e32 v104, 0x80000000, v107
	v_mov_b32_e32 v105, v106
	v_mov_b32_e32 v109, v64
	v_pk_mul_f32 v[104:105], v[76:77], v[104:105] op_sel_hi:[0,1]
	v_pk_mul_f32 v[108:109], v[108:109], v[106:107] op_sel:[0,1]
	v_pk_fma_f32 v[104:105], v[74:75], v[106:107], v[104:105]
	v_pk_fma_f32 v[64:65], v[64:65], v[106:107], v[108:109] op_sel_hi:[1,0,1]
	v_xor_b32_e32 v106, 0x80000000, v101
	v_mov_b32_e32 v107, v100
	v_pk_mul_f32 v[106:107], v[76:77], v[106:107] op_sel_hi:[0,1]
	v_pk_fma_f32 v[100:101], v[74:75], v[100:101], v[106:107]
	v_xor_b32_e32 v106, 0x80000000, v15
	v_mov_b32_e32 v107, v14
	v_pk_mul_f32 v[106:107], v[106:107], v[100:101] op_sel:[0,1]
	v_xor_b32_e32 v108, 0x80000000, v71
	v_pk_fma_f32 v[14:15], v[14:15], v[100:101], v[106:107] op_sel_hi:[1,0,1]
	v_xor_b32_e32 v106, 0x80000000, v105
	v_mov_b32_e32 v107, v104
	v_mov_b32_e32 v109, v70
	v_pk_mul_f32 v[106:107], v[76:77], v[106:107] op_sel_hi:[0,1]
	v_pk_mul_f32 v[108:109], v[108:109], v[104:105] op_sel:[0,1]
	v_pk_fma_f32 v[106:107], v[74:75], v[104:105], v[106:107]
	v_pk_fma_f32 v[70:71], v[70:71], v[104:105], v[108:109] op_sel_hi:[1,0,1]
	v_xor_b32_e32 v104, 0x80000000, v101
	v_mov_b32_e32 v105, v100
	v_pk_mul_f32 v[104:105], v[76:77], v[104:105] op_sel_hi:[0,1]
	v_pk_fma_f32 v[100:101], v[74:75], v[100:101], v[104:105]
	v_xor_b32_e32 v104, 0x80000000, v11
	v_mov_b32_e32 v105, v10
	v_pk_mul_f32 v[104:105], v[104:105], v[100:101] op_sel:[0,1]
	s_waitcnt lgkmcnt(1)
	v_xor_b32_e32 v108, 0x80000000, v63
	v_pk_fma_f32 v[10:11], v[10:11], v[100:101], v[104:105] op_sel_hi:[1,0,1]
	v_xor_b32_e32 v104, 0x80000000, v107
	v_mov_b32_e32 v105, v106
	v_mov_b32_e32 v109, v62
	v_pk_mul_f32 v[104:105], v[76:77], v[104:105] op_sel_hi:[0,1]
	v_pk_mul_f32 v[108:109], v[108:109], v[106:107] op_sel:[0,1]
	v_pk_fma_f32 v[104:105], v[74:75], v[106:107], v[104:105]
	v_pk_fma_f32 v[62:63], v[62:63], v[106:107], v[108:109] op_sel_hi:[1,0,1]
	v_xor_b32_e32 v106, 0x80000000, v101
	v_mov_b32_e32 v107, v100
	v_pk_mul_f32 v[76:77], v[76:77], v[106:107] op_sel_hi:[0,1]
	v_pk_fma_f32 v[74:75], v[74:75], v[100:101], v[76:77]
	v_xor_b32_e32 v76, 0x80000000, v7
	v_mov_b32_e32 v77, v6
	v_pk_mul_f32 v[76:77], v[76:77], v[74:75] op_sel:[0,1]
	s_nop 0
	v_pk_fma_f32 v[6:7], v[6:7], v[74:75], v[76:77] op_sel_hi:[1,0,1]
	s_waitcnt lgkmcnt(0)
	v_xor_b32_e32 v74, 0x80000000, v67
	v_mov_b32_e32 v75, v66
	v_pk_mul_f32 v[74:75], v[74:75], v[104:105] op_sel:[0,1]
	v_pk_add_f32 v[76:77], v[82:83], v[8:9]
	v_pk_fma_f32 v[66:67], v[66:67], v[104:105], v[74:75] op_sel_hi:[1,0,1]
	v_pk_add_f32 v[74:75], v[0:1], v[16:17]
	v_pk_add_f32 v[0:1], v[0:1], v[16:17] neg_lo:[0,1] neg_hi:[0,1]
	v_pk_add_f32 v[16:17], v[92:93], v[18:19]
	v_pk_add_f32 v[18:19], v[92:93], v[18:19] neg_lo:[0,1] neg_hi:[0,1]
	v_pk_add_f32 v[8:9], v[82:83], v[8:9] neg_lo:[0,1] neg_hi:[0,1]
	v_pk_add_f32 v[82:83], v[26:27], v[10:11]
	v_pk_add_f32 v[10:11], v[26:27], v[10:11] neg_lo:[0,1] neg_hi:[0,1]
	v_pk_add_f32 v[92:93], v[86:87], v[4:5]
	v_pk_add_f32 v[4:5], v[86:87], v[4:5] neg_lo:[0,1] neg_hi:[0,1]
	v_pk_add_f32 v[86:87], v[22:23], v[6:7]
	v_pk_add_f32 v[6:7], v[22:23], v[6:7] neg_lo:[0,1] neg_hi:[0,1]
	v_pk_add_f32 v[22:23], v[68:69], v[84:85]
	v_pk_add_f32 v[68:69], v[68:69], v[84:85] neg_lo:[0,1] neg_hi:[0,1]
	v_pk_add_f32 v[84:85], v[2:3], v[64:65]
	v_pk_add_f32 v[2:3], v[2:3], v[64:65] neg_lo:[0,1] neg_hi:[0,1]
	v_pk_add_f32 v[64:65], v[24:25], v[80:81]
	v_pk_add_f32 v[24:25], v[24:25], v[80:81] neg_lo:[0,1] neg_hi:[0,1]
	v_pk_add_f32 v[80:81], v[98:99], v[62:63]
	v_pk_add_f32 v[62:63], v[98:99], v[62:63] neg_lo:[0,1] neg_hi:[0,1]
	v_pk_add_f32 v[98:99], v[74:75], v[16:17]
	v_pk_add_f32 v[16:17], v[74:75], v[16:17] neg_lo:[0,1] neg_hi:[0,1]
	v_xor_b32_e32 v74, 0x80000000, v19
	v_mov_b32_e32 v75, v18
	v_pk_add_f32 v[26:27], v[78:79], v[12:13]
	v_pk_add_f32 v[12:13], v[78:79], v[12:13] neg_lo:[0,1] neg_hi:[0,1]
	v_pk_add_f32 v[78:79], v[96:97], v[14:15]
	v_pk_add_f32 v[14:15], v[96:97], v[14:15] neg_lo:[0,1] neg_hi:[0,1]
	v_pk_add_f32 v[18:19], v[0:1], v[74:75]
	v_pk_add_f32 v[0:1], v[0:1], v[74:75] neg_lo:[0,1] neg_hi:[0,1]
	v_pk_add_f32 v[74:75], v[76:77], v[82:83]
	v_pk_add_f32 v[76:77], v[76:77], v[82:83] neg_lo:[0,1] neg_hi:[0,1]
	v_xor_b32_e32 v82, 0x80000000, v11
	v_mov_b32_e32 v83, v10
	v_pk_add_f32 v[10:11], v[8:9], v[82:83]
	v_pk_add_f32 v[8:9], v[8:9], v[82:83] neg_lo:[0,1] neg_hi:[0,1]
	v_pk_add_f32 v[82:83], v[26:27], v[78:79]
	v_pk_add_f32 v[26:27], v[26:27], v[78:79] neg_lo:[0,1] neg_hi:[0,1]
	v_xor_b32_e32 v78, 0x80000000, v15
	v_mov_b32_e32 v79, v14
	v_pk_add_f32 v[14:15], v[12:13], v[78:79]
	v_pk_add_f32 v[12:13], v[12:13], v[78:79] neg_lo:[0,1] neg_hi:[0,1]
	v_pk_add_f32 v[78:79], v[92:93], v[86:87]
	v_pk_add_f32 v[86:87], v[92:93], v[86:87] neg_lo:[0,1] neg_hi:[0,1]
	v_xor_b32_e32 v92, 0x80000000, v7
	v_mov_b32_e32 v93, v6
	v_pk_add_f32 v[6:7], v[4:5], v[92:93]
	v_pk_add_f32 v[4:5], v[4:5], v[92:93] neg_lo:[0,1] neg_hi:[0,1]
	v_pk_add_f32 v[92:93], v[22:23], v[84:85]
	v_pk_add_f32 v[22:23], v[22:23], v[84:85] neg_lo:[0,1] neg_hi:[0,1]
	v_xor_b32_e32 v84, 0x80000000, v3
	v_mov_b32_e32 v85, v2
	v_pk_add_f32 v[96:97], v[72:73], v[90:91]
	v_pk_add_f32 v[72:73], v[72:73], v[90:91] neg_lo:[0,1] neg_hi:[0,1]
	v_pk_add_f32 v[90:91], v[94:95], v[70:71]
	v_pk_add_f32 v[70:71], v[94:95], v[70:71] neg_lo:[0,1] neg_hi:[0,1]
	v_pk_add_f32 v[2:3], v[68:69], v[84:85]
	v_pk_add_f32 v[68:69], v[68:69], v[84:85] neg_lo:[0,1] neg_hi:[0,1]
	v_pk_add_f32 v[84:85], v[64:65], v[80:81]
	v_pk_add_f32 v[64:65], v[64:65], v[80:81] neg_lo:[0,1] neg_hi:[0,1]
	v_xor_b32_e32 v80, 0x80000000, v63
	v_mov_b32_e32 v81, v62
	v_pk_add_f32 v[94:95], v[20:21], v[88:89]
	v_pk_add_f32 v[20:21], v[20:21], v[88:89] neg_lo:[0,1] neg_hi:[0,1]
	v_pk_add_f32 v[88:89], v[102:103], v[66:67]
	v_pk_add_f32 v[66:67], v[102:103], v[66:67] neg_lo:[0,1] neg_hi:[0,1]
	v_pk_add_f32 v[62:63], v[24:25], v[80:81]
	v_pk_add_f32 v[24:25], v[24:25], v[80:81] neg_lo:[0,1] neg_hi:[0,1]
	v_pk_add_f32 v[80:81], v[96:97], v[90:91]
	v_pk_add_f32 v[90:91], v[96:97], v[90:91] neg_lo:[0,1] neg_hi:[0,1]
	v_xor_b32_e32 v96, 0x80000000, v71
	v_mov_b32_e32 v97, v70
	v_pk_add_f32 v[70:71], v[72:73], v[96:97]
	v_pk_add_f32 v[72:73], v[72:73], v[96:97] neg_lo:[0,1] neg_hi:[0,1]
	v_pk_add_f32 v[96:97], v[94:95], v[88:89]
	v_pk_add_f32 v[88:89], v[94:95], v[88:89] neg_lo:[0,1] neg_hi:[0,1]
	v_xor_b32_e32 v94, 0x80000000, v67
	v_mov_b32_e32 v95, v66
	v_pk_add_f32 v[66:67], v[20:21], v[94:95]
	v_pk_add_f32 v[20:21], v[20:21], v[94:95] neg_lo:[0,1] neg_hi:[0,1]
	v_pk_add_f32 v[94:95], v[98:99], v[74:75]
	v_pk_add_f32 v[74:75], v[98:99], v[74:75] neg_lo:[0,1] neg_hi:[0,1]
	v_xor_b32_e32 v98, 0x80000000, v11
	v_mov_b32_e32 v99, v10
	v_pk_mul_f32 v[98:99], v[98:99], s[70:71] op_sel_hi:[1,0]
	v_xor_b32_e32 v100, 0x80000000, v9
	v_pk_fma_f32 v[10:11], v[10:11], s[70:71], v[98:99] op_sel_hi:[1,0,1]
	v_mov_b32_e32 v101, v8
	v_pk_add_f32 v[98:99], v[18:19], v[10:11]
	v_pk_add_f32 v[10:11], v[18:19], v[10:11] neg_lo:[0,1] neg_hi:[0,1]
	v_xor_b32_e32 v18, 0x80000000, v77
	v_mov_b32_e32 v19, v76
	v_pk_add_f32 v[76:77], v[16:17], v[18:19]
	v_pk_add_f32 v[16:17], v[16:17], v[18:19] neg_lo:[0,1] neg_hi:[0,1]
	v_pk_mul_f32 v[18:19], v[8:9], s[70:71] op_sel_hi:[1,0]
	s_nop 0
	v_pk_fma_f32 v[8:9], v[100:101], s[70:71], v[18:19] op_sel_hi:[1,0,1] neg_lo:[0,0,1] neg_hi:[0,0,1]
	v_xor_b32_e32 v100, 0x80000000, v5
	v_pk_add_f32 v[18:19], v[0:1], v[8:9]
	v_pk_add_f32 v[0:1], v[0:1], v[8:9] neg_lo:[0,1] neg_hi:[0,1]
	v_pk_add_f32 v[8:9], v[82:83], v[78:79]
	v_pk_add_f32 v[78:79], v[82:83], v[78:79] neg_lo:[0,1] neg_hi:[0,1]
	v_xor_b32_e32 v82, 0x80000000, v7
	v_mov_b32_e32 v83, v6
	v_pk_mul_f32 v[82:83], v[82:83], s[70:71] op_sel_hi:[1,0]
	v_mov_b32_e32 v101, v4
	v_pk_fma_f32 v[6:7], v[6:7], s[70:71], v[82:83] op_sel_hi:[1,0,1]
	s_nop 0
	v_pk_add_f32 v[82:83], v[14:15], v[6:7]
	v_pk_add_f32 v[6:7], v[14:15], v[6:7] neg_lo:[0,1] neg_hi:[0,1]
	v_xor_b32_e32 v14, 0x80000000, v87
	v_mov_b32_e32 v15, v86
	v_pk_add_f32 v[86:87], v[26:27], v[14:15]
	v_pk_add_f32 v[14:15], v[26:27], v[14:15] neg_lo:[0,1] neg_hi:[0,1]
	v_pk_mul_f32 v[26:27], v[4:5], s[70:71] op_sel_hi:[1,0]
	s_nop 0
	v_pk_fma_f32 v[4:5], v[100:101], s[70:71], v[26:27] op_sel_hi:[1,0,1] neg_lo:[0,0,1] neg_hi:[0,0,1]
	v_xor_b32_e32 v100, 0x80000000, v25
	v_pk_add_f32 v[26:27], v[12:13], v[4:5]
	v_pk_add_f32 v[4:5], v[12:13], v[4:5] neg_lo:[0,1] neg_hi:[0,1]
	v_pk_add_f32 v[12:13], v[92:93], v[84:85]
	v_pk_add_f32 v[84:85], v[92:93], v[84:85] neg_lo:[0,1] neg_hi:[0,1]
	v_xor_b32_e32 v92, 0x80000000, v63
	v_mov_b32_e32 v93, v62
	v_pk_mul_f32 v[92:93], v[92:93], s[70:71] op_sel_hi:[1,0]
	v_mov_b32_e32 v101, v24
	v_pk_fma_f32 v[62:63], v[62:63], s[70:71], v[92:93] op_sel_hi:[1,0,1]
	s_nop 0
	v_pk_add_f32 v[92:93], v[2:3], v[62:63]
	v_pk_add_f32 v[2:3], v[2:3], v[62:63] neg_lo:[0,1] neg_hi:[0,1]
	v_xor_b32_e32 v62, 0x80000000, v65
	v_mov_b32_e32 v63, v64
	v_pk_add_f32 v[64:65], v[22:23], v[62:63]
	v_pk_add_f32 v[22:23], v[22:23], v[62:63] neg_lo:[0,1] neg_hi:[0,1]
	v_pk_mul_f32 v[62:63], v[24:25], s[70:71] op_sel_hi:[1,0]
	s_nop 0
	v_pk_fma_f32 v[24:25], v[100:101], s[70:71], v[62:63] op_sel_hi:[1,0,1] neg_lo:[0,0,1] neg_hi:[0,0,1]
	v_xor_b32_e32 v100, 0x80000000, v21
	v_pk_add_f32 v[62:63], v[68:69], v[24:25]
	v_pk_add_f32 v[24:25], v[68:69], v[24:25] neg_lo:[0,1] neg_hi:[0,1]
	v_pk_add_f32 v[68:69], v[80:81], v[96:97]
	v_pk_add_f32 v[80:81], v[80:81], v[96:97] neg_lo:[0,1] neg_hi:[0,1]
	v_xor_b32_e32 v96, 0x80000000, v67
	v_mov_b32_e32 v97, v66
	v_pk_mul_f32 v[96:97], v[96:97], s[70:71] op_sel_hi:[1,0]
	v_mov_b32_e32 v101, v20
	v_pk_fma_f32 v[66:67], v[66:67], s[70:71], v[96:97] op_sel_hi:[1,0,1]
	s_nop 0
	v_pk_add_f32 v[96:97], v[70:71], v[66:67]
	v_pk_add_f32 v[66:67], v[70:71], v[66:67] neg_lo:[0,1] neg_hi:[0,1]
	v_xor_b32_e32 v70, 0x80000000, v89
	v_mov_b32_e32 v71, v88
	v_pk_add_f32 v[88:89], v[90:91], v[70:71]
	v_pk_add_f32 v[70:71], v[90:91], v[70:71] neg_lo:[0,1] neg_hi:[0,1]
	v_pk_mul_f32 v[90:91], v[20:21], s[70:71] op_sel_hi:[1,0]
	s_nop 0
	v_pk_fma_f32 v[20:21], v[100:101], s[70:71], v[90:91] op_sel_hi:[1,0,1] neg_lo:[0,0,1] neg_hi:[0,0,1]
	s_nop 0
	v_pk_add_f32 v[90:91], v[72:73], v[20:21]
	v_pk_add_f32 v[20:21], v[72:73], v[20:21] neg_lo:[0,1] neg_hi:[0,1]
	v_pk_add_f32 v[72:73], v[94:95], v[8:9]
	v_pk_add_f32 v[8:9], v[94:95], v[8:9] neg_lo:[0,1] neg_hi:[0,1]
	v_xor_b32_e32 v94, 0x80000000, v83
	v_mov_b32_e32 v95, v82
	v_pk_mul_f32 v[94:95], v[94:95], s[62:63] op_sel_hi:[1,0]
	s_nop 0
	v_pk_fma_f32 v[82:83], v[82:83], s[60:61], v[94:95] op_sel_hi:[1,0,1]
	s_nop 0
	v_pk_add_f32 v[94:95], v[98:99], v[82:83]
	v_pk_add_f32 v[82:83], v[98:99], v[82:83] neg_lo:[0,1] neg_hi:[0,1]
	v_xor_b32_e32 v98, 0x80000000, v87
	v_mov_b32_e32 v99, v86
	v_pk_mul_f32 v[98:99], v[98:99], s[70:71] op_sel_hi:[1,0]
	s_nop 0
	v_pk_fma_f32 v[86:87], v[86:87], s[70:71], v[98:99] op_sel_hi:[1,0,1]
	s_nop 0
	v_pk_add_f32 v[98:99], v[76:77], v[86:87]
	v_pk_add_f32 v[86:87], v[76:77], v[86:87] neg_lo:[0,1] neg_hi:[0,1]
	v_xor_b32_e32 v76, 0x80000000, v27
	v_mov_b32_e32 v77, v26
	v_pk_mul_f32 v[76:77], v[76:77], s[60:61] op_sel_hi:[1,0]
	s_nop 0
	v_pk_fma_f32 v[26:27], v[26:27], s[62:63], v[76:77] op_sel_hi:[1,0,1]
	v_xor_b32_e32 v76, 0x80000000, v67
	v_pk_add_f32 v[100:101], v[18:19], v[26:27]
	v_pk_add_f32 v[26:27], v[18:19], v[26:27] neg_lo:[0,1] neg_hi:[0,1]
	v_xor_b32_e32 v18, 0x80000000, v79
	v_mov_b32_e32 v19, v78
	v_pk_add_f32 v[102:103], v[74:75], v[18:19]
	v_pk_add_f32 v[104:105], v[74:75], v[18:19] neg_lo:[0,1] neg_hi:[0,1]
	v_pk_mul_f32 v[18:19], v[6:7], s[62:63] op_sel_hi:[1,0]
	v_xor_b32_e32 v74, 0x80000000, v7
	v_mov_b32_e32 v75, v6
	v_pk_fma_f32 v[6:7], v[74:75], s[60:61], v[18:19] op_sel_hi:[1,0,1] neg_lo:[0,0,1] neg_hi:[0,0,1]
	v_xor_b32_e32 v74, 0x80000000, v15
	v_pk_add_f32 v[18:19], v[10:11], v[6:7]
	v_pk_add_f32 v[6:7], v[10:11], v[6:7] neg_lo:[0,1] neg_hi:[0,1]
	v_pk_mul_f32 v[10:11], v[14:15], s[70:71] op_sel_hi:[1,0]
	v_mov_b32_e32 v75, v14
	v_pk_fma_f32 v[10:11], v[74:75], s[70:71], v[10:11] op_sel_hi:[1,0,1] neg_lo:[0,0,1] neg_hi:[0,0,1]
	v_xor_b32_e32 v74, 0x80000000, v5
	v_pk_add_f32 v[14:15], v[16:17], v[10:11]
	v_pk_add_f32 v[10:11], v[16:17], v[10:11] neg_lo:[0,1] neg_hi:[0,1]
	v_pk_mul_f32 v[16:17], v[4:5], s[60:61] op_sel_hi:[1,0]
	v_mov_b32_e32 v75, v4
	v_pk_fma_f32 v[4:5], v[74:75], s[62:63], v[16:17] op_sel_hi:[1,0,1] neg_lo:[0,0,1] neg_hi:[0,0,1]
	v_xor_b32_e32 v74, 0x80000000, v89
	v_pk_add_f32 v[16:17], v[0:1], v[4:5]
	v_pk_add_f32 v[106:107], v[0:1], v[4:5] neg_lo:[0,1] neg_hi:[0,1]
	v_pk_add_f32 v[0:1], v[12:13], v[68:69]
	v_pk_add_f32 v[4:5], v[12:13], v[68:69] neg_lo:[0,1] neg_hi:[0,1]
	v_xor_b32_e32 v12, 0x80000000, v97
	v_mov_b32_e32 v13, v96
	v_mov_b32_e32 v75, v88
	v_pk_mul_f32 v[12:13], v[12:13], s[62:63] op_sel_hi:[1,0]
	v_pk_mul_f32 v[74:75], v[74:75], s[70:71] op_sel_hi:[1,0]
	v_pk_fma_f32 v[12:13], v[96:97], s[60:61], v[12:13] op_sel_hi:[1,0,1]
	v_pk_fma_f32 v[74:75], v[88:89], s[70:71], v[74:75] op_sel_hi:[1,0,1]
	v_pk_add_f32 v[68:69], v[92:93], v[12:13]
	v_pk_add_f32 v[12:13], v[92:93], v[12:13] neg_lo:[0,1] neg_hi:[0,1]
	v_pk_add_f32 v[88:89], v[64:65], v[74:75]
	v_pk_add_f32 v[92:93], v[64:65], v[74:75] neg_lo:[0,1] neg_hi:[0,1]
	v_xor_b32_e32 v64, 0x80000000, v91
	v_mov_b32_e32 v65, v90
	v_pk_mul_f32 v[64:65], v[64:65], s[60:61] op_sel_hi:[1,0]
	v_pk_add_f32 v[78:79], v[72:73], v[0:1]
	v_pk_fma_f32 v[64:65], v[90:91], s[62:63], v[64:65] op_sel_hi:[1,0,1]
	v_xor_b32_e32 v0, 0x80000000, v69
	v_mov_b32_e32 v1, v68
	v_pk_add_f32 v[74:75], v[62:63], v[64:65]
	v_pk_add_f32 v[90:91], v[62:63], v[64:65] neg_lo:[0,1] neg_hi:[0,1]
	v_xor_b32_e32 v62, 0x80000000, v81
	v_mov_b32_e32 v63, v80
	v_pk_mul_f32 v[0:1], v[0:1], s[58:59] op_sel_hi:[1,0]
	v_pk_add_f32 v[64:65], v[84:85], v[62:63]
	v_pk_add_f32 v[80:81], v[84:85], v[62:63] neg_lo:[0,1] neg_hi:[0,1]
	v_pk_mul_f32 v[62:63], v[66:67], s[62:63] op_sel_hi:[1,0]
	v_mov_b32_e32 v77, v66
	v_pk_fma_f32 v[0:1], v[68:69], s[46:47], v[0:1] op_sel_hi:[1,0,1]
	v_pk_fma_f32 v[62:63], v[76:77], s[60:61], v[62:63] op_sel_hi:[1,0,1] neg_lo:[0,0,1] neg_hi:[0,0,1]
	v_pk_add_f32 v[76:77], v[94:95], v[0:1]
	v_xor_b32_e32 v0, 0x80000000, v89
	v_mov_b32_e32 v1, v88
	v_pk_mul_f32 v[0:1], v[0:1], s[62:63] op_sel_hi:[1,0]
	v_pk_add_f32 v[84:85], v[2:3], v[62:63]
	v_pk_fma_f32 v[0:1], v[88:89], s[60:61], v[0:1] op_sel_hi:[1,0,1]
	v_pk_add_f32 v[2:3], v[2:3], v[62:63] neg_lo:[0,1] neg_hi:[0,1]
	v_pk_add_f32 v[72:73], v[98:99], v[0:1]
	v_xor_b32_e32 v0, 0x80000000, v75
	v_mov_b32_e32 v1, v74
	v_pk_mul_f32 v[0:1], v[0:1], s[66:67] op_sel_hi:[1,0]
	v_pk_mul_f32 v[62:63], v[70:71], s[70:71] op_sel_hi:[1,0]
	v_pk_fma_f32 v[0:1], v[74:75], s[64:65], v[0:1] op_sel_hi:[1,0,1]
	v_xor_b32_e32 v66, 0x80000000, v71
	v_pk_add_f32 v[74:75], v[100:101], v[0:1]
	v_xor_b32_e32 v0, 0x80000000, v65
	v_mov_b32_e32 v1, v64
	v_pk_mul_f32 v[0:1], v[0:1], s[70:71] op_sel_hi:[1,0]
	v_mov_b32_e32 v67, v70
	v_pk_fma_f32 v[0:1], v[64:65], s[70:71], v[0:1] op_sel_hi:[1,0,1]
	v_pk_fma_f32 v[62:63], v[66:67], s[70:71], v[62:63] op_sel_hi:[1,0,1] neg_lo:[0,0,1] neg_hi:[0,0,1]
	v_pk_add_f32 v[66:67], v[102:103], v[0:1]
	v_xor_b32_e32 v0, 0x80000000, v85
	v_mov_b32_e32 v1, v84
	v_pk_mul_f32 v[0:1], v[0:1], s[64:65] op_sel_hi:[1,0]
	v_pk_add_f32 v[70:71], v[22:23], v[62:63]
	v_pk_fma_f32 v[0:1], v[84:85], s[66:67], v[0:1] op_sel_hi:[1,0,1]
	v_pk_add_f32 v[96:97], v[22:23], v[62:63] neg_lo:[0,1] neg_hi:[0,1]
	v_pk_mul_f32 v[22:23], v[20:21], s[60:61] op_sel_hi:[1,0]
	v_xor_b32_e32 v62, 0x80000000, v21
	v_mov_b32_e32 v63, v20
	v_pk_add_f32 v[68:69], v[18:19], v[0:1]
	v_xor_b32_e32 v0, 0x80000000, v71
	v_mov_b32_e32 v1, v70
	v_pk_fma_f32 v[20:21], v[62:63], s[62:63], v[22:23] op_sel_hi:[1,0,1] neg_lo:[0,0,1] neg_hi:[0,0,1]
	v_pk_mul_f32 v[0:1], v[0:1], s[60:61] op_sel_hi:[1,0]
	v_pk_add_f32 v[22:23], v[24:25], v[20:21]
	v_pk_fma_f32 v[0:1], v[70:71], s[62:63], v[0:1] op_sel_hi:[1,0,1]
	v_pk_add_f32 v[108:109], v[24:25], v[20:21] neg_lo:[0,1] neg_hi:[0,1]
	v_pk_add_f32 v[62:63], v[14:15], v[0:1]
	v_xor_b32_e32 v0, 0x80000000, v23
	v_mov_b32_e32 v1, v22
	v_pk_mul_f32 v[0:1], v[0:1], s[46:47] op_sel_hi:[1,0]
	s_nop 0
	v_pk_fma_f32 v[0:1], v[22:23], s[58:59], v[0:1] op_sel_hi:[1,0,1]
	s_nop 0
	v_pk_add_f32 v[64:65], v[16:17], v[0:1]
	v_xor_b32_e32 v0, 0x80000000, v5
	v_mov_b32_e32 v1, v4
	v_pk_add_f32 v[22:23], v[8:9], v[0:1]
	v_pk_mul_f32 v[0:1], v[12:13], s[58:59] op_sel_hi:[1,0]
	v_xor_b32_e32 v4, 0x80000000, v13
	v_mov_b32_e32 v5, v12
	v_pk_fma_f32 v[0:1], v[4:5], s[46:47], v[0:1] op_sel_hi:[1,0,1] neg_lo:[0,0,1] neg_hi:[0,0,1]
	v_xor_b32_e32 v4, 0x80000000, v93
	v_pk_add_f32 v[24:25], v[82:83], v[0:1]
	v_pk_mul_f32 v[0:1], v[92:93], s[62:63] op_sel_hi:[1,0]
	v_mov_b32_e32 v5, v92
	v_pk_fma_f32 v[0:1], v[4:5], s[60:61], v[0:1] op_sel_hi:[1,0,1] neg_lo:[0,0,1] neg_hi:[0,0,1]
	v_xor_b32_e32 v4, 0x80000000, v91
	v_pk_add_f32 v[18:19], v[86:87], v[0:1]
	v_pk_mul_f32 v[0:1], v[90:91], s[66:67] op_sel_hi:[1,0]
	v_mov_b32_e32 v5, v90
	v_pk_fma_f32 v[0:1], v[4:5], s[64:65], v[0:1] op_sel_hi:[1,0,1] neg_lo:[0,0,1] neg_hi:[0,0,1]
	v_xor_b32_e32 v4, 0x80000000, v81
	v_pk_add_f32 v[20:21], v[26:27], v[0:1]
	v_pk_mul_f32 v[0:1], v[80:81], s[70:71] op_sel_hi:[1,0]
	v_mov_b32_e32 v5, v80
	v_pk_fma_f32 v[0:1], v[4:5], s[70:71], v[0:1] op_sel_hi:[1,0,1] neg_lo:[0,0,1] neg_hi:[0,0,1]
	v_xor_b32_e32 v8, 0x80000000, v3
	v_pk_add_f32 v[4:5], v[104:105], v[0:1]
	v_pk_mul_f32 v[0:1], v[2:3], s[64:65] op_sel_hi:[1,0]
	v_mov_b32_e32 v9, v2
	v_pk_fma_f32 v[0:1], v[8:9], s[66:67], v[0:1] op_sel_hi:[1,0,1] neg_lo:[0,0,1] neg_hi:[0,0,1]
	v_xor_b32_e32 v2, 0x80000000, v97
	v_pk_add_f32 v[6:7], v[6:7], v[0:1]
	v_pk_mul_f32 v[0:1], v[96:97], s[60:61] op_sel_hi:[1,0]
	v_mov_b32_e32 v3, v96
	v_pk_fma_f32 v[0:1], v[2:3], s[62:63], v[0:1] op_sel_hi:[1,0,1] neg_lo:[0,0,1] neg_hi:[0,0,1]
	v_pk_mul_f32 v[2:3], v[108:109], s[46:47] op_sel_hi:[1,0]
	v_pk_add_f32 v[0:1], v[10:11], v[0:1]
	v_xor_b32_e32 v8, 0x80000000, v109
	v_mov_b32_e32 v9, v108
	v_mov_b32_e32 v10, v146
	v_pk_fma_f32 v[2:3], v[8:9], s[58:59], v[2:3] op_sel_hi:[1,0,1] neg_lo:[0,0,1] neg_hi:[0,0,1]
	global_load_dword v8, v145, s[0:1]
	s_movk_i32 s0, 0x200
	s_cselect_b32 s4, s0, 0x400
	s_add_i32 s0, s4, s68
	s_ashr_i32 s1, s0, 31
	s_lshl_b32 s6, s4, 2
	s_add_u32 s4, s90, s6
	s_addc_u32 s5, s91, 0
	s_lshl_b64 s[0:1], s[0:1], 14
	v_min_i32_e32 v70, 0x1ffe, v10
	v_mov_b32_e32 v9, s6
	s_add_u32 s36, s26, s0
	v_ashrrev_i32_e32 v11, 31, v10
	v_ashrrev_i32_e32 v71, 31, v70
	global_load_dword v16, v9, s[90:91]
	global_load_dword v14, v153, s[4:5] offset:2048
	global_load_dword v17, v154, s[4:5]
	global_load_dword v12, v9, s[94:95]
	s_addc_u32 s37, s27, s1
	v_max_i32_e32 v9, 1, v10
	v_lshlrev_b64 v[82:83], 1, v[10:11]
	v_lshlrev_b64 v[84:85], 1, v[70:71]
	v_lshl_add_u64 v[26:27], s[36:37], 0, v[82:83]
	v_lshlrev_b32_e32 v9, 1, v9
	v_lshl_add_u64 v[70:71], s[36:37], 0, v[84:85]
	global_load_ushort v13, v[26:27], off
	s_add_u32 s88, s30, s0
	global_load_ushort v70, v[70:71], off offset:2
	s_addc_u32 s89, s31, s1
	global_load_ushort v15, v9, s[36:37] offset:-2
	v_cmp_lt_i32_e64 s[0:1], 0, v10
	v_cmp_gt_i32_e64 s[4:5], s74, v10
	v_pk_add_f32 v[2:3], v[106:107], v[2:3]
	v_cndmask_b32_e64 v81, 0, 1.0, s[0:1]
	v_cndmask_b32_e64 v86, 0, 1.0, s[4:5]
	v_add_u32_e32 v92, 0x200, v10
	v_cmp_lt_i32_e64 s[20:21], s25, v10
	v_cmp_gt_i32_e64 s[18:19], s42, v10
	v_add_u32_e32 v90, 0x400, v10
	v_cmp_lt_i32_e64 s[16:17], s33, v10
	v_cmp_gt_i32_e64 s[0:1], s51, v10
	v_add_u32_e32 v88, 0x600, v10
	v_cmp_lt_i32_e64 s[12:13], s43, v10
	v_cmp_gt_i32_e64 s[10:11], s50, v10
	v_cmp_lt_i32_e64 s[8:9], s2, v10
	v_cmp_gt_i32_e64 s[6:7], s38, v10
	v_cmp_lt_i32_e64 s[4:5], s65, v10
	v_cmp_gt_i32_e64 s[22:23], s34, v10
	s_waitcnt vmcnt(2)
	v_lshlrev_b32_e32 v13, 16, v13
	s_waitcnt vmcnt(1)
	v_lshlrev_b32_e32 v70, 16, v70
	v_mul_f32_e32 v70, v86, v70
	s_waitcnt vmcnt(0)
	v_lshlrev_b32_e32 v15, 16, v15
	v_mul_f32_e32 v15, v81, v15
	v_mul_f32_e32 v15, v16, v15
	v_fmac_f32_e32 v15, v14, v13
	v_fmac_f32_e32 v15, v17, v70
	v_lshl_add_u64 v[70:71], s[88:89], 0, v[82:83]
	v_lshl_add_u64 v[82:83], s[88:89], 0, v[84:85]
	v_add_f32_e32 v80, v12, v15
	global_load_ushort v13, v[70:71], off
	global_load_ushort v15, v[82:83], off offset:2
	v_add_u32_e32 v84, 0x800, v10
	global_load_ushort v9, v9, s[88:89] offset:-2
	v_add_u32_e32 v82, 0xa00, v10
	s_waitcnt vmcnt(2)
	v_lshlrev_b32_e32 v13, 16, v13
	s_waitcnt vmcnt(1)
	v_lshlrev_b32_e32 v15, 16, v15
	v_mul_f32_e32 v15, v86, v15
	s_waitcnt vmcnt(0)
	v_lshlrev_b32_e32 v9, 16, v9
	v_mul_f32_e32 v9, v81, v9
	v_mul_f32_e32 v9, v16, v9
	v_fmac_f32_e32 v9, v14, v13
	v_fmac_f32_e32 v9, v17, v15
	v_add_f32_e32 v86, v12, v9
	s_cbranch_vccnz .LBB0_540
	s_lshl_b64 s[0:1], s[92:93], 1
	s_add_u32 s4, s0, s30
	s_addc_u32 s5, s1, s31
	s_add_u32 s0, s0, s26
	s_addc_u32 s1, s1, s27
	s_add_u32 s18, s96, 0x800000
	s_addc_u32 s19, s97, 0
	v_lshlrev_b32_e32 v109, 1, v10
	global_load_ushort v9, v109, s[0:1]
	global_load_ushort v11, v109, s[4:5]
	global_load_ushort v13, v109, s[36:37] offset:1022
	global_load_ushort v15, v109, s[36:37] offset:1024
	global_load_ushort v81, v109, s[36:37] offset:1026
	global_load_ushort v83, v109, s[88:89] offset:1022
	global_load_ushort v85, v109, s[88:89] offset:1024
	global_load_ushort v87, v109, s[88:89] offset:1026
	global_load_ushort v89, v109, s[0:1] offset:1024
	global_load_ushort v91, v109, s[4:5] offset:1024
	global_load_ushort v93, v109, s[36:37] offset:2046
	global_load_ushort v94, v109, s[36:37] offset:2048
	global_load_ushort v95, v109, s[36:37] offset:2050
	global_load_ushort v96, v109, s[88:89] offset:2046
	global_load_ushort v97, v109, s[88:89] offset:2048
	global_load_ushort v98, v109, s[88:89] offset:2050
	global_load_ushort v99, v109, s[0:1] offset:2048
	global_load_ushort v100, v109, s[4:5] offset:2048
	global_load_ushort v101, v109, s[36:37] offset:3070
	global_load_ushort v102, v109, s[36:37] offset:3072
	global_load_ushort v103, v109, s[36:37] offset:3074
	global_load_ushort v104, v109, s[88:89] offset:3070
	global_load_ushort v105, v109, s[88:89] offset:3072
	global_load_ushort v106, v109, s[88:89] offset:3074
	global_load_ushort v107, v109, s[0:1] offset:3072
	global_load_ushort v108, v109, s[4:5] offset:3072
	s_waitcnt vmcnt(0)
	v_lshlrev_b32_e32 v26, 10, v10
	v_fma_f32 v27, v32, v8, v78
	v_mul_f32_e32 v70, v80, v27
	v_lshlrev_b32_e32 v9, 16, v9
	v_mul_f32_e32 v84, 0xbfb8aa3b, v9
	v_exp_f32_e32 v84, v84
	s_nop 0
	v_add_f32_e32 v84, 1.0, v84
	v_div_scale_f32 v71, s[28:29], v84, v84, v9
	v_rcp_f32_e32 v82, v71
	s_nop 0
	v_fma_f32 v92, -v71, v82, 1.0
	v_fmac_f32_e32 v82, v92, v82
	v_div_scale_f32 v88, vcc, v9, v84, v9
	v_mul_f32_e32 v90, v88, v82
	v_fma_f32 v92, -v71, v90, v88
	v_fmac_f32_e32 v90, v92, v82
	v_fma_f32 v71, -v71, v90, v88
	v_div_fmas_f32 v71, v71, v82, v90
	v_div_fixup_f32 v9, v71, v84, v9
	v_mul_f32_e32 v70, v70, v9
	v_cvt_pk_bf16_f32 v70, v70, s0
	global_store_short v26, v70, s[96:97]
	v_fma_f32 v27, v34, v8, v79
	v_mul_f32_e32 v70, v86, v27
	v_lshlrev_b32_e32 v11, 16, v11
	v_mul_f32_e32 v84, 0xbfb8aa3b, v11
	v_exp_f32_e32 v84, v84
	s_nop 0
	v_add_f32_e32 v84, 1.0, v84
	v_div_scale_f32 v71, s[28:29], v84, v84, v11
	v_rcp_f32_e32 v82, v71
	s_nop 0
	v_fma_f32 v92, -v71, v82, 1.0
	v_fmac_f32_e32 v82, v92, v82
	v_div_scale_f32 v88, vcc, v11, v84, v11
	v_mul_f32_e32 v90, v88, v82
	v_fma_f32 v92, -v71, v90, v88
	v_fmac_f32_e32 v90, v92, v82
	v_fma_f32 v71, -v71, v90, v88
	v_div_fmas_f32 v71, v71, v82, v90
	v_div_fixup_f32 v11, v71, v84, v11
	v_mul_f32_e32 v70, v70, v11
	v_cvt_pk_bf16_f32 v70, v70, s0
	global_store_short v26, v70, s[18:19]
	v_add_u32_e32 v26, 0x80000, v26
	v_lshlrev_b32_e32 v15, 16, v15
	v_lshlrev_b32_e32 v81, 16, v81
	v_lshlrev_b32_e32 v13, 16, v13
	v_mul_f32_e32 v13, v16, v13
	v_fmac_f32_e32 v13, v14, v15
	v_fmac_f32_e32 v13, v17, v81
	v_add_f32_e32 v13, v12, v13
	v_fma_f32 v27, v33, v8, v76
	v_mul_f32_e32 v70, v27, v13
	v_lshlrev_b32_e32 v89, 16, v89
	v_mul_f32_e32 v84, 0xbfb8aa3b, v89
	v_exp_f32_e32 v84, v84
	s_nop 0
	v_add_f32_e32 v84, 1.0, v84
	v_div_scale_f32 v71, s[28:29], v84, v84, v89
	v_rcp_f32_e32 v82, v71
	s_nop 0
	v_fma_f32 v92, -v71, v82, 1.0
	v_fmac_f32_e32 v82, v92, v82
	v_div_scale_f32 v88, vcc, v89, v84, v89
	v_mul_f32_e32 v90, v88, v82
	v_fma_f32 v92, -v71, v90, v88
	v_fmac_f32_e32 v90, v92, v82
	v_fma_f32 v71, -v71, v90, v88
	v_div_fmas_f32 v71, v71, v82, v90
	v_div_fixup_f32 v89, v71, v84, v89
	v_mul_f32_e32 v70, v70, v89
	v_cvt_pk_bf16_f32 v70, v70, s0
	global_store_short v26, v70, s[96:97]
	v_lshlrev_b32_e32 v85, 16, v85
	v_lshlrev_b32_e32 v87, 16, v87
	v_lshlrev_b32_e32 v83, 16, v83
	v_mul_f32_e32 v83, v16, v83
	v_fmac_f32_e32 v83, v14, v85
	v_fmac_f32_e32 v83, v17, v87
	v_add_f32_e32 v83, v12, v83
	v_fma_f32 v27, v35, v8, v77
	v_mul_f32_e32 v70, v27, v83
	v_lshlrev_b32_e32 v91, 16, v91
	v_mul_f32_e32 v84, 0xbfb8aa3b, v91
	v_exp_f32_e32 v84, v84
	s_nop 0
	v_add_f32_e32 v84, 1.0, v84
	v_div_scale_f32 v71, s[28:29], v84, v84, v91
	v_rcp_f32_e32 v82, v71
	s_nop 0
	v_fma_f32 v92, -v71, v82, 1.0
	v_fmac_f32_e32 v82, v92, v82
	v_div_scale_f32 v88, vcc, v91, v84, v91
	v_mul_f32_e32 v90, v88, v82
	v_fma_f32 v92, -v71, v90, v88
	v_fmac_f32_e32 v90, v92, v82
	v_fma_f32 v71, -v71, v90, v88
	v_div_fmas_f32 v71, v71, v82, v90
	v_div_fixup_f32 v91, v71, v84, v91
	v_mul_f32_e32 v70, v70, v91
	v_cvt_pk_bf16_f32 v70, v70, s0
	global_store_short v26, v70, s[18:19]
	v_add_u32_e32 v26, 0x80000, v26
	v_lshlrev_b32_e32 v94, 16, v94
	v_lshlrev_b32_e32 v95, 16, v95
	v_lshlrev_b32_e32 v93, 16, v93
	v_mul_f32_e32 v93, v16, v93
	v_fmac_f32_e32 v93, v14, v94
	v_fmac_f32_e32 v93, v17, v95
	v_add_f32_e32 v93, v12, v93
	v_fma_f32 v27, v37, v8, v72
	v_mul_f32_e32 v70, v27, v93
	v_lshlrev_b32_e32 v99, 16, v99
	v_mul_f32_e32 v84, 0xbfb8aa3b, v99
	v_exp_f32_e32 v84, v84
	s_nop 0
	v_add_f32_e32 v84, 1.0, v84
	v_div_scale_f32 v71, s[28:29], v84, v84, v99
	v_rcp_f32_e32 v82, v71
	s_nop 0
	v_fma_f32 v92, -v71, v82, 1.0
	v_fmac_f32_e32 v82, v92, v82
	v_div_scale_f32 v88, vcc, v99, v84, v99
	v_mul_f32_e32 v90, v88, v82
	v_fma_f32 v92, -v71, v90, v88
	v_fmac_f32_e32 v90, v92, v82
	v_fma_f32 v71, -v71, v90, v88
	v_div_fmas_f32 v71, v71, v82, v90
	v_div_fixup_f32 v99, v71, v84, v99
	v_mul_f32_e32 v70, v70, v99
	v_cvt_pk_bf16_f32 v70, v70, s0
	global_store_short v26, v70, s[96:97]
	v_lshlrev_b32_e32 v97, 16, v97
	v_lshlrev_b32_e32 v98, 16, v98
	v_lshlrev_b32_e32 v96, 16, v96
	v_mul_f32_e32 v96, v16, v96
	v_fmac_f32_e32 v96, v14, v97
	v_fmac_f32_e32 v96, v17, v98
	v_add_f32_e32 v96, v12, v96
	v_fma_f32 v27, v31, v8, v73
	v_mul_f32_e32 v70, v27, v96
	v_lshlrev_b32_e32 v100, 16, v100
	v_mul_f32_e32 v84, 0xbfb8aa3b, v100
	v_exp_f32_e32 v84, v84
	s_nop 0
	v_add_f32_e32 v84, 1.0, v84
	v_div_scale_f32 v71, s[28:29], v84, v84, v100
	v_rcp_f32_e32 v82, v71
	s_nop 0
	v_fma_f32 v92, -v71, v82, 1.0
	v_fmac_f32_e32 v82, v92, v82
	v_div_scale_f32 v88, vcc, v100, v84, v100
	v_mul_f32_e32 v90, v88, v82
	v_fma_f32 v92, -v71, v90, v88
	v_fmac_f32_e32 v90, v92, v82
	v_fma_f32 v71, -v71, v90, v88
	v_div_fmas_f32 v71, v71, v82, v90
	v_div_fixup_f32 v100, v71, v84, v100
	v_mul_f32_e32 v70, v70, v100
	v_cvt_pk_bf16_f32 v70, v70, s0
	global_store_short v26, v70, s[18:19]
	v_add_u32_e32 v26, 0x80000, v26
	v_lshlrev_b32_e32 v102, 16, v102
	v_lshlrev_b32_e32 v103, 16, v103
	v_lshlrev_b32_e32 v101, 16, v101
	v_mul_f32_e32 v101, v16, v101
	v_fmac_f32_e32 v101, v14, v102
	v_fmac_f32_e32 v101, v17, v103
	v_add_f32_e32 v101, v12, v101
	v_fma_f32 v27, v36, v8, v74
	v_mul_f32_e32 v70, v27, v101
	v_lshlrev_b32_e32 v107, 16, v107
	v_mul_f32_e32 v84, 0xbfb8aa3b, v107
	v_exp_f32_e32 v84, v84
	s_nop 0
	v_add_f32_e32 v84, 1.0, v84
	v_div_scale_f32 v71, s[28:29], v84, v84, v107
	v_rcp_f32_e32 v82, v71
	s_nop 0
	v_fma_f32 v92, -v71, v82, 1.0
	v_fmac_f32_e32 v82, v92, v82
	v_div_scale_f32 v88, vcc, v107, v84, v107
	v_mul_f32_e32 v90, v88, v82
	v_fma_f32 v92, -v71, v90, v88
	v_fmac_f32_e32 v90, v92, v82
	v_fma_f32 v71, -v71, v90, v88
	v_div_fmas_f32 v71, v71, v82, v90
	v_div_fixup_f32 v107, v71, v84, v107
	v_mul_f32_e32 v70, v70, v107
	v_cvt_pk_bf16_f32 v70, v70, s0
	global_store_short v26, v70, s[96:97]
	v_lshlrev_b32_e32 v105, 16, v105
	v_lshlrev_b32_e32 v106, 16, v106
	v_lshlrev_b32_e32 v104, 16, v104
	v_mul_f32_e32 v104, v16, v104
	v_fmac_f32_e32 v104, v14, v105
	v_fmac_f32_e32 v104, v17, v106
	v_add_f32_e32 v104, v12, v104
	v_fma_f32 v27, v30, v8, v75
	v_mul_f32_e32 v70, v27, v104
	v_lshlrev_b32_e32 v108, 16, v108
	v_mul_f32_e32 v84, 0xbfb8aa3b, v108
	v_exp_f32_e32 v84, v84
	s_nop 0
	v_add_f32_e32 v84, 1.0, v84
	v_div_scale_f32 v71, s[28:29], v84, v84, v108
	v_rcp_f32_e32 v82, v71
	s_nop 0
	v_fma_f32 v92, -v71, v82, 1.0
	v_fmac_f32_e32 v82, v92, v82
	v_div_scale_f32 v88, vcc, v108, v84, v108
	v_mul_f32_e32 v90, v88, v82
	v_fma_f32 v92, -v71, v90, v88
	v_fmac_f32_e32 v90, v92, v82
	v_fma_f32 v71, -v71, v90, v88
	v_div_fmas_f32 v71, v71, v82, v90
	v_div_fixup_f32 v108, v71, v84, v108
	v_mul_f32_e32 v70, v70, v108
	v_cvt_pk_bf16_f32 v70, v70, s0
	global_store_short v26, v70, s[18:19]
	v_add_u32_e32 v109, 0x1000, v109
	global_load_ushort v9, v109, s[36:37] offset:-2
	global_load_ushort v11, v109, s[36:37]
	global_load_ushort v13, v109, s[36:37] offset:2
	global_load_ushort v15, v109, s[88:89] offset:-2
	global_load_ushort v81, v109, s[88:89]
	global_load_ushort v83, v109, s[88:89] offset:2
	global_load_ushort v85, v109, s[0:1]
	global_load_ushort v87, v109, s[4:5]
	global_load_ushort v89, v109, s[36:37] offset:1022
	global_load_ushort v91, v109, s[36:37] offset:1024
	global_load_ushort v93, v109, s[36:37] offset:1026
	global_load_ushort v94, v109, s[88:89] offset:1022
	global_load_ushort v95, v109, s[88:89] offset:1024
	global_load_ushort v96, v109, s[88:89] offset:1026
	global_load_ushort v97, v109, s[0:1] offset:1024
	global_load_ushort v98, v109, s[4:5] offset:1024
	global_load_ushort v99, v109, s[36:37] offset:2046
	global_load_ushort v100, v109, s[36:37] offset:2048
	global_load_ushort v101, v109, s[36:37] offset:2050
	global_load_ushort v102, v109, s[88:89] offset:2046
	global_load_ushort v103, v109, s[88:89] offset:2048
	global_load_ushort v104, v109, s[88:89] offset:2050
	global_load_ushort v105, v109, s[0:1] offset:2048
	global_load_ushort v106, v109, s[4:5] offset:2048
	global_load_ushort v107, v109, s[36:37] offset:3070
	global_load_ushort v108, v109, s[36:37] offset:3072
	global_load_ushort v32, v109, s[36:37] offset:3074
	global_load_ushort v78, v109, s[88:89] offset:3070
	global_load_ushort v34, v109, s[88:89] offset:3072
	global_load_ushort v79, v109, s[88:89] offset:3074
	global_load_ushort v33, v109, s[0:1] offset:3072
	global_load_ushort v76, v109, s[4:5] offset:3072
	s_waitcnt vmcnt(0)
	v_add_u32_e32 v26, 0x80000, v26
	v_lshlrev_b32_e32 v11, 16, v11
	v_lshlrev_b32_e32 v13, 16, v13
	v_lshlrev_b32_e32 v9, 16, v9
	v_mul_f32_e32 v9, v16, v9
	v_fmac_f32_e32 v9, v14, v11
	v_fmac_f32_e32 v9, v17, v13
	v_add_f32_e32 v9, v12, v9
	v_fma_f32 v27, v39, v8, v66
	v_mul_f32_e32 v70, v27, v9
	v_lshlrev_b32_e32 v85, 16, v85
	v_mul_f32_e32 v84, 0xbfb8aa3b, v85
	v_exp_f32_e32 v84, v84
	s_nop 0
	v_add_f32_e32 v84, 1.0, v84
	v_div_scale_f32 v71, s[28:29], v84, v84, v85
	v_rcp_f32_e32 v82, v71
	s_nop 0
	v_fma_f32 v92, -v71, v82, 1.0
	v_fmac_f32_e32 v82, v92, v82
	v_div_scale_f32 v88, vcc, v85, v84, v85
	v_mul_f32_e32 v90, v88, v82
	v_fma_f32 v92, -v71, v90, v88
	v_fmac_f32_e32 v90, v92, v82
	v_fma_f32 v71, -v71, v90, v88
	v_div_fmas_f32 v71, v71, v82, v90
	v_div_fixup_f32 v85, v71, v84, v85
	v_mul_f32_e32 v70, v70, v85
	v_cvt_pk_bf16_f32 v70, v70, s0
	global_store_short v26, v70, s[96:97]
	v_lshlrev_b32_e32 v81, 16, v81
	v_lshlrev_b32_e32 v83, 16, v83
	v_lshlrev_b32_e32 v15, 16, v15
	v_mul_f32_e32 v15, v16, v15
	v_fmac_f32_e32 v15, v14, v81
	v_fmac_f32_e32 v15, v17, v83
	v_add_f32_e32 v15, v12, v15
	v_fma_f32 v27, v41, v8, v67
	v_mul_f32_e32 v70, v27, v15
	v_lshlrev_b32_e32 v87, 16, v87
	v_mul_f32_e32 v84, 0xbfb8aa3b, v87
	v_exp_f32_e32 v84, v84
	s_nop 0
	v_add_f32_e32 v84, 1.0, v84
	v_div_scale_f32 v71, s[28:29], v84, v84, v87
	v_rcp_f32_e32 v82, v71
	s_nop 0
	v_fma_f32 v92, -v71, v82, 1.0
	v_fmac_f32_e32 v82, v92, v82
	v_div_scale_f32 v88, vcc, v87, v84, v87
	v_mul_f32_e32 v90, v88, v82
	v_fma_f32 v92, -v71, v90, v88
	v_fmac_f32_e32 v90, v92, v82
	v_fma_f32 v71, -v71, v90, v88
	v_div_fmas_f32 v71, v71, v82, v90
	v_div_fixup_f32 v87, v71, v84, v87
	v_mul_f32_e32 v70, v70, v87
	v_cvt_pk_bf16_f32 v70, v70, s0
	global_store_short v26, v70, s[18:19]
	v_add_u32_e32 v26, 0x80000, v26
	v_lshlrev_b32_e32 v91, 16, v91
	v_lshlrev_b32_e32 v93, 16, v93
	v_lshlrev_b32_e32 v89, 16, v89
	v_mul_f32_e32 v89, v16, v89
	v_fmac_f32_e32 v89, v14, v91
	v_fmac_f32_e32 v89, v17, v93
	v_add_f32_e32 v89, v12, v89
	v_fma_f32 v27, v38, v8, v68
	v_mul_f32_e32 v70, v27, v89
	v_lshlrev_b32_e32 v97, 16, v97
	v_mul_f32_e32 v84, 0xbfb8aa3b, v97
	v_exp_f32_e32 v84, v84
	s_nop 0
	v_add_f32_e32 v84, 1.0, v84
	v_div_scale_f32 v71, s[28:29], v84, v84, v97
	v_rcp_f32_e32 v82, v71
	s_nop 0
	v_fma_f32 v92, -v71, v82, 1.0
	v_fmac_f32_e32 v82, v92, v82
	v_div_scale_f32 v88, vcc, v97, v84, v97
	v_mul_f32_e32 v90, v88, v82
	v_fma_f32 v92, -v71, v90, v88
	v_fmac_f32_e32 v90, v92, v82
	v_fma_f32 v71, -v71, v90, v88
	v_div_fmas_f32 v71, v71, v82, v90
	v_div_fixup_f32 v97, v71, v84, v97
	v_mul_f32_e32 v70, v70, v97
	v_cvt_pk_bf16_f32 v70, v70, s0
	global_store_short v26, v70, s[96:97]
	v_lshlrev_b32_e32 v95, 16, v95
	v_lshlrev_b32_e32 v96, 16, v96
	v_lshlrev_b32_e32 v94, 16, v94
	v_mul_f32_e32 v94, v16, v94
	v_fmac_f32_e32 v94, v14, v95
	v_fmac_f32_e32 v94, v17, v96
	v_add_f32_e32 v94, v12, v94
	v_fma_f32 v27, v40, v8, v69
	v_mul_f32_e32 v70, v27, v94
	v_lshlrev_b32_e32 v98, 16, v98
	v_mul_f32_e32 v84, 0xbfb8aa3b, v98
	v_exp_f32_e32 v84, v84
	s_nop 0
	v_add_f32_e32 v84, 1.0, v84
	v_div_scale_f32 v71, s[28:29], v84, v84, v98
	v_rcp_f32_e32 v82, v71
	s_nop 0
	v_fma_f32 v92, -v71, v82, 1.0
	v_fmac_f32_e32 v82, v92, v82
	v_div_scale_f32 v88, vcc, v98, v84, v98
	v_mul_f32_e32 v90, v88, v82
	v_fma_f32 v92, -v71, v90, v88
	v_fmac_f32_e32 v90, v92, v82
	v_fma_f32 v71, -v71, v90, v88
	v_div_fmas_f32 v71, v71, v82, v90
	v_div_fixup_f32 v98, v71, v84, v98
	v_mul_f32_e32 v70, v70, v98
	v_cvt_pk_bf16_f32 v70, v70, s0
	global_store_short v26, v70, s[18:19]
	v_add_u32_e32 v26, 0x80000, v26
	v_lshlrev_b32_e32 v100, 16, v100
	v_lshlrev_b32_e32 v101, 16, v101
	v_lshlrev_b32_e32 v99, 16, v99
	v_mul_f32_e32 v99, v16, v99
	v_fmac_f32_e32 v99, v14, v100
	v_fmac_f32_e32 v99, v17, v101
	v_add_f32_e32 v99, v12, v99
	v_fma_f32 v27, v43, v8, v62
	v_mul_f32_e32 v70, v27, v99
	v_lshlrev_b32_e32 v105, 16, v105
	v_mul_f32_e32 v84, 0xbfb8aa3b, v105
	v_exp_f32_e32 v84, v84
	s_nop 0
	v_add_f32_e32 v84, 1.0, v84
	v_div_scale_f32 v71, s[28:29], v84, v84, v105
	v_rcp_f32_e32 v82, v71
	s_nop 0
	v_fma_f32 v92, -v71, v82, 1.0
	v_fmac_f32_e32 v82, v92, v82
	v_div_scale_f32 v88, vcc, v105, v84, v105
	v_mul_f32_e32 v90, v88, v82
	v_fma_f32 v92, -v71, v90, v88
	v_fmac_f32_e32 v90, v92, v82
	v_fma_f32 v71, -v71, v90, v88
	v_div_fmas_f32 v71, v71, v82, v90
	v_div_fixup_f32 v105, v71, v84, v105
	v_mul_f32_e32 v70, v70, v105
	v_cvt_pk_bf16_f32 v70, v70, s0
	global_store_short v26, v70, s[96:97]
	v_lshlrev_b32_e32 v103, 16, v103
	v_lshlrev_b32_e32 v104, 16, v104
	v_lshlrev_b32_e32 v102, 16, v102
	v_mul_f32_e32 v102, v16, v102
	v_fmac_f32_e32 v102, v14, v103
	v_fmac_f32_e32 v102, v17, v104
	v_add_f32_e32 v102, v12, v102
	v_fma_f32 v27, v45, v8, v63
	v_mul_f32_e32 v70, v27, v102
	v_lshlrev_b32_e32 v106, 16, v106
	v_mul_f32_e32 v84, 0xbfb8aa3b, v106
	v_exp_f32_e32 v84, v84
	s_nop 0
	v_add_f32_e32 v84, 1.0, v84
	v_div_scale_f32 v71, s[28:29], v84, v84, v106
	v_rcp_f32_e32 v82, v71
	s_nop 0
	v_fma_f32 v92, -v71, v82, 1.0
	v_fmac_f32_e32 v82, v92, v82
	v_div_scale_f32 v88, vcc, v106, v84, v106
	v_mul_f32_e32 v90, v88, v82
	v_fma_f32 v92, -v71, v90, v88
	v_fmac_f32_e32 v90, v92, v82
	v_fma_f32 v71, -v71, v90, v88
	v_div_fmas_f32 v71, v71, v82, v90
	v_div_fixup_f32 v106, v71, v84, v106
	v_mul_f32_e32 v70, v70, v106
	v_cvt_pk_bf16_f32 v70, v70, s0
	global_store_short v26, v70, s[18:19]
	v_add_u32_e32 v26, 0x80000, v26
	v_lshlrev_b32_e32 v108, 16, v108
	v_lshlrev_b32_e32 v32, 16, v32
	v_lshlrev_b32_e32 v107, 16, v107
	v_mul_f32_e32 v107, v16, v107
	v_fmac_f32_e32 v107, v14, v108
	v_fmac_f32_e32 v107, v17, v32
	v_add_f32_e32 v107, v12, v107
	v_fma_f32 v27, v42, v8, v64
	v_mul_f32_e32 v70, v27, v107
	v_lshlrev_b32_e32 v33, 16, v33
	v_mul_f32_e32 v84, 0xbfb8aa3b, v33
	v_exp_f32_e32 v84, v84
	s_nop 0
	v_add_f32_e32 v84, 1.0, v84
	v_div_scale_f32 v71, s[28:29], v84, v84, v33
	v_rcp_f32_e32 v82, v71
	s_nop 0
	v_fma_f32 v92, -v71, v82, 1.0
	v_fmac_f32_e32 v82, v92, v82
	v_div_scale_f32 v88, vcc, v33, v84, v33
	v_mul_f32_e32 v90, v88, v82
	v_fma_f32 v92, -v71, v90, v88
	v_fmac_f32_e32 v90, v92, v82
	v_fma_f32 v71, -v71, v90, v88
	v_div_fmas_f32 v71, v71, v82, v90
	v_div_fixup_f32 v33, v71, v84, v33
	v_mul_f32_e32 v70, v70, v33
	v_cvt_pk_bf16_f32 v70, v70, s0
	global_store_short v26, v70, s[96:97]
	v_lshlrev_b32_e32 v34, 16, v34
	v_lshlrev_b32_e32 v79, 16, v79
	v_lshlrev_b32_e32 v78, 16, v78
	v_mul_f32_e32 v78, v16, v78
	v_fmac_f32_e32 v78, v14, v34
	v_fmac_f32_e32 v78, v17, v79
	v_add_f32_e32 v78, v12, v78
	v_fma_f32 v27, v44, v8, v65
	v_mul_f32_e32 v70, v27, v78
	v_lshlrev_b32_e32 v76, 16, v76
	v_mul_f32_e32 v84, 0xbfb8aa3b, v76
	v_exp_f32_e32 v84, v84
	s_nop 0
	v_add_f32_e32 v84, 1.0, v84
	v_div_scale_f32 v71, s[28:29], v84, v84, v76
	v_rcp_f32_e32 v82, v71
	s_nop 0
	v_fma_f32 v92, -v71, v82, 1.0
	v_fmac_f32_e32 v82, v92, v82
	v_div_scale_f32 v88, vcc, v76, v84, v76
	v_mul_f32_e32 v90, v88, v82
	v_fma_f32 v92, -v71, v90, v88
	v_fmac_f32_e32 v90, v92, v82
	v_fma_f32 v71, -v71, v90, v88
	v_div_fmas_f32 v71, v71, v82, v90
	v_div_fixup_f32 v76, v71, v84, v76
	v_mul_f32_e32 v70, v70, v76
	v_cvt_pk_bf16_f32 v70, v70, s0
	global_store_short v26, v70, s[18:19]
	v_add_u32_e32 v109, 0x1000, v109
	global_load_ushort v9, v109, s[36:37] offset:-2
	global_load_ushort v11, v109, s[36:37]
	global_load_ushort v13, v109, s[36:37] offset:2
	global_load_ushort v15, v109, s[88:89] offset:-2
	global_load_ushort v81, v109, s[88:89]
	global_load_ushort v83, v109, s[88:89] offset:2
	global_load_ushort v85, v109, s[0:1]
	global_load_ushort v87, v109, s[4:5]
	global_load_ushort v89, v109, s[36:37] offset:1022
	global_load_ushort v91, v109, s[36:37] offset:1024
	global_load_ushort v93, v109, s[36:37] offset:1026
	global_load_ushort v94, v109, s[88:89] offset:1022
	global_load_ushort v95, v109, s[88:89] offset:1024
	global_load_ushort v96, v109, s[88:89] offset:1026
	global_load_ushort v97, v109, s[0:1] offset:1024
	global_load_ushort v98, v109, s[4:5] offset:1024
	global_load_ushort v99, v109, s[36:37] offset:2046
	global_load_ushort v100, v109, s[36:37] offset:2048
	global_load_ushort v101, v109, s[36:37] offset:2050
	global_load_ushort v102, v109, s[88:89] offset:2046
	global_load_ushort v103, v109, s[88:89] offset:2048
	global_load_ushort v104, v109, s[88:89] offset:2050
	global_load_ushort v105, v109, s[0:1] offset:2048
	global_load_ushort v106, v109, s[4:5] offset:2048
	global_load_ushort v107, v109, s[36:37] offset:3070
	global_load_ushort v108, v109, s[36:37] offset:3072
	global_load_ushort v32, v109, s[36:37] offset:3074
	global_load_ushort v78, v109, s[88:89] offset:3070
	global_load_ushort v34, v109, s[88:89] offset:3072
	global_load_ushort v79, v109, s[88:89] offset:3074
	global_load_ushort v33, v109, s[0:1] offset:3072
	global_load_ushort v76, v109, s[4:5] offset:3072
	s_waitcnt vmcnt(0)
	v_add_u32_e32 v26, 0x80000, v26
	v_lshlrev_b32_e32 v11, 16, v11
	v_lshlrev_b32_e32 v13, 16, v13
	v_lshlrev_b32_e32 v9, 16, v9
	v_mul_f32_e32 v9, v16, v9
	v_fmac_f32_e32 v9, v14, v11
	v_fmac_f32_e32 v9, v17, v13
	v_add_f32_e32 v9, v12, v9
	v_fma_f32 v27, v47, v8, v22
	v_mul_f32_e32 v70, v27, v9
	v_lshlrev_b32_e32 v85, 16, v85
	v_mul_f32_e32 v84, 0xbfb8aa3b, v85
	v_exp_f32_e32 v84, v84
	s_nop 0
	v_add_f32_e32 v84, 1.0, v84
	v_div_scale_f32 v71, s[28:29], v84, v84, v85
	v_rcp_f32_e32 v82, v71
	s_nop 0
	v_fma_f32 v92, -v71, v82, 1.0
	v_fmac_f32_e32 v82, v92, v82
	v_div_scale_f32 v88, vcc, v85, v84, v85
	v_mul_f32_e32 v90, v88, v82
	v_fma_f32 v92, -v71, v90, v88
	v_fmac_f32_e32 v90, v92, v82
	v_fma_f32 v71, -v71, v90, v88
	v_div_fmas_f32 v71, v71, v82, v90
	v_div_fixup_f32 v85, v71, v84, v85
	v_mul_f32_e32 v70, v70, v85
	v_cvt_pk_bf16_f32 v70, v70, s0
	global_store_short v26, v70, s[96:97]
	v_lshlrev_b32_e32 v81, 16, v81
	v_lshlrev_b32_e32 v83, 16, v83
	v_lshlrev_b32_e32 v15, 16, v15
	v_mul_f32_e32 v15, v16, v15
	v_fmac_f32_e32 v15, v14, v81
	v_fmac_f32_e32 v15, v17, v83
	v_add_f32_e32 v15, v12, v15
	v_fma_f32 v27, v49, v8, v23
	v_mul_f32_e32 v70, v27, v15
	v_lshlrev_b32_e32 v87, 16, v87
	v_mul_f32_e32 v84, 0xbfb8aa3b, v87
	v_exp_f32_e32 v84, v84
	s_nop 0
	v_add_f32_e32 v84, 1.0, v84
	v_div_scale_f32 v71, s[28:29], v84, v84, v87
	v_rcp_f32_e32 v82, v71
	s_nop 0
	v_fma_f32 v92, -v71, v82, 1.0
	v_fmac_f32_e32 v82, v92, v82
	v_div_scale_f32 v88, vcc, v87, v84, v87
	v_mul_f32_e32 v90, v88, v82
	v_fma_f32 v92, -v71, v90, v88
	v_fmac_f32_e32 v90, v92, v82
	v_fma_f32 v71, -v71, v90, v88
	v_div_fmas_f32 v71, v71, v82, v90
	v_div_fixup_f32 v87, v71, v84, v87
	v_mul_f32_e32 v70, v70, v87
	v_cvt_pk_bf16_f32 v70, v70, s0
	global_store_short v26, v70, s[18:19]
	v_add_u32_e32 v26, 0x80000, v26
	v_lshlrev_b32_e32 v91, 16, v91
	v_lshlrev_b32_e32 v93, 16, v93
	v_lshlrev_b32_e32 v89, 16, v89
	v_mul_f32_e32 v89, v16, v89
	v_fmac_f32_e32 v89, v14, v91
	v_fmac_f32_e32 v89, v17, v93
	v_add_f32_e32 v89, v12, v89
	v_fma_f32 v27, v46, v8, v24
	v_mul_f32_e32 v70, v27, v89
	v_lshlrev_b32_e32 v97, 16, v97
	v_mul_f32_e32 v84, 0xbfb8aa3b, v97
	v_exp_f32_e32 v84, v84
	s_nop 0
	v_add_f32_e32 v84, 1.0, v84
	v_div_scale_f32 v71, s[28:29], v84, v84, v97
	v_rcp_f32_e32 v82, v71
	s_nop 0
	v_fma_f32 v92, -v71, v82, 1.0
	v_fmac_f32_e32 v82, v92, v82
	v_div_scale_f32 v88, vcc, v97, v84, v97
	v_mul_f32_e32 v90, v88, v82
	v_fma_f32 v92, -v71, v90, v88
	v_fmac_f32_e32 v90, v92, v82
	v_fma_f32 v71, -v71, v90, v88
	v_div_fmas_f32 v71, v71, v82, v90
	v_div_fixup_f32 v97, v71, v84, v97
	v_mul_f32_e32 v70, v70, v97
	v_cvt_pk_bf16_f32 v70, v70, s0
	global_store_short v26, v70, s[96:97]
	v_lshlrev_b32_e32 v95, 16, v95
	v_lshlrev_b32_e32 v96, 16, v96
	v_lshlrev_b32_e32 v94, 16, v94
	v_mul_f32_e32 v94, v16, v94
	v_fmac_f32_e32 v94, v14, v95
	v_fmac_f32_e32 v94, v17, v96
	v_add_f32_e32 v94, v12, v94
	v_fma_f32 v27, v48, v8, v25
	v_mul_f32_e32 v70, v27, v94
	v_lshlrev_b32_e32 v98, 16, v98
	v_mul_f32_e32 v84, 0xbfb8aa3b, v98
	v_exp_f32_e32 v84, v84
	s_nop 0
	v_add_f32_e32 v84, 1.0, v84
	v_div_scale_f32 v71, s[28:29], v84, v84, v98
	v_rcp_f32_e32 v82, v71
	s_nop 0
	v_fma_f32 v92, -v71, v82, 1.0
	v_fmac_f32_e32 v82, v92, v82
	v_div_scale_f32 v88, vcc, v98, v84, v98
	v_mul_f32_e32 v90, v88, v82
	v_fma_f32 v92, -v71, v90, v88
	v_fmac_f32_e32 v90, v92, v82
	v_fma_f32 v71, -v71, v90, v88
	v_div_fmas_f32 v71, v71, v82, v90
	v_div_fixup_f32 v98, v71, v84, v98
	v_mul_f32_e32 v70, v70, v98
	v_cvt_pk_bf16_f32 v70, v70, s0
	global_store_short v26, v70, s[18:19]
	v_add_u32_e32 v26, 0x80000, v26
	v_lshlrev_b32_e32 v100, 16, v100
	v_lshlrev_b32_e32 v101, 16, v101
	v_lshlrev_b32_e32 v99, 16, v99
	v_mul_f32_e32 v99, v16, v99
	v_fmac_f32_e32 v99, v14, v100
	v_fmac_f32_e32 v99, v17, v101
	v_add_f32_e32 v99, v12, v99
	v_fma_f32 v27, v51, v8, v18
	v_mul_f32_e32 v70, v27, v99
	v_lshlrev_b32_e32 v105, 16, v105
	v_mul_f32_e32 v84, 0xbfb8aa3b, v105
	v_exp_f32_e32 v84, v84
	s_nop 0
	v_add_f32_e32 v84, 1.0, v84
	v_div_scale_f32 v71, s[28:29], v84, v84, v105
	v_rcp_f32_e32 v82, v71
	s_nop 0
	v_fma_f32 v92, -v71, v82, 1.0
	v_fmac_f32_e32 v82, v92, v82
	v_div_scale_f32 v88, vcc, v105, v84, v105
	v_mul_f32_e32 v90, v88, v82
	v_fma_f32 v92, -v71, v90, v88
	v_fmac_f32_e32 v90, v92, v82
	v_fma_f32 v71, -v71, v90, v88
	v_div_fmas_f32 v71, v71, v82, v90
	v_div_fixup_f32 v105, v71, v84, v105
	v_mul_f32_e32 v70, v70, v105
	v_cvt_pk_bf16_f32 v70, v70, s0
	global_store_short v26, v70, s[96:97]
	v_lshlrev_b32_e32 v103, 16, v103
	v_lshlrev_b32_e32 v104, 16, v104
	v_lshlrev_b32_e32 v102, 16, v102
	v_mul_f32_e32 v102, v16, v102
	v_fmac_f32_e32 v102, v14, v103
	v_fmac_f32_e32 v102, v17, v104
	v_add_f32_e32 v102, v12, v102
	v_fma_f32 v27, v53, v8, v19
	v_mul_f32_e32 v70, v27, v102
	v_lshlrev_b32_e32 v106, 16, v106
	v_mul_f32_e32 v84, 0xbfb8aa3b, v106
	v_exp_f32_e32 v84, v84
	s_nop 0
	v_add_f32_e32 v84, 1.0, v84
	v_div_scale_f32 v71, s[28:29], v84, v84, v106
	v_rcp_f32_e32 v82, v71
	s_nop 0
	v_fma_f32 v92, -v71, v82, 1.0
	v_fmac_f32_e32 v82, v92, v82
	v_div_scale_f32 v88, vcc, v106, v84, v106
	v_mul_f32_e32 v90, v88, v82
	v_fma_f32 v92, -v71, v90, v88
	v_fmac_f32_e32 v90, v92, v82
	v_fma_f32 v71, -v71, v90, v88
	v_div_fmas_f32 v71, v71, v82, v90
	v_div_fixup_f32 v106, v71, v84, v106
	v_mul_f32_e32 v70, v70, v106
	v_cvt_pk_bf16_f32 v70, v70, s0
	global_store_short v26, v70, s[18:19]
	v_add_u32_e32 v26, 0x80000, v26
	v_lshlrev_b32_e32 v108, 16, v108
	v_lshlrev_b32_e32 v32, 16, v32
	v_lshlrev_b32_e32 v107, 16, v107
	v_mul_f32_e32 v107, v16, v107
	v_fmac_f32_e32 v107, v14, v108
	v_fmac_f32_e32 v107, v17, v32
	v_add_f32_e32 v107, v12, v107
	v_fma_f32 v27, v50, v8, v20
	v_mul_f32_e32 v70, v27, v107
	v_lshlrev_b32_e32 v33, 16, v33
	v_mul_f32_e32 v84, 0xbfb8aa3b, v33
	v_exp_f32_e32 v84, v84
	s_nop 0
	v_add_f32_e32 v84, 1.0, v84
	v_div_scale_f32 v71, s[28:29], v84, v84, v33
	v_rcp_f32_e32 v82, v71
	s_nop 0
	v_fma_f32 v92, -v71, v82, 1.0
	v_fmac_f32_e32 v82, v92, v82
	v_div_scale_f32 v88, vcc, v33, v84, v33
	v_mul_f32_e32 v90, v88, v82
	v_fma_f32 v92, -v71, v90, v88
	v_fmac_f32_e32 v90, v92, v82
	v_fma_f32 v71, -v71, v90, v88
	v_div_fmas_f32 v71, v71, v82, v90
	v_div_fixup_f32 v33, v71, v84, v33
	v_mul_f32_e32 v70, v70, v33
	v_cvt_pk_bf16_f32 v70, v70, s0
	global_store_short v26, v70, s[96:97]
	v_lshlrev_b32_e32 v34, 16, v34
	v_lshlrev_b32_e32 v79, 16, v79
	v_lshlrev_b32_e32 v78, 16, v78
	v_mul_f32_e32 v78, v16, v78
	v_fmac_f32_e32 v78, v14, v34
	v_fmac_f32_e32 v78, v17, v79
	v_add_f32_e32 v78, v12, v78
	v_fma_f32 v27, v52, v8, v21
	v_mul_f32_e32 v70, v27, v78
	v_lshlrev_b32_e32 v76, 16, v76
	v_mul_f32_e32 v84, 0xbfb8aa3b, v76
	v_exp_f32_e32 v84, v84
	s_nop 0
	v_add_f32_e32 v84, 1.0, v84
	v_div_scale_f32 v71, s[28:29], v84, v84, v76
	v_rcp_f32_e32 v82, v71
	s_nop 0
	v_fma_f32 v92, -v71, v82, 1.0
	v_fmac_f32_e32 v82, v92, v82
	v_div_scale_f32 v88, vcc, v76, v84, v76
	v_mul_f32_e32 v90, v88, v82
	v_fma_f32 v92, -v71, v90, v88
	v_fmac_f32_e32 v90, v92, v82
	v_fma_f32 v71, -v71, v90, v88
	v_div_fmas_f32 v71, v71, v82, v90
	v_div_fixup_f32 v76, v71, v84, v76
	v_mul_f32_e32 v70, v70, v76
	v_cvt_pk_bf16_f32 v70, v70, s0
	global_store_short v26, v70, s[18:19]
	v_add_u32_e32 v52, 0x1e00, v10
	v_cmp_gt_i32_e32 vcc, 0x1fff, v52
	v_min_i32_e32 v52, 0x1ffe, v52
	v_lshlrev_b32_e32 v52, 1, v52
	s_nop 0
	v_cndmask_b32_e64 v21, 0, 1.0, vcc
	v_add_u32_e32 v109, 0x1000, v109
	global_load_ushort v9, v109, s[36:37] offset:-2
	global_load_ushort v11, v109, s[36:37]
	global_load_ushort v13, v109, s[36:37] offset:2
	global_load_ushort v15, v109, s[88:89] offset:-2
	global_load_ushort v81, v109, s[88:89]
	global_load_ushort v83, v109, s[88:89] offset:2
	global_load_ushort v85, v109, s[0:1]
	global_load_ushort v87, v109, s[4:5]
	global_load_ushort v89, v109, s[36:37] offset:1022
	global_load_ushort v91, v109, s[36:37] offset:1024
	global_load_ushort v93, v109, s[36:37] offset:1026
	global_load_ushort v94, v109, s[88:89] offset:1022
	global_load_ushort v95, v109, s[88:89] offset:1024
	global_load_ushort v96, v109, s[88:89] offset:1026
	global_load_ushort v97, v109, s[0:1] offset:1024
	global_load_ushort v98, v109, s[4:5] offset:1024
	global_load_ushort v99, v109, s[36:37] offset:2046
	global_load_ushort v100, v109, s[36:37] offset:2048
	global_load_ushort v101, v109, s[36:37] offset:2050
	global_load_ushort v102, v109, s[88:89] offset:2046
	global_load_ushort v103, v109, s[88:89] offset:2048
	global_load_ushort v104, v109, s[88:89] offset:2050
	global_load_ushort v105, v109, s[0:1] offset:2048
	global_load_ushort v106, v109, s[4:5] offset:2048
	global_load_ushort v107, v109, s[36:37] offset:3070
	global_load_ushort v108, v109, s[36:37] offset:3072
	global_load_ushort v32, v52, s[36:37] offset:2
	global_load_ushort v78, v109, s[88:89] offset:3070
	global_load_ushort v34, v109, s[88:89] offset:3072
	global_load_ushort v79, v52, s[88:89] offset:2
	global_load_ushort v33, v109, s[0:1] offset:3072
	global_load_ushort v76, v109, s[4:5] offset:3072
	s_waitcnt vmcnt(0)
	v_add_u32_e32 v26, 0x80000, v26
	v_lshlrev_b32_e32 v11, 16, v11
	v_lshlrev_b32_e32 v13, 16, v13
	v_lshlrev_b32_e32 v9, 16, v9
	v_mul_f32_e32 v9, v16, v9
	v_fmac_f32_e32 v9, v14, v11
	v_fmac_f32_e32 v9, v17, v13
	v_add_f32_e32 v9, v12, v9
	v_fma_f32 v27, v55, v8, v4
	v_mul_f32_e32 v70, v27, v9
	v_lshlrev_b32_e32 v85, 16, v85
	v_mul_f32_e32 v84, 0xbfb8aa3b, v85
	v_exp_f32_e32 v84, v84
	s_nop 0
	v_add_f32_e32 v84, 1.0, v84
	v_div_scale_f32 v71, s[28:29], v84, v84, v85
	v_rcp_f32_e32 v82, v71
	s_nop 0
	v_fma_f32 v92, -v71, v82, 1.0
	v_fmac_f32_e32 v82, v92, v82
	v_div_scale_f32 v88, vcc, v85, v84, v85
	v_mul_f32_e32 v90, v88, v82
	v_fma_f32 v92, -v71, v90, v88
	v_fmac_f32_e32 v90, v92, v82
	v_fma_f32 v71, -v71, v90, v88
	v_div_fmas_f32 v71, v71, v82, v90
	v_div_fixup_f32 v85, v71, v84, v85
	v_mul_f32_e32 v70, v70, v85
	v_cvt_pk_bf16_f32 v70, v70, s0
	global_store_short v26, v70, s[96:97]
	v_lshlrev_b32_e32 v81, 16, v81
	v_lshlrev_b32_e32 v83, 16, v83
	v_lshlrev_b32_e32 v15, 16, v15
	v_mul_f32_e32 v15, v16, v15
	v_fmac_f32_e32 v15, v14, v81
	v_fmac_f32_e32 v15, v17, v83
	v_add_f32_e32 v15, v12, v15
	v_fma_f32 v27, v57, v8, v5
	v_mul_f32_e32 v70, v27, v15
	v_lshlrev_b32_e32 v87, 16, v87
	v_mul_f32_e32 v84, 0xbfb8aa3b, v87
	v_exp_f32_e32 v84, v84
	s_nop 0
	v_add_f32_e32 v84, 1.0, v84
	v_div_scale_f32 v71, s[28:29], v84, v84, v87
	v_rcp_f32_e32 v82, v71
	s_nop 0
	v_fma_f32 v92, -v71, v82, 1.0
	v_fmac_f32_e32 v82, v92, v82
	v_div_scale_f32 v88, vcc, v87, v84, v87
	v_mul_f32_e32 v90, v88, v82
	v_fma_f32 v92, -v71, v90, v88
	v_fmac_f32_e32 v90, v92, v82
	v_fma_f32 v71, -v71, v90, v88
	v_div_fmas_f32 v71, v71, v82, v90
	v_div_fixup_f32 v87, v71, v84, v87
	v_mul_f32_e32 v70, v70, v87
	v_cvt_pk_bf16_f32 v70, v70, s0
	global_store_short v26, v70, s[18:19]
	v_add_u32_e32 v26, 0x80000, v26
	v_lshlrev_b32_e32 v91, 16, v91
	v_lshlrev_b32_e32 v93, 16, v93
	v_lshlrev_b32_e32 v89, 16, v89
	v_mul_f32_e32 v89, v16, v89
	v_fmac_f32_e32 v89, v14, v91
	v_fmac_f32_e32 v89, v17, v93
	v_add_f32_e32 v89, v12, v89
	v_fma_f32 v27, v54, v8, v6
	v_mul_f32_e32 v70, v27, v89
	v_lshlrev_b32_e32 v97, 16, v97
	v_mul_f32_e32 v84, 0xbfb8aa3b, v97
	v_exp_f32_e32 v84, v84
	s_nop 0
	v_add_f32_e32 v84, 1.0, v84
	v_div_scale_f32 v71, s[28:29], v84, v84, v97
	v_rcp_f32_e32 v82, v71
	s_nop 0
	v_fma_f32 v92, -v71, v82, 1.0
	v_fmac_f32_e32 v82, v92, v82
	v_div_scale_f32 v88, vcc, v97, v84, v97
	v_mul_f32_e32 v90, v88, v82
	v_fma_f32 v92, -v71, v90, v88
	v_fmac_f32_e32 v90, v92, v82
	v_fma_f32 v71, -v71, v90, v88
	v_div_fmas_f32 v71, v71, v82, v90
	v_div_fixup_f32 v97, v71, v84, v97
	v_mul_f32_e32 v70, v70, v97
	v_cvt_pk_bf16_f32 v70, v70, s0
	global_store_short v26, v70, s[96:97]
	v_lshlrev_b32_e32 v95, 16, v95
	v_lshlrev_b32_e32 v96, 16, v96
	v_lshlrev_b32_e32 v94, 16, v94
	v_mul_f32_e32 v94, v16, v94
	v_fmac_f32_e32 v94, v14, v95
	v_fmac_f32_e32 v94, v17, v96
	v_add_f32_e32 v94, v12, v94
	v_fma_f32 v27, v56, v8, v7
	v_mul_f32_e32 v70, v27, v94
	v_lshlrev_b32_e32 v98, 16, v98
	v_mul_f32_e32 v84, 0xbfb8aa3b, v98
	v_exp_f32_e32 v84, v84
	s_nop 0
	v_add_f32_e32 v84, 1.0, v84
	v_div_scale_f32 v71, s[28:29], v84, v84, v98
	v_rcp_f32_e32 v82, v71
	s_nop 0
	v_fma_f32 v92, -v71, v82, 1.0
	v_fmac_f32_e32 v82, v92, v82
	v_div_scale_f32 v88, vcc, v98, v84, v98
	v_mul_f32_e32 v90, v88, v82
	v_fma_f32 v92, -v71, v90, v88
	v_fmac_f32_e32 v90, v92, v82
	v_fma_f32 v71, -v71, v90, v88
	v_div_fmas_f32 v71, v71, v82, v90
	v_div_fixup_f32 v98, v71, v84, v98
	v_mul_f32_e32 v70, v70, v98
	v_cvt_pk_bf16_f32 v70, v70, s0
	global_store_short v26, v70, s[18:19]
	v_add_u32_e32 v26, 0x80000, v26
	v_lshlrev_b32_e32 v100, 16, v100
	v_lshlrev_b32_e32 v101, 16, v101
	v_lshlrev_b32_e32 v99, 16, v99
	v_mul_f32_e32 v99, v16, v99
	v_fmac_f32_e32 v99, v14, v100
	v_fmac_f32_e32 v99, v17, v101
	v_add_f32_e32 v99, v12, v99
	v_fma_f32 v27, v59, v8, v0
	v_mul_f32_e32 v70, v27, v99
	v_lshlrev_b32_e32 v105, 16, v105
	v_mul_f32_e32 v84, 0xbfb8aa3b, v105
	v_exp_f32_e32 v84, v84
	s_nop 0
	v_add_f32_e32 v84, 1.0, v84
	v_div_scale_f32 v71, s[28:29], v84, v84, v105
	v_rcp_f32_e32 v82, v71
	s_nop 0
	v_fma_f32 v92, -v71, v82, 1.0
	v_fmac_f32_e32 v82, v92, v82
	v_div_scale_f32 v88, vcc, v105, v84, v105
	v_mul_f32_e32 v90, v88, v82
	v_fma_f32 v92, -v71, v90, v88
	v_fmac_f32_e32 v90, v92, v82
	v_fma_f32 v71, -v71, v90, v88
	v_div_fmas_f32 v71, v71, v82, v90
	v_div_fixup_f32 v105, v71, v84, v105
	v_mul_f32_e32 v70, v70, v105
	v_cvt_pk_bf16_f32 v70, v70, s0
	global_store_short v26, v70, s[96:97]
	v_lshlrev_b32_e32 v103, 16, v103
	v_lshlrev_b32_e32 v104, 16, v104
	v_lshlrev_b32_e32 v102, 16, v102
	v_mul_f32_e32 v102, v16, v102
	v_fmac_f32_e32 v102, v14, v103
	v_fmac_f32_e32 v102, v17, v104
	v_add_f32_e32 v102, v12, v102
	v_fma_f32 v27, v61, v8, v1
	v_mul_f32_e32 v70, v27, v102
	v_lshlrev_b32_e32 v106, 16, v106
	v_mul_f32_e32 v84, 0xbfb8aa3b, v106
	v_exp_f32_e32 v84, v84
	s_nop 0
	v_add_f32_e32 v84, 1.0, v84
	v_div_scale_f32 v71, s[28:29], v84, v84, v106
	v_rcp_f32_e32 v82, v71
	s_nop 0
	v_fma_f32 v92, -v71, v82, 1.0
	v_fmac_f32_e32 v82, v92, v82
	v_div_scale_f32 v88, vcc, v106, v84, v106
	v_mul_f32_e32 v90, v88, v82
	v_fma_f32 v92, -v71, v90, v88
	v_fmac_f32_e32 v90, v92, v82
	v_fma_f32 v71, -v71, v90, v88
	v_div_fmas_f32 v71, v71, v82, v90
	v_div_fixup_f32 v106, v71, v84, v106
	v_mul_f32_e32 v70, v70, v106
	v_cvt_pk_bf16_f32 v70, v70, s0
	global_store_short v26, v70, s[18:19]
	v_add_u32_e32 v26, 0x80000, v26
	v_lshlrev_b32_e32 v108, 16, v108
	v_lshlrev_b32_e32 v32, 16, v32
	v_lshlrev_b32_e32 v107, 16, v107
	v_mul_f32_e32 v107, v16, v107
	v_mul_f32_e32 v32, v21, v32
	v_fmac_f32_e32 v107, v14, v108
	v_fmac_f32_e32 v107, v17, v32
	v_add_f32_e32 v107, v12, v107
	v_fma_f32 v27, v58, v8, v2
	v_mul_f32_e32 v70, v27, v107
	v_lshlrev_b32_e32 v33, 16, v33
	v_mul_f32_e32 v84, 0xbfb8aa3b, v33
	v_exp_f32_e32 v84, v84
	s_nop 0
	v_add_f32_e32 v84, 1.0, v84
	v_div_scale_f32 v71, s[28:29], v84, v84, v33
	v_rcp_f32_e32 v82, v71
	s_nop 0
	v_fma_f32 v92, -v71, v82, 1.0
	v_fmac_f32_e32 v82, v92, v82
	v_div_scale_f32 v88, vcc, v33, v84, v33
	v_mul_f32_e32 v90, v88, v82
	v_fma_f32 v92, -v71, v90, v88
	v_fmac_f32_e32 v90, v92, v82
	v_fma_f32 v71, -v71, v90, v88
	v_div_fmas_f32 v71, v71, v82, v90
	v_div_fixup_f32 v33, v71, v84, v33
	v_mul_f32_e32 v70, v70, v33
	v_cvt_pk_bf16_f32 v70, v70, s0
	global_store_short v26, v70, s[96:97]
	v_lshlrev_b32_e32 v34, 16, v34
	v_lshlrev_b32_e32 v79, 16, v79
	v_lshlrev_b32_e32 v78, 16, v78
	v_mul_f32_e32 v78, v16, v78
	v_mul_f32_e32 v79, v21, v79
	v_fmac_f32_e32 v78, v14, v34
	v_fmac_f32_e32 v78, v17, v79
	v_add_f32_e32 v78, v12, v78
	v_fma_f32 v27, v60, v8, v3
	v_mul_f32_e32 v70, v27, v78
	v_lshlrev_b32_e32 v76, 16, v76
	v_mul_f32_e32 v84, 0xbfb8aa3b, v76
	v_exp_f32_e32 v84, v84
	s_nop 0
	v_add_f32_e32 v84, 1.0, v84
	v_div_scale_f32 v71, s[28:29], v84, v84, v76
	v_rcp_f32_e32 v82, v71
	s_nop 0
	v_fma_f32 v92, -v71, v82, 1.0
	v_fmac_f32_e32 v82, v92, v82
	v_div_scale_f32 v88, vcc, v76, v84, v76
	v_mul_f32_e32 v90, v88, v82
	v_fma_f32 v92, -v71, v90, v88
	v_fmac_f32_e32 v90, v92, v82
	v_fma_f32 v71, -v71, v90, v88
	v_div_fmas_f32 v71, v71, v82, v90
	v_div_fixup_f32 v76, v71, v84, v76
	v_mul_f32_e32 v70, v70, v76
	v_cvt_pk_bf16_f32 v70, v70, s0
	global_store_short v26, v70, s[18:19]
	s_mov_b64 s[28:29], 0

.LBB0_910:
	v_mov_b32_e32 v20, v46
	v_mov_b32_e32 v21, v48
	v_mov_b32_e32 v22, v51
	v_mov_b32_e32 v23, v53
	v_pk_add_f32 v[88:89], v[20:21], 0 op_sel_hi:[1,0]
	v_pk_mul_f32 v[20:21], v[20:21], s[48:49] op_sel_hi:[1,0]
	v_xor_b32_e32 v91, 0x80000000, v46
	v_mov_b32_e32 v90, v48
	v_pk_add_f32 v[92:93], v[50:51], 0 neg_lo:[1,1] neg_hi:[1,1]
	v_mov_b32_e32 v24, v50
	v_mov_b32_e32 v25, v52
	v_pk_fma_f32 v[20:21], v[90:91], s[44:45], v[20:21] op_sel_hi:[1,0,1] neg_lo:[0,0,1] neg_hi:[0,0,1]
	v_pk_add_f32 v[90:91], v[22:23], 0 op_sel_hi:[1,0]
	v_pk_mul_f32 v[22:23], v[22:23], s[54:55] op_sel_hi:[1,0]
	v_mov_b32_e32 v92, v53
	v_mov_b32_e32 v26, v55
	v_mov_b32_e32 v27, v57
	v_pk_fma_f32 v[22:23], v[92:93], s[52:53], v[22:23] op_sel_hi:[1,0,1] neg_lo:[0,0,1] neg_hi:[0,0,1]
	v_pk_add_f32 v[92:93], v[24:25], 0 op_sel_hi:[1,0]
	v_pk_mul_f32 v[24:25], v[24:25], s[58:59] op_sel_hi:[1,0]
	v_xor_b32_e32 v95, 0x80000000, v50
	v_mov_b32_e32 v94, v52
	v_pk_add_f32 v[96:97], v[54:55], 0 neg_lo:[1,1] neg_hi:[1,1]
	v_mov_b32_e32 v64, v54
	v_mov_b32_e32 v65, v56
	v_pk_fma_f32 v[24:25], v[94:95], s[56:57], v[24:25] op_sel_hi:[1,0,1] neg_lo:[0,0,1] neg_hi:[0,0,1]
	v_pk_add_f32 v[94:95], v[26:27], 0 op_sel_hi:[1,0]
	v_pk_mul_f32 v[26:27], v[26:27], s[60:61] op_sel_hi:[1,0]
	v_mov_b32_e32 v96, v57
	v_mov_b32_e32 v66, v59
	v_mov_b32_e32 v67, v61
	v_pk_fma_f32 v[26:27], v[96:97], s[60:61], v[26:27] op_sel_hi:[1,0,1] neg_lo:[0,0,1] neg_hi:[0,0,1]
	v_pk_add_f32 v[96:97], v[64:65], 0 op_sel_hi:[1,0]
	v_pk_mul_f32 v[64:65], v[64:65], s[56:57] op_sel_hi:[1,0]
	v_xor_b32_e32 v99, 0x80000000, v54
	v_mov_b32_e32 v98, v56
	v_pk_add_f32 v[100:101], v[58:59], 0 neg_lo:[1,1] neg_hi:[1,1]
	v_mov_b32_e32 v2, v32
	v_mov_b32_e32 v3, v34
	v_mov_b32_e32 v4, v33
	v_mov_b32_e32 v5, v35
	v_mov_b32_e32 v18, v47
	v_mov_b32_e32 v19, v49
	v_mov_b32_e32 v68, v58
	v_mov_b32_e32 v69, v60
	v_pk_fma_f32 v[64:65], v[98:99], s[58:59], v[64:65] op_sel_hi:[1,0,1] neg_lo:[0,0,1] neg_hi:[0,0,1]
	v_pk_add_f32 v[98:99], v[66:67], 0 op_sel_hi:[1,0]
	v_pk_mul_f32 v[66:67], v[66:67], s[52:53] op_sel_hi:[1,0]
	v_mov_b32_e32 v100, v61
	v_pk_add_f32 v[70:71], v[2:3], 0 op_sel_hi:[1,0]
	v_pk_add_f32 v[72:73], v[4:5], 0 op_sel_hi:[1,0]
	v_pk_add_f32 v[74:75], v[32:33], 0 neg_lo:[1,1] neg_hi:[1,1]
	v_pk_add_f32 v[18:19], v[18:19], 0 op_sel_hi:[1,0]
	v_pk_fma_f32 v[66:67], v[100:101], s[54:55], v[66:67] op_sel_hi:[1,0,1] neg_lo:[0,0,1] neg_hi:[0,0,1]
	v_pk_add_f32 v[100:101], v[68:69], 0 op_sel_hi:[1,0]
	v_pk_mul_f32 v[68:69], v[68:69], s[44:45] op_sel_hi:[1,0]
	v_xor_b32_e32 v103, 0x80000000, v58
	v_mov_b32_e32 v102, v60
	v_mov_b32_e32 v74, v35
	v_pk_fma_f32 v[68:69], v[102:103], s[48:49], v[68:69] op_sel_hi:[1,0,1] neg_lo:[0,0,1] neg_hi:[0,0,1]
	v_pk_add_f32 v[102:103], v[18:19], v[70:71]
	v_pk_add_f32 v[18:19], v[70:71], v[18:19] neg_lo:[0,1] neg_hi:[0,1]
	v_pk_add_f32 v[70:71], v[88:89], v[72:73]
	v_pk_add_f32 v[72:73], v[72:73], v[88:89] neg_lo:[0,1] neg_hi:[0,1]
	v_mov_b32_e32 v6, v37
	v_mov_b32_e32 v7, v31
	v_pk_mul_f32 v[74:75], v[74:75], s[48:49] op_sel_hi:[1,0]
	v_xor_b32_e32 v89, 0x80000000, v72
	v_mov_b32_e32 v88, v73
	v_pk_fma_f32 v[4:5], v[4:5], s[44:45], v[74:75] op_sel_hi:[1,0,1]
	v_pk_add_f32 v[74:75], v[6:7], 0 op_sel_hi:[1,0]
	v_pk_add_f32 v[76:77], v[36:37], 0 neg_lo:[1,1] neg_hi:[1,1]
	v_pk_mul_f32 v[88:89], v[88:89], s[54:55] op_sel_hi:[1,0]
	v_mov_b32_e32 v76, v31
	v_pk_fma_f32 v[72:73], v[72:73], s[52:53], v[88:89] op_sel_hi:[1,0,1]
	v_pk_add_f32 v[88:89], v[90:91], v[74:75]
	v_pk_add_f32 v[74:75], v[74:75], v[90:91] neg_lo:[0,1] neg_hi:[0,1]
	v_mov_b32_e32 v8, v36
	v_mov_b32_e32 v9, v30
	v_pk_mul_f32 v[76:77], v[76:77], s[54:55] op_sel_hi:[1,0]
	v_xor_b32_e32 v91, 0x80000000, v74
	v_mov_b32_e32 v90, v75
	v_pk_fma_f32 v[6:7], v[6:7], s[52:53], v[76:77] op_sel_hi:[1,0,1]
	v_pk_add_f32 v[76:77], v[8:9], 0 op_sel_hi:[1,0]
	v_pk_mul_f32 v[90:91], v[90:91], s[60:61] op_sel_hi:[1,0]
	v_xor_b32_e32 v79, 0x80000000, v36
	v_mov_b32_e32 v78, v30
	v_pk_add_f32 v[80:81], v[38:39], 0 neg_lo:[1,1] neg_hi:[1,1]
	v_pk_fma_f32 v[74:75], v[74:75], s[60:61], v[90:91] op_sel_hi:[1,0,1]
	v_pk_add_f32 v[90:91], v[92:93], v[76:77]
	v_pk_add_f32 v[76:77], v[76:77], v[92:93] neg_lo:[0,1] neg_hi:[0,1]
	v_mov_b32_e32 v10, v39
	v_mov_b32_e32 v11, v41
	v_pk_mul_f32 v[78:79], v[78:79], s[58:59] op_sel_hi:[1,0]
	v_mov_b32_e32 v80, v41
	v_xor_b32_e32 v93, 0x80000000, v76
	v_mov_b32_e32 v92, v77
	v_mov_b32_e32 v12, v38
	v_mov_b32_e32 v13, v40
	v_pk_fma_f32 v[8:9], v[8:9], s[56:57], v[78:79] op_sel_hi:[1,0,1]
	v_pk_add_f32 v[78:79], v[10:11], 0 op_sel_hi:[1,0]
	v_pk_mul_f32 v[80:81], v[80:81], s[60:61] op_sel_hi:[1,0]
	v_pk_mul_f32 v[92:93], v[92:93], s[52:53] op_sel_hi:[1,0]
	v_pk_fma_f32 v[10:11], v[10:11], s[60:61], v[80:81] op_sel_hi:[1,0,1]
	v_pk_add_f32 v[80:81], v[12:13], 0 op_sel_hi:[1,0]
	v_xor_b32_e32 v83, 0x80000000, v38
	v_mov_b32_e32 v82, v40
	v_pk_fma_f32 v[76:77], v[76:77], s[54:55], v[92:93] op_sel_hi:[1,0,1]
	v_pk_add_f32 v[92:93], v[94:95], v[78:79]
	v_pk_add_f32 v[78:79], v[78:79], v[94:95] neg_lo:[0,1] neg_hi:[0,1]
	v_mov_b32_e32 v14, v43
	v_mov_b32_e32 v15, v45
	v_pk_mul_f32 v[82:83], v[82:83], s[56:57] op_sel_hi:[1,0]
	v_pk_add_f32 v[84:85], v[42:43], 0 neg_lo:[1,1] neg_hi:[1,1]
	v_xor_b32_e32 v95, 0x80000000, v78
	v_mov_b32_e32 v94, v79
	v_pk_add_f32 v[78:79], v[96:97], v[80:81]
	v_pk_add_f32 v[80:81], v[80:81], v[96:97] neg_lo:[0,1] neg_hi:[0,1]
	v_pk_fma_f32 v[12:13], v[12:13], s[58:59], v[82:83] op_sel_hi:[1,0,1]
	v_pk_add_f32 v[82:83], v[14:15], 0 op_sel_hi:[1,0]
	v_mov_b32_e32 v84, v45
	v_pk_mul_f32 v[96:97], v[80:81], s[54:55] op_sel_hi:[1,0]
	v_xor_b32_e32 v105, 0x80000000, v80
	v_mov_b32_e32 v104, v81
	v_mov_b32_e32 v16, v42
	v_mov_b32_e32 v17, v44
	v_pk_mul_f32 v[84:85], v[84:85], s[52:53] op_sel_hi:[1,0]
	v_xor_b32_e32 v87, 0x80000000, v42
	v_mov_b32_e32 v86, v44
	v_pk_fma_f32 v[80:81], v[104:105], s[52:53], v[96:97] op_sel_hi:[1,0,1] neg_lo:[0,0,1] neg_hi:[0,0,1]
	v_pk_add_f32 v[96:97], v[98:99], v[82:83]
	v_pk_add_f32 v[82:83], v[82:83], v[98:99] neg_lo:[0,1] neg_hi:[0,1]
	v_pk_fma_f32 v[14:15], v[14:15], s[54:55], v[84:85] op_sel_hi:[1,0,1]
	v_pk_add_f32 v[84:85], v[16:17], 0 op_sel_hi:[1,0]
	v_pk_mul_f32 v[86:87], v[86:87], s[44:45] op_sel_hi:[1,0]
	v_pk_mul_f32 v[98:99], v[82:83], s[60:61] op_sel_hi:[1,0]
	v_xor_b32_e32 v105, 0x80000000, v82
	v_mov_b32_e32 v104, v83
	v_pk_fma_f32 v[16:17], v[16:17], s[48:49], v[86:87] op_sel_hi:[1,0,1]
	v_pk_add_f32 v[86:87], v[46:47], 0 neg_lo:[1,1] neg_hi:[1,1]
	v_pk_fma_f32 v[82:83], v[104:105], s[60:61], v[98:99] op_sel_hi:[1,0,1] neg_lo:[0,0,1] neg_hi:[0,0,1]
	v_pk_add_f32 v[98:99], v[100:101], v[84:85]
	v_pk_add_f32 v[84:85], v[84:85], v[100:101] neg_lo:[0,1] neg_hi:[0,1]
	v_mov_b32_e32 v86, v49
	v_pk_mul_f32 v[100:101], v[84:85], s[52:53] op_sel_hi:[1,0]
	v_xor_b32_e32 v105, 0x80000000, v84
	v_mov_b32_e32 v104, v85
	v_pk_fma_f32 v[84:85], v[104:105], s[54:55], v[100:101] op_sel_hi:[1,0,1] neg_lo:[0,0,1] neg_hi:[0,0,1]
	v_pk_add_f32 v[100:101], v[86:87], v[2:3]
	v_pk_add_f32 v[2:3], v[2:3], v[86:87] neg_lo:[0,1] neg_hi:[0,1]
	v_pk_add_f32 v[86:87], v[20:21], v[4:5]
	v_pk_add_f32 v[4:5], v[4:5], v[20:21] neg_lo:[0,1] neg_hi:[0,1]
	v_mov_b32_e32 v63, v146
	v_xor_b32_e32 v21, 0x80000000, v4
	v_mov_b32_e32 v20, v5
	v_pk_mul_f32 v[20:21], v[20:21], s[54:55] op_sel_hi:[1,0]
	s_nop 0
	v_pk_fma_f32 v[4:5], v[4:5], s[52:53], v[20:21] op_sel_hi:[1,0,1]
	v_pk_add_f32 v[20:21], v[22:23], v[6:7]
	v_pk_add_f32 v[6:7], v[6:7], v[22:23] neg_lo:[0,1] neg_hi:[0,1]
	s_barrier
	v_xor_b32_e32 v23, 0x80000000, v6
	v_mov_b32_e32 v22, v7
	v_pk_mul_f32 v[22:23], v[22:23], s[60:61] op_sel_hi:[1,0]
	s_nop 0
	v_pk_fma_f32 v[6:7], v[6:7], s[60:61], v[22:23] op_sel_hi:[1,0,1]
	v_pk_add_f32 v[22:23], v[24:25], v[8:9]
	v_pk_add_f32 v[8:9], v[8:9], v[24:25] neg_lo:[0,1] neg_hi:[0,1]
	s_add_i32 s19, 16, 0x11000
	v_xor_b32_e32 v25, 0x80000000, v8
	v_mov_b32_e32 v24, v9
	v_pk_mul_f32 v[24:25], v[24:25], s[52:53] op_sel_hi:[1,0]
	s_add_i32 s18, 16, 0x12000
	v_pk_fma_f32 v[8:9], v[8:9], s[54:55], v[24:25] op_sel_hi:[1,0,1]
	v_pk_add_f32 v[24:25], v[26:27], v[10:11]
	v_pk_add_f32 v[10:11], v[10:11], v[26:27] neg_lo:[0,1] neg_hi:[0,1]
	s_add_i32 s17, 16, 0x13000
	v_xor_b32_e32 v27, 0x80000000, v10
	v_mov_b32_e32 v26, v11
	v_pk_add_f32 v[10:11], v[64:65], v[12:13]
	v_pk_add_f32 v[12:13], v[12:13], v[64:65] neg_lo:[0,1] neg_hi:[0,1]
	s_add_i32 s13, 16, 0x14000
	v_pk_mul_f32 v[64:65], v[12:13], s[54:55] op_sel_hi:[1,0]
	v_xor_b32_e32 v105, 0x80000000, v12
	v_mov_b32_e32 v104, v13
	v_pk_fma_f32 v[12:13], v[104:105], s[52:53], v[64:65] op_sel_hi:[1,0,1] neg_lo:[0,0,1] neg_hi:[0,0,1]
	v_pk_add_f32 v[64:65], v[66:67], v[14:15]
	v_pk_add_f32 v[14:15], v[14:15], v[66:67] neg_lo:[0,1] neg_hi:[0,1]
	s_add_i32 s12, 16, 0x15000
	v_pk_mul_f32 v[66:67], v[14:15], s[60:61] op_sel_hi:[1,0]
	v_xor_b32_e32 v105, 0x80000000, v14
	v_mov_b32_e32 v104, v15
	v_pk_fma_f32 v[14:15], v[104:105], s[60:61], v[66:67] op_sel_hi:[1,0,1] neg_lo:[0,0,1] neg_hi:[0,0,1]
	v_pk_add_f32 v[66:67], v[68:69], v[16:17]
	v_pk_add_f32 v[16:17], v[16:17], v[68:69] neg_lo:[0,1] neg_hi:[0,1]
	s_add_i32 s11, 16, 0x16000
	v_pk_mul_f32 v[68:69], v[16:17], s[52:53] op_sel_hi:[1,0]
	v_xor_b32_e32 v105, 0x80000000, v16
	v_mov_b32_e32 v104, v17
	v_pk_fma_f32 v[16:17], v[104:105], s[54:55], v[68:69] op_sel_hi:[1,0,1] neg_lo:[0,0,1] neg_hi:[0,0,1]
	v_pk_add_f32 v[68:69], v[92:93], v[102:103]
	v_pk_add_f32 v[92:93], v[102:103], v[92:93] neg_lo:[0,1] neg_hi:[0,1]
	v_pk_add_f32 v[102:103], v[78:79], v[70:71]
	v_pk_add_f32 v[70:71], v[70:71], v[78:79] neg_lo:[0,1] neg_hi:[0,1]
	s_add_i32 s10, 16, 0x17000
	v_xor_b32_e32 v79, 0x80000000, v70
	v_mov_b32_e32 v78, v71
	v_pk_mul_f32 v[78:79], v[78:79], s[60:61] op_sel_hi:[1,0]
	s_add_i32 s9, 16, 0x18000
	v_pk_fma_f32 v[70:71], v[70:71], s[60:61], v[78:79] op_sel_hi:[1,0,1]
	v_pk_add_f32 v[78:79], v[96:97], v[88:89]
	v_pk_add_f32 v[88:89], v[88:89], v[96:97] neg_lo:[0,1] neg_hi:[0,1]
	s_add_i32 s8, 16, 0x19000
	v_xor_b32_e32 v97, 0x80000000, v88
	v_mov_b32_e32 v96, v89
	v_pk_add_f32 v[88:89], v[98:99], v[90:91]
	v_pk_add_f32 v[90:91], v[90:91], v[98:99] neg_lo:[0,1] neg_hi:[0,1]
	s_add_i32 s7, 16, 0x1a000
	v_pk_mul_f32 v[98:99], v[90:91], s[60:61] op_sel_hi:[1,0]
	v_xor_b32_e32 v105, 0x80000000, v90
	v_mov_b32_e32 v104, v91
	v_pk_fma_f32 v[90:91], v[104:105], s[60:61], v[98:99] op_sel_hi:[1,0,1] neg_lo:[0,0,1] neg_hi:[0,0,1]
	v_pk_add_f32 v[98:99], v[94:95], v[18:19]
	v_pk_add_f32 v[18:19], v[18:19], v[94:95] neg_lo:[0,1] neg_hi:[0,1]
	v_pk_add_f32 v[94:95], v[80:81], v[72:73]
	v_pk_add_f32 v[72:73], v[72:73], v[80:81] neg_lo:[0,1] neg_hi:[0,1]
	s_add_i32 s6, 16, 0x1b000
	v_xor_b32_e32 v81, 0x80000000, v72
	v_mov_b32_e32 v80, v73
	v_pk_mul_f32 v[80:81], v[80:81], s[60:61] op_sel_hi:[1,0]
	s_add_i32 s5, 16, 0x1c000
	v_pk_fma_f32 v[72:73], v[72:73], s[60:61], v[80:81] op_sel_hi:[1,0,1]
	v_pk_add_f32 v[80:81], v[82:83], v[74:75]
	v_pk_add_f32 v[74:75], v[74:75], v[82:83] neg_lo:[0,1] neg_hi:[0,1]
	s_add_i32 s4, 16, 0x1d000
	v_xor_b32_e32 v83, 0x80000000, v74
	v_mov_b32_e32 v82, v75
	v_pk_add_f32 v[74:75], v[84:85], v[76:77]
	v_pk_add_f32 v[76:77], v[76:77], v[84:85] neg_lo:[0,1] neg_hi:[0,1]
	v_pk_add_f32 v[106:107], v[18:19], v[82:83]
	v_pk_mul_f32 v[84:85], v[76:77], s[60:61] op_sel_hi:[1,0]
	v_xor_b32_e32 v105, 0x80000000, v76
	v_mov_b32_e32 v104, v77
	v_pk_fma_f32 v[76:77], v[104:105], s[60:61], v[84:85] op_sel_hi:[1,0,1] neg_lo:[0,0,1] neg_hi:[0,0,1]
	v_pk_add_f32 v[84:85], v[24:25], v[100:101]
	v_pk_add_f32 v[24:25], v[100:101], v[24:25] neg_lo:[0,1] neg_hi:[0,1]
	v_pk_add_f32 v[100:101], v[10:11], v[86:87]
	v_pk_add_f32 v[10:11], v[86:87], v[10:11] neg_lo:[0,1] neg_hi:[0,1]
	v_pk_add_f32 v[18:19], v[18:19], v[82:83] neg_lo:[0,1] neg_hi:[0,1]
	v_xor_b32_e32 v87, 0x80000000, v10
	v_mov_b32_e32 v86, v11
	v_pk_mul_f32 v[86:87], v[86:87], s[60:61] op_sel_hi:[1,0]
	v_pk_add_f32 v[82:83], v[76:77], v[72:73]
	v_pk_fma_f32 v[10:11], v[10:11], s[60:61], v[86:87] op_sel_hi:[1,0,1]
	v_pk_add_f32 v[86:87], v[64:65], v[20:21]
	v_pk_add_f32 v[20:21], v[20:21], v[64:65] neg_lo:[0,1] neg_hi:[0,1]
	v_pk_add_f32 v[72:73], v[72:73], v[76:77] neg_lo:[0,1] neg_hi:[0,1]
	v_xor_b32_e32 v65, 0x80000000, v20
	v_mov_b32_e32 v64, v21
	v_pk_add_f32 v[20:21], v[66:67], v[22:23]
	v_pk_add_f32 v[22:23], v[22:23], v[66:67] neg_lo:[0,1] neg_hi:[0,1]
	v_xor_b32_e32 v77, 0x80000000, v72
	v_pk_mul_f32 v[66:67], v[22:23], s[60:61] op_sel_hi:[1,0]
	v_xor_b32_e32 v105, 0x80000000, v22
	v_mov_b32_e32 v104, v23
	v_pk_fma_f32 v[22:23], v[104:105], s[60:61], v[66:67] op_sel_hi:[1,0,1] neg_lo:[0,0,1] neg_hi:[0,0,1]
	v_pk_add_f32 v[66:67], v[2:3], v[26:27]
	v_pk_add_f32 v[2:3], v[2:3], v[26:27] neg_lo:[0,1] neg_hi:[0,1]
	v_pk_add_f32 v[26:27], v[12:13], v[4:5]
	v_pk_add_f32 v[4:5], v[4:5], v[12:13] neg_lo:[0,1] neg_hi:[0,1]
	v_mov_b32_e32 v76, v73
	v_xor_b32_e32 v13, 0x80000000, v4
	v_mov_b32_e32 v12, v5
	v_pk_mul_f32 v[12:13], v[12:13], s[60:61] op_sel_hi:[1,0]
	v_pk_add_f32 v[72:73], v[84:85], v[86:87]
	v_pk_fma_f32 v[4:5], v[4:5], s[60:61], v[12:13] op_sel_hi:[1,0,1]
	v_pk_add_f32 v[12:13], v[14:15], v[6:7]
	v_pk_add_f32 v[6:7], v[6:7], v[14:15] neg_lo:[0,1] neg_hi:[0,1]
	v_pk_add_f32 v[84:85], v[84:85], v[86:87] neg_lo:[0,1] neg_hi:[0,1]
	v_xor_b32_e32 v15, 0x80000000, v6
	v_mov_b32_e32 v14, v7
	v_pk_add_f32 v[6:7], v[16:17], v[8:9]
	v_pk_add_f32 v[8:9], v[8:9], v[16:17] neg_lo:[0,1] neg_hi:[0,1]
	v_pk_add_f32 v[86:87], v[20:21], v[100:101]
	v_pk_mul_f32 v[16:17], v[8:9], s[60:61] op_sel_hi:[1,0]
	v_xor_b32_e32 v105, 0x80000000, v8
	v_mov_b32_e32 v104, v9
	v_pk_fma_f32 v[8:9], v[104:105], s[60:61], v[16:17] op_sel_hi:[1,0,1] neg_lo:[0,0,1] neg_hi:[0,0,1]
	v_pk_add_f32 v[104:105], v[92:93], v[96:97]
	v_pk_add_f32 v[92:93], v[92:93], v[96:97] neg_lo:[0,1] neg_hi:[0,1]
	v_pk_add_f32 v[96:97], v[90:91], v[70:71]
	v_pk_add_f32 v[70:71], v[70:71], v[90:91] neg_lo:[0,1] neg_hi:[0,1]
	v_pk_add_f32 v[16:17], v[78:79], v[68:69]
	v_pk_add_f32 v[68:69], v[68:69], v[78:79] neg_lo:[0,1] neg_hi:[0,1]
	v_pk_add_f32 v[78:79], v[88:89], v[102:103]
	v_pk_add_f32 v[88:89], v[102:103], v[88:89] neg_lo:[0,1] neg_hi:[0,1]
	v_xor_b32_e32 v91, 0x80000000, v70
	v_mov_b32_e32 v90, v71
	v_pk_add_f32 v[70:71], v[98:99], v[80:81]
	v_pk_add_f32 v[98:99], v[98:99], v[80:81] neg_lo:[0,1] neg_hi:[0,1]
	v_pk_add_f32 v[80:81], v[74:75], v[94:95]
	v_pk_add_f32 v[74:75], v[94:95], v[74:75] neg_lo:[0,1] neg_hi:[0,1]
	v_pk_add_f32 v[20:21], v[100:101], v[20:21] neg_lo:[0,1] neg_hi:[0,1]
	v_pk_add_f32 v[108:109], v[24:25], v[64:65]
	v_pk_add_f32 v[24:25], v[24:25], v[64:65] neg_lo:[0,1] neg_hi:[0,1]
	v_pk_add_f32 v[64:65], v[22:23], v[10:11]
	v_pk_add_f32 v[10:11], v[10:11], v[22:23] neg_lo:[0,1] neg_hi:[0,1]
	v_pk_add_f32 v[114:115], v[6:7], v[26:27]
	v_pk_add_f32 v[6:7], v[26:27], v[6:7] neg_lo:[0,1] neg_hi:[0,1]
	v_xor_b32_e32 v103, 0x80000000, v88
	v_mov_b32_e32 v102, v89
	v_xor_b32_e32 v95, 0x80000000, v74
	v_mov_b32_e32 v94, v75
	v_xor_b32_e32 v101, 0x80000000, v20
	v_mov_b32_e32 v100, v21
	v_xor_b32_e32 v111, 0x80000000, v10
	v_mov_b32_e32 v110, v11
	v_xor_b32_e32 v27, 0x80000000, v6
	v_mov_b32_e32 v26, v7
	v_pk_add_f32 v[6:7], v[2:3], v[14:15]
	v_pk_add_f32 v[116:117], v[2:3], v[14:15] neg_lo:[0,1] neg_hi:[0,1]
	v_pk_add_f32 v[2:3], v[4:5], v[8:9] neg_lo:[0,1] neg_hi:[0,1]
	v_pk_add_f32 v[112:113], v[66:67], v[12:13]
	v_pk_add_f32 v[66:67], v[66:67], v[12:13] neg_lo:[0,1] neg_hi:[0,1]
	v_pk_add_f32 v[118:119], v[8:9], v[4:5]
	v_xor_b32_e32 v121, 0x80000000, v2
	v_mov_b32_e32 v120, v3
	v_pk_add_f32 v[2:3], v[78:79], v[16:17]
	v_pk_add_f32 v[88:89], v[16:17], v[78:79] neg_lo:[0,1] neg_hi:[0,1]
	v_pk_add_f32 v[122:123], v[68:69], v[102:103]
	v_pk_add_f32 v[20:21], v[68:69], v[102:103] neg_lo:[0,1] neg_hi:[0,1]
	v_pk_add_f32 v[78:79], v[104:105], v[96:97]
	v_pk_add_f32 v[74:75], v[104:105], v[96:97] neg_lo:[0,1] neg_hi:[0,1]
	v_pk_add_f32 v[96:97], v[92:93], v[90:91]
	v_pk_add_f32 v[8:9], v[92:93], v[90:91] neg_lo:[0,1] neg_hi:[0,1]
	v_pk_add_f32 v[102:103], v[98:99], v[94:95]
	v_pk_add_f32 v[12:13], v[98:99], v[94:95] neg_lo:[0,1] neg_hi:[0,1]
	v_pk_add_f32 v[98:99], v[18:19], v[76:77]
	v_pk_add_f32 v[4:5], v[18:19], v[76:77] neg_lo:[0,1] neg_hi:[0,1]
	v_pk_add_f32 v[18:19], v[72:73], v[86:87]
	v_pk_add_f32 v[92:93], v[72:73], v[86:87] neg_lo:[0,1] neg_hi:[0,1]
	v_pk_add_f32 v[86:87], v[84:85], v[100:101]
	v_pk_add_f32 v[22:23], v[84:85], v[100:101] neg_lo:[0,1] neg_hi:[0,1]
	v_pk_add_f32 v[100:101], v[24:25], v[110:111]
	v_pk_add_f32 v[10:11], v[24:25], v[110:111] neg_lo:[0,1] neg_hi:[0,1]
	v_mov_b32_e32 v24, v63
	v_pk_add_f32 v[84:85], v[108:109], v[64:65]
	v_cvt_f32_i32_e32 v24, v24
	v_pk_add_f32 v[76:77], v[108:109], v[64:65] neg_lo:[0,1] neg_hi:[0,1]
	v_pk_add_f32 v[104:105], v[66:67], v[26:27]
	v_pk_add_f32 v[14:15], v[66:67], v[26:27] neg_lo:[0,1] neg_hi:[0,1]
	v_mul_f32_e32 v25, 0x38800000, v24
	v_cos_f32_e32 v24, v25
	v_sin_f32_e32 v25, v25
	v_xor_b32_e32 v95, 0x80000000, v18
	v_mov_b32_e32 v94, v19
	v_add_f32_e32 v62, v24, v24
	v_pk_mul_f32 v[26:27], v[24:25], v[24:25]
	v_mul_f32_e32 v62, v25, v62
	v_xor_b32_e32 v72, 0x80000000, v25
	v_mov_b32_e32 v73, v24
	v_mov_b32_e32 v108, v25
	v_pk_add_f32 v[26:27], v[26:27], v[26:27] op_sel:[0,1] op_sel_hi:[0,1] neg_lo:[0,1] neg_hi:[0,1]
	v_pk_mul_f32 v[72:73], v[72:73], v[62:63] op_sel_hi:[1,0]
	v_pk_mul_f32 v[94:95], v[94:95], v[108:109] op_sel_hi:[1,0]
	v_pk_add_f32 v[16:17], v[70:71], v[80:81]
	v_pk_fma_f32 v[72:73], v[24:25], v[26:27], v[72:73]
	v_pk_fma_f32 v[18:19], v[18:19], v[24:25], v[94:95] op_sel_hi:[1,0,1]
	v_pk_mul_f32 v[24:25], v[62:63], s[46:47] op_sel_hi:[0,1]
	v_pk_fma_f32 v[94:95], v[26:27], s[40:41], v[24:25]
	v_xor_b32_e32 v25, 0x80000000, v16
	v_mov_b32_e32 v24, v17
	v_pk_mul_f32 v[24:25], v[24:25], v[94:95] op_sel:[0,1]
	v_pk_add_f32 v[64:65], v[112:113], v[114:115]
	v_pk_fma_f32 v[24:25], v[16:17], v[94:95], v[24:25] op_sel_hi:[1,0,1]
	v_xor_b32_e32 v16, 0x80000000, v73
	v_mov_b32_e32 v17, v72
	v_pk_mul_f32 v[16:17], v[62:63], v[16:17] op_sel_hi:[0,1]
	v_pk_fma_f32 v[108:109], v[26:27], v[72:73], v[16:17]
	v_xor_b32_e32 v17, 0x80000000, v64
	v_mov_b32_e32 v16, v65
	v_pk_mul_f32 v[16:17], v[16:17], v[72:73] op_sel:[0,1]
	v_pk_add_f32 v[90:91], v[106:107], v[82:83]
	v_pk_fma_f32 v[16:17], v[64:65], v[72:73], v[16:17] op_sel_hi:[1,0,1]
	v_xor_b32_e32 v64, 0x80000000, v95
	v_mov_b32_e32 v65, v94
	v_pk_mul_f32 v[64:65], v[62:63], v[64:65] op_sel_hi:[0,1]
	v_pk_fma_f32 v[94:95], v[26:27], v[94:95], v[64:65]
	v_xor_b32_e32 v65, 0x80000000, v78
	v_mov_b32_e32 v64, v79
	v_pk_mul_f32 v[64:65], v[64:65], v[94:95] op_sel:[0,1]
	v_pk_add_f32 v[66:67], v[6:7], v[118:119]
	v_pk_fma_f32 v[72:73], v[78:79], v[94:95], v[64:65] op_sel_hi:[1,0,1]
	v_xor_b32_e32 v64, 0x80000000, v109
	v_mov_b32_e32 v65, v108
	v_pk_mul_f32 v[64:65], v[62:63], v[64:65] op_sel_hi:[0,1]
	v_pk_fma_f32 v[110:111], v[26:27], v[108:109], v[64:65]
	v_xor_b32_e32 v65, 0x80000000, v84
	v_mov_b32_e32 v64, v85
	v_xor_b32_e32 v78, 0x80000000, v95
	v_mov_b32_e32 v79, v94
	v_pk_mul_f32 v[64:65], v[64:65], v[108:109] op_sel:[0,1]
	v_pk_mul_f32 v[78:79], v[62:63], v[78:79] op_sel_hi:[0,1]
	v_pk_fma_f32 v[64:65], v[84:85], v[108:109], v[64:65] op_sel_hi:[1,0,1]
	v_pk_fma_f32 v[84:85], v[26:27], v[94:95], v[78:79]
	v_xor_b32_e32 v79, 0x80000000, v90
	v_mov_b32_e32 v78, v91
	v_pk_mul_f32 v[78:79], v[78:79], v[84:85] op_sel:[0,1]
	v_pk_add_f32 v[68:69], v[106:107], v[82:83] neg_lo:[0,1] neg_hi:[0,1]
	v_pk_fma_f32 v[78:79], v[90:91], v[84:85], v[78:79] op_sel_hi:[1,0,1]
	v_xor_b32_e32 v90, 0x80000000, v111
	v_mov_b32_e32 v91, v110
	v_pk_mul_f32 v[90:91], v[62:63], v[90:91] op_sel_hi:[0,1]
	v_pk_fma_f32 v[94:95], v[26:27], v[110:111], v[90:91]
	v_xor_b32_e32 v91, 0x80000000, v66
	v_mov_b32_e32 v90, v67
	v_pk_mul_f32 v[90:91], v[90:91], v[110:111] op_sel:[0,1]
	v_pk_add_f32 v[106:107], v[116:117], v[120:121]
	v_pk_fma_f32 v[66:67], v[66:67], v[110:111], v[90:91] op_sel_hi:[1,0,1]
	v_xor_b32_e32 v90, 0x80000000, v85
	v_mov_b32_e32 v91, v84
	v_pk_mul_f32 v[90:91], v[62:63], v[90:91] op_sel_hi:[0,1]
	v_pk_fma_f32 v[108:109], v[26:27], v[84:85], v[90:91]
	v_xor_b32_e32 v85, 0x80000000, v122
	v_mov_b32_e32 v84, v123
	v_pk_mul_f32 v[84:85], v[84:85], v[108:109] op_sel:[0,1]
	v_pk_add_f32 v[80:81], v[70:71], v[80:81] neg_lo:[0,1] neg_hi:[0,1]
	v_pk_fma_f32 v[90:91], v[122:123], v[108:109], v[84:85] op_sel_hi:[1,0,1]
	v_xor_b32_e32 v84, 0x80000000, v95
	v_mov_b32_e32 v85, v94
	v_pk_mul_f32 v[84:85], v[62:63], v[84:85] op_sel_hi:[0,1]
	v_pk_fma_f32 v[110:111], v[26:27], v[94:95], v[84:85]
	v_xor_b32_e32 v85, 0x80000000, v86
	v_mov_b32_e32 v84, v87
	v_pk_mul_f32 v[84:85], v[84:85], v[94:95] op_sel:[0,1]
	v_pk_add_f32 v[82:83], v[112:113], v[114:115] neg_lo:[0,1] neg_hi:[0,1]
	v_pk_fma_f32 v[84:85], v[86:87], v[94:95], v[84:85] op_sel_hi:[1,0,1]
	v_xor_b32_e32 v86, 0x80000000, v109
	v_mov_b32_e32 v87, v108
	v_pk_mul_f32 v[86:87], v[62:63], v[86:87] op_sel_hi:[0,1]
	v_pk_fma_f32 v[108:109], v[26:27], v[108:109], v[86:87]
	v_xor_b32_e32 v87, 0x80000000, v102
	v_mov_b32_e32 v86, v103
	v_pk_mul_f32 v[86:87], v[86:87], v[108:109] op_sel:[0,1]
	v_pk_add_f32 v[70:71], v[6:7], v[118:119] neg_lo:[0,1] neg_hi:[0,1]
	v_pk_fma_f32 v[94:95], v[102:103], v[108:109], v[86:87] op_sel_hi:[1,0,1]
	v_xor_b32_e32 v86, 0x80000000, v111
	v_mov_b32_e32 v87, v110
	v_pk_mul_f32 v[86:87], v[62:63], v[86:87] op_sel_hi:[0,1]
	v_pk_fma_f32 v[102:103], v[26:27], v[110:111], v[86:87]
	v_xor_b32_e32 v87, 0x80000000, v104
	v_mov_b32_e32 v86, v105
	v_pk_mul_f32 v[86:87], v[86:87], v[110:111] op_sel:[0,1]
	v_pk_add_f32 v[6:7], v[116:117], v[120:121] neg_lo:[0,1] neg_hi:[0,1]
	v_pk_fma_f32 v[86:87], v[104:105], v[110:111], v[86:87] op_sel_hi:[1,0,1]
	v_xor_b32_e32 v104, 0x80000000, v109
	v_mov_b32_e32 v105, v108
	v_pk_mul_f32 v[104:105], v[62:63], v[104:105] op_sel_hi:[0,1]
	v_pk_fma_f32 v[104:105], v[26:27], v[108:109], v[104:105]
	v_xor_b32_e32 v109, 0x80000000, v96
	v_mov_b32_e32 v108, v97
	v_pk_mul_f32 v[108:109], v[108:109], v[104:105] op_sel:[0,1]
	v_xor_b32_e32 v111, 0x80000000, v100
	v_pk_fma_f32 v[96:97], v[96:97], v[104:105], v[108:109] op_sel_hi:[1,0,1]
	v_xor_b32_e32 v108, 0x80000000, v103
	v_mov_b32_e32 v109, v102
	v_mov_b32_e32 v110, v101
	v_pk_mul_f32 v[108:109], v[62:63], v[108:109] op_sel_hi:[0,1]
	v_pk_mul_f32 v[110:111], v[110:111], v[102:103] op_sel:[0,1]
	v_pk_fma_f32 v[108:109], v[26:27], v[102:103], v[108:109]
	v_pk_fma_f32 v[100:101], v[100:101], v[102:103], v[110:111] op_sel_hi:[1,0,1]
	v_xor_b32_e32 v102, 0x80000000, v105
	v_mov_b32_e32 v103, v104
	v_pk_mul_f32 v[102:103], v[62:63], v[102:103] op_sel_hi:[0,1]
	v_pk_fma_f32 v[102:103], v[26:27], v[104:105], v[102:103]
	v_xor_b32_e32 v105, 0x80000000, v98
	v_mov_b32_e32 v104, v99
	v_pk_mul_f32 v[104:105], v[104:105], v[102:103] op_sel:[0,1]
	v_xor_b32_e32 v111, 0x80000000, v106
	v_pk_fma_f32 v[98:99], v[98:99], v[102:103], v[104:105] op_sel_hi:[1,0,1]
	v_xor_b32_e32 v104, 0x80000000, v109
	v_mov_b32_e32 v105, v108
	v_mov_b32_e32 v110, v107
	v_pk_mul_f32 v[104:105], v[62:63], v[104:105] op_sel_hi:[0,1]
	v_pk_mul_f32 v[110:111], v[110:111], v[108:109] op_sel:[0,1]
	v_pk_fma_f32 v[104:105], v[26:27], v[108:109], v[104:105]
	v_pk_fma_f32 v[106:107], v[106:107], v[108:109], v[110:111] op_sel_hi:[1,0,1]
	v_xor_b32_e32 v108, 0x80000000, v103
	v_mov_b32_e32 v109, v102
	v_pk_mul_f32 v[108:109], v[62:63], v[108:109] op_sel_hi:[0,1]
	v_pk_fma_f32 v[102:103], v[26:27], v[102:103], v[108:109]
	v_xor_b32_e32 v109, 0x80000000, v88
	v_mov_b32_e32 v108, v89
	v_pk_mul_f32 v[108:109], v[108:109], v[102:103] op_sel:[0,1]
	v_xor_b32_e32 v111, 0x80000000, v92
	v_pk_fma_f32 v[88:89], v[88:89], v[102:103], v[108:109] op_sel_hi:[1,0,1]
	v_xor_b32_e32 v108, 0x80000000, v105
	v_mov_b32_e32 v109, v104
	v_mov_b32_e32 v110, v93
	v_pk_mul_f32 v[108:109], v[62:63], v[108:109] op_sel_hi:[0,1]
	v_pk_mul_f32 v[110:111], v[110:111], v[104:105] op_sel:[0,1]
	v_pk_fma_f32 v[108:109], v[26:27], v[104:105], v[108:109]
	v_pk_fma_f32 v[92:93], v[92:93], v[104:105], v[110:111] op_sel_hi:[1,0,1]
	v_xor_b32_e32 v104, 0x80000000, v103
	v_mov_b32_e32 v105, v102
	v_pk_mul_f32 v[104:105], v[62:63], v[104:105] op_sel_hi:[0,1]
	v_pk_fma_f32 v[102:103], v[26:27], v[102:103], v[104:105]
	v_xor_b32_e32 v105, 0x80000000, v80
	v_mov_b32_e32 v104, v81
	v_pk_mul_f32 v[104:105], v[104:105], v[102:103] op_sel:[0,1]
	v_xor_b32_e32 v111, 0x80000000, v82
	v_pk_fma_f32 v[80:81], v[80:81], v[102:103], v[104:105] op_sel_hi:[1,0,1]
	v_xor_b32_e32 v104, 0x80000000, v109
	v_mov_b32_e32 v105, v108
	v_mov_b32_e32 v110, v83
	v_pk_mul_f32 v[104:105], v[62:63], v[104:105] op_sel_hi:[0,1]
	v_pk_mul_f32 v[110:111], v[110:111], v[108:109] op_sel:[0,1]
	v_pk_fma_f32 v[104:105], v[26:27], v[108:109], v[104:105]
	v_pk_fma_f32 v[82:83], v[82:83], v[108:109], v[110:111] op_sel_hi:[1,0,1]
	v_xor_b32_e32 v108, 0x80000000, v103
	v_mov_b32_e32 v109, v102
	v_pk_mul_f32 v[108:109], v[62:63], v[108:109] op_sel_hi:[0,1]
	v_pk_fma_f32 v[102:103], v[26:27], v[102:103], v[108:109]
	v_xor_b32_e32 v109, 0x80000000, v74
	v_mov_b32_e32 v108, v75
	v_pk_mul_f32 v[108:109], v[108:109], v[102:103] op_sel:[0,1]
	v_xor_b32_e32 v111, 0x80000000, v76
	v_pk_fma_f32 v[74:75], v[74:75], v[102:103], v[108:109] op_sel_hi:[1,0,1]
	v_xor_b32_e32 v108, 0x80000000, v105
	v_mov_b32_e32 v109, v104
	v_mov_b32_e32 v110, v77
	v_pk_mul_f32 v[108:109], v[62:63], v[108:109] op_sel_hi:[0,1]
	v_pk_mul_f32 v[110:111], v[110:111], v[104:105] op_sel:[0,1]
	v_pk_fma_f32 v[108:109], v[26:27], v[104:105], v[108:109]
	v_pk_fma_f32 v[76:77], v[76:77], v[104:105], v[110:111] op_sel_hi:[1,0,1]
	v_xor_b32_e32 v104, 0x80000000, v103
	v_mov_b32_e32 v105, v102
	v_pk_mul_f32 v[104:105], v[62:63], v[104:105] op_sel_hi:[0,1]
	v_pk_fma_f32 v[102:103], v[26:27], v[102:103], v[104:105]
	v_xor_b32_e32 v105, 0x80000000, v68
	v_mov_b32_e32 v104, v69
	v_pk_mul_f32 v[104:105], v[104:105], v[102:103] op_sel:[0,1]
	v_xor_b32_e32 v111, 0x80000000, v70
	v_pk_fma_f32 v[68:69], v[68:69], v[102:103], v[104:105] op_sel_hi:[1,0,1]
	v_xor_b32_e32 v104, 0x80000000, v109
	v_mov_b32_e32 v105, v108
	v_mov_b32_e32 v110, v71
	v_pk_mul_f32 v[104:105], v[62:63], v[104:105] op_sel_hi:[0,1]
	v_pk_mul_f32 v[110:111], v[110:111], v[108:109] op_sel:[0,1]
	v_pk_fma_f32 v[104:105], v[26:27], v[108:109], v[104:105]
	v_pk_fma_f32 v[70:71], v[70:71], v[108:109], v[110:111] op_sel_hi:[1,0,1]
	v_xor_b32_e32 v108, 0x80000000, v103
	v_mov_b32_e32 v109, v102
	v_pk_mul_f32 v[108:109], v[62:63], v[108:109] op_sel_hi:[0,1]
	v_pk_fma_f32 v[102:103], v[26:27], v[102:103], v[108:109]
	v_xor_b32_e32 v109, 0x80000000, v20
	v_mov_b32_e32 v108, v21
	v_pk_mul_f32 v[108:109], v[108:109], v[102:103] op_sel:[0,1]
	v_xor_b32_e32 v111, 0x80000000, v22
	v_pk_fma_f32 v[20:21], v[20:21], v[102:103], v[108:109] op_sel_hi:[1,0,1]
	v_xor_b32_e32 v108, 0x80000000, v105
	v_mov_b32_e32 v109, v104
	v_mov_b32_e32 v110, v23
	v_pk_mul_f32 v[108:109], v[62:63], v[108:109] op_sel_hi:[0,1]
	v_pk_mul_f32 v[110:111], v[110:111], v[104:105] op_sel:[0,1]
	v_pk_fma_f32 v[108:109], v[26:27], v[104:105], v[108:109]
	v_pk_fma_f32 v[22:23], v[22:23], v[104:105], v[110:111] op_sel_hi:[1,0,1]
	v_xor_b32_e32 v104, 0x80000000, v103
	v_mov_b32_e32 v105, v102
	v_pk_mul_f32 v[104:105], v[62:63], v[104:105] op_sel_hi:[0,1]
	v_pk_fma_f32 v[102:103], v[26:27], v[102:103], v[104:105]
	v_xor_b32_e32 v105, 0x80000000, v12
	v_mov_b32_e32 v104, v13
	v_pk_mul_f32 v[104:105], v[104:105], v[102:103] op_sel:[0,1]
	v_xor_b32_e32 v111, 0x80000000, v14
	v_pk_fma_f32 v[12:13], v[12:13], v[102:103], v[104:105] op_sel_hi:[1,0,1]
	v_xor_b32_e32 v104, 0x80000000, v109
	v_mov_b32_e32 v105, v108
	v_mov_b32_e32 v110, v15
	v_pk_mul_f32 v[104:105], v[62:63], v[104:105] op_sel_hi:[0,1]
	v_pk_mul_f32 v[110:111], v[110:111], v[108:109] op_sel:[0,1]
	v_pk_fma_f32 v[104:105], v[26:27], v[108:109], v[104:105]
	v_pk_fma_f32 v[14:15], v[14:15], v[108:109], v[110:111] op_sel_hi:[1,0,1]
	v_xor_b32_e32 v108, 0x80000000, v103
	v_mov_b32_e32 v109, v102
	v_pk_mul_f32 v[108:109], v[62:63], v[108:109] op_sel_hi:[0,1]
	v_pk_fma_f32 v[102:103], v[26:27], v[102:103], v[108:109]
	v_xor_b32_e32 v109, 0x80000000, v8
	v_mov_b32_e32 v108, v9
	v_pk_mul_f32 v[108:109], v[108:109], v[102:103] op_sel:[0,1]
	v_xor_b32_e32 v111, 0x80000000, v10
	v_pk_fma_f32 v[8:9], v[8:9], v[102:103], v[108:109] op_sel_hi:[1,0,1]
	v_xor_b32_e32 v108, 0x80000000, v105
	v_mov_b32_e32 v109, v104
	v_mov_b32_e32 v110, v11
	v_pk_mul_f32 v[108:109], v[62:63], v[108:109] op_sel_hi:[0,1]
	v_pk_mul_f32 v[110:111], v[110:111], v[104:105] op_sel:[0,1]
	v_pk_fma_f32 v[108:109], v[26:27], v[104:105], v[108:109]
	v_pk_fma_f32 v[10:11], v[10:11], v[104:105], v[110:111] op_sel_hi:[1,0,1]
	v_xor_b32_e32 v104, 0x80000000, v103
	v_mov_b32_e32 v105, v102
	v_pk_mul_f32 v[104:105], v[62:63], v[104:105] op_sel_hi:[0,1]
	v_pk_fma_f32 v[26:27], v[26:27], v[102:103], v[104:105]
	v_xor_b32_e32 v103, 0x80000000, v4
	v_mov_b32_e32 v102, v5
	v_pk_mul_f32 v[102:103], v[102:103], v[26:27] op_sel:[0,1]
	s_add_i32 s1, 16, 0x1e000
	v_pk_fma_f32 v[4:5], v[4:5], v[26:27], v[102:103] op_sel_hi:[1,0,1]
	v_xor_b32_e32 v27, 0x80000000, v6
	v_mov_b32_e32 v26, v7
	v_pk_mul_f32 v[26:27], v[26:27], v[108:109] op_sel:[0,1]
	s_add_i32 s0, 16, 0x1f000
	v_pk_fma_f32 v[6:7], v[6:7], v[108:109], v[26:27] op_sel_hi:[1,0,1]
	v_lshrrev_b32_e32 v26, 5, v63
	v_bitop3_b32 v26, v26, v63, 15 bitop3:0x6c
	v_lshlrev_b32_e32 v26, 3, v26
	v_bfe_u32 v27, v63, 5, 4
	v_add_u32_e32 v62, 16, v26
	ds_write_b64 v62, v[2:3]
	v_bitop3_b32 v2, v27, v63, 16 bitop3:0x36
	v_lshlrev_b32_e32 v2, 3, v2
	v_add_u32_e32 v3, 16, v2
	ds_write_b64 v3, v[88:89] offset:4096
	ds_write_b64 v62, v[90:91] offset:8192
	ds_write_b64 v3, v[20:21] offset:12288
	ds_write_b64 v62, v[72:73] offset:16384
	ds_write_b64 v3, v[74:75] offset:20480
	ds_write_b64 v62, v[96:97] offset:24576
	ds_write_b64 v3, v[8:9] offset:28672
	ds_write_b64 v62, v[24:25] offset:32768
	ds_write_b64 v3, v[80:81] offset:36864
	ds_write_b64 v62, v[94:95] offset:40960
	ds_write_b64 v3, v[12:13] offset:45056
	ds_write_b64 v62, v[78:79] offset:49152
	ds_write_b64 v3, v[68:69] offset:53248
	ds_write_b64 v62, v[98:99] offset:57344
	ds_write_b64 v3, v[4:5] offset:61440
	v_add_u32_e32 v3, s79, v26
	ds_write_b64 v3, v[18:19]
	v_add_u32_e32 v3, s19, v2
	ds_write_b64 v3, v[92:93]
	v_add_u32_e32 v3, s18, v26
	ds_write_b64 v3, v[84:85]
	v_add_u32_e32 v3, s17, v2
	ds_write_b64 v3, v[22:23]
	v_add_u32_e32 v3, s13, v26
	ds_write_b64 v3, v[64:65]
	v_add_u32_e32 v3, s12, v2
	ds_write_b64 v3, v[76:77]
	v_add_u32_e32 v3, s11, v26
	ds_write_b64 v3, v[100:101]
	v_add_u32_e32 v3, s10, v2
	ds_write_b64 v3, v[10:11]
	v_add_u32_e32 v3, s9, v26
	ds_write_b64 v3, v[16:17]
	v_add_u32_e32 v3, s8, v2
	ds_write_b64 v3, v[82:83]
	v_add_u32_e32 v3, s7, v26
	ds_write_b64 v3, v[86:87]
	v_add_u32_e32 v3, s6, v2
	ds_write_b64 v3, v[14:15]
	v_add_u32_e32 v3, s5, v26
	ds_write_b64 v3, v[66:67]
	v_add_u32_e32 v3, s4, v2
	ds_write_b64 v3, v[70:71]
	v_add_u32_e32 v3, s1, v26
	v_add_u32_e32 v2, s0, v2
	v_mov_b32_e32 v21, v146
	ds_write_b64 v3, v[106:107]
	ds_write_b64 v2, v[6:7]
	s_waitcnt lgkmcnt(0)
	s_barrier
	s_lshl_b32 s42, s16, 14
	v_lshlrev_b32_e32 v2, 5, v21
	v_and_b32_e32 v4, 0xfffffe00, v2
	v_and_b32_e32 v20, 15, v21
	v_and_or_b32 v2, v21, 16, v4
	v_bitop3_b32 v4, v4, 16, v21 bitop3:0x34
	v_bitop3_b32 v72, v21, 8, 15 bitop3:0x6c
	v_lshl_add_u32 v26, v2, 3, 16
	v_lshlrev_b32_e32 v5, 3, v20
	v_lshl_add_u32 v126, v4, 3, 16
	v_lshlrev_b32_e32 v74, 3, v72
	v_add_u32_e32 v27, v26, v5
	v_add_u32_e32 v96, v126, v5
	v_add_u32_e32 v111, v26, v74
	v_add_u32_e32 v112, v126, v74
	ds_read_b64 v[2:3], v27
	ds_read_b64 v[4:5], v96
	v_bitop3_b32 v6, v21, 1, 15 bitop3:0x6c
	ds_read_b64 v[72:73], v111 offset:2048
	ds_read_b64 v[74:75], v112 offset:2048
	v_bitop3_b32 v76, v21, 9, 15 bitop3:0x6c
	v_lshlrev_b32_e32 v8, 3, v6
	v_lshlrev_b32_e32 v78, 3, v76
	v_add_u32_e32 v97, v26, v8
	v_add_u32_e32 v113, v26, v78
	ds_read_b64 v[6:7], v97 offset:256
	ds_read_b64 v[76:77], v113 offset:2304
	v_add_u32_e32 v98, v126, v8
	v_add_u32_e32 v114, v126, v78
	ds_read_b64 v[8:9], v98 offset:256
	ds_read_b64 v[78:79], v114 offset:2304
	s_waitcnt lgkmcnt(5)
	v_pk_add_f32 v[136:137], v[2:3], v[72:73]
	v_pk_add_f32 v[2:3], v[2:3], v[72:73] neg_lo:[0,1] neg_hi:[0,1]
	s_waitcnt lgkmcnt(4)
	v_pk_add_f32 v[72:73], v[4:5], v[74:75]
	v_pk_add_f32 v[4:5], v[4:5], v[74:75] neg_lo:[0,1] neg_hi:[0,1]
	v_bitop3_b32 v10, v21, 2, 15 bitop3:0x6c
	v_bitop3_b32 v80, v21, 10, 15 bitop3:0x6c
	v_xor_b32_e32 v75, 0x80000000, v4
	v_mov_b32_e32 v74, v5
	v_lshlrev_b32_e32 v12, 3, v10
	v_lshlrev_b32_e32 v82, 3, v80
	v_pk_mul_f32 v[74:75], v[74:75], s[48:49] op_sel_hi:[1,0]
	v_add_u32_e32 v99, v26, v12
	v_add_u32_e32 v115, v26, v82
	v_pk_fma_f32 v[4:5], v[4:5], s[44:45], v[74:75] op_sel_hi:[1,0,1]
	s_waitcnt lgkmcnt(2)
	v_pk_add_f32 v[74:75], v[6:7], v[76:77]
	v_pk_add_f32 v[6:7], v[6:7], v[76:77] neg_lo:[0,1] neg_hi:[0,1]
	ds_read_b64 v[10:11], v99 offset:512
	ds_read_b64 v[80:81], v115 offset:2560
	v_xor_b32_e32 v77, 0x80000000, v6
	v_mov_b32_e32 v76, v7
	v_pk_mul_f32 v[76:77], v[76:77], s[54:55] op_sel_hi:[1,0]
	v_add_u32_e32 v100, v126, v12
	v_bitop3_b32 v14, v21, 3, 15 bitop3:0x6c
	v_add_u32_e32 v116, v126, v82
	v_bitop3_b32 v84, v21, 11, 15 bitop3:0x6c
	v_pk_fma_f32 v[6:7], v[6:7], s[52:53], v[76:77] op_sel_hi:[1,0,1]
	s_waitcnt lgkmcnt(2)
	v_pk_add_f32 v[76:77], v[8:9], v[78:79]
	v_pk_add_f32 v[8:9], v[8:9], v[78:79] neg_lo:[0,1] neg_hi:[0,1]
	ds_read_b64 v[12:13], v100 offset:512
	v_lshlrev_b32_e32 v16, 3, v14
	ds_read_b64 v[82:83], v116 offset:2560
	v_lshlrev_b32_e32 v86, 3, v84
	v_xor_b32_e32 v79, 0x80000000, v8
	v_mov_b32_e32 v78, v9
	v_add_u32_e32 v101, v26, v16
	v_add_u32_e32 v102, v126, v16
	v_add_u32_e32 v117, v26, v86
	v_add_u32_e32 v118, v126, v86
	v_pk_mul_f32 v[78:79], v[78:79], s[58:59] op_sel_hi:[1,0]
	ds_read_b64 v[14:15], v101 offset:768
	ds_read_b64 v[16:17], v102 offset:768
	ds_read_b64 v[84:85], v117 offset:2816
	ds_read_b64 v[86:87], v118 offset:2816
	v_pk_fma_f32 v[8:9], v[8:9], s[56:57], v[78:79] op_sel_hi:[1,0,1]
	s_waitcnt lgkmcnt(6)
	v_pk_add_f32 v[78:79], v[10:11], v[80:81]
	v_pk_add_f32 v[10:11], v[10:11], v[80:81] neg_lo:[0,1] neg_hi:[0,1]
	v_bitop3_b32 v18, v21, 4, 15 bitop3:0x6c
	v_xor_b32_e32 v81, 0x80000000, v10
	v_mov_b32_e32 v80, v11
	v_pk_mul_f32 v[80:81], v[80:81], s[60:61] op_sel_hi:[1,0]
	v_bitop3_b32 v88, v21, 12, 15 bitop3:0x6c
	v_pk_fma_f32 v[10:11], v[10:11], s[60:61], v[80:81] op_sel_hi:[1,0,1]
	s_waitcnt lgkmcnt(4)
	v_pk_add_f32 v[80:81], v[12:13], v[82:83]
	v_pk_add_f32 v[12:13], v[12:13], v[82:83] neg_lo:[0,1] neg_hi:[0,1]
	v_lshlrev_b32_e32 v22, 3, v18
	v_xor_b32_e32 v83, 0x80000000, v12
	v_mov_b32_e32 v82, v13
	v_lshlrev_b32_e32 v90, 3, v88
	v_pk_mul_f32 v[82:83], v[82:83], s[56:57] op_sel_hi:[1,0]
	v_add_u32_e32 v103, v26, v22
	v_add_u32_e32 v119, v26, v90
	v_pk_fma_f32 v[12:13], v[12:13], s[58:59], v[82:83] op_sel_hi:[1,0,1]
	s_waitcnt lgkmcnt(1)
	v_pk_add_f32 v[82:83], v[14:15], v[84:85]
	v_pk_add_f32 v[14:15], v[14:15], v[84:85] neg_lo:[0,1] neg_hi:[0,1]
	ds_read_b64 v[18:19], v103 offset:1024
	v_add_u32_e32 v104, v126, v22
	v_bitop3_b32 v24, v21, 5, 15 bitop3:0x6c
	ds_read_b64 v[88:89], v119 offset:3072
	v_add_u32_e32 v120, v126, v90
	v_bitop3_b32 v92, v21, 13, 15 bitop3:0x6c
	v_xor_b32_e32 v85, 0x80000000, v14
	v_mov_b32_e32 v84, v15
	ds_read_b64 v[22:23], v104 offset:1024
	v_lshlrev_b32_e32 v62, 3, v24
	ds_read_b64 v[90:91], v120 offset:3072
	v_lshlrev_b32_e32 v94, 3, v92
	v_pk_mul_f32 v[84:85], v[84:85], s[52:53] op_sel_hi:[1,0]
	v_add_u32_e32 v105, v26, v62
	v_add_u32_e32 v121, v26, v94
	v_pk_fma_f32 v[14:15], v[14:15], s[54:55], v[84:85] op_sel_hi:[1,0,1]
	s_waitcnt lgkmcnt(4)
	v_pk_add_f32 v[84:85], v[16:17], v[86:87]
	v_pk_add_f32 v[16:17], v[16:17], v[86:87] neg_lo:[0,1] neg_hi:[0,1]
	ds_read_b64 v[24:25], v105 offset:1280
	ds_read_b64 v[92:93], v121 offset:3328
	v_xor_b32_e32 v87, 0x80000000, v16
	v_mov_b32_e32 v86, v17
	v_add_u32_e32 v106, v126, v62
	v_bitop3_b32 v64, v21, 6, 15 bitop3:0x6c
	v_add_u32_e32 v122, v126, v94
	v_bitop3_b32 v123, v21, 14, 15 bitop3:0x6c
	v_pk_mul_f32 v[86:87], v[86:87], s[44:45] op_sel_hi:[1,0]
	ds_read_b64 v[62:63], v106 offset:1280
	v_lshlrev_b32_e32 v66, 3, v64
	ds_read_b64 v[94:95], v122 offset:3328
	v_lshlrev_b32_e32 v124, 3, v123
	v_pk_fma_f32 v[16:17], v[16:17], s[48:49], v[86:87] op_sel_hi:[1,0,1]
	s_waitcnt lgkmcnt(6)
	v_pk_add_f32 v[86:87], v[18:19], v[88:89]
	v_pk_add_f32 v[18:19], v[18:19], v[88:89] neg_lo:[0,1] neg_hi:[0,1]
	v_add_u32_e32 v107, v26, v66
	v_add_u32_e32 v123, v26, v124
	v_xor_b32_e32 v89, 0x80000000, v18
	v_mov_b32_e32 v88, v19
	s_waitcnt lgkmcnt(4)
	v_pk_add_f32 v[18:19], v[22:23], v[90:91]
	v_pk_add_f32 v[22:23], v[22:23], v[90:91] neg_lo:[0,1] neg_hi:[0,1]
	ds_read_b64 v[64:65], v107 offset:1536
	ds_read_b64 v[128:129], v123 offset:3584
	v_pk_mul_f32 v[90:91], v[22:23], s[48:49] op_sel_hi:[1,0]
	v_xor_b32_e32 v139, 0x80000000, v22
	v_mov_b32_e32 v138, v23
	v_add_u32_e32 v108, v126, v66
	v_bitop3_b32 v68, v21, 7, 15 bitop3:0x6c
	v_add_u32_e32 v124, v126, v124
	v_bitop3_b32 v21, v21, 15, v21 bitop3:0xc
	v_pk_fma_f32 v[22:23], v[138:139], s[44:45], v[90:91] op_sel_hi:[1,0,1] neg_lo:[0,0,1] neg_hi:[0,0,1]
	s_waitcnt lgkmcnt(4)
	v_pk_add_f32 v[90:91], v[24:25], v[92:93]
	v_pk_add_f32 v[24:25], v[24:25], v[92:93] neg_lo:[0,1] neg_hi:[0,1]
	ds_read_b64 v[66:67], v108 offset:1536
	v_lshlrev_b32_e32 v70, 3, v68
	ds_read_b64 v[130:131], v124 offset:3584
	v_lshlrev_b32_e32 v21, 3, v21
	v_pk_mul_f32 v[92:93], v[24:25], s[54:55] op_sel_hi:[1,0]
	v_xor_b32_e32 v139, 0x80000000, v24
	v_mov_b32_e32 v138, v25
	v_add_u32_e32 v109, v26, v70
	v_add_u32_e32 v125, v26, v21
	v_pk_fma_f32 v[24:25], v[138:139], s[52:53], v[92:93] op_sel_hi:[1,0,1] neg_lo:[0,0,1] neg_hi:[0,0,1]
	s_waitcnt lgkmcnt(4)
	v_pk_add_f32 v[92:93], v[62:63], v[94:95]
	v_pk_add_f32 v[62:63], v[62:63], v[94:95] neg_lo:[0,1] neg_hi:[0,1]
	ds_read_b64 v[68:69], v109 offset:1792
	v_add_u32_e32 v110, v126, v70
	ds_read_b64 v[132:133], v125 offset:3840
	v_add_u32_e32 v126, v126, v21
	v_pk_mul_f32 v[94:95], v[62:63], s[58:59] op_sel_hi:[1,0]
	v_xor_b32_e32 v139, 0x80000000, v62
	v_mov_b32_e32 v138, v63
	ds_read_b64 v[70:71], v110 offset:1792
	ds_read_b64 v[134:135], v126 offset:3840
	v_pk_fma_f32 v[62:63], v[138:139], s[56:57], v[94:95] op_sel_hi:[1,0,1] neg_lo:[0,0,1] neg_hi:[0,0,1]
	s_waitcnt lgkmcnt(6)
	v_pk_add_f32 v[94:95], v[64:65], v[128:129]
	v_pk_add_f32 v[64:65], v[64:65], v[128:129] neg_lo:[0,1] neg_hi:[0,1]
	v_lshl_add_u64 v[0:1], s[42:43], 2, v[28:29]
	v_pk_mul_f32 v[128:129], v[64:65], s[60:61] op_sel_hi:[1,0]
	v_xor_b32_e32 v139, 0x80000000, v64
	v_mov_b32_e32 v138, v65
	v_pk_fma_f32 v[64:65], v[138:139], s[60:61], v[128:129] op_sel_hi:[1,0,1] neg_lo:[0,0,1] neg_hi:[0,0,1]
	s_waitcnt lgkmcnt(4)
	v_pk_add_f32 v[128:129], v[66:67], v[130:131]
	v_pk_add_f32 v[66:67], v[66:67], v[130:131] neg_lo:[0,1] neg_hi:[0,1]
	v_cvt_f32_i32_e32 v20, v20
	v_pk_mul_f32 v[130:131], v[66:67], s[56:57] op_sel_hi:[1,0]
	v_xor_b32_e32 v139, 0x80000000, v66
	v_mov_b32_e32 v138, v67
	v_pk_fma_f32 v[66:67], v[138:139], s[58:59], v[130:131] op_sel_hi:[1,0,1] neg_lo:[0,0,1] neg_hi:[0,0,1]
	s_waitcnt lgkmcnt(2)
	v_pk_add_f32 v[130:131], v[68:69], v[132:133]
	v_pk_add_f32 v[68:69], v[68:69], v[132:133] neg_lo:[0,1] neg_hi:[0,1]
	v_mul_f32_e32 v21, 0x3b000000, v20
	v_pk_mul_f32 v[132:133], v[68:69], s[52:53] op_sel_hi:[1,0]
	v_xor_b32_e32 v139, 0x80000000, v68
	v_mov_b32_e32 v138, v69
	v_pk_fma_f32 v[68:69], v[138:139], s[54:55], v[132:133] op_sel_hi:[1,0,1] neg_lo:[0,0,1] neg_hi:[0,0,1]
	s_waitcnt lgkmcnt(0)
	v_pk_add_f32 v[132:133], v[70:71], v[134:135]
	v_pk_add_f32 v[70:71], v[70:71], v[134:135] neg_lo:[0,1] neg_hi:[0,1]
	v_cos_f32_e32 v20, v21
	v_pk_mul_f32 v[134:135], v[70:71], s[44:45] op_sel_hi:[1,0]
	v_xor_b32_e32 v139, 0x80000000, v70
	v_mov_b32_e32 v138, v71
	v_pk_fma_f32 v[70:71], v[138:139], s[48:49], v[134:135] op_sel_hi:[1,0,1] neg_lo:[0,0,1] neg_hi:[0,0,1]
	v_pk_add_f32 v[134:135], v[136:137], v[86:87]
	v_pk_add_f32 v[86:87], v[136:137], v[86:87] neg_lo:[0,1] neg_hi:[0,1]
	v_pk_add_f32 v[136:137], v[72:73], v[18:19]
	v_pk_add_f32 v[18:19], v[72:73], v[18:19] neg_lo:[0,1] neg_hi:[0,1]
	v_sin_f32_e32 v21, v21
	v_xor_b32_e32 v73, 0x80000000, v18
	v_mov_b32_e32 v72, v19
	v_pk_mul_f32 v[72:73], v[72:73], s[54:55] op_sel_hi:[1,0]
	v_add_f32_e32 v26, v20, v20
	v_pk_fma_f32 v[18:19], v[18:19], s[52:53], v[72:73] op_sel_hi:[1,0,1]
	v_pk_add_f32 v[72:73], v[74:75], v[90:91]
	v_pk_add_f32 v[74:75], v[74:75], v[90:91] neg_lo:[0,1] neg_hi:[0,1]
	v_mul_f32_e32 v26, v21, v26
	v_xor_b32_e32 v91, 0x80000000, v74
	v_mov_b32_e32 v90, v75
	v_pk_mul_f32 v[90:91], v[90:91], s[60:61] op_sel_hi:[1,0]
	s_lshl_b32 s42, s16, 9
	v_pk_fma_f32 v[74:75], v[74:75], s[60:61], v[90:91] op_sel_hi:[1,0,1]
	v_pk_add_f32 v[90:91], v[76:77], v[92:93]
	v_pk_add_f32 v[76:77], v[76:77], v[92:93] neg_lo:[0,1] neg_hi:[0,1]
	s_mov_b64 s[74:75], -1
	v_xor_b32_e32 v93, 0x80000000, v76
	v_mov_b32_e32 v92, v77
	v_pk_mul_f32 v[92:93], v[92:93], s[52:53] op_sel_hi:[1,0]
	s_nop 0
	v_pk_fma_f32 v[76:77], v[76:77], s[54:55], v[92:93] op_sel_hi:[1,0,1]
	v_pk_add_f32 v[92:93], v[78:79], v[94:95]
	v_pk_add_f32 v[78:79], v[78:79], v[94:95] neg_lo:[0,1] neg_hi:[0,1]
	s_nop 0
	v_xor_b32_e32 v95, 0x80000000, v78
	v_mov_b32_e32 v94, v79
	v_pk_add_f32 v[78:79], v[80:81], v[128:129]
	v_pk_add_f32 v[80:81], v[80:81], v[128:129] neg_lo:[0,1] neg_hi:[0,1]
	s_nop 0
	v_pk_mul_f32 v[128:129], v[80:81], s[54:55] op_sel_hi:[1,0]
	v_xor_b32_e32 v139, 0x80000000, v80
	v_mov_b32_e32 v138, v81
	v_pk_fma_f32 v[80:81], v[138:139], s[52:53], v[128:129] op_sel_hi:[1,0,1] neg_lo:[0,0,1] neg_hi:[0,0,1]
	v_pk_add_f32 v[128:129], v[82:83], v[130:131]
	v_pk_add_f32 v[82:83], v[82:83], v[130:131] neg_lo:[0,1] neg_hi:[0,1]
	s_nop 0
	v_pk_mul_f32 v[130:131], v[82:83], s[60:61] op_sel_hi:[1,0]
	v_xor_b32_e32 v139, 0x80000000, v82
	v_mov_b32_e32 v138, v83
	v_pk_fma_f32 v[82:83], v[138:139], s[60:61], v[130:131] op_sel_hi:[1,0,1] neg_lo:[0,0,1] neg_hi:[0,0,1]
	v_pk_add_f32 v[130:131], v[84:85], v[132:133]
	v_pk_add_f32 v[84:85], v[84:85], v[132:133] neg_lo:[0,1] neg_hi:[0,1]
	s_nop 0
	v_pk_mul_f32 v[132:133], v[84:85], s[52:53] op_sel_hi:[1,0]
	v_xor_b32_e32 v139, 0x80000000, v84
	v_mov_b32_e32 v138, v85
	v_pk_fma_f32 v[84:85], v[138:139], s[54:55], v[132:133] op_sel_hi:[1,0,1] neg_lo:[0,0,1] neg_hi:[0,0,1]
	v_pk_add_f32 v[132:133], v[2:3], v[88:89]
	v_pk_add_f32 v[2:3], v[2:3], v[88:89] neg_lo:[0,1] neg_hi:[0,1]
	v_pk_add_f32 v[88:89], v[4:5], v[22:23]
	v_pk_add_f32 v[4:5], v[4:5], v[22:23] neg_lo:[0,1] neg_hi:[0,1]
	s_nop 0
	v_xor_b32_e32 v23, 0x80000000, v4
	v_mov_b32_e32 v22, v5
	v_pk_mul_f32 v[22:23], v[22:23], s[54:55] op_sel_hi:[1,0]
	s_nop 0
	v_pk_fma_f32 v[4:5], v[4:5], s[52:53], v[22:23] op_sel_hi:[1,0,1]
	v_pk_add_f32 v[22:23], v[6:7], v[24:25]
	v_pk_add_f32 v[6:7], v[6:7], v[24:25] neg_lo:[0,1] neg_hi:[0,1]
	s_nop 0
	v_xor_b32_e32 v25, 0x80000000, v6
	v_mov_b32_e32 v24, v7
	v_pk_mul_f32 v[24:25], v[24:25], s[60:61] op_sel_hi:[1,0]
	s_nop 0
	v_pk_fma_f32 v[6:7], v[6:7], s[60:61], v[24:25] op_sel_hi:[1,0,1]
	v_pk_add_f32 v[24:25], v[8:9], v[62:63]
	v_pk_add_f32 v[8:9], v[8:9], v[62:63] neg_lo:[0,1] neg_hi:[0,1]
	s_nop 0
	v_xor_b32_e32 v63, 0x80000000, v8
	v_mov_b32_e32 v62, v9
	v_pk_mul_f32 v[62:63], v[62:63], s[52:53] op_sel_hi:[1,0]
	s_nop 0
	v_pk_fma_f32 v[8:9], v[8:9], s[54:55], v[62:63] op_sel_hi:[1,0,1]
	v_pk_add_f32 v[62:63], v[10:11], v[64:65]
	v_pk_add_f32 v[10:11], v[10:11], v[64:65] neg_lo:[0,1] neg_hi:[0,1]
	s_nop 0
	v_xor_b32_e32 v65, 0x80000000, v10
	v_mov_b32_e32 v64, v11
	v_pk_add_f32 v[10:11], v[12:13], v[66:67]
	v_pk_add_f32 v[12:13], v[12:13], v[66:67] neg_lo:[0,1] neg_hi:[0,1]
	s_nop 0
	v_pk_mul_f32 v[66:67], v[12:13], s[54:55] op_sel_hi:[1,0]
	v_xor_b32_e32 v139, 0x80000000, v12
	v_mov_b32_e32 v138, v13
	v_pk_fma_f32 v[12:13], v[138:139], s[52:53], v[66:67] op_sel_hi:[1,0,1] neg_lo:[0,0,1] neg_hi:[0,0,1]
	v_pk_add_f32 v[66:67], v[14:15], v[68:69]
	v_pk_add_f32 v[14:15], v[14:15], v[68:69] neg_lo:[0,1] neg_hi:[0,1]
	s_nop 0
	v_pk_mul_f32 v[68:69], v[14:15], s[60:61] op_sel_hi:[1,0]
	v_xor_b32_e32 v139, 0x80000000, v14
	v_mov_b32_e32 v138, v15
	v_pk_fma_f32 v[14:15], v[138:139], s[60:61], v[68:69] op_sel_hi:[1,0,1] neg_lo:[0,0,1] neg_hi:[0,0,1]
	v_pk_add_f32 v[68:69], v[16:17], v[70:71]
	v_pk_add_f32 v[16:17], v[16:17], v[70:71] neg_lo:[0,1] neg_hi:[0,1]
	s_nop 0
	v_pk_mul_f32 v[70:71], v[16:17], s[52:53] op_sel_hi:[1,0]
	v_xor_b32_e32 v139, 0x80000000, v16
	v_mov_b32_e32 v138, v17
	v_pk_fma_f32 v[16:17], v[138:139], s[54:55], v[70:71] op_sel_hi:[1,0,1] neg_lo:[0,0,1] neg_hi:[0,0,1]
	v_pk_add_f32 v[70:71], v[134:135], v[92:93]
	v_pk_add_f32 v[92:93], v[134:135], v[92:93] neg_lo:[0,1] neg_hi:[0,1]
	v_pk_add_f32 v[134:135], v[136:137], v[78:79]
	v_pk_add_f32 v[78:79], v[136:137], v[78:79] neg_lo:[0,1] neg_hi:[0,1]
	s_nop 0
	v_xor_b32_e32 v137, 0x80000000, v78
	v_mov_b32_e32 v136, v79
	v_pk_mul_f32 v[136:137], v[136:137], s[60:61] op_sel_hi:[1,0]
	s_nop 0
	v_pk_fma_f32 v[78:79], v[78:79], s[60:61], v[136:137] op_sel_hi:[1,0,1]
	v_pk_add_f32 v[136:137], v[72:73], v[128:129]
	v_pk_add_f32 v[72:73], v[72:73], v[128:129] neg_lo:[0,1] neg_hi:[0,1]
	s_nop 0
	v_xor_b32_e32 v129, 0x80000000, v72
	v_mov_b32_e32 v128, v73
	v_pk_add_f32 v[72:73], v[90:91], v[130:131]
	v_pk_add_f32 v[90:91], v[90:91], v[130:131] neg_lo:[0,1] neg_hi:[0,1]
	s_nop 0
	v_pk_mul_f32 v[130:131], v[90:91], s[60:61] op_sel_hi:[1,0]
	v_xor_b32_e32 v139, 0x80000000, v90
	v_mov_b32_e32 v138, v91
	v_pk_fma_f32 v[90:91], v[138:139], s[60:61], v[130:131] op_sel_hi:[1,0,1] neg_lo:[0,0,1] neg_hi:[0,0,1]
	v_pk_add_f32 v[130:131], v[86:87], v[94:95]
	v_pk_add_f32 v[86:87], v[86:87], v[94:95] neg_lo:[0,1] neg_hi:[0,1]
	v_pk_add_f32 v[94:95], v[18:19], v[80:81]
	v_pk_add_f32 v[18:19], v[18:19], v[80:81] neg_lo:[0,1] neg_hi:[0,1]
	s_nop 0
	v_xor_b32_e32 v81, 0x80000000, v18
	v_mov_b32_e32 v80, v19
	v_pk_mul_f32 v[80:81], v[80:81], s[60:61] op_sel_hi:[1,0]
	s_nop 0
	v_pk_fma_f32 v[18:19], v[18:19], s[60:61], v[80:81] op_sel_hi:[1,0,1]
	v_pk_add_f32 v[80:81], v[74:75], v[82:83]
	v_pk_add_f32 v[74:75], v[74:75], v[82:83] neg_lo:[0,1] neg_hi:[0,1]
	s_nop 0
	v_xor_b32_e32 v83, 0x80000000, v74
	v_mov_b32_e32 v82, v75
	v_pk_add_f32 v[74:75], v[76:77], v[84:85]
	v_pk_add_f32 v[76:77], v[76:77], v[84:85] neg_lo:[0,1] neg_hi:[0,1]
	s_nop 0
	v_pk_mul_f32 v[84:85], v[76:77], s[60:61] op_sel_hi:[1,0]
	v_xor_b32_e32 v139, 0x80000000, v76
	v_mov_b32_e32 v138, v77
	v_pk_fma_f32 v[76:77], v[138:139], s[60:61], v[84:85] op_sel_hi:[1,0,1] neg_lo:[0,0,1] neg_hi:[0,0,1]
	v_pk_add_f32 v[84:85], v[132:133], v[62:63]
	v_pk_add_f32 v[62:63], v[132:133], v[62:63] neg_lo:[0,1] neg_hi:[0,1]
	v_pk_add_f32 v[132:133], v[88:89], v[10:11]
	v_pk_add_f32 v[10:11], v[88:89], v[10:11] neg_lo:[0,1] neg_hi:[0,1]
	s_nop 0
	v_xor_b32_e32 v89, 0x80000000, v10
	v_mov_b32_e32 v88, v11
	v_pk_mul_f32 v[88:89], v[88:89], s[60:61] op_sel_hi:[1,0]
	s_nop 0
	v_pk_fma_f32 v[10:11], v[10:11], s[60:61], v[88:89] op_sel_hi:[1,0,1]
	v_pk_add_f32 v[88:89], v[22:23], v[66:67]
	v_pk_add_f32 v[22:23], v[22:23], v[66:67] neg_lo:[0,1] neg_hi:[0,1]
	s_nop 0
	v_xor_b32_e32 v67, 0x80000000, v22
	v_mov_b32_e32 v66, v23
	v_pk_add_f32 v[22:23], v[24:25], v[68:69]
	v_pk_add_f32 v[24:25], v[24:25], v[68:69] neg_lo:[0,1] neg_hi:[0,1]
	s_nop 0
	v_pk_mul_f32 v[68:69], v[24:25], s[60:61] op_sel_hi:[1,0]
	v_xor_b32_e32 v139, 0x80000000, v24
	v_mov_b32_e32 v138, v25
	v_pk_fma_f32 v[24:25], v[138:139], s[60:61], v[68:69] op_sel_hi:[1,0,1] neg_lo:[0,0,1] neg_hi:[0,0,1]
	v_pk_add_f32 v[68:69], v[2:3], v[64:65]
	v_pk_add_f32 v[2:3], v[2:3], v[64:65] neg_lo:[0,1] neg_hi:[0,1]
	v_pk_add_f32 v[64:65], v[4:5], v[12:13]
	v_pk_add_f32 v[4:5], v[4:5], v[12:13] neg_lo:[0,1] neg_hi:[0,1]
	s_nop 0
	v_xor_b32_e32 v13, 0x80000000, v4
	v_mov_b32_e32 v12, v5
	v_pk_mul_f32 v[12:13], v[12:13], s[60:61] op_sel_hi:[1,0]
	s_nop 0
	v_pk_fma_f32 v[4:5], v[4:5], s[60:61], v[12:13] op_sel_hi:[1,0,1]
	v_pk_add_f32 v[12:13], v[6:7], v[14:15]
	v_pk_add_f32 v[6:7], v[6:7], v[14:15] neg_lo:[0,1] neg_hi:[0,1]
	v_pk_add_f32 v[140:141], v[68:69], v[12:13]
	v_xor_b32_e32 v15, 0x80000000, v6
	v_mov_b32_e32 v14, v7
	v_pk_add_f32 v[6:7], v[8:9], v[16:17]
	v_pk_add_f32 v[8:9], v[8:9], v[16:17] neg_lo:[0,1] neg_hi:[0,1]
	v_pk_add_f32 v[142:143], v[64:65], v[6:7]
	v_pk_mul_f32 v[16:17], v[8:9], s[60:61] op_sel_hi:[1,0]
	v_xor_b32_e32 v139, 0x80000000, v8
	v_mov_b32_e32 v138, v9
	v_pk_fma_f32 v[8:9], v[138:139], s[60:61], v[16:17] op_sel_hi:[1,0,1] neg_lo:[0,0,1] neg_hi:[0,0,1]
	v_pk_add_f32 v[16:17], v[70:71], v[136:137]
	v_pk_add_f32 v[70:71], v[70:71], v[136:137] neg_lo:[0,1] neg_hi:[0,1]
	v_pk_add_f32 v[136:137], v[134:135], v[72:73]
	v_pk_add_f32 v[72:73], v[134:135], v[72:73] neg_lo:[0,1] neg_hi:[0,1]
	v_pk_add_f32 v[138:139], v[84:85], v[88:89] neg_lo:[0,1] neg_hi:[0,1]
	v_xor_b32_e32 v135, 0x80000000, v72
	v_mov_b32_e32 v134, v73
	v_pk_add_f32 v[72:73], v[92:93], v[128:129]
	v_pk_add_f32 v[92:93], v[92:93], v[128:129] neg_lo:[0,1] neg_hi:[0,1]
	v_pk_add_f32 v[128:129], v[78:79], v[90:91]
	v_pk_add_f32 v[78:79], v[78:79], v[90:91] neg_lo:[0,1] neg_hi:[0,1]
	v_pk_add_f32 v[6:7], v[64:65], v[6:7] neg_lo:[0,1] neg_hi:[0,1]
	v_xor_b32_e32 v91, 0x80000000, v78
	v_mov_b32_e32 v90, v79
	v_pk_add_f32 v[78:79], v[130:131], v[80:81]
	v_pk_add_f32 v[130:131], v[130:131], v[80:81] neg_lo:[0,1] neg_hi:[0,1]
	v_pk_add_f32 v[80:81], v[94:95], v[74:75]
	v_pk_add_f32 v[74:75], v[94:95], v[74:75] neg_lo:[0,1] neg_hi:[0,1]
	v_xor_b32_e32 v149, 0x80000000, v6
	v_xor_b32_e32 v95, 0x80000000, v74
	v_mov_b32_e32 v94, v75
	v_pk_add_f32 v[74:75], v[86:87], v[82:83]
	v_pk_add_f32 v[82:83], v[86:87], v[82:83] neg_lo:[0,1] neg_hi:[0,1]
	v_pk_add_f32 v[86:87], v[18:19], v[76:77]
	v_pk_add_f32 v[18:19], v[18:19], v[76:77] neg_lo:[0,1] neg_hi:[0,1]
	v_mov_b32_e32 v148, v7
	v_xor_b32_e32 v77, 0x80000000, v18
	v_mov_b32_e32 v76, v19
	v_pk_add_f32 v[18:19], v[84:85], v[88:89]
	v_pk_add_f32 v[88:89], v[132:133], v[22:23]
	v_pk_add_f32 v[22:23], v[132:133], v[22:23] neg_lo:[0,1] neg_hi:[0,1]
	v_pk_add_f32 v[6:7], v[2:3], v[14:15]
	v_xor_b32_e32 v133, 0x80000000, v22
	v_mov_b32_e32 v132, v23
	v_pk_add_f32 v[22:23], v[62:63], v[66:67]
	v_pk_add_f32 v[62:63], v[62:63], v[66:67] neg_lo:[0,1] neg_hi:[0,1]
	v_pk_add_f32 v[66:67], v[10:11], v[24:25]
	v_pk_add_f32 v[10:11], v[10:11], v[24:25] neg_lo:[0,1] neg_hi:[0,1]
	v_pk_add_f32 v[154:155], v[2:3], v[14:15] neg_lo:[0,1] neg_hi:[0,1]
	v_xor_b32_e32 v25, 0x80000000, v10
	v_mov_b32_e32 v24, v11
	v_pk_add_f32 v[2:3], v[4:5], v[8:9] neg_lo:[0,1] neg_hi:[0,1]
	v_pk_add_f32 v[68:69], v[68:69], v[12:13] neg_lo:[0,1] neg_hi:[0,1]
	v_pk_add_f32 v[156:157], v[4:5], v[8:9]
	v_xor_b32_e32 v159, 0x80000000, v2
	v_mov_b32_e32 v158, v3
	v_pk_add_f32 v[2:3], v[16:17], v[136:137]
	v_pk_add_f32 v[84:85], v[16:17], v[136:137] neg_lo:[0,1] neg_hi:[0,1]
	v_pk_add_f32 v[136:137], v[70:71], v[134:135]
	v_pk_add_f32 v[16:17], v[70:71], v[134:135] neg_lo:[0,1] neg_hi:[0,1]
	v_pk_add_f32 v[134:135], v[72:73], v[128:129]
	v_pk_add_f32 v[70:71], v[72:73], v[128:129] neg_lo:[0,1] neg_hi:[0,1]
	v_pk_add_f32 v[128:129], v[92:93], v[90:91]
	v_pk_add_f32 v[8:9], v[92:93], v[90:91] neg_lo:[0,1] neg_hi:[0,1]
	v_pk_add_f32 v[72:73], v[78:79], v[80:81]
	v_pk_add_f32 v[80:81], v[78:79], v[80:81] neg_lo:[0,1] neg_hi:[0,1]
	v_pk_add_f32 v[92:93], v[130:131], v[94:95]
	v_pk_add_f32 v[12:13], v[130:131], v[94:95] neg_lo:[0,1] neg_hi:[0,1]
	v_pk_add_f32 v[78:79], v[74:75], v[86:87]
	v_pk_add_f32 v[64:65], v[74:75], v[86:87] neg_lo:[0,1] neg_hi:[0,1]
	v_pk_add_f32 v[130:131], v[82:83], v[76:77]
	v_pk_add_f32 v[4:5], v[82:83], v[76:77] neg_lo:[0,1] neg_hi:[0,1]
	v_pk_add_f32 v[76:77], v[18:19], v[88:89]
	v_pk_add_f32 v[88:89], v[18:19], v[88:89] neg_lo:[0,1] neg_hi:[0,1]
	v_pk_add_f32 v[86:87], v[138:139], v[132:133]
	v_pk_add_f32 v[18:19], v[138:139], v[132:133] neg_lo:[0,1] neg_hi:[0,1]
	v_pk_add_f32 v[132:133], v[62:63], v[24:25]
	v_pk_add_f32 v[10:11], v[62:63], v[24:25] neg_lo:[0,1] neg_hi:[0,1]
	v_pk_mul_f32 v[24:25], v[20:21], v[20:21]
	v_xor_b32_e32 v62, 0x80000000, v21
	v_mov_b32_e32 v63, v20
	v_pk_add_f32 v[24:25], v[24:25], v[24:25] op_sel:[0,1] op_sel_hi:[0,1] neg_lo:[0,1] neg_hi:[0,1]
	v_pk_mul_f32 v[62:63], v[62:63], v[26:27] op_sel_hi:[1,0]
	v_pk_add_f32 v[90:91], v[22:23], v[66:67]
	v_pk_add_f32 v[74:75], v[22:23], v[66:67] neg_lo:[0,1] neg_hi:[0,1]
	v_pk_add_f32 v[22:23], v[140:141], v[142:143]
	v_pk_add_f32 v[82:83], v[140:141], v[142:143] neg_lo:[0,1] neg_hi:[0,1]
	v_pk_add_f32 v[138:139], v[68:69], v[148:149]
	v_pk_add_f32 v[14:15], v[68:69], v[148:149] neg_lo:[0,1] neg_hi:[0,1]
	v_pk_fma_f32 v[68:69], v[20:21], v[24:25], v[62:63]
	v_xor_b32_e32 v63, 0x80000000, v76
	v_mov_b32_e32 v62, v77
	v_mov_b32_e32 v142, v21
	v_pk_mul_f32 v[62:63], v[142:143], v[62:63] op_sel_hi:[0,1]
	v_pk_fma_f32 v[20:21], v[20:21], v[76:77], v[62:63] op_sel_hi:[0,1,1]
	v_pk_mul_f32 v[62:63], v[26:27], s[46:47] op_sel_hi:[0,1]
	v_pk_fma_f32 v[76:77], v[24:25], s[40:41], v[62:63]
	v_xor_b32_e32 v63, 0x80000000, v72
	v_mov_b32_e32 v62, v73
	v_pk_mul_f32 v[62:63], v[76:77], v[62:63] op_sel:[1,0]
	v_pk_add_f32 v[94:95], v[6:7], v[156:157]
	v_pk_fma_f32 v[62:63], v[72:73], v[76:77], v[62:63] op_sel_hi:[1,0,1]
	v_xor_b32_e32 v72, 0x80000000, v69
	v_mov_b32_e32 v73, v68
	v_pk_mul_f32 v[72:73], v[26:27], v[72:73] op_sel_hi:[0,1]
	v_pk_fma_f32 v[142:143], v[24:25], v[68:69], v[72:73]
	v_xor_b32_e32 v73, 0x80000000, v22
	v_mov_b32_e32 v72, v23
	v_pk_mul_f32 v[72:73], v[68:69], v[72:73] op_sel:[1,0]
	v_pk_add_f32 v[140:141], v[154:155], v[158:159]
	v_pk_fma_f32 v[22:23], v[68:69], v[22:23], v[72:73] op_sel_hi:[0,1,1]
	v_xor_b32_e32 v68, 0x80000000, v77
	v_mov_b32_e32 v69, v76
	v_pk_mul_f32 v[68:69], v[26:27], v[68:69] op_sel_hi:[0,1]
	v_pk_fma_f32 v[76:77], v[24:25], v[76:77], v[68:69]
	v_xor_b32_e32 v69, 0x80000000, v134
	v_mov_b32_e32 v68, v135
	v_pk_mul_f32 v[68:69], v[68:69], v[76:77] op_sel:[0,1]
	v_pk_add_f32 v[66:67], v[6:7], v[156:157] neg_lo:[0,1] neg_hi:[0,1]
	v_pk_fma_f32 v[72:73], v[134:135], v[76:77], v[68:69] op_sel_hi:[1,0,1]
	v_xor_b32_e32 v68, 0x80000000, v143
	v_mov_b32_e32 v69, v142
	v_pk_mul_f32 v[68:69], v[26:27], v[68:69] op_sel_hi:[0,1]
	v_pk_fma_f32 v[134:135], v[24:25], v[142:143], v[68:69]
	v_xor_b32_e32 v69, 0x80000000, v90
	v_mov_b32_e32 v68, v91
	v_pk_mul_f32 v[68:69], v[142:143], v[68:69] op_sel:[1,0]
	v_pk_add_f32 v[6:7], v[154:155], v[158:159] neg_lo:[0,1] neg_hi:[0,1]
	v_pk_fma_f32 v[68:69], v[90:91], v[142:143], v[68:69] op_sel_hi:[1,0,1]
	v_xor_b32_e32 v90, 0x80000000, v77
	v_mov_b32_e32 v91, v76
	v_pk_mul_f32 v[90:91], v[26:27], v[90:91] op_sel_hi:[0,1]
	v_pk_fma_f32 v[90:91], v[24:25], v[76:77], v[90:91]
	v_xor_b32_e32 v77, 0x80000000, v78
	v_mov_b32_e32 v76, v79
	v_pk_mul_f32 v[76:77], v[76:77], v[90:91] op_sel:[0,1]
	s_nop 0
	v_pk_fma_f32 v[78:79], v[78:79], v[90:91], v[76:77] op_sel_hi:[1,0,1]
	v_xor_b32_e32 v76, 0x80000000, v135
	v_mov_b32_e32 v77, v134
	v_pk_mul_f32 v[76:77], v[26:27], v[76:77] op_sel_hi:[0,1]
	v_pk_fma_f32 v[142:143], v[24:25], v[134:135], v[76:77]
	v_xor_b32_e32 v77, 0x80000000, v94
	v_mov_b32_e32 v76, v95
	v_pk_mul_f32 v[76:77], v[134:135], v[76:77] op_sel:[1,0]
	s_nop 0
	v_pk_fma_f32 v[76:77], v[94:95], v[134:135], v[76:77] op_sel_hi:[1,0,1]
	v_xor_b32_e32 v94, 0x80000000, v91
	v_mov_b32_e32 v95, v90
	v_pk_mul_f32 v[94:95], v[26:27], v[94:95] op_sel_hi:[0,1]
	v_pk_fma_f32 v[94:95], v[24:25], v[90:91], v[94:95]
	v_xor_b32_e32 v91, 0x80000000, v136
	v_mov_b32_e32 v90, v137
	v_pk_mul_f32 v[90:91], v[90:91], v[94:95] op_sel:[0,1]
	v_xor_b32_e32 v134, 0x80000000, v143
	v_pk_fma_f32 v[90:91], v[136:137], v[94:95], v[90:91] op_sel_hi:[1,0,1]
	v_xor_b32_e32 v137, 0x80000000, v86
	v_mov_b32_e32 v136, v87
	v_pk_mul_f32 v[136:137], v[136:137], v[142:143] op_sel:[0,1]
	v_mov_b32_e32 v135, v142
	v_pk_fma_f32 v[86:87], v[86:87], v[142:143], v[136:137] op_sel_hi:[1,0,1]
	v_xor_b32_e32 v136, 0x80000000, v95
	v_mov_b32_e32 v137, v94
	v_pk_mul_f32 v[136:137], v[26:27], v[136:137] op_sel_hi:[0,1]
	v_pk_mul_f32 v[134:135], v[26:27], v[134:135] op_sel_hi:[0,1]
	v_pk_fma_f32 v[136:137], v[24:25], v[94:95], v[136:137]
	v_xor_b32_e32 v95, 0x80000000, v92
	v_mov_b32_e32 v94, v93
	v_pk_fma_f32 v[134:135], v[24:25], v[142:143], v[134:135]
	v_pk_mul_f32 v[94:95], v[94:95], v[136:137] op_sel:[0,1]
	s_nop 0
	v_pk_fma_f32 v[94:95], v[92:93], v[136:137], v[94:95] op_sel_hi:[1,0,1]
	v_xor_b32_e32 v92, 0x80000000, v135
	v_mov_b32_e32 v93, v134
	v_pk_mul_f32 v[92:93], v[26:27], v[92:93] op_sel_hi:[0,1]
	v_pk_fma_f32 v[142:143], v[24:25], v[134:135], v[92:93]
	v_xor_b32_e32 v93, 0x80000000, v138
	v_mov_b32_e32 v92, v139
	v_pk_mul_f32 v[92:93], v[92:93], v[134:135] op_sel:[0,1]
	s_nop 0
	v_pk_fma_f32 v[92:93], v[138:139], v[134:135], v[92:93] op_sel_hi:[1,0,1]
	v_xor_b32_e32 v134, 0x80000000, v137
	v_mov_b32_e32 v135, v136
	v_pk_mul_f32 v[134:135], v[26:27], v[134:135] op_sel_hi:[0,1]
	v_xor_b32_e32 v139, 0x80000000, v132
	v_mov_b32_e32 v138, v133
	v_pk_fma_f32 v[134:135], v[24:25], v[136:137], v[134:135]
	v_xor_b32_e32 v137, 0x80000000, v128
	v_mov_b32_e32 v136, v129
	v_pk_mul_f32 v[138:139], v[138:139], v[142:143] op_sel:[0,1]
	v_pk_mul_f32 v[136:137], v[136:137], v[134:135] op_sel:[0,1]
	v_pk_fma_f32 v[132:133], v[132:133], v[142:143], v[138:139] op_sel_hi:[1,0,1]
	v_xor_b32_e32 v138, 0x80000000, v135
	v_mov_b32_e32 v139, v134
	v_pk_fma_f32 v[128:129], v[128:129], v[134:135], v[136:137] op_sel_hi:[1,0,1]
	v_xor_b32_e32 v136, 0x80000000, v143
	v_mov_b32_e32 v137, v142
	v_pk_mul_f32 v[138:139], v[26:27], v[138:139] op_sel_hi:[0,1]
	v_pk_mul_f32 v[136:137], v[26:27], v[136:137] op_sel_hi:[0,1]
	v_pk_fma_f32 v[134:135], v[24:25], v[134:135], v[138:139]
	v_xor_b32_e32 v139, 0x80000000, v130
	v_mov_b32_e32 v138, v131
	v_pk_fma_f32 v[136:137], v[24:25], v[142:143], v[136:137]
	v_pk_mul_f32 v[138:139], v[138:139], v[134:135] op_sel:[0,1]
	v_xor_b32_e32 v143, 0x80000000, v140
	v_pk_fma_f32 v[130:131], v[130:131], v[134:135], v[138:139] op_sel_hi:[1,0,1]
	v_xor_b32_e32 v138, 0x80000000, v137
	v_mov_b32_e32 v139, v136
	v_mov_b32_e32 v142, v141
	v_pk_mul_f32 v[138:139], v[26:27], v[138:139] op_sel_hi:[0,1]
	v_pk_mul_f32 v[142:143], v[142:143], v[136:137] op_sel:[0,1]
	v_pk_fma_f32 v[138:139], v[24:25], v[136:137], v[138:139]
	v_pk_fma_f32 v[136:137], v[140:141], v[136:137], v[142:143] op_sel_hi:[1,0,1]
	v_xor_b32_e32 v140, 0x80000000, v135
	v_mov_b32_e32 v141, v134
	v_pk_mul_f32 v[140:141], v[26:27], v[140:141] op_sel_hi:[0,1]
	v_pk_fma_f32 v[134:135], v[24:25], v[134:135], v[140:141]
	v_xor_b32_e32 v141, 0x80000000, v84
	v_mov_b32_e32 v140, v85
	v_pk_mul_f32 v[140:141], v[140:141], v[134:135] op_sel:[0,1]
	v_xor_b32_e32 v143, 0x80000000, v88
	v_pk_fma_f32 v[84:85], v[84:85], v[134:135], v[140:141] op_sel_hi:[1,0,1]
	v_xor_b32_e32 v140, 0x80000000, v139
	v_mov_b32_e32 v141, v138
	v_mov_b32_e32 v142, v89
	v_pk_mul_f32 v[140:141], v[26:27], v[140:141] op_sel_hi:[0,1]
	v_pk_mul_f32 v[142:143], v[142:143], v[138:139] op_sel:[0,1]
	v_pk_fma_f32 v[140:141], v[24:25], v[138:139], v[140:141]
	v_pk_fma_f32 v[88:89], v[88:89], v[138:139], v[142:143] op_sel_hi:[1,0,1]
	v_xor_b32_e32 v138, 0x80000000, v135
	v_mov_b32_e32 v139, v134
	v_pk_mul_f32 v[138:139], v[26:27], v[138:139] op_sel_hi:[0,1]
	v_pk_fma_f32 v[134:135], v[24:25], v[134:135], v[138:139]
	v_xor_b32_e32 v139, 0x80000000, v80
	v_mov_b32_e32 v138, v81
	v_pk_mul_f32 v[138:139], v[138:139], v[134:135] op_sel:[0,1]
	v_xor_b32_e32 v143, 0x80000000, v82
	v_pk_fma_f32 v[80:81], v[80:81], v[134:135], v[138:139] op_sel_hi:[1,0,1]
	v_xor_b32_e32 v138, 0x80000000, v141
	v_mov_b32_e32 v139, v140
	v_mov_b32_e32 v142, v83
	v_pk_mul_f32 v[138:139], v[26:27], v[138:139] op_sel_hi:[0,1]
	v_pk_mul_f32 v[142:143], v[142:143], v[140:141] op_sel:[0,1]
	v_pk_fma_f32 v[138:139], v[24:25], v[140:141], v[138:139]
	v_pk_fma_f32 v[82:83], v[82:83], v[140:141], v[142:143] op_sel_hi:[1,0,1]
	v_xor_b32_e32 v140, 0x80000000, v135
	v_mov_b32_e32 v141, v134
	v_pk_mul_f32 v[140:141], v[26:27], v[140:141] op_sel_hi:[0,1]
	v_pk_fma_f32 v[134:135], v[24:25], v[134:135], v[140:141]
	v_xor_b32_e32 v141, 0x80000000, v70
	v_mov_b32_e32 v140, v71
	v_pk_mul_f32 v[140:141], v[140:141], v[134:135] op_sel:[0,1]
	v_xor_b32_e32 v143, 0x80000000, v74
	v_pk_fma_f32 v[70:71], v[70:71], v[134:135], v[140:141] op_sel_hi:[1,0,1]
	v_xor_b32_e32 v140, 0x80000000, v139
	v_mov_b32_e32 v141, v138
	v_mov_b32_e32 v142, v75
	v_pk_mul_f32 v[140:141], v[26:27], v[140:141] op_sel_hi:[0,1]
	v_pk_mul_f32 v[142:143], v[142:143], v[138:139] op_sel:[0,1]
	v_pk_fma_f32 v[140:141], v[24:25], v[138:139], v[140:141]
	v_pk_fma_f32 v[74:75], v[74:75], v[138:139], v[142:143] op_sel_hi:[1,0,1]
	v_xor_b32_e32 v138, 0x80000000, v135
	v_mov_b32_e32 v139, v134
	v_pk_mul_f32 v[138:139], v[26:27], v[138:139] op_sel_hi:[0,1]
	v_pk_fma_f32 v[134:135], v[24:25], v[134:135], v[138:139]
	v_xor_b32_e32 v139, 0x80000000, v64
	v_mov_b32_e32 v138, v65
	v_pk_mul_f32 v[138:139], v[138:139], v[134:135] op_sel:[0,1]
	v_xor_b32_e32 v143, 0x80000000, v66
	v_pk_fma_f32 v[64:65], v[64:65], v[134:135], v[138:139] op_sel_hi:[1,0,1]
	v_xor_b32_e32 v138, 0x80000000, v141
	v_mov_b32_e32 v139, v140
	v_mov_b32_e32 v142, v67
	v_pk_mul_f32 v[138:139], v[26:27], v[138:139] op_sel_hi:[0,1]
	v_pk_mul_f32 v[142:143], v[142:143], v[140:141] op_sel:[0,1]
	v_pk_fma_f32 v[138:139], v[24:25], v[140:141], v[138:139]
	v_pk_fma_f32 v[66:67], v[66:67], v[140:141], v[142:143] op_sel_hi:[1,0,1]
	v_xor_b32_e32 v140, 0x80000000, v135
	v_mov_b32_e32 v141, v134
	v_pk_mul_f32 v[140:141], v[26:27], v[140:141] op_sel_hi:[0,1]
	v_pk_fma_f32 v[134:135], v[24:25], v[134:135], v[140:141]
	v_xor_b32_e32 v141, 0x80000000, v16
	v_mov_b32_e32 v140, v17
	v_pk_mul_f32 v[140:141], v[140:141], v[134:135] op_sel:[0,1]
	v_xor_b32_e32 v143, 0x80000000, v18
	v_pk_fma_f32 v[16:17], v[16:17], v[134:135], v[140:141] op_sel_hi:[1,0,1]
	v_xor_b32_e32 v140, 0x80000000, v139
	v_mov_b32_e32 v141, v138
	v_mov_b32_e32 v142, v19
	v_pk_mul_f32 v[140:141], v[26:27], v[140:141] op_sel_hi:[0,1]
	v_pk_mul_f32 v[142:143], v[142:143], v[138:139] op_sel:[0,1]
	v_pk_fma_f32 v[140:141], v[24:25], v[138:139], v[140:141]
	v_pk_fma_f32 v[18:19], v[18:19], v[138:139], v[142:143] op_sel_hi:[1,0,1]
	v_xor_b32_e32 v138, 0x80000000, v135
	v_mov_b32_e32 v139, v134
	v_pk_mul_f32 v[138:139], v[26:27], v[138:139] op_sel_hi:[0,1]
	v_pk_fma_f32 v[134:135], v[24:25], v[134:135], v[138:139]
	v_xor_b32_e32 v139, 0x80000000, v12
	v_mov_b32_e32 v138, v13
	v_pk_mul_f32 v[138:139], v[138:139], v[134:135] op_sel:[0,1]
	v_xor_b32_e32 v143, 0x80000000, v14
	v_pk_fma_f32 v[12:13], v[12:13], v[134:135], v[138:139] op_sel_hi:[1,0,1]
	v_xor_b32_e32 v138, 0x80000000, v141
	v_mov_b32_e32 v139, v140
	v_mov_b32_e32 v142, v15
	v_pk_mul_f32 v[138:139], v[26:27], v[138:139] op_sel_hi:[0,1]
	v_pk_mul_f32 v[142:143], v[142:143], v[140:141] op_sel:[0,1]
	v_pk_fma_f32 v[138:139], v[24:25], v[140:141], v[138:139]
	v_pk_fma_f32 v[14:15], v[14:15], v[140:141], v[142:143] op_sel_hi:[1,0,1]
	v_xor_b32_e32 v140, 0x80000000, v135
	v_mov_b32_e32 v141, v134
	v_pk_mul_f32 v[140:141], v[26:27], v[140:141] op_sel_hi:[0,1]
	v_pk_fma_f32 v[134:135], v[24:25], v[134:135], v[140:141]
	v_xor_b32_e32 v141, 0x80000000, v8
	v_mov_b32_e32 v140, v9
	v_pk_mul_f32 v[140:141], v[140:141], v[134:135] op_sel:[0,1]
	v_xor_b32_e32 v143, 0x80000000, v10
	v_pk_fma_f32 v[8:9], v[8:9], v[134:135], v[140:141] op_sel_hi:[1,0,1]
	v_xor_b32_e32 v140, 0x80000000, v139
	v_mov_b32_e32 v141, v138
	v_mov_b32_e32 v142, v11
	v_pk_mul_f32 v[140:141], v[26:27], v[140:141] op_sel_hi:[0,1]
	v_pk_mul_f32 v[142:143], v[142:143], v[138:139] op_sel:[0,1]
	v_pk_fma_f32 v[140:141], v[24:25], v[138:139], v[140:141]
	v_pk_fma_f32 v[10:11], v[10:11], v[138:139], v[142:143] op_sel_hi:[1,0,1]
	v_xor_b32_e32 v138, 0x80000000, v135
	v_mov_b32_e32 v139, v134
	v_pk_mul_f32 v[138:139], v[26:27], v[138:139] op_sel_hi:[0,1]
	v_pk_fma_f32 v[24:25], v[24:25], v[134:135], v[138:139]
	v_xor_b32_e32 v135, 0x80000000, v4
	v_mov_b32_e32 v134, v5
	v_pk_mul_f32 v[134:135], v[134:135], v[24:25] op_sel:[0,1]
	s_nop 0
	v_pk_fma_f32 v[4:5], v[4:5], v[24:25], v[134:135] op_sel_hi:[1,0,1]
	v_xor_b32_e32 v25, 0x80000000, v6
	v_mov_b32_e32 v24, v7
	v_pk_mul_f32 v[24:25], v[24:25], v[140:141] op_sel:[0,1]
	s_nop 0
	v_pk_fma_f32 v[6:7], v[6:7], v[140:141], v[24:25] op_sel_hi:[1,0,1]
	ds_write_b64 v27, v[2:3]
	ds_write_b64 v96, v[84:85]
	ds_write_b64 v97, v[90:91] offset:256
	ds_write_b64 v98, v[16:17] offset:256
	ds_write_b64 v99, v[72:73] offset:512
	ds_write_b64 v100, v[70:71] offset:512
	ds_write_b64 v101, v[128:129] offset:768
	ds_write_b64 v102, v[8:9] offset:768
	ds_write_b64 v103, v[62:63] offset:1024
	ds_write_b64 v104, v[80:81] offset:1024
	ds_write_b64 v105, v[94:95] offset:1280
	ds_write_b64 v106, v[12:13] offset:1280
	ds_write_b64 v107, v[78:79] offset:1536
	ds_write_b64 v108, v[64:65] offset:1536
	ds_write_b64 v109, v[130:131] offset:1792
	ds_write_b64 v110, v[4:5] offset:1792
	ds_write_b64 v111, v[20:21] offset:2048
	ds_write_b64 v112, v[88:89] offset:2048
	ds_write_b64 v113, v[86:87] offset:2304
	ds_write_b64 v114, v[18:19] offset:2304
	ds_write_b64 v115, v[68:69] offset:2560
	ds_write_b64 v116, v[74:75] offset:2560
	ds_write_b64 v117, v[132:133] offset:2816
	ds_write_b64 v118, v[10:11] offset:2816
	ds_write_b64 v119, v[22:23] offset:3072
	ds_write_b64 v120, v[82:83] offset:3072
	ds_write_b64 v121, v[92:93] offset:3328
	ds_write_b64 v122, v[14:15] offset:3328
	ds_write_b64 v123, v[76:77] offset:3584
	ds_write_b64 v124, v[66:67] offset:3584
	ds_write_b64 v125, v[136:137] offset:3840
	ds_write_b64 v126, v[6:7] offset:3840
	v_mov_b32_e32 v2, v146
	s_waitcnt lgkmcnt(0)
	s_barrier
	s_nop 0
	v_lshlrev_b32_e32 v3, 4, v2
	v_lshrrev_b32_e32 v4, 1, v2
	v_bfe_u32 v2, v2, 1, 4
	v_bitop3_b32 v5, v4, v3, 16 bitop3:0x6c
	v_lshl_add_u32 v5, v5, 3, 16
	v_lshlrev_b32_e32 v2, 3, v2
	v_add_u32_e32 v6, v5, v2
	ds_read_b64 v[12:13], v6
	v_bitop3_b32 v6, v4, 1, 15 bitop3:0x6c
	v_lshlrev_b32_e32 v8, 3, v6
	v_add_u32_e32 v6, v5, v8
	ds_read_b64 v[14:15], v6
	v_bitop3_b32 v6, v4, 2, 15 bitop3:0x6c
	v_lshlrev_b32_e32 v9, 3, v6
	v_add_u32_e32 v6, v5, v9
	ds_read_b64 v[16:17], v6
	v_bitop3_b32 v6, v4, 3, 15 bitop3:0x6c
	v_lshlrev_b32_e32 v10, 3, v6
	v_add_u32_e32 v6, v5, v10
	ds_read_b64 v[18:19], v6
	v_bitop3_b32 v6, v4, 4, 15 bitop3:0x6c
	v_lshlrev_b32_e32 v11, 3, v6
	v_add_u32_e32 v6, v5, v11
	ds_read_b64 v[20:21], v6
	v_bitop3_b32 v6, v4, 5, 15 bitop3:0x6c
	v_lshlrev_b32_e32 v82, 3, v6
	v_add_u32_e32 v6, v5, v82
	ds_read_b64 v[22:23], v6
	v_bitop3_b32 v6, v4, 6, 15 bitop3:0x6c
	v_lshlrev_b32_e32 v83, 3, v6
	v_add_u32_e32 v6, v5, v83
	ds_read_b64 v[24:25], v6
	v_bitop3_b32 v6, v4, 7, 15 bitop3:0x6c
	v_lshlrev_b32_e32 v84, 3, v6
	v_add_u32_e32 v6, v5, v84
	ds_read_b64 v[26:27], v6
	v_bitop3_b32 v6, v4, 8, 15 bitop3:0x6c
	v_lshlrev_b32_e32 v85, 3, v6
	v_add_u32_e32 v6, v5, v85
	ds_read_b64 v[62:63], v6
	v_bitop3_b32 v6, v4, 9, 15 bitop3:0x6c
	v_lshlrev_b32_e32 v86, 3, v6
	v_add_u32_e32 v6, v5, v86
	ds_read_b64 v[64:65], v6
	v_bitop3_b32 v6, v4, 10, 15 bitop3:0x6c
	v_lshlrev_b32_e32 v87, 3, v6
	v_add_u32_e32 v6, v5, v87
	ds_read_b64 v[66:67], v6
	v_bitop3_b32 v6, v4, 11, 15 bitop3:0x6c
	v_lshlrev_b32_e32 v88, 3, v6
	v_add_u32_e32 v6, v5, v88
	ds_read_b64 v[68:69], v6
	v_bitop3_b32 v6, v4, 12, 15 bitop3:0x6c
	v_lshlrev_b32_e32 v89, 3, v6
	v_add_u32_e32 v6, v5, v89
	ds_read_b64 v[70:71], v6
	v_bitop3_b32 v6, v4, 13, 15 bitop3:0x6c
	v_lshlrev_b32_e32 v90, 3, v6
	v_add_u32_e32 v6, v5, v90
	ds_read_b64 v[72:73], v6
	v_bitop3_b32 v6, v4, 14, 15 bitop3:0x6c
	v_lshlrev_b32_e32 v91, 3, v6
	v_add_u32_e32 v6, v5, v91
	v_add_u32_e32 v3, 0x2000, v3
	ds_read_b64 v[74:75], v6
	v_bitop3_b32 v6, v4, 15, v4 bitop3:0xc
	v_bitop3_b32 v3, v3, v4, 16 bitop3:0x78
	v_lshlrev_b32_e32 v106, 3, v6
	v_lshl_add_u32 v107, v3, 3, 16
	v_add_u32_e32 v5, v5, v106
	v_add_u32_e32 v2, v107, v2
	ds_read_b64 v[76:77], v5
	ds_read_b64 v[6:7], v2
	v_add_u32_e32 v2, v107, v8
	ds_read_b64 v[78:79], v2
	v_add_u32_e32 v2, v107, v9
	ds_read_b64 v[8:9], v2
	v_add_u32_e32 v2, v107, v10
	ds_read_b64 v[80:81], v2
	v_add_u32_e32 v2, v107, v11
	ds_read_b64 v[10:11], v2
	v_add_u32_e32 v2, v107, v82
	v_add_u32_e32 v82, v107, v84
	v_add_u32_e32 v84, v107, v85
	ds_read_b64 v[4:5], v2
	ds_read_b64 v[92:93], v84
	v_add_u32_e32 v2, v107, v83
	v_add_u32_e32 v84, v107, v86
	ds_read_b64 v[2:3], v2
	ds_read_b64 v[82:83], v82
	ds_read_b64 v[94:95], v84
	v_add_u32_e32 v84, v107, v87
	ds_read_b64 v[96:97], v84
	v_add_u32_e32 v84, v107, v88
	ds_read_b64 v[98:99], v84
	v_add_u32_e32 v84, v107, v89
	ds_read_b64 v[100:101], v84
	v_add_u32_e32 v84, v107, v90
	ds_read_b64 v[102:103], v84
	v_add_u32_e32 v84, v107, v91
	ds_read_b64 v[104:105], v84
	v_add_u32_e32 v84, v107, v106
	ds_read_b64 v[106:107], v84
	s_waitcnt lgkmcnt(14)
	v_pk_add_f32 v[84:85], v[12:13], v[62:63]
	v_pk_add_f32 v[12:13], v[12:13], v[62:63] neg_lo:[0,1] neg_hi:[0,1]
	v_pk_add_f32 v[62:63], v[14:15], v[64:65]
	v_pk_add_f32 v[14:15], v[14:15], v[64:65] neg_lo:[0,1] neg_hi:[0,1]
	s_nop 0
	v_xor_b32_e32 v65, 0x80000000, v14
	v_mov_b32_e32 v64, v15
	v_pk_mul_f32 v[64:65], v[64:65], s[54:55] op_sel_hi:[1,0]
	s_nop 0
	v_pk_fma_f32 v[14:15], v[14:15], s[52:53], v[64:65] op_sel_hi:[1,0,1]
	v_pk_add_f32 v[64:65], v[16:17], v[66:67]
	v_pk_add_f32 v[16:17], v[16:17], v[66:67] neg_lo:[0,1] neg_hi:[0,1]
	s_nop 0
	v_xor_b32_e32 v67, 0x80000000, v16
	v_mov_b32_e32 v66, v17
	v_pk_mul_f32 v[66:67], v[66:67], s[60:61] op_sel_hi:[1,0]
	s_nop 0
	v_pk_fma_f32 v[16:17], v[16:17], s[60:61], v[66:67] op_sel_hi:[1,0,1]
	v_pk_add_f32 v[66:67], v[18:19], v[68:69]
	v_pk_add_f32 v[18:19], v[18:19], v[68:69] neg_lo:[0,1] neg_hi:[0,1]
	s_nop 0
	v_xor_b32_e32 v69, 0x80000000, v18
	v_mov_b32_e32 v68, v19
	v_pk_mul_f32 v[68:69], v[68:69], s[52:53] op_sel_hi:[1,0]
	s_nop 0
	v_pk_fma_f32 v[18:19], v[18:19], s[54:55], v[68:69] op_sel_hi:[1,0,1]
	v_pk_add_f32 v[68:69], v[20:21], v[70:71]
	v_pk_add_f32 v[20:21], v[20:21], v[70:71] neg_lo:[0,1] neg_hi:[0,1]
	s_nop 0
	v_xor_b32_e32 v71, 0x80000000, v20
	v_mov_b32_e32 v70, v21
	v_pk_add_f32 v[20:21], v[22:23], v[72:73]
	v_pk_add_f32 v[22:23], v[22:23], v[72:73] neg_lo:[0,1] neg_hi:[0,1]
	s_nop 0
	v_pk_mul_f32 v[72:73], v[22:23], s[54:55] op_sel_hi:[1,0]
	v_xor_b32_e32 v87, 0x80000000, v22
	v_mov_b32_e32 v86, v23
	v_pk_fma_f32 v[22:23], v[86:87], s[52:53], v[72:73] op_sel_hi:[1,0,1] neg_lo:[0,0,1] neg_hi:[0,0,1]
	v_pk_add_f32 v[72:73], v[24:25], v[74:75]
	v_pk_add_f32 v[24:25], v[24:25], v[74:75] neg_lo:[0,1] neg_hi:[0,1]
	s_nop 0
	v_pk_mul_f32 v[74:75], v[24:25], s[60:61] op_sel_hi:[1,0]
	v_xor_b32_e32 v87, 0x80000000, v24
	v_mov_b32_e32 v86, v25
	v_pk_fma_f32 v[24:25], v[86:87], s[60:61], v[74:75] op_sel_hi:[1,0,1] neg_lo:[0,0,1] neg_hi:[0,0,1]
	v_pk_add_f32 v[74:75], v[26:27], v[76:77]
	v_pk_add_f32 v[26:27], v[26:27], v[76:77] neg_lo:[0,1] neg_hi:[0,1]
	s_nop 0
	v_pk_mul_f32 v[76:77], v[26:27], s[52:53] op_sel_hi:[1,0]
	v_xor_b32_e32 v87, 0x80000000, v26
	v_mov_b32_e32 v86, v27
	v_pk_fma_f32 v[26:27], v[86:87], s[54:55], v[76:77] op_sel_hi:[1,0,1] neg_lo:[0,0,1] neg_hi:[0,0,1]
	v_pk_add_f32 v[76:77], v[84:85], v[68:69]
	v_pk_add_f32 v[68:69], v[84:85], v[68:69] neg_lo:[0,1] neg_hi:[0,1]
	v_pk_add_f32 v[84:85], v[62:63], v[20:21]
	v_pk_add_f32 v[20:21], v[62:63], v[20:21] neg_lo:[0,1] neg_hi:[0,1]
	s_nop 0
	v_xor_b32_e32 v63, 0x80000000, v20
	v_mov_b32_e32 v62, v21
	v_pk_mul_f32 v[62:63], v[62:63], s[60:61] op_sel_hi:[1,0]
	s_nop 0
	v_pk_fma_f32 v[20:21], v[20:21], s[60:61], v[62:63] op_sel_hi:[1,0,1]
	v_pk_add_f32 v[62:63], v[64:65], v[72:73]
	v_pk_add_f32 v[64:65], v[64:65], v[72:73] neg_lo:[0,1] neg_hi:[0,1]
	s_nop 0
	v_xor_b32_e32 v73, 0x80000000, v64
	v_mov_b32_e32 v72, v65
	v_pk_add_f32 v[64:65], v[66:67], v[74:75]
	v_pk_add_f32 v[66:67], v[66:67], v[74:75] neg_lo:[0,1] neg_hi:[0,1]
	s_nop 0
	v_pk_mul_f32 v[74:75], v[66:67], s[60:61] op_sel_hi:[1,0]
	v_xor_b32_e32 v87, 0x80000000, v66
	v_mov_b32_e32 v86, v67
	v_pk_fma_f32 v[66:67], v[86:87], s[60:61], v[74:75] op_sel_hi:[1,0,1] neg_lo:[0,0,1] neg_hi:[0,0,1]
	v_pk_add_f32 v[74:75], v[12:13], v[70:71]
	v_pk_add_f32 v[12:13], v[12:13], v[70:71] neg_lo:[0,1] neg_hi:[0,1]
	v_pk_add_f32 v[70:71], v[14:15], v[22:23]
	v_pk_add_f32 v[14:15], v[14:15], v[22:23] neg_lo:[0,1] neg_hi:[0,1]
	s_nop 0
	v_xor_b32_e32 v23, 0x80000000, v14
	v_mov_b32_e32 v22, v15
	v_pk_mul_f32 v[22:23], v[22:23], s[60:61] op_sel_hi:[1,0]
	s_nop 0
	v_pk_fma_f32 v[14:15], v[14:15], s[60:61], v[22:23] op_sel_hi:[1,0,1]
	v_pk_add_f32 v[22:23], v[16:17], v[24:25]
	v_pk_add_f32 v[16:17], v[16:17], v[24:25] neg_lo:[0,1] neg_hi:[0,1]
	s_nop 0
	v_xor_b32_e32 v25, 0x80000000, v16
	v_mov_b32_e32 v24, v17
	v_pk_add_f32 v[16:17], v[18:19], v[26:27]
	v_pk_add_f32 v[18:19], v[18:19], v[26:27] neg_lo:[0,1] neg_hi:[0,1]
	v_pk_add_f32 v[108:109], v[12:13], v[24:25]
	v_pk_mul_f32 v[26:27], v[18:19], s[60:61] op_sel_hi:[1,0]
	v_xor_b32_e32 v87, 0x80000000, v18
	v_mov_b32_e32 v86, v19
	v_pk_fma_f32 v[18:19], v[86:87], s[60:61], v[26:27] op_sel_hi:[1,0,1] neg_lo:[0,0,1] neg_hi:[0,0,1]
	v_pk_add_f32 v[26:27], v[76:77], v[62:63]
	v_pk_add_f32 v[62:63], v[76:77], v[62:63] neg_lo:[0,1] neg_hi:[0,1]
	v_pk_add_f32 v[76:77], v[84:85], v[64:65]
	v_pk_add_f32 v[64:65], v[84:85], v[64:65] neg_lo:[0,1] neg_hi:[0,1]
	v_pk_add_f32 v[110:111], v[12:13], v[24:25] neg_lo:[0,1] neg_hi:[0,1]
	v_xor_b32_e32 v85, 0x80000000, v64
	v_mov_b32_e32 v84, v65
	v_pk_add_f32 v[64:65], v[68:69], v[72:73]
	v_pk_add_f32 v[68:69], v[68:69], v[72:73] neg_lo:[0,1] neg_hi:[0,1]
	v_pk_add_f32 v[72:73], v[20:21], v[66:67]
	v_pk_add_f32 v[20:21], v[20:21], v[66:67] neg_lo:[0,1] neg_hi:[0,1]
	v_pk_add_f32 v[12:13], v[14:15], v[18:19] neg_lo:[0,1] neg_hi:[0,1]
	v_xor_b32_e32 v67, 0x80000000, v20
	v_mov_b32_e32 v66, v21
	v_pk_add_f32 v[112:113], v[14:15], v[18:19]
	v_xor_b32_e32 v115, 0x80000000, v12
	v_mov_b32_e32 v114, v13
	v_pk_add_f32 v[12:13], v[26:27], v[76:77]
	v_pk_add_f32 v[14:15], v[26:27], v[76:77] neg_lo:[0,1] neg_hi:[0,1]
	v_pk_add_f32 v[24:25], v[68:69], v[66:67]
	v_pk_add_f32 v[26:27], v[68:69], v[66:67] neg_lo:[0,1] neg_hi:[0,1]
	s_waitcnt lgkmcnt(6)
	v_pk_add_f32 v[66:67], v[78:79], v[94:95] neg_lo:[0,1] neg_hi:[0,1]
	v_pk_add_f32 v[86:87], v[74:75], v[22:23]
	v_xor_b32_e32 v77, 0x80000000, v66
	v_mov_b32_e32 v76, v67
	v_pk_mul_f32 v[76:77], v[76:77], s[54:55] op_sel_hi:[1,0]
	v_pk_add_f32 v[74:75], v[74:75], v[22:23] neg_lo:[0,1] neg_hi:[0,1]
	v_pk_fma_f32 v[66:67], v[66:67], s[52:53], v[76:77] op_sel_hi:[1,0,1]
	s_waitcnt lgkmcnt(5)
	v_pk_add_f32 v[76:77], v[8:9], v[96:97]
	v_pk_add_f32 v[8:9], v[8:9], v[96:97] neg_lo:[0,1] neg_hi:[0,1]
	v_pk_add_f32 v[20:21], v[64:65], v[72:73]
	v_pk_add_f32 v[22:23], v[64:65], v[72:73] neg_lo:[0,1] neg_hi:[0,1]
	v_pk_add_f32 v[64:65], v[78:79], v[94:95]
	v_xor_b32_e32 v79, 0x80000000, v8
	v_mov_b32_e32 v78, v9
	v_pk_mul_f32 v[78:79], v[78:79], s[60:61] op_sel_hi:[1,0]
	v_pk_add_f32 v[88:89], v[70:71], v[16:17]
	v_pk_add_f32 v[16:17], v[70:71], v[16:17] neg_lo:[0,1] neg_hi:[0,1]
	v_pk_fma_f32 v[8:9], v[8:9], s[60:61], v[78:79] op_sel_hi:[1,0,1]
	s_waitcnt lgkmcnt(4)
	v_pk_add_f32 v[78:79], v[80:81], v[98:99]
	v_pk_add_f32 v[80:81], v[80:81], v[98:99] neg_lo:[0,1] neg_hi:[0,1]
	v_xor_b32_e32 v91, 0x80000000, v16
	v_mov_b32_e32 v90, v17
	v_pk_add_f32 v[16:17], v[62:63], v[84:85]
	v_pk_add_f32 v[18:19], v[62:63], v[84:85] neg_lo:[0,1] neg_hi:[0,1]
	v_pk_add_f32 v[62:63], v[6:7], v[92:93]
	v_pk_add_f32 v[6:7], v[6:7], v[92:93] neg_lo:[0,1] neg_hi:[0,1]
	v_xor_b32_e32 v93, 0x80000000, v80
	v_mov_b32_e32 v92, v81
	v_pk_mul_f32 v[92:93], v[92:93], s[52:53] op_sel_hi:[1,0]
	v_pk_add_f32 v[68:69], v[86:87], v[88:89]
	v_pk_fma_f32 v[80:81], v[80:81], s[54:55], v[92:93] op_sel_hi:[1,0,1]
	s_waitcnt lgkmcnt(3)
	v_pk_add_f32 v[92:93], v[10:11], v[100:101]
	v_pk_add_f32 v[10:11], v[10:11], v[100:101] neg_lo:[0,1] neg_hi:[0,1]
	v_pk_add_f32 v[70:71], v[86:87], v[88:89] neg_lo:[0,1] neg_hi:[0,1]
	v_xor_b32_e32 v95, 0x80000000, v10
	v_mov_b32_e32 v94, v11
	s_waitcnt lgkmcnt(2)
	v_pk_add_f32 v[10:11], v[4:5], v[102:103]
	v_pk_add_f32 v[4:5], v[4:5], v[102:103] neg_lo:[0,1] neg_hi:[0,1]
	v_pk_add_f32 v[84:85], v[108:109], v[112:113]
	v_pk_mul_f32 v[96:97], v[4:5], s[54:55] op_sel_hi:[1,0]
	v_xor_b32_e32 v99, 0x80000000, v4
	v_mov_b32_e32 v98, v5
	v_pk_fma_f32 v[4:5], v[98:99], s[52:53], v[96:97] op_sel_hi:[1,0,1] neg_lo:[0,0,1] neg_hi:[0,0,1]
	s_waitcnt lgkmcnt(1)
	v_pk_add_f32 v[96:97], v[2:3], v[104:105]
	v_pk_add_f32 v[2:3], v[2:3], v[104:105] neg_lo:[0,1] neg_hi:[0,1]
	v_pk_add_f32 v[86:87], v[108:109], v[112:113] neg_lo:[0,1] neg_hi:[0,1]
	v_pk_mul_f32 v[98:99], v[2:3], s[60:61] op_sel_hi:[1,0]
	v_xor_b32_e32 v101, 0x80000000, v2
	v_mov_b32_e32 v100, v3
	v_pk_fma_f32 v[2:3], v[100:101], s[60:61], v[98:99] op_sel_hi:[1,0,1] neg_lo:[0,0,1] neg_hi:[0,0,1]
	s_waitcnt lgkmcnt(0)
	v_pk_add_f32 v[98:99], v[82:83], v[106:107]
	v_pk_add_f32 v[82:83], v[82:83], v[106:107] neg_lo:[0,1] neg_hi:[0,1]
	v_pk_add_f32 v[72:73], v[74:75], v[90:91]
	v_pk_mul_f32 v[100:101], v[82:83], s[52:53] op_sel_hi:[1,0]
	v_xor_b32_e32 v103, 0x80000000, v82
	v_mov_b32_e32 v102, v83
	v_pk_fma_f32 v[82:83], v[102:103], s[54:55], v[100:101] op_sel_hi:[1,0,1] neg_lo:[0,0,1] neg_hi:[0,0,1]
	v_pk_add_f32 v[100:101], v[62:63], v[92:93]
	v_pk_add_f32 v[62:63], v[62:63], v[92:93] neg_lo:[0,1] neg_hi:[0,1]
	v_pk_add_f32 v[92:93], v[64:65], v[10:11]
	v_pk_add_f32 v[10:11], v[64:65], v[10:11] neg_lo:[0,1] neg_hi:[0,1]
	v_pk_add_f32 v[74:75], v[74:75], v[90:91] neg_lo:[0,1] neg_hi:[0,1]
	v_xor_b32_e32 v65, 0x80000000, v10
	v_mov_b32_e32 v64, v11
	v_pk_mul_f32 v[64:65], v[64:65], s[60:61] op_sel_hi:[1,0]
	v_pk_add_f32 v[88:89], v[110:111], v[114:115]
	v_pk_fma_f32 v[10:11], v[10:11], s[60:61], v[64:65] op_sel_hi:[1,0,1]
	v_pk_add_f32 v[64:65], v[76:77], v[96:97]
	v_pk_add_f32 v[76:77], v[76:77], v[96:97] neg_lo:[0,1] neg_hi:[0,1]
	v_pk_add_f32 v[90:91], v[110:111], v[114:115] neg_lo:[0,1] neg_hi:[0,1]
	v_xor_b32_e32 v97, 0x80000000, v76
	v_mov_b32_e32 v96, v77
	v_pk_add_f32 v[76:77], v[78:79], v[98:99]
	v_pk_add_f32 v[78:79], v[78:79], v[98:99] neg_lo:[0,1] neg_hi:[0,1]
	s_nop 0
	v_pk_mul_f32 v[98:99], v[78:79], s[60:61] op_sel_hi:[1,0]
	v_xor_b32_e32 v103, 0x80000000, v78
	v_mov_b32_e32 v102, v79
	v_pk_fma_f32 v[78:79], v[102:103], s[60:61], v[98:99] op_sel_hi:[1,0,1] neg_lo:[0,0,1] neg_hi:[0,0,1]
	v_pk_add_f32 v[98:99], v[6:7], v[94:95]
	v_pk_add_f32 v[6:7], v[6:7], v[94:95] neg_lo:[0,1] neg_hi:[0,1]
	v_pk_add_f32 v[94:95], v[66:67], v[4:5]
	v_pk_add_f32 v[4:5], v[66:67], v[4:5] neg_lo:[0,1] neg_hi:[0,1]
	s_nop 0
	v_xor_b32_e32 v67, 0x80000000, v4
	v_mov_b32_e32 v66, v5
	v_pk_mul_f32 v[66:67], v[66:67], s[60:61] op_sel_hi:[1,0]
	s_nop 0
	v_pk_fma_f32 v[4:5], v[4:5], s[60:61], v[66:67] op_sel_hi:[1,0,1]
	v_pk_add_f32 v[66:67], v[8:9], v[2:3]
	v_pk_add_f32 v[2:3], v[8:9], v[2:3] neg_lo:[0,1] neg_hi:[0,1]
	v_pk_add_f32 v[106:107], v[98:99], v[66:67] neg_lo:[0,1] neg_hi:[0,1]
	v_xor_b32_e32 v9, 0x80000000, v2
	v_mov_b32_e32 v8, v3
	v_pk_add_f32 v[2:3], v[80:81], v[82:83]
	v_pk_add_f32 v[80:81], v[80:81], v[82:83] neg_lo:[0,1] neg_hi:[0,1]
	v_pk_add_f32 v[108:109], v[94:95], v[2:3]
	v_pk_mul_f32 v[82:83], v[80:81], s[60:61] op_sel_hi:[1,0]
	v_xor_b32_e32 v103, 0x80000000, v80
	v_mov_b32_e32 v102, v81
	v_pk_fma_f32 v[80:81], v[102:103], s[60:61], v[82:83] op_sel_hi:[1,0,1] neg_lo:[0,0,1] neg_hi:[0,0,1]
	v_pk_add_f32 v[82:83], v[100:101], v[64:65]
	v_pk_add_f32 v[64:65], v[100:101], v[64:65] neg_lo:[0,1] neg_hi:[0,1]
	v_pk_add_f32 v[100:101], v[92:93], v[76:77]
	v_pk_add_f32 v[76:77], v[92:93], v[76:77] neg_lo:[0,1] neg_hi:[0,1]
	v_pk_add_f32 v[102:103], v[10:11], v[78:79]
	v_xor_b32_e32 v93, 0x80000000, v76
	v_mov_b32_e32 v92, v77
	v_pk_add_f32 v[76:77], v[62:63], v[96:97]
	v_pk_add_f32 v[10:11], v[10:11], v[78:79] neg_lo:[0,1] neg_hi:[0,1]
	v_pk_add_f32 v[2:3], v[94:95], v[2:3] neg_lo:[0,1] neg_hi:[0,1]
	v_pk_add_f32 v[62:63], v[62:63], v[96:97] neg_lo:[0,1] neg_hi:[0,1]
	v_xor_b32_e32 v105, 0x80000000, v10
	v_mov_b32_e32 v104, v11
	v_pk_add_f32 v[10:11], v[98:99], v[66:67]
	v_xor_b32_e32 v111, 0x80000000, v2
	v_mov_b32_e32 v110, v3
	v_pk_add_f32 v[112:113], v[6:7], v[8:9]
	v_pk_add_f32 v[114:115], v[6:7], v[8:9] neg_lo:[0,1] neg_hi:[0,1]
	v_pk_add_f32 v[6:7], v[4:5], v[80:81]
	v_pk_add_f32 v[2:3], v[4:5], v[80:81] neg_lo:[0,1] neg_hi:[0,1]
	v_pk_add_f32 v[98:99], v[82:83], v[100:101]
	v_pk_add_f32 v[96:97], v[82:83], v[100:101] neg_lo:[0,1] neg_hi:[0,1]
	v_pk_add_f32 v[82:83], v[76:77], v[102:103]
	v_pk_add_f32 v[80:81], v[76:77], v[102:103] neg_lo:[0,1] neg_hi:[0,1]
	global_load_dwordx4 v[100:103], v[0:1], off
	v_pk_add_f32 v[78:79], v[62:63], v[104:105]
	v_pk_add_f32 v[76:77], v[62:63], v[104:105] neg_lo:[0,1] neg_hi:[0,1]
	v_xor_b32_e32 v5, 0x80000000, v2
	v_mov_b32_e32 v4, v3
	v_pk_add_f32 v[62:63], v[106:107], v[110:111]
	v_pk_add_f32 v[2:3], v[106:107], v[110:111] neg_lo:[0,1] neg_hi:[0,1]
	v_xor_b32_e32 v106, 0x80000000, v13
	v_mov_b32_e32 v107, v12
	v_pk_add_f32 v[94:95], v[64:65], v[92:93]
	v_pk_add_f32 v[92:93], v[64:65], v[92:93] neg_lo:[0,1] neg_hi:[0,1]
	v_pk_add_f32 v[66:67], v[10:11], v[108:109]
	v_pk_add_f32 v[64:65], v[10:11], v[108:109] neg_lo:[0,1] neg_hi:[0,1]
	v_pk_add_f32 v[10:11], v[112:113], v[6:7]
	v_pk_add_f32 v[8:9], v[112:113], v[6:7] neg_lo:[0,1] neg_hi:[0,1]
	v_pk_add_f32 v[6:7], v[114:115], v[4:5]
	v_pk_add_f32 v[4:5], v[114:115], v[4:5] neg_lo:[0,1] neg_hi:[0,1]
	s_waitcnt vmcnt(0)
	v_cvt_f32_f16_e32 v104, v100
	v_cvt_f32_f16_sdwa v100, v100 dst_sel:DWORD dst_unused:UNUSED_PAD src0_sel:WORD_1
	v_mul_f32_e32 v104, 0x38800000, v104
	v_mul_f32_e32 v100, 0x38800000, v100
	v_pk_mul_f32 v[106:107], v[106:107], v[100:101] op_sel_hi:[1,0]
	v_cvt_f32_f16_e32 v100, v101
	v_cvt_f32_f16_sdwa v101, v101 dst_sel:DWORD dst_unused:UNUSED_PAD src0_sel:WORD_1
	v_pk_fma_f32 v[12:13], v[12:13], v[104:105], v[106:107] op_sel_hi:[1,0,1]
	v_xor_b32_e32 v106, 0x80000000, v15
	v_mov_b32_e32 v107, v14
	v_mul_f32_e32 v104, 0x38800000, v101
	v_mul_f32_e32 v100, 0x38800000, v100
	v_pk_mul_f32 v[104:105], v[106:107], v[104:105] op_sel_hi:[1,0]
	v_xor_b32_e32 v106, 0x80000000, v21
	v_pk_fma_f32 v[14:15], v[14:15], v[100:101], v[104:105] op_sel_hi:[1,0,1]
	v_cvt_f32_f16_sdwa v101, v102 dst_sel:DWORD dst_unused:UNUSED_PAD src0_sel:WORD_1
	v_cvt_f32_f16_e32 v100, v102
	v_xor_b32_e32 v104, 0x80000000, v17
	v_mov_b32_e32 v105, v16
	v_mul_f32_e32 v102, 0x38800000, v101
	v_mul_f32_e32 v100, 0x38800000, v100
	v_pk_mul_f32 v[104:105], v[104:105], v[102:103] op_sel_hi:[1,0]
	v_mov_b32_e32 v107, v20
	v_pk_fma_f32 v[16:17], v[16:17], v[100:101], v[104:105] op_sel_hi:[1,0,1]
	v_cvt_f32_f16_sdwa v101, v103 dst_sel:DWORD dst_unused:UNUSED_PAD src0_sel:WORD_1
	v_cvt_f32_f16_e32 v100, v103
	v_xor_b32_e32 v104, 0x80000000, v19
	v_mov_b32_e32 v105, v18
	v_mul_f32_e32 v102, 0x38800000, v101
	v_mul_f32_e32 v100, 0x38800000, v100
	v_pk_mul_f32 v[102:103], v[104:105], v[102:103] op_sel_hi:[1,0]
	s_nop 0
	v_pk_fma_f32 v[18:19], v[18:19], v[100:101], v[102:103] op_sel_hi:[1,0,1]
	global_load_dwordx4 v[100:103], v[0:1], off offset:16
	s_waitcnt vmcnt(0)
	v_cvt_f32_f16_e32 v104, v100
	v_cvt_f32_f16_sdwa v100, v100 dst_sel:DWORD dst_unused:UNUSED_PAD src0_sel:WORD_1
	v_mul_f32_e32 v104, 0x38800000, v104
	v_mul_f32_e32 v100, 0x38800000, v100
	v_pk_mul_f32 v[106:107], v[106:107], v[100:101] op_sel_hi:[1,0]
	v_cvt_f32_f16_e32 v100, v101
	v_cvt_f32_f16_sdwa v101, v101 dst_sel:DWORD dst_unused:UNUSED_PAD src0_sel:WORD_1
	v_pk_fma_f32 v[20:21], v[20:21], v[104:105], v[106:107] op_sel_hi:[1,0,1]
	v_xor_b32_e32 v106, 0x80000000, v23
	v_mov_b32_e32 v107, v22
	v_mul_f32_e32 v104, 0x38800000, v101
	v_mul_f32_e32 v100, 0x38800000, v100
	v_pk_mul_f32 v[104:105], v[106:107], v[104:105] op_sel_hi:[1,0]
	v_xor_b32_e32 v106, 0x80000000, v69
	v_pk_fma_f32 v[22:23], v[22:23], v[100:101], v[104:105] op_sel_hi:[1,0,1]
	v_cvt_f32_f16_sdwa v101, v102 dst_sel:DWORD dst_unused:UNUSED_PAD src0_sel:WORD_1
	v_cvt_f32_f16_e32 v100, v102
	v_xor_b32_e32 v104, 0x80000000, v25
	v_mov_b32_e32 v105, v24
	v_mul_f32_e32 v102, 0x38800000, v101
	v_mul_f32_e32 v100, 0x38800000, v100
	v_pk_mul_f32 v[104:105], v[104:105], v[102:103] op_sel_hi:[1,0]
	v_mov_b32_e32 v107, v68
	v_pk_fma_f32 v[24:25], v[24:25], v[100:101], v[104:105] op_sel_hi:[1,0,1]
	v_cvt_f32_f16_sdwa v101, v103 dst_sel:DWORD dst_unused:UNUSED_PAD src0_sel:WORD_1
	v_cvt_f32_f16_e32 v100, v103
	v_xor_b32_e32 v104, 0x80000000, v27
	v_mov_b32_e32 v105, v26
	v_mul_f32_e32 v102, 0x38800000, v101
	v_mul_f32_e32 v100, 0x38800000, v100
	v_pk_mul_f32 v[102:103], v[104:105], v[102:103] op_sel_hi:[1,0]
	s_nop 0
	v_pk_fma_f32 v[26:27], v[26:27], v[100:101], v[102:103] op_sel_hi:[1,0,1]
	global_load_dwordx4 v[100:103], v[0:1], off offset:32
	s_waitcnt vmcnt(0)
	v_cvt_f32_f16_e32 v104, v100
	v_cvt_f32_f16_sdwa v100, v100 dst_sel:DWORD dst_unused:UNUSED_PAD src0_sel:WORD_1
	v_mul_f32_e32 v104, 0x38800000, v104
	v_mul_f32_e32 v100, 0x38800000, v100
	v_pk_mul_f32 v[106:107], v[106:107], v[100:101] op_sel_hi:[1,0]
	v_cvt_f32_f16_e32 v100, v101
	v_cvt_f32_f16_sdwa v101, v101 dst_sel:DWORD dst_unused:UNUSED_PAD src0_sel:WORD_1
	v_pk_fma_f32 v[68:69], v[68:69], v[104:105], v[106:107] op_sel_hi:[1,0,1]
	v_xor_b32_e32 v106, 0x80000000, v71
	v_mov_b32_e32 v107, v70
	v_mul_f32_e32 v104, 0x38800000, v101
	v_mul_f32_e32 v100, 0x38800000, v100
	v_pk_mul_f32 v[104:105], v[106:107], v[104:105] op_sel_hi:[1,0]
	v_xor_b32_e32 v106, 0x80000000, v85
	v_pk_fma_f32 v[70:71], v[70:71], v[100:101], v[104:105] op_sel_hi:[1,0,1]
	v_cvt_f32_f16_sdwa v101, v102 dst_sel:DWORD dst_unused:UNUSED_PAD src0_sel:WORD_1
	v_cvt_f32_f16_e32 v100, v102
	v_xor_b32_e32 v104, 0x80000000, v73
	v_mov_b32_e32 v105, v72
	v_mul_f32_e32 v102, 0x38800000, v101
	v_mul_f32_e32 v100, 0x38800000, v100
	v_pk_mul_f32 v[104:105], v[104:105], v[102:103] op_sel_hi:[1,0]
	v_mov_b32_e32 v107, v84
	v_pk_fma_f32 v[72:73], v[72:73], v[100:101], v[104:105] op_sel_hi:[1,0,1]
	v_cvt_f32_f16_sdwa v101, v103 dst_sel:DWORD dst_unused:UNUSED_PAD src0_sel:WORD_1
	v_cvt_f32_f16_e32 v100, v103
	v_xor_b32_e32 v104, 0x80000000, v75
	v_mov_b32_e32 v105, v74
	v_mul_f32_e32 v102, 0x38800000, v101
	v_mul_f32_e32 v100, 0x38800000, v100
	v_pk_mul_f32 v[102:103], v[104:105], v[102:103] op_sel_hi:[1,0]
	s_nop 0
	v_pk_fma_f32 v[74:75], v[74:75], v[100:101], v[102:103] op_sel_hi:[1,0,1]
	global_load_dwordx4 v[100:103], v[0:1], off offset:48
	s_waitcnt vmcnt(0)
	v_cvt_f32_f16_e32 v104, v100
	v_cvt_f32_f16_sdwa v100, v100 dst_sel:DWORD dst_unused:UNUSED_PAD src0_sel:WORD_1
	v_mul_f32_e32 v104, 0x38800000, v104
	v_mul_f32_e32 v100, 0x38800000, v100
	v_pk_mul_f32 v[106:107], v[106:107], v[100:101] op_sel_hi:[1,0]
	v_cvt_f32_f16_e32 v100, v101
	v_cvt_f32_f16_sdwa v101, v101 dst_sel:DWORD dst_unused:UNUSED_PAD src0_sel:WORD_1
	v_pk_fma_f32 v[84:85], v[84:85], v[104:105], v[106:107] op_sel_hi:[1,0,1]
	v_xor_b32_e32 v106, 0x80000000, v87
	v_mov_b32_e32 v107, v86
	v_mul_f32_e32 v104, 0x38800000, v101
	v_mul_f32_e32 v100, 0x38800000, v100
	v_pk_mul_f32 v[104:105], v[106:107], v[104:105] op_sel_hi:[1,0]
	v_xor_b32_e32 v106, 0x80000000, v99
	v_pk_fma_f32 v[86:87], v[86:87], v[100:101], v[104:105] op_sel_hi:[1,0,1]
	v_cvt_f32_f16_sdwa v101, v102 dst_sel:DWORD dst_unused:UNUSED_PAD src0_sel:WORD_1
	v_cvt_f32_f16_e32 v100, v102
	v_xor_b32_e32 v104, 0x80000000, v89
	v_mov_b32_e32 v105, v88
	v_mul_f32_e32 v102, 0x38800000, v101
	v_mul_f32_e32 v100, 0x38800000, v100
	v_pk_mul_f32 v[104:105], v[104:105], v[102:103] op_sel_hi:[1,0]
	v_mov_b32_e32 v107, v98
	v_pk_fma_f32 v[88:89], v[88:89], v[100:101], v[104:105] op_sel_hi:[1,0,1]
	v_cvt_f32_f16_sdwa v101, v103 dst_sel:DWORD dst_unused:UNUSED_PAD src0_sel:WORD_1
	v_cvt_f32_f16_e32 v100, v103
	v_xor_b32_e32 v104, 0x80000000, v91
	v_mov_b32_e32 v105, v90
	v_mul_f32_e32 v102, 0x38800000, v101
	v_mul_f32_e32 v100, 0x38800000, v100
	v_pk_mul_f32 v[102:103], v[104:105], v[102:103] op_sel_hi:[1,0]
	s_nop 0
	v_pk_fma_f32 v[90:91], v[90:91], v[100:101], v[102:103] op_sel_hi:[1,0,1]
	global_load_dwordx4 v[100:103], v[0:1], off offset:64
	s_waitcnt vmcnt(0)
	v_cvt_f32_f16_e32 v104, v100
	v_cvt_f32_f16_sdwa v100, v100 dst_sel:DWORD dst_unused:UNUSED_PAD src0_sel:WORD_1
	v_mul_f32_e32 v104, 0x38800000, v104
	v_mul_f32_e32 v100, 0x38800000, v100
	v_pk_mul_f32 v[106:107], v[106:107], v[100:101] op_sel_hi:[1,0]
	v_cvt_f32_f16_e32 v100, v101
	v_cvt_f32_f16_sdwa v101, v101 dst_sel:DWORD dst_unused:UNUSED_PAD src0_sel:WORD_1
	v_pk_fma_f32 v[98:99], v[98:99], v[104:105], v[106:107] op_sel_hi:[1,0,1]
	v_xor_b32_e32 v106, 0x80000000, v97
	v_mov_b32_e32 v107, v96
	v_mul_f32_e32 v104, 0x38800000, v101
	v_mul_f32_e32 v100, 0x38800000, v100
	v_pk_mul_f32 v[104:105], v[106:107], v[104:105] op_sel_hi:[1,0]
	v_xor_b32_e32 v106, 0x80000000, v83
	v_pk_fma_f32 v[96:97], v[96:97], v[100:101], v[104:105] op_sel_hi:[1,0,1]
	v_cvt_f32_f16_sdwa v101, v102 dst_sel:DWORD dst_unused:UNUSED_PAD src0_sel:WORD_1
	v_cvt_f32_f16_e32 v100, v102
	v_xor_b32_e32 v104, 0x80000000, v95
	v_mov_b32_e32 v105, v94
	v_mul_f32_e32 v102, 0x38800000, v101
	v_mul_f32_e32 v100, 0x38800000, v100
	v_pk_mul_f32 v[104:105], v[104:105], v[102:103] op_sel_hi:[1,0]
	v_mov_b32_e32 v107, v82
	v_pk_fma_f32 v[94:95], v[94:95], v[100:101], v[104:105] op_sel_hi:[1,0,1]
	v_cvt_f32_f16_sdwa v101, v103 dst_sel:DWORD dst_unused:UNUSED_PAD src0_sel:WORD_1
	v_cvt_f32_f16_e32 v100, v103
	v_xor_b32_e32 v104, 0x80000000, v93
	v_mov_b32_e32 v105, v92
	v_mul_f32_e32 v102, 0x38800000, v101
	v_mul_f32_e32 v100, 0x38800000, v100
	v_pk_mul_f32 v[102:103], v[104:105], v[102:103] op_sel_hi:[1,0]
	s_nop 0
	v_pk_fma_f32 v[92:93], v[92:93], v[100:101], v[102:103] op_sel_hi:[1,0,1]
	global_load_dwordx4 v[100:103], v[0:1], off offset:80
	s_waitcnt vmcnt(0)
	v_cvt_f32_f16_e32 v104, v100
	v_cvt_f32_f16_sdwa v100, v100 dst_sel:DWORD dst_unused:UNUSED_PAD src0_sel:WORD_1
	v_mul_f32_e32 v104, 0x38800000, v104
	v_mul_f32_e32 v100, 0x38800000, v100
	v_pk_mul_f32 v[106:107], v[106:107], v[100:101] op_sel_hi:[1,0]
	v_cvt_f32_f16_e32 v100, v101
	v_cvt_f32_f16_sdwa v101, v101 dst_sel:DWORD dst_unused:UNUSED_PAD src0_sel:WORD_1
	v_pk_fma_f32 v[82:83], v[82:83], v[104:105], v[106:107] op_sel_hi:[1,0,1]
	v_xor_b32_e32 v106, 0x80000000, v81
	v_mov_b32_e32 v107, v80
	v_mul_f32_e32 v104, 0x38800000, v101
	v_mul_f32_e32 v100, 0x38800000, v100
	v_pk_mul_f32 v[104:105], v[106:107], v[104:105] op_sel_hi:[1,0]
	v_xor_b32_e32 v106, 0x80000000, v67
	v_pk_fma_f32 v[80:81], v[80:81], v[100:101], v[104:105] op_sel_hi:[1,0,1]
	v_cvt_f32_f16_sdwa v101, v102 dst_sel:DWORD dst_unused:UNUSED_PAD src0_sel:WORD_1
	v_cvt_f32_f16_e32 v100, v102
	v_xor_b32_e32 v104, 0x80000000, v79
	v_mov_b32_e32 v105, v78
	v_mul_f32_e32 v102, 0x38800000, v101
	v_mul_f32_e32 v100, 0x38800000, v100
	v_pk_mul_f32 v[104:105], v[104:105], v[102:103] op_sel_hi:[1,0]
	v_mov_b32_e32 v107, v66
	v_pk_fma_f32 v[78:79], v[78:79], v[100:101], v[104:105] op_sel_hi:[1,0,1]
	v_cvt_f32_f16_sdwa v101, v103 dst_sel:DWORD dst_unused:UNUSED_PAD src0_sel:WORD_1
	v_cvt_f32_f16_e32 v100, v103
	v_xor_b32_e32 v104, 0x80000000, v77
	v_mov_b32_e32 v105, v76
	v_mul_f32_e32 v102, 0x38800000, v101
	v_mul_f32_e32 v100, 0x38800000, v100
	v_pk_mul_f32 v[102:103], v[104:105], v[102:103] op_sel_hi:[1,0]
	s_nop 0
	v_pk_fma_f32 v[76:77], v[76:77], v[100:101], v[102:103] op_sel_hi:[1,0,1]
	global_load_dwordx4 v[100:103], v[0:1], off offset:96
	s_waitcnt vmcnt(0)
	v_cvt_f32_f16_e32 v104, v100
	v_cvt_f32_f16_sdwa v100, v100 dst_sel:DWORD dst_unused:UNUSED_PAD src0_sel:WORD_1
	v_mul_f32_e32 v104, 0x38800000, v104
	v_mul_f32_e32 v100, 0x38800000, v100
	v_pk_mul_f32 v[106:107], v[106:107], v[100:101] op_sel_hi:[1,0]
	v_cvt_f32_f16_e32 v100, v101
	v_cvt_f32_f16_sdwa v101, v101 dst_sel:DWORD dst_unused:UNUSED_PAD src0_sel:WORD_1
	v_pk_fma_f32 v[66:67], v[66:67], v[104:105], v[106:107] op_sel_hi:[1,0,1]
	v_xor_b32_e32 v106, 0x80000000, v65
	v_mov_b32_e32 v107, v64
	v_mul_f32_e32 v104, 0x38800000, v101
	v_mul_f32_e32 v100, 0x38800000, v100
	v_pk_mul_f32 v[104:105], v[106:107], v[104:105] op_sel_hi:[1,0]
	s_nop 0
	v_pk_fma_f32 v[64:65], v[64:65], v[100:101], v[104:105] op_sel_hi:[1,0,1]
	v_cvt_f32_f16_sdwa v101, v102 dst_sel:DWORD dst_unused:UNUSED_PAD src0_sel:WORD_1
	v_cvt_f32_f16_e32 v100, v102
	v_xor_b32_e32 v104, 0x80000000, v63
	v_mov_b32_e32 v105, v62
	v_mul_f32_e32 v102, 0x38800000, v101
	v_mul_f32_e32 v100, 0x38800000, v100
	v_pk_mul_f32 v[104:105], v[104:105], v[102:103] op_sel_hi:[1,0]
	s_nop 0
	v_pk_fma_f32 v[62:63], v[62:63], v[100:101], v[104:105] op_sel_hi:[1,0,1]
	v_cvt_f32_f16_sdwa v101, v103 dst_sel:DWORD dst_unused:UNUSED_PAD src0_sel:WORD_1
	v_cvt_f32_f16_e32 v100, v103
	v_xor_b32_e32 v104, 0x80000000, v3
	v_mov_b32_e32 v105, v2
	v_mul_f32_e32 v102, 0x38800000, v101
	v_mul_f32_e32 v100, 0x38800000, v100
	v_pk_mul_f32 v[102:103], v[104:105], v[102:103] op_sel_hi:[1,0]
	v_xor_b32_e32 v104, 0x80000000, v11
	v_pk_fma_f32 v[100:101], v[2:3], v[100:101], v[102:103] op_sel_hi:[1,0,1]
	global_load_dwordx4 v[0:3], v[0:1], off offset:112
	v_mov_b32_e32 v105, v10
	s_waitcnt vmcnt(0)
	v_cvt_f32_f16_e32 v102, v0
	v_cvt_f32_f16_sdwa v0, v0 dst_sel:DWORD dst_unused:UNUSED_PAD src0_sel:WORD_1
	v_mul_f32_e32 v102, 0x38800000, v102
	v_mul_f32_e32 v0, 0x38800000, v0
	v_pk_mul_f32 v[104:105], v[104:105], v[0:1] op_sel_hi:[1,0]
	v_cvt_f32_f16_e32 v0, v1
	v_cvt_f32_f16_sdwa v1, v1 dst_sel:DWORD dst_unused:UNUSED_PAD src0_sel:WORD_1
	v_pk_fma_f32 v[10:11], v[10:11], v[102:103], v[104:105] op_sel_hi:[1,0,1]
	v_xor_b32_e32 v104, 0x80000000, v9
	v_mov_b32_e32 v105, v8
	v_mul_f32_e32 v102, 0x38800000, v1
	v_mul_f32_e32 v0, 0x38800000, v0
	v_pk_mul_f32 v[102:103], v[104:105], v[102:103] op_sel_hi:[1,0]
	s_nop 0
	v_pk_fma_f32 v[0:1], v[8:9], v[0:1], v[102:103] op_sel_hi:[1,0,1]
	v_cvt_f32_f16_e32 v8, v2
	v_cvt_f32_f16_sdwa v2, v2 dst_sel:DWORD dst_unused:UNUSED_PAD src0_sel:WORD_1
	v_xor_b32_e32 v102, 0x80000000, v7
	v_mov_b32_e32 v103, v6
	v_mul_f32_e32 v8, 0x38800000, v8
	v_mul_f32_e32 v2, 0x38800000, v2
	v_pk_mul_f32 v[102:103], v[102:103], v[2:3] op_sel_hi:[1,0]
	v_cvt_f32_f16_e32 v2, v3
	v_cvt_f32_f16_sdwa v3, v3 dst_sel:DWORD dst_unused:UNUSED_PAD src0_sel:WORD_1
	v_pk_fma_f32 v[6:7], v[6:7], v[8:9], v[102:103] op_sel_hi:[1,0,1]
	v_xor_b32_e32 v102, 0x80000000, v5
	v_mov_b32_e32 v103, v4
	v_mul_f32_e32 v8, 0x38800000, v3
	v_mul_f32_e32 v2, 0x38800000, v2
	v_pk_mul_f32 v[8:9], v[102:103], v[8:9] op_sel_hi:[1,0]
	v_mov_b32_e32 v102, v146
	v_pk_fma_f32 v[2:3], v[4:5], v[2:3], v[8:9] op_sel_hi:[1,0,1]
	v_pk_add_f32 v[4:5], v[12:13], v[14:15]
	v_pk_add_f32 v[8:9], v[12:13], v[14:15] neg_lo:[0,1] neg_hi:[0,1]
	v_pk_add_f32 v[12:13], v[16:17], v[18:19]
	v_pk_add_f32 v[14:15], v[16:17], v[18:19] neg_lo:[0,1] neg_hi:[0,1]
	v_pk_add_f32 v[16:17], v[20:21], v[22:23]
	v_pk_add_f32 v[18:19], v[20:21], v[22:23] neg_lo:[0,1] neg_hi:[0,1]
	v_pk_add_f32 v[20:21], v[24:25], v[26:27]
	v_pk_add_f32 v[22:23], v[24:25], v[26:27] neg_lo:[0,1] neg_hi:[0,1]
	v_pk_add_f32 v[24:25], v[68:69], v[70:71]
	v_pk_add_f32 v[26:27], v[68:69], v[70:71] neg_lo:[0,1] neg_hi:[0,1]
	v_pk_add_f32 v[68:69], v[72:73], v[74:75]
	v_pk_add_f32 v[70:71], v[72:73], v[74:75] neg_lo:[0,1] neg_hi:[0,1]
	v_pk_add_f32 v[72:73], v[84:85], v[86:87]
	v_pk_add_f32 v[74:75], v[84:85], v[86:87] neg_lo:[0,1] neg_hi:[0,1]
	v_pk_add_f32 v[84:85], v[88:89], v[90:91]
	v_pk_add_f32 v[86:87], v[88:89], v[90:91] neg_lo:[0,1] neg_hi:[0,1]
	v_pk_add_f32 v[88:89], v[4:5], v[12:13]
	v_pk_add_f32 v[4:5], v[4:5], v[12:13] neg_lo:[0,1] neg_hi:[0,1]
	v_xor_b32_e32 v12, 0x80000000, v15
	v_mov_b32_e32 v13, v14
	v_pk_add_f32 v[14:15], v[8:9], v[12:13]
	v_pk_add_f32 v[8:9], v[8:9], v[12:13] neg_lo:[0,1] neg_hi:[0,1]
	v_pk_add_f32 v[12:13], v[16:17], v[20:21]
	v_pk_add_f32 v[16:17], v[16:17], v[20:21] neg_lo:[0,1] neg_hi:[0,1]
	v_xor_b32_e32 v20, 0x80000000, v23
	v_mov_b32_e32 v21, v22
	v_pk_add_f32 v[22:23], v[18:19], v[20:21]
	v_pk_add_f32 v[18:19], v[18:19], v[20:21] neg_lo:[0,1] neg_hi:[0,1]
	v_pk_add_f32 v[20:21], v[24:25], v[68:69]
	v_pk_add_f32 v[24:25], v[24:25], v[68:69] neg_lo:[0,1] neg_hi:[0,1]
	v_xor_b32_e32 v68, 0x80000000, v71
	v_mov_b32_e32 v69, v70
	v_pk_add_f32 v[70:71], v[26:27], v[68:69]
	v_pk_add_f32 v[26:27], v[26:27], v[68:69] neg_lo:[0,1] neg_hi:[0,1]
	v_pk_add_f32 v[68:69], v[72:73], v[84:85]
	v_pk_add_f32 v[72:73], v[72:73], v[84:85] neg_lo:[0,1] neg_hi:[0,1]
	v_xor_b32_e32 v84, 0x80000000, v87
	v_mov_b32_e32 v85, v86
	v_pk_add_f32 v[86:87], v[74:75], v[84:85]
	v_pk_add_f32 v[74:75], v[74:75], v[84:85] neg_lo:[0,1] neg_hi:[0,1]
	v_pk_add_f32 v[84:85], v[88:89], v[12:13]
	v_pk_add_f32 v[12:13], v[88:89], v[12:13] neg_lo:[0,1] neg_hi:[0,1]
	v_xor_b32_e32 v88, 0x80000000, v23
	v_mov_b32_e32 v89, v22
	v_pk_mul_f32 v[88:89], v[88:89], s[60:61] op_sel_hi:[1,0]
	v_xor_b32_e32 v90, 0x80000000, v19
	v_pk_fma_f32 v[22:23], v[22:23], s[60:61], v[88:89] op_sel_hi:[1,0,1]
	v_mov_b32_e32 v91, v18
	v_pk_add_f32 v[88:89], v[14:15], v[22:23]
	v_pk_add_f32 v[14:15], v[14:15], v[22:23] neg_lo:[0,1] neg_hi:[0,1]
	v_xor_b32_e32 v22, 0x80000000, v17
	v_mov_b32_e32 v23, v16
	v_pk_add_f32 v[16:17], v[4:5], v[22:23]
	v_pk_add_f32 v[4:5], v[4:5], v[22:23] neg_lo:[0,1] neg_hi:[0,1]
	v_pk_mul_f32 v[22:23], v[18:19], s[60:61] op_sel_hi:[1,0]
	s_nop 0
	v_pk_fma_f32 v[18:19], v[90:91], s[60:61], v[22:23] op_sel_hi:[1,0,1] neg_lo:[0,0,1] neg_hi:[0,0,1]
	v_xor_b32_e32 v90, 0x80000000, v75
	v_pk_add_f32 v[22:23], v[8:9], v[18:19]
	v_pk_add_f32 v[8:9], v[8:9], v[18:19] neg_lo:[0,1] neg_hi:[0,1]
	v_pk_add_f32 v[18:19], v[20:21], v[68:69]
	v_pk_add_f32 v[20:21], v[20:21], v[68:69] neg_lo:[0,1] neg_hi:[0,1]
	v_xor_b32_e32 v68, 0x80000000, v87
	v_mov_b32_e32 v69, v86
	v_pk_mul_f32 v[68:69], v[68:69], s[60:61] op_sel_hi:[1,0]
	v_mov_b32_e32 v91, v74
	v_pk_fma_f32 v[68:69], v[86:87], s[60:61], v[68:69] op_sel_hi:[1,0,1]
	s_nop 0
	v_pk_add_f32 v[86:87], v[70:71], v[68:69]
	v_pk_add_f32 v[68:69], v[70:71], v[68:69] neg_lo:[0,1] neg_hi:[0,1]
	v_xor_b32_e32 v70, 0x80000000, v73
	v_mov_b32_e32 v71, v72
	v_pk_add_f32 v[72:73], v[24:25], v[70:71]
	v_pk_add_f32 v[24:25], v[24:25], v[70:71] neg_lo:[0,1] neg_hi:[0,1]
	v_pk_mul_f32 v[70:71], v[74:75], s[60:61] op_sel_hi:[1,0]
	s_nop 0
	v_pk_fma_f32 v[70:71], v[90:91], s[60:61], v[70:71] op_sel_hi:[1,0,1] neg_lo:[0,0,1] neg_hi:[0,0,1]
	v_xor_b32_e32 v90, 0x80000000, v69
	v_pk_add_f32 v[74:75], v[26:27], v[70:71]
	v_pk_add_f32 v[26:27], v[26:27], v[70:71] neg_lo:[0,1] neg_hi:[0,1]
	v_pk_add_f32 v[70:71], v[84:85], v[18:19]
	v_pk_add_f32 v[18:19], v[84:85], v[18:19] neg_lo:[0,1] neg_hi:[0,1]
	v_xor_b32_e32 v84, 0x80000000, v87
	v_mov_b32_e32 v85, v86
	v_pk_mul_f32 v[84:85], v[84:85], s[54:55] op_sel_hi:[1,0]
	v_mov_b32_e32 v91, v68
	v_pk_fma_f32 v[84:85], v[86:87], s[52:53], v[84:85] op_sel_hi:[1,0,1]
	s_nop 0
	v_pk_add_f32 v[86:87], v[88:89], v[84:85]
	v_pk_add_f32 v[84:85], v[88:89], v[84:85] neg_lo:[0,1] neg_hi:[0,1]
	v_xor_b32_e32 v88, 0x80000000, v73
	v_mov_b32_e32 v89, v72
	v_pk_mul_f32 v[88:89], v[88:89], s[60:61] op_sel_hi:[1,0]
	s_nop 0
	v_pk_fma_f32 v[72:73], v[72:73], s[60:61], v[88:89] op_sel_hi:[1,0,1]
	s_nop 0
	v_pk_add_f32 v[88:89], v[16:17], v[72:73]
	v_pk_add_f32 v[16:17], v[16:17], v[72:73] neg_lo:[0,1] neg_hi:[0,1]
	v_xor_b32_e32 v72, 0x80000000, v75
	v_mov_b32_e32 v73, v74
	v_pk_mul_f32 v[72:73], v[72:73], s[52:53] op_sel_hi:[1,0]
	s_nop 0
	v_pk_fma_f32 v[72:73], v[74:75], s[54:55], v[72:73] op_sel_hi:[1,0,1]
	s_nop 0
	v_pk_add_f32 v[74:75], v[22:23], v[72:73]
	v_pk_add_f32 v[22:23], v[22:23], v[72:73] neg_lo:[0,1] neg_hi:[0,1]
	v_xor_b32_e32 v72, 0x80000000, v21
	v_mov_b32_e32 v73, v20
	v_pk_add_f32 v[20:21], v[12:13], v[72:73]
	v_pk_add_f32 v[12:13], v[12:13], v[72:73] neg_lo:[0,1] neg_hi:[0,1]
	v_pk_mul_f32 v[72:73], v[68:69], s[54:55] op_sel_hi:[1,0]
	s_nop 0
	v_pk_fma_f32 v[68:69], v[90:91], s[52:53], v[72:73] op_sel_hi:[1,0,1] neg_lo:[0,0,1] neg_hi:[0,0,1]
	v_xor_b32_e32 v90, 0x80000000, v25
	v_pk_add_f32 v[72:73], v[14:15], v[68:69]
	v_pk_add_f32 v[14:15], v[14:15], v[68:69] neg_lo:[0,1] neg_hi:[0,1]
	v_pk_mul_f32 v[68:69], v[24:25], s[60:61] op_sel_hi:[1,0]
	v_mov_b32_e32 v91, v24
	v_pk_fma_f32 v[24:25], v[90:91], s[60:61], v[68:69] op_sel_hi:[1,0,1] neg_lo:[0,0,1] neg_hi:[0,0,1]
	v_xor_b32_e32 v90, 0x80000000, v27
	v_pk_add_f32 v[68:69], v[4:5], v[24:25]
	v_pk_add_f32 v[4:5], v[4:5], v[24:25] neg_lo:[0,1] neg_hi:[0,1]
	v_pk_mul_f32 v[24:25], v[26:27], s[52:53] op_sel_hi:[1,0]
	v_mov_b32_e32 v91, v26
	v_pk_fma_f32 v[24:25], v[90:91], s[54:55], v[24:25] op_sel_hi:[1,0,1] neg_lo:[0,0,1] neg_hi:[0,0,1]
	v_pk_add_f32 v[90:91], v[98:99], v[96:97] neg_lo:[0,1] neg_hi:[0,1]
	v_pk_add_f32 v[26:27], v[8:9], v[24:25]
	v_pk_add_f32 v[8:9], v[8:9], v[24:25] neg_lo:[0,1] neg_hi:[0,1]
	v_pk_add_f32 v[24:25], v[98:99], v[96:97]
	v_pk_add_f32 v[96:97], v[94:95], v[92:93]
	v_pk_add_f32 v[92:93], v[94:95], v[92:93] neg_lo:[0,1] neg_hi:[0,1]
	v_pk_add_f32 v[94:95], v[82:83], v[80:81]
	v_pk_add_f32 v[80:81], v[82:83], v[80:81] neg_lo:[0,1] neg_hi:[0,1]
	v_pk_add_f32 v[82:83], v[78:79], v[76:77]
	v_pk_add_f32 v[76:77], v[78:79], v[76:77] neg_lo:[0,1] neg_hi:[0,1]
	v_pk_add_f32 v[98:99], v[10:11], v[0:1]
	v_pk_add_f32 v[0:1], v[10:11], v[0:1] neg_lo:[0,1] neg_hi:[0,1]
	v_pk_add_f32 v[10:11], v[6:7], v[2:3]
	v_pk_add_f32 v[2:3], v[6:7], v[2:3] neg_lo:[0,1] neg_hi:[0,1]
	v_pk_add_f32 v[6:7], v[24:25], v[96:97]
	v_pk_add_f32 v[24:25], v[24:25], v[96:97] neg_lo:[0,1] neg_hi:[0,1]
	v_xor_b32_e32 v96, 0x80000000, v93
	v_mov_b32_e32 v97, v92
	v_pk_add_f32 v[78:79], v[66:67], v[64:65]
	v_pk_add_f32 v[64:65], v[66:67], v[64:65] neg_lo:[0,1] neg_hi:[0,1]
	v_pk_add_f32 v[66:67], v[62:63], v[100:101]
	v_pk_add_f32 v[62:63], v[62:63], v[100:101] neg_lo:[0,1] neg_hi:[0,1]
	v_pk_add_f32 v[92:93], v[90:91], v[96:97]
	v_pk_add_f32 v[90:91], v[90:91], v[96:97] neg_lo:[0,1] neg_hi:[0,1]
	v_pk_add_f32 v[96:97], v[94:95], v[82:83]
	v_pk_add_f32 v[82:83], v[94:95], v[82:83] neg_lo:[0,1] neg_hi:[0,1]
	v_xor_b32_e32 v94, 0x80000000, v77
	v_mov_b32_e32 v95, v76
	v_pk_add_f32 v[76:77], v[80:81], v[94:95]
	v_pk_add_f32 v[80:81], v[80:81], v[94:95] neg_lo:[0,1] neg_hi:[0,1]
	v_pk_add_f32 v[94:95], v[78:79], v[66:67]
	v_pk_add_f32 v[66:67], v[78:79], v[66:67] neg_lo:[0,1] neg_hi:[0,1]
	v_xor_b32_e32 v78, 0x80000000, v63
	v_mov_b32_e32 v79, v62
	v_pk_add_f32 v[62:63], v[64:65], v[78:79]
	v_pk_add_f32 v[64:65], v[64:65], v[78:79] neg_lo:[0,1] neg_hi:[0,1]
	v_pk_add_f32 v[78:79], v[98:99], v[10:11]
	v_pk_add_f32 v[10:11], v[98:99], v[10:11] neg_lo:[0,1] neg_hi:[0,1]
	v_xor_b32_e32 v98, 0x80000000, v3
	v_mov_b32_e32 v99, v2
	v_pk_add_f32 v[2:3], v[0:1], v[98:99]
	v_pk_add_f32 v[0:1], v[0:1], v[98:99] neg_lo:[0,1] neg_hi:[0,1]
	v_pk_add_f32 v[98:99], v[6:7], v[96:97]
	v_pk_add_f32 v[6:7], v[6:7], v[96:97] neg_lo:[0,1] neg_hi:[0,1]
	v_xor_b32_e32 v96, 0x80000000, v77
	v_mov_b32_e32 v97, v76
	v_pk_mul_f32 v[96:97], v[96:97], s[60:61] op_sel_hi:[1,0]
	v_xor_b32_e32 v100, 0x80000000, v81
	v_pk_fma_f32 v[76:77], v[76:77], s[60:61], v[96:97] op_sel_hi:[1,0,1]
	v_mov_b32_e32 v101, v80
	v_pk_add_f32 v[96:97], v[92:93], v[76:77]
	v_pk_add_f32 v[76:77], v[92:93], v[76:77] neg_lo:[0,1] neg_hi:[0,1]
	v_xor_b32_e32 v92, 0x80000000, v83
	v_mov_b32_e32 v93, v82
	v_pk_add_f32 v[82:83], v[24:25], v[92:93]
	v_pk_add_f32 v[24:25], v[24:25], v[92:93] neg_lo:[0,1] neg_hi:[0,1]
	v_pk_mul_f32 v[92:93], v[80:81], s[60:61] op_sel_hi:[1,0]
	s_nop 0
	v_pk_fma_f32 v[80:81], v[100:101], s[60:61], v[92:93] op_sel_hi:[1,0,1] neg_lo:[0,0,1] neg_hi:[0,0,1]
	v_xor_b32_e32 v100, 0x80000000, v1
	v_pk_add_f32 v[92:93], v[90:91], v[80:81]
	v_pk_add_f32 v[80:81], v[90:91], v[80:81] neg_lo:[0,1] neg_hi:[0,1]
	v_pk_add_f32 v[90:91], v[94:95], v[78:79]
	v_pk_add_f32 v[78:79], v[94:95], v[78:79] neg_lo:[0,1] neg_hi:[0,1]
	v_xor_b32_e32 v94, 0x80000000, v3
	v_mov_b32_e32 v95, v2
	v_pk_mul_f32 v[94:95], v[94:95], s[60:61] op_sel_hi:[1,0]
	v_mov_b32_e32 v101, v0
	v_pk_fma_f32 v[2:3], v[2:3], s[60:61], v[94:95] op_sel_hi:[1,0,1]
	s_nop 0
	v_pk_add_f32 v[94:95], v[62:63], v[2:3]
	v_pk_add_f32 v[2:3], v[62:63], v[2:3] neg_lo:[0,1] neg_hi:[0,1]
	v_xor_b32_e32 v62, 0x80000000, v11
	v_mov_b32_e32 v63, v10
	v_pk_add_f32 v[10:11], v[66:67], v[62:63]
	v_pk_add_f32 v[62:63], v[66:67], v[62:63] neg_lo:[0,1] neg_hi:[0,1]
	v_pk_mul_f32 v[66:67], v[0:1], s[60:61] op_sel_hi:[1,0]
	s_nop 0
	v_pk_fma_f32 v[0:1], v[100:101], s[60:61], v[66:67] op_sel_hi:[1,0,1] neg_lo:[0,0,1] neg_hi:[0,0,1]
	v_xor_b32_e32 v100, 0x80000000, v3
	v_pk_add_f32 v[66:67], v[64:65], v[0:1]
	v_pk_add_f32 v[0:1], v[64:65], v[0:1] neg_lo:[0,1] neg_hi:[0,1]
	v_pk_add_f32 v[64:65], v[98:99], v[90:91]
	v_pk_add_f32 v[90:91], v[98:99], v[90:91] neg_lo:[0,1] neg_hi:[0,1]
	v_xor_b32_e32 v98, 0x80000000, v95
	v_mov_b32_e32 v99, v94
	v_pk_mul_f32 v[98:99], v[98:99], s[54:55] op_sel_hi:[1,0]
	v_mov_b32_e32 v101, v2
	v_pk_fma_f32 v[94:95], v[94:95], s[52:53], v[98:99] op_sel_hi:[1,0,1]
	s_nop 0
	v_pk_add_f32 v[98:99], v[96:97], v[94:95]
	v_pk_add_f32 v[94:95], v[96:97], v[94:95] neg_lo:[0,1] neg_hi:[0,1]
	v_xor_b32_e32 v96, 0x80000000, v11
	v_mov_b32_e32 v97, v10
	v_pk_mul_f32 v[96:97], v[96:97], s[60:61] op_sel_hi:[1,0]
	s_nop 0
	v_pk_fma_f32 v[10:11], v[10:11], s[60:61], v[96:97] op_sel_hi:[1,0,1]
	s_nop 0
	v_pk_add_f32 v[96:97], v[82:83], v[10:11]
	v_pk_add_f32 v[10:11], v[82:83], v[10:11] neg_lo:[0,1] neg_hi:[0,1]
	v_xor_b32_e32 v82, 0x80000000, v67
	v_mov_b32_e32 v83, v66
	v_pk_mul_f32 v[82:83], v[82:83], s[52:53] op_sel_hi:[1,0]
	s_nop 0
	v_pk_fma_f32 v[66:67], v[66:67], s[54:55], v[82:83] op_sel_hi:[1,0,1]
	s_nop 0
	v_pk_add_f32 v[82:83], v[92:93], v[66:67]
	v_pk_add_f32 v[66:67], v[92:93], v[66:67] neg_lo:[0,1] neg_hi:[0,1]
	v_xor_b32_e32 v92, 0x80000000, v79
	v_mov_b32_e32 v93, v78
	v_pk_add_f32 v[78:79], v[6:7], v[92:93]
	v_pk_add_f32 v[6:7], v[6:7], v[92:93] neg_lo:[0,1] neg_hi:[0,1]
	v_pk_mul_f32 v[92:93], v[2:3], s[54:55] op_sel_hi:[1,0]
	s_nop 0
	v_pk_fma_f32 v[2:3], v[100:101], s[52:53], v[92:93] op_sel_hi:[1,0,1] neg_lo:[0,0,1] neg_hi:[0,0,1]
	v_xor_b32_e32 v100, 0x80000000, v63
	v_pk_add_f32 v[92:93], v[76:77], v[2:3]
	v_pk_add_f32 v[2:3], v[76:77], v[2:3] neg_lo:[0,1] neg_hi:[0,1]
	v_pk_mul_f32 v[76:77], v[62:63], s[60:61] op_sel_hi:[1,0]
	v_mov_b32_e32 v101, v62
	v_pk_fma_f32 v[62:63], v[100:101], s[60:61], v[76:77] op_sel_hi:[1,0,1] neg_lo:[0,0,1] neg_hi:[0,0,1]
	v_xor_b32_e32 v100, 0x80000000, v1
	v_pk_add_f32 v[76:77], v[24:25], v[62:63]
	v_pk_add_f32 v[24:25], v[24:25], v[62:63] neg_lo:[0,1] neg_hi:[0,1]
	v_pk_mul_f32 v[62:63], v[0:1], s[52:53] op_sel_hi:[1,0]
	v_mov_b32_e32 v101, v0
	v_pk_fma_f32 v[0:1], v[100:101], s[54:55], v[62:63] op_sel_hi:[1,0,1] neg_lo:[0,0,1] neg_hi:[0,0,1]
	v_bfe_u32 v100, v102, 1, 4
	v_pk_add_f32 v[62:63], v[80:81], v[0:1]
	v_pk_add_f32 v[0:1], v[80:81], v[0:1] neg_lo:[0,1] neg_hi:[0,1]
	v_lshlrev_b32_e32 v80, 4, v102
	v_lshrrev_b32_e32 v81, 1, v102
	v_bitop3_b32 v101, v81, v80, 16 bitop3:0x6c
	v_lshl_add_u32 v101, v101, 3, 16
	v_lshlrev_b32_e32 v100, 3, v100
	v_add_u32_e32 v102, v101, v100
	ds_write_b64 v102, v[70:71]
	v_bitop3_b32 v70, v81, 1, 15 bitop3:0x6c
	v_lshlrev_b32_e32 v70, 3, v70
	v_add_u32_e32 v71, v101, v70
	ds_write_b64 v71, v[86:87]
	v_bitop3_b32 v71, v81, 2, 15 bitop3:0x6c
	v_lshlrev_b32_e32 v71, 3, v71
	v_add_u32_e32 v86, v101, v71
	ds_write_b64 v86, v[88:89]
	v_bitop3_b32 v86, v81, 3, 15 bitop3:0x6c
	v_lshlrev_b32_e32 v86, 3, v86
	v_add_u32_e32 v87, v101, v86
	ds_write_b64 v87, v[74:75]
	v_bitop3_b32 v74, v81, 4, 15 bitop3:0x6c
	v_lshlrev_b32_e32 v74, 3, v74
	v_add_u32_e32 v75, v101, v74
	ds_write_b64 v75, v[20:21]
	v_bitop3_b32 v20, v81, 5, 15 bitop3:0x6c
	v_lshlrev_b32_e32 v20, 3, v20
	v_add_u32_e32 v21, v101, v20
	ds_write_b64 v21, v[72:73]
	v_bitop3_b32 v21, v81, 6, 15 bitop3:0x6c
	v_lshlrev_b32_e32 v21, 3, v21
	v_add_u32_e32 v72, v101, v21
	ds_write_b64 v72, v[68:69]
	v_bitop3_b32 v68, v81, 7, 15 bitop3:0x6c
	v_lshlrev_b32_e32 v68, 3, v68
	v_add_u32_e32 v69, v101, v68
	ds_write_b64 v69, v[26:27]
	v_bitop3_b32 v26, v81, 8, 15 bitop3:0x6c
	v_lshlrev_b32_e32 v26, 3, v26
	v_add_u32_e32 v27, v101, v26
	ds_write_b64 v27, v[18:19]
	v_bitop3_b32 v18, v81, 9, 15 bitop3:0x6c
	v_lshlrev_b32_e32 v18, 3, v18
	v_add_u32_e32 v19, v101, v18
	ds_write_b64 v19, v[84:85]
	v_bitop3_b32 v19, v81, 10, 15 bitop3:0x6c
	v_lshlrev_b32_e32 v19, 3, v19
	v_add_u32_e32 v27, v101, v19
	ds_write_b64 v27, v[16:17]
	v_bitop3_b32 v16, v81, 11, 15 bitop3:0x6c
	v_lshlrev_b32_e32 v16, 3, v16
	v_add_u32_e32 v17, v101, v16
	ds_write_b64 v17, v[22:23]
	v_bitop3_b32 v17, v81, 12, 15 bitop3:0x6c
	v_lshlrev_b32_e32 v17, 3, v17
	v_add_u32_e32 v22, v101, v17
	ds_write_b64 v22, v[12:13]
	v_bitop3_b32 v12, v81, 13, 15 bitop3:0x6c
	v_lshlrev_b32_e32 v12, 3, v12
	v_add_u32_e32 v13, v101, v12
	ds_write_b64 v13, v[14:15]
	v_bitop3_b32 v13, v81, 14, 15 bitop3:0x6c
	v_lshlrev_b32_e32 v13, 3, v13
	v_add_u32_e32 v14, v101, v13
	ds_write_b64 v14, v[4:5]
	v_bitop3_b32 v4, v81, 15, v81 bitop3:0xc
	v_lshlrev_b32_e32 v4, 3, v4
	v_add_u32_e32 v5, v101, v4
	ds_write_b64 v5, v[8:9]
	v_add_u32_e32 v5, 0x2000, v80
	v_bitop3_b32 v5, v5, v81, 16 bitop3:0x78
	v_lshl_add_u32 v5, v5, 3, 16
	v_add_u32_e32 v8, v5, v100
	ds_write_b64 v8, v[64:65]
	v_add_u32_e32 v8, v5, v70
	ds_write_b64 v8, v[98:99]
	v_add_u32_e32 v8, v5, v71
	ds_write_b64 v8, v[96:97]
	v_add_u32_e32 v8, v5, v86
	ds_write_b64 v8, v[82:83]
	v_add_u32_e32 v8, v5, v74
	ds_write_b64 v8, v[78:79]
	v_add_u32_e32 v8, v5, v20
	ds_write_b64 v8, v[92:93]
	v_add_u32_e32 v8, v5, v21
	ds_write_b64 v8, v[76:77]
	v_add_u32_e32 v8, v5, v68
	ds_write_b64 v8, v[62:63]
	v_add_u32_e32 v8, v5, v26
	ds_write_b64 v8, v[90:91]
	v_add_u32_e32 v8, v5, v18
	ds_write_b64 v8, v[94:95]
	v_add_u32_e32 v8, v5, v19
	ds_write_b64 v8, v[10:11]
	v_add_u32_e32 v8, v5, v16
	ds_write_b64 v8, v[66:67]
	v_add_u32_e32 v8, v5, v17
	ds_write_b64 v8, v[6:7]
	v_add_u32_e32 v6, v5, v12
	ds_write_b64 v6, v[2:3]
	v_add_u32_e32 v2, v5, v13
	ds_write_b64 v2, v[24:25]
	v_add_u32_e32 v2, v5, v4
	v_mov_b32_e32 v22, v146
	ds_write_b64 v2, v[0:1]
	s_waitcnt lgkmcnt(0)
	s_barrier
	s_nop 0
	v_lshlrev_b32_e32 v0, 5, v22
	v_and_b32_e32 v2, 0xfffffe00, v0
	v_and_or_b32 v0, v22, 16, v2
	v_bitop3_b32 v2, v2, 16, v22 bitop3:0x34
	v_bitop3_b32 v6, v22, 4, 15 bitop3:0x6c
	v_bitop3_b32 v14, v22, 8, 15 bitop3:0x6c
	v_lshl_add_u32 v23, v0, 3, 16
	v_lshl_add_u32 v65, v2, 3, 16
	v_lshlrev_b32_e32 v6, 3, v6
	v_lshlrev_b32_e32 v14, 3, v14
	v_bitop3_b32 v2, v22, 1, 15 bitop3:0x6c
	v_add_u32_e32 v105, v23, v6
	v_add_u32_e32 v106, v65, v6
	v_bitop3_b32 v6, v22, 5, 15 bitop3:0x6c
	v_add_u32_e32 v113, v23, v14
	v_add_u32_e32 v114, v65, v14
	v_bitop3_b32 v14, v22, 9, 15 bitop3:0x6c
	v_lshlrev_b32_e32 v2, 3, v2
	v_lshlrev_b32_e32 v6, 3, v6
	v_lshlrev_b32_e32 v14, 3, v14
	v_add_u32_e32 v99, v23, v2
	v_add_u32_e32 v100, v65, v2
	v_bitop3_b32 v2, v22, 2, 15 bitop3:0x6c
	v_add_u32_e32 v107, v23, v6
	v_add_u32_e32 v108, v65, v6
	v_bitop3_b32 v6, v22, 6, 15 bitop3:0x6c
	v_add_u32_e32 v115, v23, v14
	v_add_u32_e32 v116, v65, v14
	v_bitop3_b32 v14, v22, 10, 15 bitop3:0x6c
	v_bitop3_b32 v26, v22, 12, 15 bitop3:0x6c
	v_lshlrev_b32_e32 v2, 3, v2
	v_lshlrev_b32_e32 v6, 3, v6
	v_lshlrev_b32_e32 v14, 3, v14
	v_lshlrev_b32_e32 v26, 3, v26
	v_and_b32_e32 v64, 15, v22
	v_add_u32_e32 v101, v23, v2
	v_add_u32_e32 v102, v65, v2
	v_bitop3_b32 v2, v22, 3, 15 bitop3:0x6c
	v_add_u32_e32 v109, v23, v6
	v_add_u32_e32 v110, v65, v6
	v_bitop3_b32 v6, v22, 7, 15 bitop3:0x6c
	v_add_u32_e32 v117, v23, v14
	v_add_u32_e32 v118, v65, v14
	v_bitop3_b32 v14, v22, 11, 15 bitop3:0x6c
	v_add_u32_e32 v121, v23, v26
	v_add_u32_e32 v122, v65, v26
	v_bitop3_b32 v26, v22, 13, 15 bitop3:0x6c
	v_bitop3_b32 v66, v22, 14, 15 bitop3:0x6c
	v_bitop3_b32 v22, v22, 15, v22 bitop3:0xc
	v_lshlrev_b32_e32 v3, 3, v64
	v_lshlrev_b32_e32 v2, 3, v2
	v_lshlrev_b32_e32 v6, 3, v6
	v_lshlrev_b32_e32 v14, 3, v14
	v_lshlrev_b32_e32 v26, 3, v26
	v_lshlrev_b32_e32 v66, 3, v66
	v_lshlrev_b32_e32 v22, 3, v22
	v_add_u32_e32 v67, v23, v3
	v_add_u32_e32 v98, v65, v3
	v_add_u32_e32 v103, v23, v2
	v_add_u32_e32 v104, v65, v2
	v_add_u32_e32 v111, v23, v6
	v_add_u32_e32 v112, v65, v6
	v_add_u32_e32 v119, v23, v14
	v_add_u32_e32 v120, v65, v14
	v_add_u32_e32 v123, v23, v26
	v_add_u32_e32 v124, v65, v26
	v_add_u32_e32 v125, v23, v66
	v_add_u32_e32 v126, v65, v66
	v_add_u32_e32 v127, v23, v22
	v_add_u32_e32 v128, v65, v22
	ds_read_b64 v[0:1], v67
	ds_read_b64 v[12:13], v98
	ds_read_b64 v[74:75], v99 offset:256
	ds_read_b64 v[4:5], v100 offset:256
	ds_read_b64 v[76:77], v101 offset:512
	ds_read_b64 v[10:11], v102 offset:512
	ds_read_b64 v[70:71], v103 offset:768
	ds_read_b64 v[2:3], v104 offset:768
	ds_read_b64 v[62:63], v105 offset:1024
	ds_read_b64 v[20:21], v106 offset:1024
	ds_read_b64 v[90:91], v107 offset:1280
	ds_read_b64 v[8:9], v108 offset:1280
	ds_read_b64 v[84:85], v109 offset:1536
	ds_read_b64 v[16:17], v110 offset:1536
	ds_read_b64 v[82:83], v111 offset:1792
	ds_read_b64 v[6:7], v112 offset:1792
	ds_read_b64 v[24:25], v113 offset:2048
	ds_read_b64 v[78:79], v114 offset:2048
	ds_read_b64 v[96:97], v115 offset:2304
	ds_read_b64 v[18:19], v116 offset:2304
	ds_read_b64 v[86:87], v117 offset:2560
	ds_read_b64 v[72:73], v118 offset:2560
	ds_read_b64 v[130:131], v119 offset:2816
	ds_read_b64 v[14:15], v120 offset:2816
	ds_read_b64 v[80:81], v121 offset:3072
	ds_read_b64 v[92:93], v122 offset:3072
	ds_read_b64 v[132:133], v123 offset:3328
	ds_read_b64 v[26:27], v124 offset:3328
	ds_read_b64 v[94:95], v125 offset:3584
	ds_read_b64 v[88:89], v126 offset:3584
	ds_read_b64 v[134:135], v127 offset:3840
	ds_read_b64 v[22:23], v128 offset:3840
	s_waitcnt lgkmcnt(14)
	v_xor_b32_e32 v138, 0x80000000, v25
	v_cvt_f32_i32_e32 v64, v64
	v_mov_b32_e32 v139, v24
	v_mul_f32_e32 v64, 0x3b000000, v64
	v_cos_f32_e32 v68, v64
	v_sin_f32_e32 v69, v64
	v_add_f32_e32 v66, v68, v68
	v_pk_mul_f32 v[64:65], v[68:69], v[68:69]
	v_mul_f32_e32 v66, v69, v66
	v_xor_b32_e32 v136, 0x80000000, v69
	v_mov_b32_e32 v137, v68
	v_mov_b32_e32 v140, v69
	v_pk_add_f32 v[64:65], v[64:65], v[64:65] op_sel:[0,1] op_sel_hi:[0,1] neg_lo:[0,1] neg_hi:[0,1]
	v_pk_mul_f32 v[136:137], v[136:137], v[66:67] op_sel_hi:[1,0]
	v_pk_mul_f32 v[138:139], v[138:139], v[140:141] op_sel_hi:[1,0]
	v_pk_fma_f32 v[136:137], v[68:69], v[64:65], v[136:137]
	v_pk_fma_f32 v[24:25], v[24:25], v[68:69], v[138:139] op_sel_hi:[1,0,1]
	v_pk_mul_f32 v[68:69], v[66:67], s[46:47] op_sel_hi:[0,1]
	v_pk_fma_f32 v[138:139], v[64:65], s[40:41], v[68:69]
	v_xor_b32_e32 v68, 0x80000000, v63
	v_mov_b32_e32 v69, v62
	v_pk_mul_f32 v[68:69], v[68:69], v[138:139] op_sel:[0,1]
	s_nop 0
	v_pk_fma_f32 v[68:69], v[62:63], v[138:139], v[68:69] op_sel_hi:[1,0,1]
	v_xor_b32_e32 v62, 0x80000000, v137
	v_mov_b32_e32 v63, v136
	v_pk_mul_f32 v[62:63], v[66:67], v[62:63] op_sel_hi:[0,1]
	v_pk_fma_f32 v[140:141], v[64:65], v[136:137], v[62:63]
	s_waitcnt lgkmcnt(7)
	v_xor_b32_e32 v62, 0x80000000, v81
	v_mov_b32_e32 v63, v80
	v_pk_mul_f32 v[62:63], v[62:63], v[136:137] op_sel:[0,1]
	s_nop 0
	v_pk_fma_f32 v[62:63], v[80:81], v[136:137], v[62:63] op_sel_hi:[1,0,1]
	v_xor_b32_e32 v80, 0x80000000, v139
	v_mov_b32_e32 v81, v138
	v_pk_mul_f32 v[80:81], v[66:67], v[80:81] op_sel_hi:[0,1]
	v_pk_fma_f32 v[136:137], v[64:65], v[138:139], v[80:81]
	v_xor_b32_e32 v80, 0x80000000, v77
	v_mov_b32_e32 v81, v76
	v_pk_mul_f32 v[80:81], v[80:81], v[136:137] op_sel:[0,1]
	s_nop 0
	v_pk_fma_f32 v[80:81], v[76:77], v[136:137], v[80:81] op_sel_hi:[1,0,1]
	v_xor_b32_e32 v76, 0x80000000, v141
	v_mov_b32_e32 v77, v140
	v_pk_mul_f32 v[76:77], v[66:67], v[76:77] op_sel_hi:[0,1]
	v_pk_fma_f32 v[138:139], v[64:65], v[140:141], v[76:77]
	v_xor_b32_e32 v76, 0x80000000, v87
	v_mov_b32_e32 v77, v86
	v_pk_mul_f32 v[76:77], v[76:77], v[140:141] op_sel:[0,1]
	s_nop 0
	v_pk_fma_f32 v[76:77], v[86:87], v[140:141], v[76:77] op_sel_hi:[1,0,1]
	v_xor_b32_e32 v86, 0x80000000, v137
	v_mov_b32_e32 v87, v136
	v_pk_mul_f32 v[86:87], v[66:67], v[86:87] op_sel_hi:[0,1]
	v_pk_fma_f32 v[136:137], v[64:65], v[136:137], v[86:87]
	v_xor_b32_e32 v86, 0x80000000, v85
	v_mov_b32_e32 v87, v84
	v_pk_mul_f32 v[86:87], v[86:87], v[136:137] op_sel:[0,1]
	s_nop 0
	v_pk_fma_f32 v[86:87], v[84:85], v[136:137], v[86:87] op_sel_hi:[1,0,1]
	v_xor_b32_e32 v84, 0x80000000, v139
	v_mov_b32_e32 v85, v138
	v_pk_mul_f32 v[84:85], v[66:67], v[84:85] op_sel_hi:[0,1]
	v_pk_fma_f32 v[140:141], v[64:65], v[138:139], v[84:85]
	s_waitcnt lgkmcnt(3)
	v_xor_b32_e32 v84, 0x80000000, v95
	v_mov_b32_e32 v85, v94
	v_pk_mul_f32 v[84:85], v[84:85], v[138:139] op_sel:[0,1]
	s_nop 0
	v_pk_fma_f32 v[84:85], v[94:95], v[138:139], v[84:85] op_sel_hi:[1,0,1]
	v_xor_b32_e32 v94, 0x80000000, v137
	v_mov_b32_e32 v95, v136
	v_pk_mul_f32 v[94:95], v[66:67], v[94:95] op_sel_hi:[0,1]
	v_pk_fma_f32 v[136:137], v[64:65], v[136:137], v[94:95]
	v_xor_b32_e32 v94, 0x80000000, v75
	v_mov_b32_e32 v95, v74
	v_pk_mul_f32 v[94:95], v[94:95], v[136:137] op_sel:[0,1]
	s_nop 0
	v_pk_fma_f32 v[94:95], v[74:75], v[136:137], v[94:95] op_sel_hi:[1,0,1]
	v_xor_b32_e32 v74, 0x80000000, v141
	v_mov_b32_e32 v75, v140
	v_pk_mul_f32 v[74:75], v[66:67], v[74:75] op_sel_hi:[0,1]
	v_pk_fma_f32 v[138:139], v[64:65], v[140:141], v[74:75]
	v_xor_b32_e32 v74, 0x80000000, v97
	v_mov_b32_e32 v75, v96
	v_pk_mul_f32 v[74:75], v[74:75], v[140:141] op_sel:[0,1]
	s_nop 0
	v_pk_fma_f32 v[74:75], v[96:97], v[140:141], v[74:75] op_sel_hi:[1,0,1]
	v_xor_b32_e32 v96, 0x80000000, v137
	v_mov_b32_e32 v97, v136
	v_pk_mul_f32 v[96:97], v[66:67], v[96:97] op_sel_hi:[0,1]
	v_pk_fma_f32 v[136:137], v[64:65], v[136:137], v[96:97]
	v_xor_b32_e32 v96, 0x80000000, v91
	v_mov_b32_e32 v97, v90
	v_pk_mul_f32 v[96:97], v[96:97], v[136:137] op_sel:[0,1]
	s_nop 0
	v_pk_fma_f32 v[96:97], v[90:91], v[136:137], v[96:97] op_sel_hi:[1,0,1]
	v_xor_b32_e32 v90, 0x80000000, v139
	v_mov_b32_e32 v91, v138
	v_pk_mul_f32 v[90:91], v[66:67], v[90:91] op_sel_hi:[0,1]
	v_pk_fma_f32 v[140:141], v[64:65], v[138:139], v[90:91]
	v_xor_b32_e32 v90, 0x80000000, v133
	v_mov_b32_e32 v91, v132
	v_pk_mul_f32 v[90:91], v[90:91], v[138:139] op_sel:[0,1]
	s_nop 0
	v_pk_fma_f32 v[90:91], v[132:133], v[138:139], v[90:91] op_sel_hi:[1,0,1]
	v_xor_b32_e32 v132, 0x80000000, v137
	v_mov_b32_e32 v133, v136
	v_pk_mul_f32 v[132:133], v[66:67], v[132:133] op_sel_hi:[0,1]
	v_xor_b32_e32 v138, 0x80000000, v131
	v_mov_b32_e32 v139, v130
	v_pk_fma_f32 v[132:133], v[64:65], v[136:137], v[132:133]
	v_xor_b32_e32 v136, 0x80000000, v71
	v_mov_b32_e32 v137, v70
	v_pk_mul_f32 v[138:139], v[138:139], v[140:141] op_sel:[0,1]
	v_pk_mul_f32 v[136:137], v[136:137], v[132:133] op_sel:[0,1]
	v_pk_fma_f32 v[130:131], v[130:131], v[140:141], v[138:139] op_sel_hi:[1,0,1]
	v_xor_b32_e32 v138, 0x80000000, v133
	v_mov_b32_e32 v139, v132
	v_pk_fma_f32 v[70:71], v[70:71], v[132:133], v[136:137] op_sel_hi:[1,0,1]
	v_xor_b32_e32 v136, 0x80000000, v141
	v_mov_b32_e32 v137, v140
	v_pk_mul_f32 v[138:139], v[66:67], v[138:139] op_sel_hi:[0,1]
	v_pk_mul_f32 v[136:137], v[66:67], v[136:137] op_sel_hi:[0,1]
	v_pk_fma_f32 v[132:133], v[64:65], v[132:133], v[138:139]
	v_xor_b32_e32 v138, 0x80000000, v83
	v_mov_b32_e32 v139, v82
	v_pk_fma_f32 v[136:137], v[64:65], v[140:141], v[136:137]
	v_pk_mul_f32 v[138:139], v[138:139], v[132:133] op_sel:[0,1]
	s_waitcnt lgkmcnt(1)
	v_xor_b32_e32 v140, 0x80000000, v135
	v_pk_fma_f32 v[82:83], v[82:83], v[132:133], v[138:139] op_sel_hi:[1,0,1]
	v_xor_b32_e32 v138, 0x80000000, v137
	v_mov_b32_e32 v139, v136
	v_mov_b32_e32 v141, v134
	v_pk_mul_f32 v[138:139], v[66:67], v[138:139] op_sel_hi:[0,1]
	v_pk_mul_f32 v[140:141], v[140:141], v[136:137] op_sel:[0,1]
	v_pk_fma_f32 v[138:139], v[64:65], v[136:137], v[138:139]
	v_pk_fma_f32 v[134:135], v[134:135], v[136:137], v[140:141] op_sel_hi:[1,0,1]
	v_xor_b32_e32 v136, 0x80000000, v133
	v_mov_b32_e32 v137, v132
	v_pk_mul_f32 v[136:137], v[66:67], v[136:137] op_sel_hi:[0,1]
	v_pk_fma_f32 v[132:133], v[64:65], v[132:133], v[136:137]
	v_xor_b32_e32 v136, 0x80000000, v13
	v_mov_b32_e32 v137, v12
	v_pk_mul_f32 v[136:137], v[136:137], v[132:133] op_sel:[0,1]
	v_xor_b32_e32 v140, 0x80000000, v79
	v_pk_fma_f32 v[12:13], v[12:13], v[132:133], v[136:137] op_sel_hi:[1,0,1]
	v_xor_b32_e32 v136, 0x80000000, v139
	v_mov_b32_e32 v137, v138
	v_mov_b32_e32 v141, v78
	v_pk_mul_f32 v[136:137], v[66:67], v[136:137] op_sel_hi:[0,1]
	v_pk_mul_f32 v[140:141], v[140:141], v[138:139] op_sel:[0,1]
	v_pk_fma_f32 v[136:137], v[64:65], v[138:139], v[136:137]
	v_pk_fma_f32 v[78:79], v[78:79], v[138:139], v[140:141] op_sel_hi:[1,0,1]
	v_xor_b32_e32 v138, 0x80000000, v133
	v_mov_b32_e32 v139, v132
	v_pk_mul_f32 v[138:139], v[66:67], v[138:139] op_sel_hi:[0,1]
	v_pk_fma_f32 v[132:133], v[64:65], v[132:133], v[138:139]
	v_xor_b32_e32 v138, 0x80000000, v21
	v_mov_b32_e32 v139, v20
	v_pk_mul_f32 v[138:139], v[138:139], v[132:133] op_sel:[0,1]
	v_xor_b32_e32 v140, 0x80000000, v93
	v_pk_fma_f32 v[20:21], v[20:21], v[132:133], v[138:139] op_sel_hi:[1,0,1]
	v_xor_b32_e32 v138, 0x80000000, v137
	v_mov_b32_e32 v139, v136
	v_mov_b32_e32 v141, v92
	v_pk_mul_f32 v[138:139], v[66:67], v[138:139] op_sel_hi:[0,1]
	v_pk_mul_f32 v[140:141], v[140:141], v[136:137] op_sel:[0,1]
	v_pk_fma_f32 v[138:139], v[64:65], v[136:137], v[138:139]
	v_pk_fma_f32 v[92:93], v[92:93], v[136:137], v[140:141] op_sel_hi:[1,0,1]
	v_xor_b32_e32 v136, 0x80000000, v133
	v_mov_b32_e32 v137, v132
	v_pk_mul_f32 v[136:137], v[66:67], v[136:137] op_sel_hi:[0,1]
	v_pk_fma_f32 v[132:133], v[64:65], v[132:133], v[136:137]
	v_xor_b32_e32 v136, 0x80000000, v11
	v_mov_b32_e32 v137, v10
	v_pk_mul_f32 v[136:137], v[136:137], v[132:133] op_sel:[0,1]
	v_xor_b32_e32 v140, 0x80000000, v73
	v_pk_fma_f32 v[10:11], v[10:11], v[132:133], v[136:137] op_sel_hi:[1,0,1]
	v_xor_b32_e32 v136, 0x80000000, v139
	v_mov_b32_e32 v137, v138
	v_mov_b32_e32 v141, v72
	v_pk_mul_f32 v[136:137], v[66:67], v[136:137] op_sel_hi:[0,1]
	v_pk_mul_f32 v[140:141], v[140:141], v[138:139] op_sel:[0,1]
	v_pk_fma_f32 v[136:137], v[64:65], v[138:139], v[136:137]
	v_pk_fma_f32 v[72:73], v[72:73], v[138:139], v[140:141] op_sel_hi:[1,0,1]
	v_xor_b32_e32 v138, 0x80000000, v133
	v_mov_b32_e32 v139, v132
	v_pk_mul_f32 v[138:139], v[66:67], v[138:139] op_sel_hi:[0,1]
	v_pk_fma_f32 v[132:133], v[64:65], v[132:133], v[138:139]
	v_xor_b32_e32 v138, 0x80000000, v17
	v_mov_b32_e32 v139, v16
	v_pk_mul_f32 v[138:139], v[138:139], v[132:133] op_sel:[0,1]
	v_xor_b32_e32 v140, 0x80000000, v89
	v_pk_fma_f32 v[16:17], v[16:17], v[132:133], v[138:139] op_sel_hi:[1,0,1]
	v_xor_b32_e32 v138, 0x80000000, v137
	v_mov_b32_e32 v139, v136
	v_mov_b32_e32 v141, v88
	v_pk_mul_f32 v[138:139], v[66:67], v[138:139] op_sel_hi:[0,1]
	v_pk_mul_f32 v[140:141], v[140:141], v[136:137] op_sel:[0,1]
	v_pk_fma_f32 v[138:139], v[64:65], v[136:137], v[138:139]
	v_pk_fma_f32 v[88:89], v[88:89], v[136:137], v[140:141] op_sel_hi:[1,0,1]
	v_xor_b32_e32 v136, 0x80000000, v133
	v_mov_b32_e32 v137, v132
	v_pk_mul_f32 v[136:137], v[66:67], v[136:137] op_sel_hi:[0,1]
	v_pk_fma_f32 v[132:133], v[64:65], v[132:133], v[136:137]
	v_xor_b32_e32 v136, 0x80000000, v5
	v_mov_b32_e32 v137, v4
	v_pk_mul_f32 v[136:137], v[136:137], v[132:133] op_sel:[0,1]
	v_xor_b32_e32 v140, 0x80000000, v19
	v_pk_fma_f32 v[4:5], v[4:5], v[132:133], v[136:137] op_sel_hi:[1,0,1]
	v_xor_b32_e32 v136, 0x80000000, v139
	v_mov_b32_e32 v137, v138
	v_mov_b32_e32 v141, v18
	v_pk_mul_f32 v[136:137], v[66:67], v[136:137] op_sel_hi:[0,1]
	v_pk_mul_f32 v[140:141], v[140:141], v[138:139] op_sel:[0,1]
	v_pk_fma_f32 v[136:137], v[64:65], v[138:139], v[136:137]
	v_pk_fma_f32 v[18:19], v[18:19], v[138:139], v[140:141] op_sel_hi:[1,0,1]
	v_xor_b32_e32 v138, 0x80000000, v133
	v_mov_b32_e32 v139, v132
	v_pk_mul_f32 v[138:139], v[66:67], v[138:139] op_sel_hi:[0,1]
	v_pk_fma_f32 v[132:133], v[64:65], v[132:133], v[138:139]
	v_xor_b32_e32 v138, 0x80000000, v9
	v_mov_b32_e32 v139, v8
	v_pk_mul_f32 v[138:139], v[138:139], v[132:133] op_sel:[0,1]
	v_xor_b32_e32 v140, 0x80000000, v27
	v_pk_fma_f32 v[8:9], v[8:9], v[132:133], v[138:139] op_sel_hi:[1,0,1]
	v_xor_b32_e32 v138, 0x80000000, v137
	v_mov_b32_e32 v139, v136
	v_mov_b32_e32 v141, v26
	v_pk_mul_f32 v[138:139], v[66:67], v[138:139] op_sel_hi:[0,1]
	v_pk_mul_f32 v[140:141], v[140:141], v[136:137] op_sel:[0,1]
	v_pk_fma_f32 v[138:139], v[64:65], v[136:137], v[138:139]
	v_pk_fma_f32 v[26:27], v[26:27], v[136:137], v[140:141] op_sel_hi:[1,0,1]
	v_xor_b32_e32 v136, 0x80000000, v133
	v_mov_b32_e32 v137, v132
	v_pk_mul_f32 v[136:137], v[66:67], v[136:137] op_sel_hi:[0,1]
	v_pk_fma_f32 v[132:133], v[64:65], v[132:133], v[136:137]
	v_xor_b32_e32 v136, 0x80000000, v3
	v_mov_b32_e32 v137, v2
	v_pk_mul_f32 v[136:137], v[136:137], v[132:133] op_sel:[0,1]
	v_xor_b32_e32 v140, 0x80000000, v15
	v_pk_fma_f32 v[2:3], v[2:3], v[132:133], v[136:137] op_sel_hi:[1,0,1]
	v_xor_b32_e32 v136, 0x80000000, v139
	v_mov_b32_e32 v137, v138
	v_mov_b32_e32 v141, v14
	v_pk_mul_f32 v[136:137], v[66:67], v[136:137] op_sel_hi:[0,1]
	v_pk_mul_f32 v[140:141], v[140:141], v[138:139] op_sel:[0,1]
	v_pk_fma_f32 v[136:137], v[64:65], v[138:139], v[136:137]
	v_pk_fma_f32 v[14:15], v[14:15], v[138:139], v[140:141] op_sel_hi:[1,0,1]
	v_xor_b32_e32 v138, 0x80000000, v133
	v_mov_b32_e32 v139, v132
	v_pk_mul_f32 v[138:139], v[66:67], v[138:139] op_sel_hi:[0,1]
	v_pk_fma_f32 v[64:65], v[64:65], v[132:133], v[138:139]
	v_xor_b32_e32 v132, 0x80000000, v7
	v_mov_b32_e32 v133, v6
	v_pk_mul_f32 v[132:133], v[132:133], v[64:65] op_sel:[0,1]
	s_nop 0
	v_pk_fma_f32 v[6:7], v[6:7], v[64:65], v[132:133] op_sel_hi:[1,0,1]
	s_waitcnt lgkmcnt(0)
	v_xor_b32_e32 v64, 0x80000000, v23
	v_mov_b32_e32 v65, v22
	v_pk_mul_f32 v[64:65], v[64:65], v[136:137] op_sel:[0,1]
	s_nop 0
	v_pk_fma_f32 v[22:23], v[22:23], v[136:137], v[64:65] op_sel_hi:[1,0,1]
	v_pk_add_f32 v[64:65], v[0:1], v[12:13]
	v_pk_add_f32 v[0:1], v[0:1], v[12:13] neg_lo:[0,1] neg_hi:[0,1]
	v_pk_add_f32 v[12:13], v[94:95], v[4:5]
	v_pk_add_f32 v[4:5], v[94:95], v[4:5] neg_lo:[0,1] neg_hi:[0,1]
	v_pk_add_f32 v[94:95], v[80:81], v[10:11]
	v_pk_add_f32 v[10:11], v[80:81], v[10:11] neg_lo:[0,1] neg_hi:[0,1]
	v_pk_add_f32 v[80:81], v[70:71], v[2:3]
	v_pk_add_f32 v[2:3], v[70:71], v[2:3] neg_lo:[0,1] neg_hi:[0,1]
	v_pk_add_f32 v[132:133], v[64:65], v[12:13]
	v_pk_add_f32 v[12:13], v[64:65], v[12:13] neg_lo:[0,1] neg_hi:[0,1]
	v_xor_b32_e32 v64, 0x80000000, v5
	v_mov_b32_e32 v65, v4
	v_pk_add_f32 v[70:71], v[68:69], v[20:21]
	v_pk_add_f32 v[20:21], v[68:69], v[20:21] neg_lo:[0,1] neg_hi:[0,1]
	v_pk_add_f32 v[68:69], v[96:97], v[8:9]
	v_pk_add_f32 v[8:9], v[96:97], v[8:9] neg_lo:[0,1] neg_hi:[0,1]
	v_pk_add_f32 v[4:5], v[0:1], v[64:65]
	v_pk_add_f32 v[0:1], v[0:1], v[64:65] neg_lo:[0,1] neg_hi:[0,1]
	v_pk_add_f32 v[64:65], v[94:95], v[80:81]
	v_pk_add_f32 v[80:81], v[94:95], v[80:81] neg_lo:[0,1] neg_hi:[0,1]
	v_xor_b32_e32 v94, 0x80000000, v3
	v_mov_b32_e32 v95, v2
	v_pk_add_f32 v[96:97], v[86:87], v[16:17]
	v_pk_add_f32 v[16:17], v[86:87], v[16:17] neg_lo:[0,1] neg_hi:[0,1]
	v_pk_add_f32 v[86:87], v[82:83], v[6:7]
	v_pk_add_f32 v[6:7], v[82:83], v[6:7] neg_lo:[0,1] neg_hi:[0,1]
	v_pk_add_f32 v[2:3], v[10:11], v[94:95]
	v_pk_add_f32 v[10:11], v[10:11], v[94:95] neg_lo:[0,1] neg_hi:[0,1]
	v_pk_add_f32 v[94:95], v[70:71], v[68:69]
	v_pk_add_f32 v[68:69], v[70:71], v[68:69] neg_lo:[0,1] neg_hi:[0,1]
	v_xor_b32_e32 v70, 0x80000000, v9
	v_mov_b32_e32 v71, v8
	v_pk_add_f32 v[82:83], v[24:25], v[78:79]
	v_pk_add_f32 v[24:25], v[24:25], v[78:79] neg_lo:[0,1] neg_hi:[0,1]
	v_pk_add_f32 v[78:79], v[74:75], v[18:19]
	v_pk_add_f32 v[18:19], v[74:75], v[18:19] neg_lo:[0,1] neg_hi:[0,1]
	v_pk_add_f32 v[8:9], v[20:21], v[70:71]
	v_pk_add_f32 v[20:21], v[20:21], v[70:71] neg_lo:[0,1] neg_hi:[0,1]
	v_pk_add_f32 v[70:71], v[96:97], v[86:87]
	v_pk_add_f32 v[86:87], v[96:97], v[86:87] neg_lo:[0,1] neg_hi:[0,1]
	v_xor_b32_e32 v96, 0x80000000, v7
	v_mov_b32_e32 v97, v6
	v_pk_add_f32 v[74:75], v[76:77], v[72:73]
	v_pk_add_f32 v[72:73], v[76:77], v[72:73] neg_lo:[0,1] neg_hi:[0,1]
	v_pk_add_f32 v[76:77], v[130:131], v[14:15]
	v_pk_add_f32 v[14:15], v[130:131], v[14:15] neg_lo:[0,1] neg_hi:[0,1]
	v_pk_add_f32 v[6:7], v[16:17], v[96:97]
	v_pk_add_f32 v[16:17], v[16:17], v[96:97] neg_lo:[0,1] neg_hi:[0,1]
	v_pk_add_f32 v[96:97], v[82:83], v[78:79]
	v_pk_add_f32 v[78:79], v[82:83], v[78:79] neg_lo:[0,1] neg_hi:[0,1]
	v_xor_b32_e32 v82, 0x80000000, v19
	v_mov_b32_e32 v83, v18
	v_pk_add_f32 v[130:131], v[62:63], v[92:93]
	v_pk_add_f32 v[62:63], v[62:63], v[92:93] neg_lo:[0,1] neg_hi:[0,1]
	v_pk_add_f32 v[92:93], v[90:91], v[26:27]
	v_pk_add_f32 v[26:27], v[90:91], v[26:27] neg_lo:[0,1] neg_hi:[0,1]
	v_pk_add_f32 v[18:19], v[24:25], v[82:83]
	v_pk_add_f32 v[24:25], v[24:25], v[82:83] neg_lo:[0,1] neg_hi:[0,1]
	v_pk_add_f32 v[82:83], v[74:75], v[76:77]
	v_pk_add_f32 v[74:75], v[74:75], v[76:77] neg_lo:[0,1] neg_hi:[0,1]
	v_xor_b32_e32 v76, 0x80000000, v15
	v_mov_b32_e32 v77, v14
	v_pk_add_f32 v[90:91], v[84:85], v[88:89]
	v_pk_add_f32 v[84:85], v[84:85], v[88:89] neg_lo:[0,1] neg_hi:[0,1]
	v_pk_add_f32 v[88:89], v[134:135], v[22:23]
	v_pk_add_f32 v[22:23], v[134:135], v[22:23] neg_lo:[0,1] neg_hi:[0,1]
	v_pk_add_f32 v[14:15], v[72:73], v[76:77]
	v_pk_add_f32 v[72:73], v[72:73], v[76:77] neg_lo:[0,1] neg_hi:[0,1]
	v_pk_add_f32 v[76:77], v[130:131], v[92:93]
	v_pk_add_f32 v[92:93], v[130:131], v[92:93] neg_lo:[0,1] neg_hi:[0,1]
	v_xor_b32_e32 v130, 0x80000000, v27
	v_mov_b32_e32 v131, v26
	v_pk_add_f32 v[26:27], v[62:63], v[130:131]
	v_pk_add_f32 v[62:63], v[62:63], v[130:131] neg_lo:[0,1] neg_hi:[0,1]
	v_pk_add_f32 v[130:131], v[90:91], v[88:89]
	v_pk_add_f32 v[88:89], v[90:91], v[88:89] neg_lo:[0,1] neg_hi:[0,1]
	v_xor_b32_e32 v90, 0x80000000, v23
	v_mov_b32_e32 v91, v22
	v_pk_add_f32 v[22:23], v[84:85], v[90:91]
	v_pk_add_f32 v[84:85], v[84:85], v[90:91] neg_lo:[0,1] neg_hi:[0,1]
	v_pk_add_f32 v[90:91], v[132:133], v[64:65]
	v_pk_add_f32 v[64:65], v[132:133], v[64:65] neg_lo:[0,1] neg_hi:[0,1]
	v_xor_b32_e32 v132, 0x80000000, v3
	v_mov_b32_e32 v133, v2
	v_pk_mul_f32 v[132:133], v[132:133], s[60:61] op_sel_hi:[1,0]
	v_xor_b32_e32 v134, 0x80000000, v11
	v_pk_fma_f32 v[2:3], v[2:3], s[60:61], v[132:133] op_sel_hi:[1,0,1]
	v_mov_b32_e32 v135, v10
	v_pk_add_f32 v[132:133], v[4:5], v[2:3]
	v_pk_add_f32 v[2:3], v[4:5], v[2:3] neg_lo:[0,1] neg_hi:[0,1]
	v_xor_b32_e32 v4, 0x80000000, v81
	v_mov_b32_e32 v5, v80
	v_pk_add_f32 v[80:81], v[12:13], v[4:5]
	v_pk_add_f32 v[4:5], v[12:13], v[4:5] neg_lo:[0,1] neg_hi:[0,1]
	v_pk_mul_f32 v[12:13], v[10:11], s[60:61] op_sel_hi:[1,0]
	s_nop 0
	v_pk_fma_f32 v[10:11], v[134:135], s[60:61], v[12:13] op_sel_hi:[1,0,1] neg_lo:[0,0,1] neg_hi:[0,0,1]
	v_xor_b32_e32 v134, 0x80000000, v17
	v_pk_add_f32 v[12:13], v[0:1], v[10:11]
	v_pk_add_f32 v[0:1], v[0:1], v[10:11] neg_lo:[0,1] neg_hi:[0,1]
	v_pk_add_f32 v[10:11], v[94:95], v[70:71]
	v_pk_add_f32 v[70:71], v[94:95], v[70:71] neg_lo:[0,1] neg_hi:[0,1]
	v_xor_b32_e32 v94, 0x80000000, v7
	v_mov_b32_e32 v95, v6
	v_pk_mul_f32 v[94:95], v[94:95], s[60:61] op_sel_hi:[1,0]
	v_mov_b32_e32 v135, v16
	v_pk_fma_f32 v[6:7], v[6:7], s[60:61], v[94:95] op_sel_hi:[1,0,1]
	s_nop 0
	v_pk_add_f32 v[94:95], v[8:9], v[6:7]
	v_pk_add_f32 v[6:7], v[8:9], v[6:7] neg_lo:[0,1] neg_hi:[0,1]
	v_xor_b32_e32 v8, 0x80000000, v87
	v_mov_b32_e32 v9, v86
	v_pk_add_f32 v[86:87], v[68:69], v[8:9]
	v_pk_add_f32 v[8:9], v[68:69], v[8:9] neg_lo:[0,1] neg_hi:[0,1]
	v_pk_mul_f32 v[68:69], v[16:17], s[60:61] op_sel_hi:[1,0]
	s_nop 0
	v_pk_fma_f32 v[16:17], v[134:135], s[60:61], v[68:69] op_sel_hi:[1,0,1] neg_lo:[0,0,1] neg_hi:[0,0,1]
	v_xor_b32_e32 v134, 0x80000000, v73
	v_pk_add_f32 v[68:69], v[20:21], v[16:17]
	v_pk_add_f32 v[16:17], v[20:21], v[16:17] neg_lo:[0,1] neg_hi:[0,1]
	v_pk_add_f32 v[20:21], v[96:97], v[82:83]
	v_pk_add_f32 v[82:83], v[96:97], v[82:83] neg_lo:[0,1] neg_hi:[0,1]
	v_xor_b32_e32 v96, 0x80000000, v15
	v_mov_b32_e32 v97, v14
	v_pk_mul_f32 v[96:97], v[96:97], s[60:61] op_sel_hi:[1,0]
	v_mov_b32_e32 v135, v72
	v_pk_fma_f32 v[14:15], v[14:15], s[60:61], v[96:97] op_sel_hi:[1,0,1]
	s_nop 0
	v_pk_add_f32 v[96:97], v[18:19], v[14:15]
	v_pk_add_f32 v[14:15], v[18:19], v[14:15] neg_lo:[0,1] neg_hi:[0,1]
	v_xor_b32_e32 v18, 0x80000000, v75
	v_mov_b32_e32 v19, v74
	v_pk_add_f32 v[74:75], v[78:79], v[18:19]
	v_pk_add_f32 v[18:19], v[78:79], v[18:19] neg_lo:[0,1] neg_hi:[0,1]
	v_pk_mul_f32 v[78:79], v[72:73], s[60:61] op_sel_hi:[1,0]
	s_nop 0
	v_pk_fma_f32 v[72:73], v[134:135], s[60:61], v[78:79] op_sel_hi:[1,0,1] neg_lo:[0,0,1] neg_hi:[0,0,1]
	v_xor_b32_e32 v134, 0x80000000, v85
	v_pk_add_f32 v[78:79], v[24:25], v[72:73]
	v_pk_add_f32 v[24:25], v[24:25], v[72:73] neg_lo:[0,1] neg_hi:[0,1]
	v_pk_add_f32 v[72:73], v[76:77], v[130:131]
	v_pk_add_f32 v[76:77], v[76:77], v[130:131] neg_lo:[0,1] neg_hi:[0,1]
	v_xor_b32_e32 v130, 0x80000000, v23
	v_mov_b32_e32 v131, v22
	v_pk_mul_f32 v[130:131], v[130:131], s[60:61] op_sel_hi:[1,0]
	v_mov_b32_e32 v135, v84
	v_pk_fma_f32 v[22:23], v[22:23], s[60:61], v[130:131] op_sel_hi:[1,0,1]
	s_nop 0
	v_pk_add_f32 v[130:131], v[26:27], v[22:23]
	v_pk_add_f32 v[22:23], v[26:27], v[22:23] neg_lo:[0,1] neg_hi:[0,1]
	v_xor_b32_e32 v26, 0x80000000, v89
	v_mov_b32_e32 v27, v88
	v_pk_add_f32 v[88:89], v[92:93], v[26:27]
	v_pk_add_f32 v[26:27], v[92:93], v[26:27] neg_lo:[0,1] neg_hi:[0,1]
	v_pk_mul_f32 v[92:93], v[84:85], s[60:61] op_sel_hi:[1,0]
	s_nop 0
	v_pk_fma_f32 v[84:85], v[134:135], s[60:61], v[92:93] op_sel_hi:[1,0,1] neg_lo:[0,0,1] neg_hi:[0,0,1]
	v_xor_b32_e32 v134, 0x80000000, v7
	v_pk_add_f32 v[92:93], v[62:63], v[84:85]
	v_pk_add_f32 v[62:63], v[62:63], v[84:85] neg_lo:[0,1] neg_hi:[0,1]
	v_pk_add_f32 v[84:85], v[90:91], v[10:11]
	v_pk_add_f32 v[10:11], v[90:91], v[10:11] neg_lo:[0,1] neg_hi:[0,1]
	v_xor_b32_e32 v90, 0x80000000, v95
	v_mov_b32_e32 v91, v94
	v_pk_mul_f32 v[90:91], v[90:91], s[54:55] op_sel_hi:[1,0]
	v_mov_b32_e32 v135, v6
	v_pk_fma_f32 v[90:91], v[94:95], s[52:53], v[90:91] op_sel_hi:[1,0,1]
	s_nop 0
	v_pk_add_f32 v[94:95], v[132:133], v[90:91]
	v_pk_add_f32 v[90:91], v[132:133], v[90:91] neg_lo:[0,1] neg_hi:[0,1]
	v_xor_b32_e32 v132, 0x80000000, v87
	v_mov_b32_e32 v133, v86
	v_pk_mul_f32 v[132:133], v[132:133], s[60:61] op_sel_hi:[1,0]
	s_nop 0
	v_pk_fma_f32 v[86:87], v[86:87], s[60:61], v[132:133] op_sel_hi:[1,0,1]
	s_nop 0
	v_pk_add_f32 v[132:133], v[80:81], v[86:87]
	v_pk_add_f32 v[80:81], v[80:81], v[86:87] neg_lo:[0,1] neg_hi:[0,1]
	v_xor_b32_e32 v86, 0x80000000, v69
	v_mov_b32_e32 v87, v68
	v_pk_mul_f32 v[86:87], v[86:87], s[52:53] op_sel_hi:[1,0]
	s_nop 0
	v_pk_fma_f32 v[68:69], v[68:69], s[54:55], v[86:87] op_sel_hi:[1,0,1]
	s_nop 0
	v_pk_add_f32 v[86:87], v[12:13], v[68:69]
	v_pk_add_f32 v[12:13], v[12:13], v[68:69] neg_lo:[0,1] neg_hi:[0,1]
	v_xor_b32_e32 v68, 0x80000000, v71
	v_mov_b32_e32 v69, v70
	v_pk_add_f32 v[70:71], v[64:65], v[68:69]
	v_pk_add_f32 v[64:65], v[64:65], v[68:69] neg_lo:[0,1] neg_hi:[0,1]
	v_pk_mul_f32 v[68:69], v[6:7], s[54:55] op_sel_hi:[1,0]
	s_nop 0
	v_pk_fma_f32 v[6:7], v[134:135], s[52:53], v[68:69] op_sel_hi:[1,0,1] neg_lo:[0,0,1] neg_hi:[0,0,1]
	v_xor_b32_e32 v134, 0x80000000, v9
	v_pk_add_f32 v[68:69], v[2:3], v[6:7]
	v_pk_add_f32 v[2:3], v[2:3], v[6:7] neg_lo:[0,1] neg_hi:[0,1]
	v_pk_mul_f32 v[6:7], v[8:9], s[60:61] op_sel_hi:[1,0]
	v_mov_b32_e32 v135, v8
	v_pk_fma_f32 v[6:7], v[134:135], s[60:61], v[6:7] op_sel_hi:[1,0,1] neg_lo:[0,0,1] neg_hi:[0,0,1]
	v_xor_b32_e32 v134, 0x80000000, v17
	v_pk_add_f32 v[8:9], v[4:5], v[6:7]
	v_pk_add_f32 v[4:5], v[4:5], v[6:7] neg_lo:[0,1] neg_hi:[0,1]
	v_pk_mul_f32 v[6:7], v[16:17], s[52:53] op_sel_hi:[1,0]
	v_mov_b32_e32 v135, v16
	v_pk_fma_f32 v[6:7], v[134:135], s[54:55], v[6:7] op_sel_hi:[1,0,1] neg_lo:[0,0,1] neg_hi:[0,0,1]
	v_xor_b32_e32 v134, 0x80000000, v23
	v_pk_add_f32 v[16:17], v[0:1], v[6:7]
	v_pk_add_f32 v[0:1], v[0:1], v[6:7] neg_lo:[0,1] neg_hi:[0,1]
	v_pk_add_f32 v[6:7], v[20:21], v[72:73]
	v_pk_add_f32 v[20:21], v[20:21], v[72:73] neg_lo:[0,1] neg_hi:[0,1]
	v_xor_b32_e32 v72, 0x80000000, v131
	v_mov_b32_e32 v73, v130
	v_pk_mul_f32 v[72:73], v[72:73], s[54:55] op_sel_hi:[1,0]
	v_mov_b32_e32 v135, v22
	v_pk_fma_f32 v[72:73], v[130:131], s[52:53], v[72:73] op_sel_hi:[1,0,1]
	s_nop 0
	v_pk_add_f32 v[130:131], v[96:97], v[72:73]
	v_pk_add_f32 v[72:73], v[96:97], v[72:73] neg_lo:[0,1] neg_hi:[0,1]
	v_xor_b32_e32 v96, 0x80000000, v89
	v_mov_b32_e32 v97, v88
	v_pk_mul_f32 v[96:97], v[96:97], s[60:61] op_sel_hi:[1,0]
	s_nop 0
	v_pk_fma_f32 v[88:89], v[88:89], s[60:61], v[96:97] op_sel_hi:[1,0,1]
	s_nop 0
	v_pk_add_f32 v[96:97], v[74:75], v[88:89]
	v_pk_add_f32 v[74:75], v[74:75], v[88:89] neg_lo:[0,1] neg_hi:[0,1]
	v_xor_b32_e32 v88, 0x80000000, v93
	v_mov_b32_e32 v89, v92
	v_pk_mul_f32 v[88:89], v[88:89], s[52:53] op_sel_hi:[1,0]
	s_nop 0
	v_pk_fma_f32 v[88:89], v[92:93], s[54:55], v[88:89] op_sel_hi:[1,0,1]
	s_nop 0
	v_pk_add_f32 v[92:93], v[78:79], v[88:89]
	v_pk_add_f32 v[78:79], v[78:79], v[88:89] neg_lo:[0,1] neg_hi:[0,1]
	v_xor_b32_e32 v88, 0x80000000, v77
	v_mov_b32_e32 v89, v76
	v_pk_add_f32 v[76:77], v[82:83], v[88:89]
	v_pk_add_f32 v[82:83], v[82:83], v[88:89] neg_lo:[0,1] neg_hi:[0,1]
	v_pk_mul_f32 v[88:89], v[22:23], s[54:55] op_sel_hi:[1,0]
	s_nop 0
	v_pk_fma_f32 v[22:23], v[134:135], s[52:53], v[88:89] op_sel_hi:[1,0,1] neg_lo:[0,0,1] neg_hi:[0,0,1]
	v_xor_b32_e32 v134, 0x80000000, v27
	v_pk_add_f32 v[88:89], v[14:15], v[22:23]
	v_pk_add_f32 v[14:15], v[14:15], v[22:23] neg_lo:[0,1] neg_hi:[0,1]
	v_pk_mul_f32 v[22:23], v[26:27], s[60:61] op_sel_hi:[1,0]
	v_mov_b32_e32 v135, v26
	v_pk_fma_f32 v[22:23], v[134:135], s[60:61], v[22:23] op_sel_hi:[1,0,1] neg_lo:[0,0,1] neg_hi:[0,0,1]
	v_xor_b32_e32 v134, 0x80000000, v63
	v_pk_add_f32 v[26:27], v[18:19], v[22:23]
	v_pk_add_f32 v[18:19], v[18:19], v[22:23] neg_lo:[0,1] neg_hi:[0,1]
	v_pk_mul_f32 v[22:23], v[62:63], s[52:53] op_sel_hi:[1,0]
	v_mov_b32_e32 v135, v62
	v_pk_fma_f32 v[22:23], v[134:135], s[54:55], v[22:23] op_sel_hi:[1,0,1] neg_lo:[0,0,1] neg_hi:[0,0,1]
	v_xor_b32_e32 v134, 0x80000000, v73
	v_pk_add_f32 v[62:63], v[24:25], v[22:23]
	v_pk_add_f32 v[22:23], v[24:25], v[22:23] neg_lo:[0,1] neg_hi:[0,1]
	v_pk_add_f32 v[24:25], v[84:85], v[6:7]
	v_pk_add_f32 v[6:7], v[84:85], v[6:7] neg_lo:[0,1] neg_hi:[0,1]
	v_xor_b32_e32 v84, 0x80000000, v131
	v_mov_b32_e32 v85, v130
	v_pk_mul_f32 v[84:85], v[84:85], s[48:49] op_sel_hi:[1,0]
	v_mov_b32_e32 v135, v72
	v_pk_fma_f32 v[84:85], v[130:131], s[44:45], v[84:85] op_sel_hi:[1,0,1]
	s_nop 0
	v_pk_add_f32 v[130:131], v[94:95], v[84:85]
	v_pk_add_f32 v[84:85], v[94:95], v[84:85] neg_lo:[0,1] neg_hi:[0,1]
	v_xor_b32_e32 v94, 0x80000000, v97
	v_mov_b32_e32 v95, v96
	v_pk_mul_f32 v[94:95], v[94:95], s[54:55] op_sel_hi:[1,0]
	s_nop 0
	v_pk_fma_f32 v[94:95], v[96:97], s[52:53], v[94:95] op_sel_hi:[1,0,1]
	s_nop 0
	v_pk_add_f32 v[96:97], v[132:133], v[94:95]
	v_pk_add_f32 v[94:95], v[132:133], v[94:95] neg_lo:[0,1] neg_hi:[0,1]
	v_xor_b32_e32 v132, 0x80000000, v93
	v_mov_b32_e32 v133, v92
	v_pk_mul_f32 v[132:133], v[132:133], s[58:59] op_sel_hi:[1,0]
	s_nop 0
	v_pk_fma_f32 v[92:93], v[92:93], s[56:57], v[132:133] op_sel_hi:[1,0,1]
	s_nop 0
	v_pk_add_f32 v[132:133], v[86:87], v[92:93]
	v_pk_add_f32 v[86:87], v[86:87], v[92:93] neg_lo:[0,1] neg_hi:[0,1]
	v_xor_b32_e32 v92, 0x80000000, v77
	v_mov_b32_e32 v93, v76
	v_pk_mul_f32 v[92:93], v[92:93], s[60:61] op_sel_hi:[1,0]
	s_nop 0
	v_pk_fma_f32 v[76:77], v[76:77], s[60:61], v[92:93] op_sel_hi:[1,0,1]
	s_nop 0
	v_pk_add_f32 v[92:93], v[70:71], v[76:77]
	v_pk_add_f32 v[70:71], v[70:71], v[76:77] neg_lo:[0,1] neg_hi:[0,1]
	v_xor_b32_e32 v76, 0x80000000, v89
	v_mov_b32_e32 v77, v88
	v_pk_mul_f32 v[76:77], v[76:77], s[56:57] op_sel_hi:[1,0]
	s_nop 0
	v_pk_fma_f32 v[76:77], v[88:89], s[58:59], v[76:77] op_sel_hi:[1,0,1]
	s_nop 0
	v_pk_add_f32 v[88:89], v[68:69], v[76:77]
	v_pk_add_f32 v[68:69], v[68:69], v[76:77] neg_lo:[0,1] neg_hi:[0,1]
	v_xor_b32_e32 v76, 0x80000000, v27
	v_mov_b32_e32 v77, v26
	v_pk_mul_f32 v[76:77], v[76:77], s[52:53] op_sel_hi:[1,0]
	s_nop 0
	v_pk_fma_f32 v[26:27], v[26:27], s[54:55], v[76:77] op_sel_hi:[1,0,1]
	s_nop 0
	v_pk_add_f32 v[76:77], v[8:9], v[26:27]
	v_pk_add_f32 v[8:9], v[8:9], v[26:27] neg_lo:[0,1] neg_hi:[0,1]
	v_xor_b32_e32 v26, 0x80000000, v63
	v_mov_b32_e32 v27, v62
	v_pk_mul_f32 v[26:27], v[26:27], s[44:45] op_sel_hi:[1,0]
	s_nop 0
	v_pk_fma_f32 v[26:27], v[62:63], s[48:49], v[26:27] op_sel_hi:[1,0,1]
	s_nop 0
	v_pk_add_f32 v[62:63], v[16:17], v[26:27]
	v_pk_add_f32 v[16:17], v[16:17], v[26:27] neg_lo:[0,1] neg_hi:[0,1]
	v_xor_b32_e32 v26, 0x80000000, v21
	v_mov_b32_e32 v27, v20
	v_pk_add_f32 v[20:21], v[10:11], v[26:27]
	v_pk_add_f32 v[10:11], v[10:11], v[26:27] neg_lo:[0,1] neg_hi:[0,1]
	v_pk_mul_f32 v[26:27], v[72:73], s[48:49] op_sel_hi:[1,0]
	s_nop 0
	v_pk_fma_f32 v[26:27], v[134:135], s[44:45], v[26:27] op_sel_hi:[1,0,1] neg_lo:[0,0,1] neg_hi:[0,0,1]
	v_xor_b32_e32 v134, 0x80000000, v75
	v_pk_add_f32 v[72:73], v[90:91], v[26:27]
	v_pk_add_f32 v[26:27], v[90:91], v[26:27] neg_lo:[0,1] neg_hi:[0,1]
	v_pk_mul_f32 v[90:91], v[74:75], s[54:55] op_sel_hi:[1,0]
	v_mov_b32_e32 v135, v74
	v_pk_fma_f32 v[74:75], v[134:135], s[52:53], v[90:91] op_sel_hi:[1,0,1] neg_lo:[0,0,1] neg_hi:[0,0,1]
	v_xor_b32_e32 v134, 0x80000000, v79
	v_pk_add_f32 v[90:91], v[80:81], v[74:75]
	v_pk_add_f32 v[74:75], v[80:81], v[74:75] neg_lo:[0,1] neg_hi:[0,1]
	v_pk_mul_f32 v[80:81], v[78:79], s[58:59] op_sel_hi:[1,0]
	v_mov_b32_e32 v135, v78
	v_pk_fma_f32 v[78:79], v[134:135], s[56:57], v[80:81] op_sel_hi:[1,0,1] neg_lo:[0,0,1] neg_hi:[0,0,1]
	v_xor_b32_e32 v134, 0x80000000, v83
	v_pk_add_f32 v[80:81], v[12:13], v[78:79]
	v_pk_add_f32 v[12:13], v[12:13], v[78:79] neg_lo:[0,1] neg_hi:[0,1]
	v_pk_mul_f32 v[78:79], v[82:83], s[60:61] op_sel_hi:[1,0]
	v_mov_b32_e32 v135, v82
	v_pk_fma_f32 v[78:79], v[134:135], s[60:61], v[78:79] op_sel_hi:[1,0,1] neg_lo:[0,0,1] neg_hi:[0,0,1]
	v_xor_b32_e32 v134, 0x80000000, v15
	v_pk_add_f32 v[82:83], v[64:65], v[78:79]
	v_pk_add_f32 v[64:65], v[64:65], v[78:79] neg_lo:[0,1] neg_hi:[0,1]
	v_pk_mul_f32 v[78:79], v[14:15], s[56:57] op_sel_hi:[1,0]
	v_mov_b32_e32 v135, v14
	v_pk_fma_f32 v[14:15], v[134:135], s[58:59], v[78:79] op_sel_hi:[1,0,1] neg_lo:[0,0,1] neg_hi:[0,0,1]
	v_xor_b32_e32 v134, 0x80000000, v19
	v_pk_add_f32 v[78:79], v[2:3], v[14:15]
	v_pk_add_f32 v[2:3], v[2:3], v[14:15] neg_lo:[0,1] neg_hi:[0,1]
	v_pk_mul_f32 v[14:15], v[18:19], s[52:53] op_sel_hi:[1,0]
	v_mov_b32_e32 v135, v18
	v_pk_fma_f32 v[14:15], v[134:135], s[54:55], v[14:15] op_sel_hi:[1,0,1] neg_lo:[0,0,1] neg_hi:[0,0,1]
	v_xor_b32_e32 v134, 0x80000000, v23
	v_pk_add_f32 v[18:19], v[4:5], v[14:15]
	v_pk_add_f32 v[4:5], v[4:5], v[14:15] neg_lo:[0,1] neg_hi:[0,1]
	v_pk_mul_f32 v[14:15], v[22:23], s[44:45] op_sel_hi:[1,0]
	v_mov_b32_e32 v135, v22
	v_pk_fma_f32 v[14:15], v[134:135], s[48:49], v[14:15] op_sel_hi:[1,0,1] neg_lo:[0,0,1] neg_hi:[0,0,1]
	s_nop 0
	v_pk_add_f32 v[22:23], v[0:1], v[14:15]
	v_pk_add_f32 v[0:1], v[0:1], v[14:15] neg_lo:[0,1] neg_hi:[0,1]
	ds_write_b64 v67, v[24:25]
	ds_write_b64 v98, v[130:131]
	ds_write_b64 v99, v[96:97] offset:256
	ds_write_b64 v100, v[132:133] offset:256
	ds_write_b64 v101, v[92:93] offset:512
	ds_write_b64 v102, v[88:89] offset:512
	ds_write_b64 v103, v[76:77] offset:768
	ds_write_b64 v104, v[62:63] offset:768
	ds_write_b64 v105, v[20:21] offset:1024
	ds_write_b64 v106, v[72:73] offset:1024
	ds_write_b64 v107, v[90:91] offset:1280
	ds_write_b64 v108, v[80:81] offset:1280
	ds_write_b64 v109, v[82:83] offset:1536
	ds_write_b64 v110, v[78:79] offset:1536
	ds_write_b64 v111, v[18:19] offset:1792
	ds_write_b64 v112, v[22:23] offset:1792
	ds_write_b64 v113, v[6:7] offset:2048
	ds_write_b64 v114, v[84:85] offset:2048
	ds_write_b64 v115, v[94:95] offset:2304
	ds_write_b64 v116, v[86:87] offset:2304
	ds_write_b64 v117, v[70:71] offset:2560
	ds_write_b64 v118, v[68:69] offset:2560
	ds_write_b64 v119, v[8:9] offset:2816
	ds_write_b64 v120, v[16:17] offset:2816
	ds_write_b64 v121, v[10:11] offset:3072
	ds_write_b64 v122, v[26:27] offset:3072
	ds_write_b64 v123, v[74:75] offset:3328
	ds_write_b64 v124, v[12:13] offset:3328
	ds_write_b64 v125, v[64:65] offset:3584
	ds_write_b64 v126, v[2:3] offset:3584
	ds_write_b64 v127, v[4:5] offset:3840
	ds_write_b64 v128, v[0:1] offset:3840
	v_mov_b32_e32 v74, v146
	s_waitcnt lgkmcnt(0)
	s_barrier
	s_nop 0
	v_lshrrev_b32_e32 v0, 5, v74
	v_bfe_u32 v4, v74, 5, 4
	v_bitop3_b32 v0, v0, v74, 15 bitop3:0x6c
	v_bitop3_b32 v4, v4, v74, 16 bitop3:0x36
	v_lshlrev_b32_e32 v66, 3, v0
	v_lshlrev_b32_e32 v67, 3, v4
	v_add_u32_e32 v5, 16, v66
	v_add_u32_e32 v4, 16, v67
	v_add_u32_e32 v62, s79, v66
	v_add_u32_e32 v70, s9, v66
	ds_read2st64_b64 v[0:3], v5 offset1:16
	ds_read2st64_b64 v[16:19], v4 offset0:8 offset1:24
	ds_read2st64_b64 v[24:27], v5 offset0:32 offset1:48
	ds_read2st64_b64 v[8:11], v4 offset0:40 offset1:56
	ds_read2st64_b64 v[92:95], v5 offset0:64 offset1:80
	ds_read2st64_b64 v[12:15], v4 offset0:72 offset1:88
	ds_read2st64_b64 v[20:23], v5 offset0:96 offset1:112
	ds_read2st64_b64 v[4:7], v4 offset0:104 offset1:120
	ds_read_b64 v[68:69], v62
	ds_read_b64 v[72:73], v70
	v_add_u32_e32 v62, s19, v67
	v_add_u32_e32 v70, s8, v67
	ds_read_b64 v[84:85], v62
	ds_read_b64 v[90:91], v70
	v_add_u32_e32 v62, s18, v66
	v_add_u32_e32 v70, s7, v66
	ds_read_b64 v[96:97], v62
	ds_read_b64 v[100:101], v70
	v_add_u32_e32 v62, s17, v67
	v_add_u32_e32 v70, s6, v67
	ds_read_b64 v[64:65], v62
	ds_read_b64 v[70:71], v70
	v_add_u32_e32 v62, s13, v66
	v_add_u32_e32 v75, s5, v66
	ds_read_b64 v[86:87], v62
	ds_read_b64 v[102:103], v75
	v_add_u32_e32 v62, s12, v67
	v_add_u32_e32 v75, s4, v67
	ds_read_b64 v[80:81], v62
	ds_read_b64 v[88:89], v75
	v_add_u32_e32 v62, s11, v66
	v_add_u32_e32 v66, s1, v66
	ds_read_b64 v[98:99], v62
	ds_read_b64 v[104:105], v66
	v_add_u32_e32 v62, s10, v67
	v_add_u32_e32 v66, s0, v67
	ds_read_b64 v[62:63], v62
	ds_read_b64 v[66:67], v66
	s_waitcnt lgkmcnt(14)
	v_xor_b32_e32 v106, 0x80000000, v69
	v_cvt_f32_i32_e32 v74, v74
	v_mov_b32_e32 v107, v68
	s_lshl_b64 s[0:1], s[42:43], 2
	s_add_u32 s0, s45, s0
	v_mul_f32_e32 v74, 0x38800000, v74
	v_cos_f32_e32 v78, v74
	v_sin_f32_e32 v79, v74
	s_addc_u32 s1, s24, s1
	s_and_b64 vcc, s[14:15], exec
	v_add_f32_e32 v76, v78, v78
	v_pk_mul_f32 v[74:75], v[78:79], v[78:79]
	v_mul_f32_e32 v76, v79, v76
	v_xor_b32_e32 v82, 0x80000000, v79
	v_mov_b32_e32 v83, v78
	v_mov_b32_e32 v108, v79
	v_pk_add_f32 v[74:75], v[74:75], v[74:75] op_sel:[0,1] op_sel_hi:[0,1] neg_lo:[0,1] neg_hi:[0,1]
	v_pk_mul_f32 v[82:83], v[82:83], v[76:77] op_sel_hi:[1,0]
	v_pk_mul_f32 v[106:107], v[106:107], v[108:109] op_sel_hi:[1,0]
	v_pk_fma_f32 v[82:83], v[78:79], v[74:75], v[82:83]
	v_pk_fma_f32 v[68:69], v[68:69], v[78:79], v[106:107] op_sel_hi:[1,0,1]
	v_pk_mul_f32 v[78:79], v[76:77], s[46:47] op_sel_hi:[0,1]
	v_pk_fma_f32 v[106:107], v[74:75], s[40:41], v[78:79]
	v_xor_b32_e32 v78, 0x80000000, v93
	v_mov_b32_e32 v79, v92
	v_pk_mul_f32 v[78:79], v[78:79], v[106:107] op_sel:[0,1]
	v_xor_b32_e32 v108, 0x80000000, v73
	v_pk_fma_f32 v[78:79], v[92:93], v[106:107], v[78:79] op_sel_hi:[1,0,1]
	v_xor_b32_e32 v92, 0x80000000, v83
	v_mov_b32_e32 v93, v82
	v_mov_b32_e32 v109, v72
	v_pk_mul_f32 v[92:93], v[76:77], v[92:93] op_sel_hi:[0,1]
	v_pk_mul_f32 v[108:109], v[108:109], v[82:83] op_sel:[0,1]
	v_pk_fma_f32 v[92:93], v[74:75], v[82:83], v[92:93]
	v_pk_fma_f32 v[72:73], v[72:73], v[82:83], v[108:109] op_sel_hi:[1,0,1]
	v_xor_b32_e32 v82, 0x80000000, v107
	v_mov_b32_e32 v83, v106
	v_pk_mul_f32 v[82:83], v[76:77], v[82:83] op_sel_hi:[0,1]
	v_pk_fma_f32 v[106:107], v[74:75], v[106:107], v[82:83]
	v_xor_b32_e32 v82, 0x80000000, v25
	v_mov_b32_e32 v83, v24
	v_pk_mul_f32 v[82:83], v[82:83], v[106:107] op_sel:[0,1]
	s_nop 0
	v_pk_fma_f32 v[82:83], v[24:25], v[106:107], v[82:83] op_sel_hi:[1,0,1]
	v_xor_b32_e32 v24, 0x80000000, v93
	v_mov_b32_e32 v25, v92
	v_pk_mul_f32 v[24:25], v[76:77], v[24:25] op_sel_hi:[0,1]
	v_pk_fma_f32 v[108:109], v[74:75], v[92:93], v[24:25]
	s_waitcnt lgkmcnt(7)
	v_xor_b32_e32 v24, 0x80000000, v87
	v_mov_b32_e32 v25, v86
	v_pk_mul_f32 v[24:25], v[24:25], v[92:93] op_sel:[0,1]
	s_nop 0
	v_pk_fma_f32 v[24:25], v[86:87], v[92:93], v[24:25] op_sel_hi:[1,0,1]
	v_xor_b32_e32 v86, 0x80000000, v107
	v_mov_b32_e32 v87, v106
	v_pk_mul_f32 v[86:87], v[76:77], v[86:87] op_sel_hi:[0,1]
	v_pk_fma_f32 v[92:93], v[74:75], v[106:107], v[86:87]
	v_xor_b32_e32 v86, 0x80000000, v21
	v_mov_b32_e32 v87, v20
	v_pk_mul_f32 v[86:87], v[86:87], v[92:93] op_sel:[0,1]
	s_nop 0
	v_pk_fma_f32 v[86:87], v[20:21], v[92:93], v[86:87] op_sel_hi:[1,0,1]
	v_xor_b32_e32 v20, 0x80000000, v109
	v_mov_b32_e32 v21, v108
	v_pk_mul_f32 v[20:21], v[76:77], v[20:21] op_sel_hi:[0,1]
	v_pk_fma_f32 v[106:107], v[74:75], v[108:109], v[20:21]
	s_waitcnt lgkmcnt(6)
	v_xor_b32_e32 v20, 0x80000000, v103
	v_mov_b32_e32 v21, v102
	v_pk_mul_f32 v[20:21], v[20:21], v[108:109] op_sel:[0,1]
	s_nop 0
	v_pk_fma_f32 v[20:21], v[102:103], v[108:109], v[20:21] op_sel_hi:[1,0,1]
	v_xor_b32_e32 v102, 0x80000000, v93
	v_mov_b32_e32 v103, v92
	v_pk_mul_f32 v[102:103], v[76:77], v[102:103] op_sel_hi:[0,1]
	v_pk_fma_f32 v[102:103], v[74:75], v[92:93], v[102:103]
	v_xor_b32_e32 v92, 0x80000000, v3
	v_mov_b32_e32 v93, v2
	v_pk_mul_f32 v[92:93], v[92:93], v[102:103] op_sel:[0,1]
	s_nop 0
	v_pk_fma_f32 v[92:93], v[2:3], v[102:103], v[92:93] op_sel_hi:[1,0,1]
	v_xor_b32_e32 v2, 0x80000000, v107
	v_mov_b32_e32 v3, v106
	v_pk_mul_f32 v[2:3], v[76:77], v[2:3] op_sel_hi:[0,1]
	v_pk_fma_f32 v[108:109], v[74:75], v[106:107], v[2:3]
	v_xor_b32_e32 v2, 0x80000000, v97
	v_mov_b32_e32 v3, v96
	v_pk_mul_f32 v[2:3], v[2:3], v[106:107] op_sel:[0,1]
	s_nop 0
	v_pk_fma_f32 v[2:3], v[96:97], v[106:107], v[2:3] op_sel_hi:[1,0,1]
	v_xor_b32_e32 v96, 0x80000000, v103
	v_mov_b32_e32 v97, v102
	v_pk_mul_f32 v[96:97], v[76:77], v[96:97] op_sel_hi:[0,1]
	v_pk_fma_f32 v[102:103], v[74:75], v[102:103], v[96:97]
	v_xor_b32_e32 v96, 0x80000000, v95
	v_mov_b32_e32 v97, v94
	v_pk_mul_f32 v[96:97], v[96:97], v[102:103] op_sel:[0,1]
	s_nop 0
	v_pk_fma_f32 v[96:97], v[94:95], v[102:103], v[96:97] op_sel_hi:[1,0,1]
	v_xor_b32_e32 v94, 0x80000000, v109
	v_mov_b32_e32 v95, v108
	v_pk_mul_f32 v[94:95], v[76:77], v[94:95] op_sel_hi:[0,1]
	v_pk_fma_f32 v[106:107], v[74:75], v[108:109], v[94:95]
	v_xor_b32_e32 v94, 0x80000000, v101
	v_mov_b32_e32 v95, v100
	v_pk_mul_f32 v[94:95], v[94:95], v[108:109] op_sel:[0,1]
	s_nop 0
	v_pk_fma_f32 v[94:95], v[100:101], v[108:109], v[94:95] op_sel_hi:[1,0,1]
	v_xor_b32_e32 v100, 0x80000000, v103
	v_mov_b32_e32 v101, v102
	v_pk_mul_f32 v[100:101], v[76:77], v[100:101] op_sel_hi:[0,1]
	v_pk_fma_f32 v[100:101], v[74:75], v[102:103], v[100:101]
	v_xor_b32_e32 v102, 0x80000000, v27
	v_mov_b32_e32 v103, v26
	v_pk_mul_f32 v[102:103], v[102:103], v[100:101] op_sel:[0,1]
	s_waitcnt lgkmcnt(3)
	v_xor_b32_e32 v108, 0x80000000, v99
	v_pk_fma_f32 v[26:27], v[26:27], v[100:101], v[102:103] op_sel_hi:[1,0,1]
	v_xor_b32_e32 v102, 0x80000000, v107
	v_mov_b32_e32 v103, v106
	v_mov_b32_e32 v109, v98
	v_pk_mul_f32 v[102:103], v[76:77], v[102:103] op_sel_hi:[0,1]
	v_pk_mul_f32 v[108:109], v[108:109], v[106:107] op_sel:[0,1]
	v_pk_fma_f32 v[102:103], v[74:75], v[106:107], v[102:103]
	v_pk_fma_f32 v[98:99], v[98:99], v[106:107], v[108:109] op_sel_hi:[1,0,1]
	v_xor_b32_e32 v106, 0x80000000, v101
	v_mov_b32_e32 v107, v100
	v_pk_mul_f32 v[106:107], v[76:77], v[106:107] op_sel_hi:[0,1]
	v_pk_fma_f32 v[100:101], v[74:75], v[100:101], v[106:107]
	v_xor_b32_e32 v106, 0x80000000, v23
	v_mov_b32_e32 v107, v22
	v_pk_mul_f32 v[106:107], v[106:107], v[100:101] op_sel:[0,1]
	s_waitcnt lgkmcnt(2)
	v_xor_b32_e32 v108, 0x80000000, v105
	v_pk_fma_f32 v[22:23], v[22:23], v[100:101], v[106:107] op_sel_hi:[1,0,1]
	v_xor_b32_e32 v106, 0x80000000, v103
	v_mov_b32_e32 v107, v102
	v_mov_b32_e32 v109, v104
	v_pk_mul_f32 v[106:107], v[76:77], v[106:107] op_sel_hi:[0,1]
	v_pk_mul_f32 v[108:109], v[108:109], v[102:103] op_sel:[0,1]
	v_pk_fma_f32 v[106:107], v[74:75], v[102:103], v[106:107]
	v_pk_fma_f32 v[102:103], v[104:105], v[102:103], v[108:109] op_sel_hi:[1,0,1]
	v_xor_b32_e32 v104, 0x80000000, v101
	v_mov_b32_e32 v105, v100
	v_pk_mul_f32 v[104:105], v[76:77], v[104:105] op_sel_hi:[0,1]
	v_pk_fma_f32 v[100:101], v[74:75], v[100:101], v[104:105]
	v_xor_b32_e32 v104, 0x80000000, v17
	v_mov_b32_e32 v105, v16
	v_pk_mul_f32 v[104:105], v[104:105], v[100:101] op_sel:[0,1]
	v_xor_b32_e32 v108, 0x80000000, v85
	v_pk_fma_f32 v[16:17], v[16:17], v[100:101], v[104:105] op_sel_hi:[1,0,1]
	v_xor_b32_e32 v104, 0x80000000, v107
	v_mov_b32_e32 v105, v106
	v_mov_b32_e32 v109, v84
	v_pk_mul_f32 v[104:105], v[76:77], v[104:105] op_sel_hi:[0,1]
	v_pk_mul_f32 v[108:109], v[108:109], v[106:107] op_sel:[0,1]
	v_pk_fma_f32 v[104:105], v[74:75], v[106:107], v[104:105]
	v_pk_fma_f32 v[84:85], v[84:85], v[106:107], v[108:109] op_sel_hi:[1,0,1]
	v_xor_b32_e32 v106, 0x80000000, v101
	v_mov_b32_e32 v107, v100
	v_pk_mul_f32 v[106:107], v[76:77], v[106:107] op_sel_hi:[0,1]
	v_pk_fma_f32 v[100:101], v[74:75], v[100:101], v[106:107]
	v_xor_b32_e32 v106, 0x80000000, v13
	v_mov_b32_e32 v107, v12
	v_pk_mul_f32 v[106:107], v[106:107], v[100:101] op_sel:[0,1]
	v_xor_b32_e32 v108, 0x80000000, v91
	v_pk_fma_f32 v[12:13], v[12:13], v[100:101], v[106:107] op_sel_hi:[1,0,1]
	v_xor_b32_e32 v106, 0x80000000, v105
	v_mov_b32_e32 v107, v104
	v_mov_b32_e32 v109, v90
	v_pk_mul_f32 v[106:107], v[76:77], v[106:107] op_sel_hi:[0,1]
	v_pk_mul_f32 v[108:109], v[108:109], v[104:105] op_sel:[0,1]
	v_pk_fma_f32 v[106:107], v[74:75], v[104:105], v[106:107]
	v_pk_fma_f32 v[90:91], v[90:91], v[104:105], v[108:109] op_sel_hi:[1,0,1]
	v_xor_b32_e32 v104, 0x80000000, v101
	v_mov_b32_e32 v105, v100
	v_pk_mul_f32 v[104:105], v[76:77], v[104:105] op_sel_hi:[0,1]
	v_pk_fma_f32 v[100:101], v[74:75], v[100:101], v[104:105]
	v_xor_b32_e32 v104, 0x80000000, v9
	v_mov_b32_e32 v105, v8
	v_pk_mul_f32 v[104:105], v[104:105], v[100:101] op_sel:[0,1]
	v_xor_b32_e32 v108, 0x80000000, v81
	v_pk_fma_f32 v[8:9], v[8:9], v[100:101], v[104:105] op_sel_hi:[1,0,1]
	v_xor_b32_e32 v104, 0x80000000, v107
	v_mov_b32_e32 v105, v106
	v_mov_b32_e32 v109, v80
	v_pk_mul_f32 v[104:105], v[76:77], v[104:105] op_sel_hi:[0,1]
	v_pk_mul_f32 v[108:109], v[108:109], v[106:107] op_sel:[0,1]
	v_pk_fma_f32 v[104:105], v[74:75], v[106:107], v[104:105]
	v_pk_fma_f32 v[80:81], v[80:81], v[106:107], v[108:109] op_sel_hi:[1,0,1]
	v_xor_b32_e32 v106, 0x80000000, v101
	v_mov_b32_e32 v107, v100
	v_pk_mul_f32 v[106:107], v[76:77], v[106:107] op_sel_hi:[0,1]
	v_pk_fma_f32 v[100:101], v[74:75], v[100:101], v[106:107]
	v_xor_b32_e32 v106, 0x80000000, v5
	v_mov_b32_e32 v107, v4
	v_pk_mul_f32 v[106:107], v[106:107], v[100:101] op_sel:[0,1]
	v_xor_b32_e32 v108, 0x80000000, v89
	v_pk_fma_f32 v[4:5], v[4:5], v[100:101], v[106:107] op_sel_hi:[1,0,1]
	v_xor_b32_e32 v106, 0x80000000, v105
	v_mov_b32_e32 v107, v104
	v_mov_b32_e32 v109, v88
	v_pk_mul_f32 v[106:107], v[76:77], v[106:107] op_sel_hi:[0,1]
	v_pk_mul_f32 v[108:109], v[108:109], v[104:105] op_sel:[0,1]
	v_pk_fma_f32 v[106:107], v[74:75], v[104:105], v[106:107]
	v_pk_fma_f32 v[88:89], v[88:89], v[104:105], v[108:109] op_sel_hi:[1,0,1]
	v_xor_b32_e32 v104, 0x80000000, v101
	v_mov_b32_e32 v105, v100
	v_pk_mul_f32 v[104:105], v[76:77], v[104:105] op_sel_hi:[0,1]
	v_pk_fma_f32 v[100:101], v[74:75], v[100:101], v[104:105]
	v_xor_b32_e32 v104, 0x80000000, v19
	v_mov_b32_e32 v105, v18
	v_pk_mul_f32 v[104:105], v[104:105], v[100:101] op_sel:[0,1]
	v_xor_b32_e32 v108, 0x80000000, v65
	v_pk_fma_f32 v[18:19], v[18:19], v[100:101], v[104:105] op_sel_hi:[1,0,1]
	v_xor_b32_e32 v104, 0x80000000, v107
	v_mov_b32_e32 v105, v106
	v_mov_b32_e32 v109, v64
	v_pk_mul_f32 v[104:105], v[76:77], v[104:105] op_sel_hi:[0,1]
	v_pk_mul_f32 v[108:109], v[108:109], v[106:107] op_sel:[0,1]
	v_pk_fma_f32 v[104:105], v[74:75], v[106:107], v[104:105]
	v_pk_fma_f32 v[64:65], v[64:65], v[106:107], v[108:109] op_sel_hi:[1,0,1]
	v_xor_b32_e32 v106, 0x80000000, v101
	v_mov_b32_e32 v107, v100
	v_pk_mul_f32 v[106:107], v[76:77], v[106:107] op_sel_hi:[0,1]
	v_pk_fma_f32 v[100:101], v[74:75], v[100:101], v[106:107]
	v_xor_b32_e32 v106, 0x80000000, v15
	v_mov_b32_e32 v107, v14
	v_pk_mul_f32 v[106:107], v[106:107], v[100:101] op_sel:[0,1]
	v_xor_b32_e32 v108, 0x80000000, v71
	v_pk_fma_f32 v[14:15], v[14:15], v[100:101], v[106:107] op_sel_hi:[1,0,1]
	v_xor_b32_e32 v106, 0x80000000, v105
	v_mov_b32_e32 v107, v104
	v_mov_b32_e32 v109, v70
	v_pk_mul_f32 v[106:107], v[76:77], v[106:107] op_sel_hi:[0,1]
	v_pk_mul_f32 v[108:109], v[108:109], v[104:105] op_sel:[0,1]
	v_pk_fma_f32 v[106:107], v[74:75], v[104:105], v[106:107]
	v_pk_fma_f32 v[70:71], v[70:71], v[104:105], v[108:109] op_sel_hi:[1,0,1]
	v_xor_b32_e32 v104, 0x80000000, v101
	v_mov_b32_e32 v105, v100
	v_pk_mul_f32 v[104:105], v[76:77], v[104:105] op_sel_hi:[0,1]
	v_pk_fma_f32 v[100:101], v[74:75], v[100:101], v[104:105]
	v_xor_b32_e32 v104, 0x80000000, v11
	v_mov_b32_e32 v105, v10
	v_pk_mul_f32 v[104:105], v[104:105], v[100:101] op_sel:[0,1]
	s_waitcnt lgkmcnt(1)
	v_xor_b32_e32 v108, 0x80000000, v63
	v_pk_fma_f32 v[10:11], v[10:11], v[100:101], v[104:105] op_sel_hi:[1,0,1]
	v_xor_b32_e32 v104, 0x80000000, v107
	v_mov_b32_e32 v105, v106
	v_mov_b32_e32 v109, v62
	v_pk_mul_f32 v[104:105], v[76:77], v[104:105] op_sel_hi:[0,1]
	v_pk_mul_f32 v[108:109], v[108:109], v[106:107] op_sel:[0,1]
	v_pk_fma_f32 v[104:105], v[74:75], v[106:107], v[104:105]
	v_pk_fma_f32 v[62:63], v[62:63], v[106:107], v[108:109] op_sel_hi:[1,0,1]
	v_xor_b32_e32 v106, 0x80000000, v101
	v_mov_b32_e32 v107, v100
	v_pk_mul_f32 v[76:77], v[76:77], v[106:107] op_sel_hi:[0,1]
	v_pk_fma_f32 v[74:75], v[74:75], v[100:101], v[76:77]
	v_xor_b32_e32 v76, 0x80000000, v7
	v_mov_b32_e32 v77, v6
	v_pk_mul_f32 v[76:77], v[76:77], v[74:75] op_sel:[0,1]
	s_nop 0
	v_pk_fma_f32 v[6:7], v[6:7], v[74:75], v[76:77] op_sel_hi:[1,0,1]
	s_waitcnt lgkmcnt(0)
	v_xor_b32_e32 v74, 0x80000000, v67
	v_mov_b32_e32 v75, v66
	v_pk_mul_f32 v[74:75], v[74:75], v[104:105] op_sel:[0,1]
	v_pk_add_f32 v[76:77], v[82:83], v[8:9]
	v_pk_fma_f32 v[66:67], v[66:67], v[104:105], v[74:75] op_sel_hi:[1,0,1]
	v_pk_add_f32 v[74:75], v[0:1], v[16:17]
	v_pk_add_f32 v[0:1], v[0:1], v[16:17] neg_lo:[0,1] neg_hi:[0,1]
	v_pk_add_f32 v[16:17], v[92:93], v[18:19]
	v_pk_add_f32 v[18:19], v[92:93], v[18:19] neg_lo:[0,1] neg_hi:[0,1]
	v_pk_add_f32 v[8:9], v[82:83], v[8:9] neg_lo:[0,1] neg_hi:[0,1]
	v_pk_add_f32 v[82:83], v[26:27], v[10:11]
	v_pk_add_f32 v[10:11], v[26:27], v[10:11] neg_lo:[0,1] neg_hi:[0,1]
	v_pk_add_f32 v[92:93], v[86:87], v[4:5]
	v_pk_add_f32 v[4:5], v[86:87], v[4:5] neg_lo:[0,1] neg_hi:[0,1]
	v_pk_add_f32 v[86:87], v[22:23], v[6:7]
	v_pk_add_f32 v[6:7], v[22:23], v[6:7] neg_lo:[0,1] neg_hi:[0,1]
	v_pk_add_f32 v[22:23], v[68:69], v[84:85]
	v_pk_add_f32 v[68:69], v[68:69], v[84:85] neg_lo:[0,1] neg_hi:[0,1]
	v_pk_add_f32 v[84:85], v[2:3], v[64:65]
	v_pk_add_f32 v[2:3], v[2:3], v[64:65] neg_lo:[0,1] neg_hi:[0,1]
	v_pk_add_f32 v[64:65], v[24:25], v[80:81]
	v_pk_add_f32 v[24:25], v[24:25], v[80:81] neg_lo:[0,1] neg_hi:[0,1]
	v_pk_add_f32 v[80:81], v[98:99], v[62:63]
	v_pk_add_f32 v[62:63], v[98:99], v[62:63] neg_lo:[0,1] neg_hi:[0,1]
	v_pk_add_f32 v[98:99], v[74:75], v[16:17]
	v_pk_add_f32 v[16:17], v[74:75], v[16:17] neg_lo:[0,1] neg_hi:[0,1]
	v_xor_b32_e32 v74, 0x80000000, v19
	v_mov_b32_e32 v75, v18
	v_pk_add_f32 v[26:27], v[78:79], v[12:13]
	v_pk_add_f32 v[12:13], v[78:79], v[12:13] neg_lo:[0,1] neg_hi:[0,1]
	v_pk_add_f32 v[78:79], v[96:97], v[14:15]
	v_pk_add_f32 v[14:15], v[96:97], v[14:15] neg_lo:[0,1] neg_hi:[0,1]
	v_pk_add_f32 v[18:19], v[0:1], v[74:75]
	v_pk_add_f32 v[0:1], v[0:1], v[74:75] neg_lo:[0,1] neg_hi:[0,1]
	v_pk_add_f32 v[74:75], v[76:77], v[82:83]
	v_pk_add_f32 v[76:77], v[76:77], v[82:83] neg_lo:[0,1] neg_hi:[0,1]
	v_xor_b32_e32 v82, 0x80000000, v11
	v_mov_b32_e32 v83, v10
	v_pk_add_f32 v[10:11], v[8:9], v[82:83]
	v_pk_add_f32 v[8:9], v[8:9], v[82:83] neg_lo:[0,1] neg_hi:[0,1]
	v_pk_add_f32 v[82:83], v[26:27], v[78:79]
	v_pk_add_f32 v[26:27], v[26:27], v[78:79] neg_lo:[0,1] neg_hi:[0,1]
	v_xor_b32_e32 v78, 0x80000000, v15
	v_mov_b32_e32 v79, v14
	v_pk_add_f32 v[14:15], v[12:13], v[78:79]
	v_pk_add_f32 v[12:13], v[12:13], v[78:79] neg_lo:[0,1] neg_hi:[0,1]
	v_pk_add_f32 v[78:79], v[92:93], v[86:87]
	v_pk_add_f32 v[86:87], v[92:93], v[86:87] neg_lo:[0,1] neg_hi:[0,1]
	v_xor_b32_e32 v92, 0x80000000, v7
	v_mov_b32_e32 v93, v6
	v_pk_add_f32 v[6:7], v[4:5], v[92:93]
	v_pk_add_f32 v[4:5], v[4:5], v[92:93] neg_lo:[0,1] neg_hi:[0,1]
	v_pk_add_f32 v[92:93], v[22:23], v[84:85]
	v_pk_add_f32 v[22:23], v[22:23], v[84:85] neg_lo:[0,1] neg_hi:[0,1]
	v_xor_b32_e32 v84, 0x80000000, v3
	v_mov_b32_e32 v85, v2
	v_pk_add_f32 v[96:97], v[72:73], v[90:91]
	v_pk_add_f32 v[72:73], v[72:73], v[90:91] neg_lo:[0,1] neg_hi:[0,1]
	v_pk_add_f32 v[90:91], v[94:95], v[70:71]
	v_pk_add_f32 v[70:71], v[94:95], v[70:71] neg_lo:[0,1] neg_hi:[0,1]
	v_pk_add_f32 v[2:3], v[68:69], v[84:85]
	v_pk_add_f32 v[68:69], v[68:69], v[84:85] neg_lo:[0,1] neg_hi:[0,1]
	v_pk_add_f32 v[84:85], v[64:65], v[80:81]
	v_pk_add_f32 v[64:65], v[64:65], v[80:81] neg_lo:[0,1] neg_hi:[0,1]
	v_xor_b32_e32 v80, 0x80000000, v63
	v_mov_b32_e32 v81, v62
	v_pk_add_f32 v[94:95], v[20:21], v[88:89]
	v_pk_add_f32 v[20:21], v[20:21], v[88:89] neg_lo:[0,1] neg_hi:[0,1]
	v_pk_add_f32 v[88:89], v[102:103], v[66:67]
	v_pk_add_f32 v[66:67], v[102:103], v[66:67] neg_lo:[0,1] neg_hi:[0,1]
	v_pk_add_f32 v[62:63], v[24:25], v[80:81]
	v_pk_add_f32 v[24:25], v[24:25], v[80:81] neg_lo:[0,1] neg_hi:[0,1]
	v_pk_add_f32 v[80:81], v[96:97], v[90:91]
	v_pk_add_f32 v[90:91], v[96:97], v[90:91] neg_lo:[0,1] neg_hi:[0,1]
	v_xor_b32_e32 v96, 0x80000000, v71
	v_mov_b32_e32 v97, v70
	v_pk_add_f32 v[70:71], v[72:73], v[96:97]
	v_pk_add_f32 v[72:73], v[72:73], v[96:97] neg_lo:[0,1] neg_hi:[0,1]
	v_pk_add_f32 v[96:97], v[94:95], v[88:89]
	v_pk_add_f32 v[88:89], v[94:95], v[88:89] neg_lo:[0,1] neg_hi:[0,1]
	v_xor_b32_e32 v94, 0x80000000, v67
	v_mov_b32_e32 v95, v66
	v_pk_add_f32 v[66:67], v[20:21], v[94:95]
	v_pk_add_f32 v[20:21], v[20:21], v[94:95] neg_lo:[0,1] neg_hi:[0,1]
	v_pk_add_f32 v[94:95], v[98:99], v[74:75]
	v_pk_add_f32 v[74:75], v[98:99], v[74:75] neg_lo:[0,1] neg_hi:[0,1]
	v_xor_b32_e32 v98, 0x80000000, v11
	v_mov_b32_e32 v99, v10
	v_pk_mul_f32 v[98:99], v[98:99], s[60:61] op_sel_hi:[1,0]
	v_xor_b32_e32 v100, 0x80000000, v9
	v_pk_fma_f32 v[10:11], v[10:11], s[60:61], v[98:99] op_sel_hi:[1,0,1]
	v_mov_b32_e32 v101, v8
	v_pk_add_f32 v[98:99], v[18:19], v[10:11]
	v_pk_add_f32 v[10:11], v[18:19], v[10:11] neg_lo:[0,1] neg_hi:[0,1]
	v_xor_b32_e32 v18, 0x80000000, v77
	v_mov_b32_e32 v19, v76
	v_pk_add_f32 v[76:77], v[16:17], v[18:19]
	v_pk_add_f32 v[16:17], v[16:17], v[18:19] neg_lo:[0,1] neg_hi:[0,1]
	v_pk_mul_f32 v[18:19], v[8:9], s[60:61] op_sel_hi:[1,0]
	s_nop 0
	v_pk_fma_f32 v[8:9], v[100:101], s[60:61], v[18:19] op_sel_hi:[1,0,1] neg_lo:[0,0,1] neg_hi:[0,0,1]
	v_xor_b32_e32 v100, 0x80000000, v5
	v_pk_add_f32 v[18:19], v[0:1], v[8:9]
	v_pk_add_f32 v[0:1], v[0:1], v[8:9] neg_lo:[0,1] neg_hi:[0,1]
	v_pk_add_f32 v[8:9], v[82:83], v[78:79]
	v_pk_add_f32 v[78:79], v[82:83], v[78:79] neg_lo:[0,1] neg_hi:[0,1]
	v_xor_b32_e32 v82, 0x80000000, v7
	v_mov_b32_e32 v83, v6
	v_pk_mul_f32 v[82:83], v[82:83], s[60:61] op_sel_hi:[1,0]
	v_mov_b32_e32 v101, v4
	v_pk_fma_f32 v[6:7], v[6:7], s[60:61], v[82:83] op_sel_hi:[1,0,1]
	s_nop 0
	v_pk_add_f32 v[82:83], v[14:15], v[6:7]
	v_pk_add_f32 v[6:7], v[14:15], v[6:7] neg_lo:[0,1] neg_hi:[0,1]
	v_xor_b32_e32 v14, 0x80000000, v87
	v_mov_b32_e32 v15, v86
	v_pk_add_f32 v[86:87], v[26:27], v[14:15]
	v_pk_add_f32 v[14:15], v[26:27], v[14:15] neg_lo:[0,1] neg_hi:[0,1]
	v_pk_mul_f32 v[26:27], v[4:5], s[60:61] op_sel_hi:[1,0]
	s_nop 0
	v_pk_fma_f32 v[4:5], v[100:101], s[60:61], v[26:27] op_sel_hi:[1,0,1] neg_lo:[0,0,1] neg_hi:[0,0,1]
	v_xor_b32_e32 v100, 0x80000000, v25
	v_pk_add_f32 v[26:27], v[12:13], v[4:5]
	v_pk_add_f32 v[4:5], v[12:13], v[4:5] neg_lo:[0,1] neg_hi:[0,1]
	v_pk_add_f32 v[12:13], v[92:93], v[84:85]
	v_pk_add_f32 v[84:85], v[92:93], v[84:85] neg_lo:[0,1] neg_hi:[0,1]
	v_xor_b32_e32 v92, 0x80000000, v63
	v_mov_b32_e32 v93, v62
	v_pk_mul_f32 v[92:93], v[92:93], s[60:61] op_sel_hi:[1,0]
	v_mov_b32_e32 v101, v24
	v_pk_fma_f32 v[62:63], v[62:63], s[60:61], v[92:93] op_sel_hi:[1,0,1]
	s_nop 0
	v_pk_add_f32 v[92:93], v[2:3], v[62:63]
	v_pk_add_f32 v[2:3], v[2:3], v[62:63] neg_lo:[0,1] neg_hi:[0,1]
	v_xor_b32_e32 v62, 0x80000000, v65
	v_mov_b32_e32 v63, v64
	v_pk_add_f32 v[64:65], v[22:23], v[62:63]
	v_pk_add_f32 v[22:23], v[22:23], v[62:63] neg_lo:[0,1] neg_hi:[0,1]
	v_pk_mul_f32 v[62:63], v[24:25], s[60:61] op_sel_hi:[1,0]
	s_nop 0
	v_pk_fma_f32 v[24:25], v[100:101], s[60:61], v[62:63] op_sel_hi:[1,0,1] neg_lo:[0,0,1] neg_hi:[0,0,1]
	v_xor_b32_e32 v100, 0x80000000, v21
	v_pk_add_f32 v[62:63], v[68:69], v[24:25]
	v_pk_add_f32 v[24:25], v[68:69], v[24:25] neg_lo:[0,1] neg_hi:[0,1]
	v_pk_add_f32 v[68:69], v[80:81], v[96:97]
	v_pk_add_f32 v[80:81], v[80:81], v[96:97] neg_lo:[0,1] neg_hi:[0,1]
	v_xor_b32_e32 v96, 0x80000000, v67
	v_mov_b32_e32 v97, v66
	v_pk_mul_f32 v[96:97], v[96:97], s[60:61] op_sel_hi:[1,0]
	v_mov_b32_e32 v101, v20
	v_pk_fma_f32 v[66:67], v[66:67], s[60:61], v[96:97] op_sel_hi:[1,0,1]
	s_nop 0
	v_pk_add_f32 v[96:97], v[70:71], v[66:67]
	v_pk_add_f32 v[66:67], v[70:71], v[66:67] neg_lo:[0,1] neg_hi:[0,1]
	v_xor_b32_e32 v70, 0x80000000, v89
	v_mov_b32_e32 v71, v88
	v_pk_add_f32 v[88:89], v[90:91], v[70:71]
	v_pk_add_f32 v[70:71], v[90:91], v[70:71] neg_lo:[0,1] neg_hi:[0,1]
	v_pk_mul_f32 v[90:91], v[20:21], s[60:61] op_sel_hi:[1,0]
	s_nop 0
	v_pk_fma_f32 v[20:21], v[100:101], s[60:61], v[90:91] op_sel_hi:[1,0,1] neg_lo:[0,0,1] neg_hi:[0,0,1]
	s_nop 0
	v_pk_add_f32 v[90:91], v[72:73], v[20:21]
	v_pk_add_f32 v[20:21], v[72:73], v[20:21] neg_lo:[0,1] neg_hi:[0,1]
	v_pk_add_f32 v[72:73], v[94:95], v[8:9]
	v_pk_add_f32 v[8:9], v[94:95], v[8:9] neg_lo:[0,1] neg_hi:[0,1]
	v_xor_b32_e32 v94, 0x80000000, v83
	v_mov_b32_e32 v95, v82
	v_pk_mul_f32 v[94:95], v[94:95], s[54:55] op_sel_hi:[1,0]
	s_nop 0
	v_pk_fma_f32 v[82:83], v[82:83], s[52:53], v[94:95] op_sel_hi:[1,0,1]
	s_nop 0
	v_pk_add_f32 v[94:95], v[98:99], v[82:83]
	v_pk_add_f32 v[82:83], v[98:99], v[82:83] neg_lo:[0,1] neg_hi:[0,1]
	v_xor_b32_e32 v98, 0x80000000, v87
	v_mov_b32_e32 v99, v86
	v_pk_mul_f32 v[98:99], v[98:99], s[60:61] op_sel_hi:[1,0]
	s_nop 0
	v_pk_fma_f32 v[86:87], v[86:87], s[60:61], v[98:99] op_sel_hi:[1,0,1]
	s_nop 0
	v_pk_add_f32 v[98:99], v[76:77], v[86:87]
	v_pk_add_f32 v[86:87], v[76:77], v[86:87] neg_lo:[0,1] neg_hi:[0,1]
	v_xor_b32_e32 v76, 0x80000000, v27
	v_mov_b32_e32 v77, v26
	v_pk_mul_f32 v[76:77], v[76:77], s[52:53] op_sel_hi:[1,0]
	s_nop 0
	v_pk_fma_f32 v[26:27], v[26:27], s[54:55], v[76:77] op_sel_hi:[1,0,1]
	v_xor_b32_e32 v76, 0x80000000, v67
	v_pk_add_f32 v[100:101], v[18:19], v[26:27]
	v_pk_add_f32 v[26:27], v[18:19], v[26:27] neg_lo:[0,1] neg_hi:[0,1]
	v_xor_b32_e32 v18, 0x80000000, v79
	v_mov_b32_e32 v19, v78
	v_pk_add_f32 v[102:103], v[74:75], v[18:19]
	v_pk_add_f32 v[104:105], v[74:75], v[18:19] neg_lo:[0,1] neg_hi:[0,1]
	v_pk_mul_f32 v[18:19], v[6:7], s[54:55] op_sel_hi:[1,0]
	v_xor_b32_e32 v74, 0x80000000, v7
	v_mov_b32_e32 v75, v6
	v_pk_fma_f32 v[6:7], v[74:75], s[52:53], v[18:19] op_sel_hi:[1,0,1] neg_lo:[0,0,1] neg_hi:[0,0,1]
	v_xor_b32_e32 v74, 0x80000000, v15
	v_pk_add_f32 v[18:19], v[10:11], v[6:7]
	v_pk_add_f32 v[6:7], v[10:11], v[6:7] neg_lo:[0,1] neg_hi:[0,1]
	v_pk_mul_f32 v[10:11], v[14:15], s[60:61] op_sel_hi:[1,0]
	v_mov_b32_e32 v75, v14
	v_pk_fma_f32 v[10:11], v[74:75], s[60:61], v[10:11] op_sel_hi:[1,0,1] neg_lo:[0,0,1] neg_hi:[0,0,1]
	v_xor_b32_e32 v74, 0x80000000, v5
	v_pk_add_f32 v[14:15], v[16:17], v[10:11]
	v_pk_add_f32 v[10:11], v[16:17], v[10:11] neg_lo:[0,1] neg_hi:[0,1]
	v_pk_mul_f32 v[16:17], v[4:5], s[52:53] op_sel_hi:[1,0]
	v_mov_b32_e32 v75, v4
	v_pk_fma_f32 v[4:5], v[74:75], s[54:55], v[16:17] op_sel_hi:[1,0,1] neg_lo:[0,0,1] neg_hi:[0,0,1]
	v_xor_b32_e32 v74, 0x80000000, v89
	v_pk_add_f32 v[16:17], v[0:1], v[4:5]
	v_pk_add_f32 v[106:107], v[0:1], v[4:5] neg_lo:[0,1] neg_hi:[0,1]
	v_pk_add_f32 v[0:1], v[12:13], v[68:69]
	v_pk_add_f32 v[4:5], v[12:13], v[68:69] neg_lo:[0,1] neg_hi:[0,1]
	v_xor_b32_e32 v12, 0x80000000, v97
	v_mov_b32_e32 v13, v96
	v_mov_b32_e32 v75, v88
	v_pk_mul_f32 v[12:13], v[12:13], s[54:55] op_sel_hi:[1,0]
	v_pk_mul_f32 v[74:75], v[74:75], s[60:61] op_sel_hi:[1,0]
	v_pk_fma_f32 v[12:13], v[96:97], s[52:53], v[12:13] op_sel_hi:[1,0,1]
	v_pk_fma_f32 v[74:75], v[88:89], s[60:61], v[74:75] op_sel_hi:[1,0,1]
	v_pk_add_f32 v[68:69], v[92:93], v[12:13]
	v_pk_add_f32 v[12:13], v[92:93], v[12:13] neg_lo:[0,1] neg_hi:[0,1]
	v_pk_add_f32 v[88:89], v[64:65], v[74:75]
	v_pk_add_f32 v[92:93], v[64:65], v[74:75] neg_lo:[0,1] neg_hi:[0,1]
	v_xor_b32_e32 v64, 0x80000000, v91
	v_mov_b32_e32 v65, v90
	v_pk_mul_f32 v[64:65], v[64:65], s[52:53] op_sel_hi:[1,0]
	v_pk_add_f32 v[78:79], v[72:73], v[0:1]
	v_pk_fma_f32 v[64:65], v[90:91], s[54:55], v[64:65] op_sel_hi:[1,0,1]
	v_xor_b32_e32 v0, 0x80000000, v69
	v_mov_b32_e32 v1, v68
	v_pk_add_f32 v[74:75], v[62:63], v[64:65]
	v_pk_add_f32 v[90:91], v[62:63], v[64:65] neg_lo:[0,1] neg_hi:[0,1]
	v_xor_b32_e32 v62, 0x80000000, v81
	v_mov_b32_e32 v63, v80
	v_pk_mul_f32 v[0:1], v[0:1], s[48:49] op_sel_hi:[1,0]
	v_pk_add_f32 v[64:65], v[84:85], v[62:63]
	v_pk_add_f32 v[80:81], v[84:85], v[62:63] neg_lo:[0,1] neg_hi:[0,1]
	v_pk_mul_f32 v[62:63], v[66:67], s[54:55] op_sel_hi:[1,0]
	v_mov_b32_e32 v77, v66
	v_pk_fma_f32 v[0:1], v[68:69], s[44:45], v[0:1] op_sel_hi:[1,0,1]
	v_pk_fma_f32 v[62:63], v[76:77], s[52:53], v[62:63] op_sel_hi:[1,0,1] neg_lo:[0,0,1] neg_hi:[0,0,1]
	v_pk_add_f32 v[76:77], v[94:95], v[0:1]
	v_xor_b32_e32 v0, 0x80000000, v89
	v_mov_b32_e32 v1, v88
	v_pk_mul_f32 v[0:1], v[0:1], s[54:55] op_sel_hi:[1,0]
	v_pk_add_f32 v[84:85], v[2:3], v[62:63]
	v_pk_fma_f32 v[0:1], v[88:89], s[52:53], v[0:1] op_sel_hi:[1,0,1]
	v_pk_add_f32 v[2:3], v[2:3], v[62:63] neg_lo:[0,1] neg_hi:[0,1]
	v_pk_add_f32 v[72:73], v[98:99], v[0:1]
	v_xor_b32_e32 v0, 0x80000000, v75
	v_mov_b32_e32 v1, v74
	v_pk_mul_f32 v[0:1], v[0:1], s[58:59] op_sel_hi:[1,0]
	v_pk_mul_f32 v[62:63], v[70:71], s[60:61] op_sel_hi:[1,0]
	v_pk_fma_f32 v[0:1], v[74:75], s[56:57], v[0:1] op_sel_hi:[1,0,1]
	v_xor_b32_e32 v66, 0x80000000, v71
	v_pk_add_f32 v[74:75], v[100:101], v[0:1]
	v_xor_b32_e32 v0, 0x80000000, v65
	v_mov_b32_e32 v1, v64
	v_pk_mul_f32 v[0:1], v[0:1], s[60:61] op_sel_hi:[1,0]
	v_mov_b32_e32 v67, v70
	v_pk_fma_f32 v[0:1], v[64:65], s[60:61], v[0:1] op_sel_hi:[1,0,1]
	v_pk_fma_f32 v[62:63], v[66:67], s[60:61], v[62:63] op_sel_hi:[1,0,1] neg_lo:[0,0,1] neg_hi:[0,0,1]
	v_pk_add_f32 v[66:67], v[102:103], v[0:1]
	v_xor_b32_e32 v0, 0x80000000, v85
	v_mov_b32_e32 v1, v84
	v_pk_mul_f32 v[0:1], v[0:1], s[56:57] op_sel_hi:[1,0]
	v_pk_add_f32 v[70:71], v[22:23], v[62:63]
	v_pk_fma_f32 v[0:1], v[84:85], s[58:59], v[0:1] op_sel_hi:[1,0,1]
	v_pk_add_f32 v[96:97], v[22:23], v[62:63] neg_lo:[0,1] neg_hi:[0,1]
	v_pk_mul_f32 v[22:23], v[20:21], s[52:53] op_sel_hi:[1,0]
	v_xor_b32_e32 v62, 0x80000000, v21
	v_mov_b32_e32 v63, v20
	v_pk_add_f32 v[68:69], v[18:19], v[0:1]
	v_xor_b32_e32 v0, 0x80000000, v71
	v_mov_b32_e32 v1, v70
	v_pk_fma_f32 v[20:21], v[62:63], s[54:55], v[22:23] op_sel_hi:[1,0,1] neg_lo:[0,0,1] neg_hi:[0,0,1]
	v_pk_mul_f32 v[0:1], v[0:1], s[52:53] op_sel_hi:[1,0]
	v_pk_add_f32 v[22:23], v[24:25], v[20:21]
	v_pk_fma_f32 v[0:1], v[70:71], s[54:55], v[0:1] op_sel_hi:[1,0,1]
	v_pk_add_f32 v[108:109], v[24:25], v[20:21] neg_lo:[0,1] neg_hi:[0,1]
	v_pk_add_f32 v[62:63], v[14:15], v[0:1]
	v_xor_b32_e32 v0, 0x80000000, v23
	v_mov_b32_e32 v1, v22
	v_pk_mul_f32 v[0:1], v[0:1], s[44:45] op_sel_hi:[1,0]
	s_nop 0
	v_pk_fma_f32 v[0:1], v[22:23], s[48:49], v[0:1] op_sel_hi:[1,0,1]
	s_nop 0
	v_pk_add_f32 v[64:65], v[16:17], v[0:1]
	v_xor_b32_e32 v0, 0x80000000, v5
	v_mov_b32_e32 v1, v4
	v_pk_add_f32 v[22:23], v[8:9], v[0:1]
	v_pk_mul_f32 v[0:1], v[12:13], s[48:49] op_sel_hi:[1,0]
	v_xor_b32_e32 v4, 0x80000000, v13
	v_mov_b32_e32 v5, v12
	v_pk_fma_f32 v[0:1], v[4:5], s[44:45], v[0:1] op_sel_hi:[1,0,1] neg_lo:[0,0,1] neg_hi:[0,0,1]
	v_xor_b32_e32 v4, 0x80000000, v93
	v_pk_add_f32 v[24:25], v[82:83], v[0:1]
	v_pk_mul_f32 v[0:1], v[92:93], s[54:55] op_sel_hi:[1,0]
	v_mov_b32_e32 v5, v92
	v_pk_fma_f32 v[0:1], v[4:5], s[52:53], v[0:1] op_sel_hi:[1,0,1] neg_lo:[0,0,1] neg_hi:[0,0,1]
	v_xor_b32_e32 v4, 0x80000000, v91
	v_pk_add_f32 v[18:19], v[86:87], v[0:1]
	v_pk_mul_f32 v[0:1], v[90:91], s[58:59] op_sel_hi:[1,0]
	v_mov_b32_e32 v5, v90
	v_pk_fma_f32 v[0:1], v[4:5], s[56:57], v[0:1] op_sel_hi:[1,0,1] neg_lo:[0,0,1] neg_hi:[0,0,1]
	v_xor_b32_e32 v4, 0x80000000, v81
	v_pk_add_f32 v[20:21], v[26:27], v[0:1]
	v_pk_mul_f32 v[0:1], v[80:81], s[60:61] op_sel_hi:[1,0]
	v_mov_b32_e32 v5, v80
	v_pk_fma_f32 v[0:1], v[4:5], s[60:61], v[0:1] op_sel_hi:[1,0,1] neg_lo:[0,0,1] neg_hi:[0,0,1]
	v_xor_b32_e32 v8, 0x80000000, v3
	v_pk_add_f32 v[4:5], v[104:105], v[0:1]
	v_pk_mul_f32 v[0:1], v[2:3], s[56:57] op_sel_hi:[1,0]
	v_mov_b32_e32 v9, v2
	v_pk_fma_f32 v[0:1], v[8:9], s[58:59], v[0:1] op_sel_hi:[1,0,1] neg_lo:[0,0,1] neg_hi:[0,0,1]
	v_xor_b32_e32 v2, 0x80000000, v97
	v_pk_add_f32 v[6:7], v[6:7], v[0:1]
	v_pk_mul_f32 v[0:1], v[96:97], s[52:53] op_sel_hi:[1,0]
	v_mov_b32_e32 v3, v96
	v_pk_fma_f32 v[0:1], v[2:3], s[54:55], v[0:1] op_sel_hi:[1,0,1] neg_lo:[0,0,1] neg_hi:[0,0,1]
	v_pk_mul_f32 v[2:3], v[108:109], s[44:45] op_sel_hi:[1,0]
	v_pk_add_f32 v[0:1], v[10:11], v[0:1]
	v_xor_b32_e32 v8, 0x80000000, v109
	v_mov_b32_e32 v9, v108
	v_mov_b32_e32 v10, v146
	v_pk_fma_f32 v[2:3], v[8:9], s[48:49], v[2:3] op_sel_hi:[1,0,1] neg_lo:[0,0,1] neg_hi:[0,0,1]
	global_load_dword v8, v145, s[0:1]
	s_movk_i32 s0, 0x200
	s_cselect_b32 s4, s0, 0x400
	s_add_i32 s0, s4, s62
	s_ashr_i32 s1, s0, 31
	s_lshl_b32 s6, s4, 2
	s_add_u32 s4, s64, s6
	s_addc_u32 s5, s65, 0
	s_lshl_b64 s[0:1], s[0:1], 14
	v_min_i32_e32 v70, 0x1ffe, v10
	v_mov_b32_e32 v9, s6
	s_add_u32 s36, s26, s0
	v_ashrrev_i32_e32 v11, 31, v10
	v_ashrrev_i32_e32 v71, 31, v70
	global_load_dword v16, v9, s[64:65]
	global_load_dword v14, v151, s[4:5] offset:2048
	global_load_dword v17, v152, s[4:5]
	global_load_dword v12, v9, s[68:69]
	s_addc_u32 s37, s27, s1
	v_max_i32_e32 v9, 1, v10
	v_lshlrev_b64 v[82:83], 1, v[10:11]
	v_lshlrev_b64 v[84:85], 1, v[70:71]
	v_lshl_add_u64 v[26:27], s[36:37], 0, v[82:83]
	v_lshlrev_b32_e32 v9, 1, v9
	v_lshl_add_u64 v[70:71], s[36:37], 0, v[84:85]
	global_load_ushort v13, v[26:27], off
	s_add_u32 s72, s30, s0
	global_load_ushort v70, v[70:71], off offset:2
	s_addc_u32 s73, s31, s1
	global_load_ushort v15, v9, s[36:37] offset:-2
	v_cmp_lt_i32_e64 s[0:1], 0, v10
	v_cmp_gt_i32_e64 s[4:5], s88, v10
	v_pk_add_f32 v[2:3], v[106:107], v[2:3]
	v_cndmask_b32_e64 v81, 0, 1.0, s[0:1]
	v_cndmask_b32_e64 v86, 0, 1.0, s[4:5]
	v_add_u32_e32 v92, 0x200, v10
	v_cmp_lt_i32_e64 s[20:21], s33, v10
	v_cmp_gt_i32_e64 s[18:19], s92, v10
	v_add_u32_e32 v90, 0x400, v10
	v_cmp_lt_i32_e64 s[16:17], s81, v10
	v_cmp_gt_i32_e64 s[0:1], s38, v10
	v_add_u32_e32 v88, 0x600, v10
	v_cmp_lt_i32_e64 s[12:13], s93, v10
	v_cmp_gt_i32_e64 s[10:11], s3, v10
	v_cmp_lt_i32_e64 s[8:9], s50, v10
	v_cmp_gt_i32_e64 s[6:7], s90, v10
	v_cmp_lt_i32_e64 s[4:5], s39, v10
	v_cmp_gt_i32_e64 s[22:23], s51, v10
	s_waitcnt vmcnt(2)
	v_lshlrev_b32_e32 v13, 16, v13
	s_waitcnt vmcnt(1)
	v_lshlrev_b32_e32 v70, 16, v70
	v_mul_f32_e32 v70, v86, v70
	s_waitcnt vmcnt(0)
	v_lshlrev_b32_e32 v15, 16, v15
	v_mul_f32_e32 v15, v81, v15
	v_mul_f32_e32 v15, v16, v15
	v_fmac_f32_e32 v15, v14, v13
	v_fmac_f32_e32 v15, v17, v70
	v_lshl_add_u64 v[70:71], s[72:73], 0, v[82:83]
	v_lshl_add_u64 v[82:83], s[72:73], 0, v[84:85]
	v_add_f32_e32 v80, v12, v15
	global_load_ushort v13, v[70:71], off
	global_load_ushort v15, v[82:83], off offset:2
	v_add_u32_e32 v84, 0x800, v10
	global_load_ushort v9, v9, s[72:73] offset:-2
	v_add_u32_e32 v82, 0xa00, v10
	s_waitcnt vmcnt(2)
	v_lshlrev_b32_e32 v13, 16, v13
	s_waitcnt vmcnt(1)
	v_lshlrev_b32_e32 v15, 16, v15
	v_mul_f32_e32 v15, v86, v15
	s_waitcnt vmcnt(0)
	v_lshlrev_b32_e32 v9, 16, v9
	v_mul_f32_e32 v9, v81, v9
	v_mul_f32_e32 v9, v16, v9
	v_fmac_f32_e32 v9, v14, v13
	v_fmac_f32_e32 v9, v17, v15
	v_add_f32_e32 v86, v12, v9
	s_cbranch_vccnz .LBB0_912
	s_lshl_b64 s[0:1], s[66:67], 1
	s_add_u32 s4, s0, s30
	s_addc_u32 s5, s1, s31
	s_add_u32 s0, s0, s26
	s_addc_u32 s1, s1, s27
	s_add_u32 s18, s70, 0x800000
	s_addc_u32 s19, s71, 0
	v_lshlrev_b32_e32 v109, 1, v10
	global_load_ushort v9, v109, s[0:1]
	global_load_ushort v11, v109, s[4:5]
	global_load_ushort v13, v109, s[36:37] offset:1022
	global_load_ushort v15, v109, s[36:37] offset:1024
	global_load_ushort v81, v109, s[36:37] offset:1026
	global_load_ushort v83, v109, s[72:73] offset:1022
	global_load_ushort v85, v109, s[72:73] offset:1024
	global_load_ushort v87, v109, s[72:73] offset:1026
	global_load_ushort v89, v109, s[0:1] offset:1024
	global_load_ushort v91, v109, s[4:5] offset:1024
	global_load_ushort v93, v109, s[36:37] offset:2046
	global_load_ushort v94, v109, s[36:37] offset:2048
	global_load_ushort v95, v109, s[36:37] offset:2050
	global_load_ushort v96, v109, s[72:73] offset:2046
	global_load_ushort v97, v109, s[72:73] offset:2048
	global_load_ushort v98, v109, s[72:73] offset:2050
	global_load_ushort v99, v109, s[0:1] offset:2048
	global_load_ushort v100, v109, s[4:5] offset:2048
	global_load_ushort v101, v109, s[36:37] offset:3070
	global_load_ushort v102, v109, s[36:37] offset:3072
	global_load_ushort v103, v109, s[36:37] offset:3074
	global_load_ushort v104, v109, s[72:73] offset:3070
	global_load_ushort v105, v109, s[72:73] offset:3072
	global_load_ushort v106, v109, s[72:73] offset:3074
	global_load_ushort v107, v109, s[0:1] offset:3072
	global_load_ushort v108, v109, s[4:5] offset:3072
	s_waitcnt vmcnt(0)
	v_lshlrev_b32_e32 v26, 10, v10
	v_fma_f32 v27, v32, v8, v78
	v_mul_f32_e32 v70, v80, v27
	v_lshlrev_b32_e32 v9, 16, v9
	v_mul_f32_e32 v84, 0xbfb8aa3b, v9
	v_exp_f32_e32 v84, v84
	s_nop 0
	v_add_f32_e32 v84, 1.0, v84
	v_div_scale_f32 v71, s[74:75], v84, v84, v9
	v_rcp_f32_e32 v82, v71
	s_nop 0
	v_fma_f32 v92, -v71, v82, 1.0
	v_fmac_f32_e32 v82, v92, v82
	v_div_scale_f32 v88, vcc, v9, v84, v9
	v_mul_f32_e32 v90, v88, v82
	v_fma_f32 v92, -v71, v90, v88
	v_fmac_f32_e32 v90, v92, v82
	v_fma_f32 v71, -v71, v90, v88
	v_div_fmas_f32 v71, v71, v82, v90
	v_div_fixup_f32 v9, v71, v84, v9
	v_mul_f32_e32 v70, v70, v9
	v_cvt_pk_bf16_f32 v70, v70, s0
	global_store_short v26, v70, s[70:71]
	v_fma_f32 v27, v34, v8, v79
	v_mul_f32_e32 v70, v86, v27
	v_lshlrev_b32_e32 v11, 16, v11
	v_mul_f32_e32 v84, 0xbfb8aa3b, v11
	v_exp_f32_e32 v84, v84
	s_nop 0
	v_add_f32_e32 v84, 1.0, v84
	v_div_scale_f32 v71, s[74:75], v84, v84, v11
	v_rcp_f32_e32 v82, v71
	s_nop 0
	v_fma_f32 v92, -v71, v82, 1.0
	v_fmac_f32_e32 v82, v92, v82
	v_div_scale_f32 v88, vcc, v11, v84, v11
	v_mul_f32_e32 v90, v88, v82
	v_fma_f32 v92, -v71, v90, v88
	v_fmac_f32_e32 v90, v92, v82
	v_fma_f32 v71, -v71, v90, v88
	v_div_fmas_f32 v71, v71, v82, v90
	v_div_fixup_f32 v11, v71, v84, v11
	v_mul_f32_e32 v70, v70, v11
	v_cvt_pk_bf16_f32 v70, v70, s0
	global_store_short v26, v70, s[18:19]
	v_add_u32_e32 v26, 0x80000, v26
	v_lshlrev_b32_e32 v15, 16, v15
	v_lshlrev_b32_e32 v81, 16, v81
	v_lshlrev_b32_e32 v13, 16, v13
	v_mul_f32_e32 v13, v16, v13
	v_fmac_f32_e32 v13, v14, v15
	v_fmac_f32_e32 v13, v17, v81
	v_add_f32_e32 v13, v12, v13
	v_fma_f32 v27, v33, v8, v76
	v_mul_f32_e32 v70, v27, v13
	v_lshlrev_b32_e32 v89, 16, v89
	v_mul_f32_e32 v84, 0xbfb8aa3b, v89
	v_exp_f32_e32 v84, v84
	s_nop 0
	v_add_f32_e32 v84, 1.0, v84
	v_div_scale_f32 v71, s[74:75], v84, v84, v89
	v_rcp_f32_e32 v82, v71
	s_nop 0
	v_fma_f32 v92, -v71, v82, 1.0
	v_fmac_f32_e32 v82, v92, v82
	v_div_scale_f32 v88, vcc, v89, v84, v89
	v_mul_f32_e32 v90, v88, v82
	v_fma_f32 v92, -v71, v90, v88
	v_fmac_f32_e32 v90, v92, v82
	v_fma_f32 v71, -v71, v90, v88
	v_div_fmas_f32 v71, v71, v82, v90
	v_div_fixup_f32 v89, v71, v84, v89
	v_mul_f32_e32 v70, v70, v89
	v_cvt_pk_bf16_f32 v70, v70, s0
	global_store_short v26, v70, s[70:71]
	v_lshlrev_b32_e32 v85, 16, v85
	v_lshlrev_b32_e32 v87, 16, v87
	v_lshlrev_b32_e32 v83, 16, v83
	v_mul_f32_e32 v83, v16, v83
	v_fmac_f32_e32 v83, v14, v85
	v_fmac_f32_e32 v83, v17, v87
	v_add_f32_e32 v83, v12, v83
	v_fma_f32 v27, v35, v8, v77
	v_mul_f32_e32 v70, v27, v83
	v_lshlrev_b32_e32 v91, 16, v91
	v_mul_f32_e32 v84, 0xbfb8aa3b, v91
	v_exp_f32_e32 v84, v84
	s_nop 0
	v_add_f32_e32 v84, 1.0, v84
	v_div_scale_f32 v71, s[74:75], v84, v84, v91
	v_rcp_f32_e32 v82, v71
	s_nop 0
	v_fma_f32 v92, -v71, v82, 1.0
	v_fmac_f32_e32 v82, v92, v82
	v_div_scale_f32 v88, vcc, v91, v84, v91
	v_mul_f32_e32 v90, v88, v82
	v_fma_f32 v92, -v71, v90, v88
	v_fmac_f32_e32 v90, v92, v82
	v_fma_f32 v71, -v71, v90, v88
	v_div_fmas_f32 v71, v71, v82, v90
	v_div_fixup_f32 v91, v71, v84, v91
	v_mul_f32_e32 v70, v70, v91
	v_cvt_pk_bf16_f32 v70, v70, s0
	global_store_short v26, v70, s[18:19]
	v_add_u32_e32 v26, 0x80000, v26
	v_lshlrev_b32_e32 v94, 16, v94
	v_lshlrev_b32_e32 v95, 16, v95
	v_lshlrev_b32_e32 v93, 16, v93
	v_mul_f32_e32 v93, v16, v93
	v_fmac_f32_e32 v93, v14, v94
	v_fmac_f32_e32 v93, v17, v95
	v_add_f32_e32 v93, v12, v93
	v_fma_f32 v27, v37, v8, v72
	v_mul_f32_e32 v70, v27, v93
	v_lshlrev_b32_e32 v99, 16, v99
	v_mul_f32_e32 v84, 0xbfb8aa3b, v99
	v_exp_f32_e32 v84, v84
	s_nop 0
	v_add_f32_e32 v84, 1.0, v84
	v_div_scale_f32 v71, s[74:75], v84, v84, v99
	v_rcp_f32_e32 v82, v71
	s_nop 0
	v_fma_f32 v92, -v71, v82, 1.0
	v_fmac_f32_e32 v82, v92, v82
	v_div_scale_f32 v88, vcc, v99, v84, v99
	v_mul_f32_e32 v90, v88, v82
	v_fma_f32 v92, -v71, v90, v88
	v_fmac_f32_e32 v90, v92, v82
	v_fma_f32 v71, -v71, v90, v88
	v_div_fmas_f32 v71, v71, v82, v90
	v_div_fixup_f32 v99, v71, v84, v99
	v_mul_f32_e32 v70, v70, v99
	v_cvt_pk_bf16_f32 v70, v70, s0
	global_store_short v26, v70, s[70:71]
	v_lshlrev_b32_e32 v97, 16, v97
	v_lshlrev_b32_e32 v98, 16, v98
	v_lshlrev_b32_e32 v96, 16, v96
	v_mul_f32_e32 v96, v16, v96
	v_fmac_f32_e32 v96, v14, v97
	v_fmac_f32_e32 v96, v17, v98
	v_add_f32_e32 v96, v12, v96
	v_fma_f32 v27, v31, v8, v73
	v_mul_f32_e32 v70, v27, v96
	v_lshlrev_b32_e32 v100, 16, v100
	v_mul_f32_e32 v84, 0xbfb8aa3b, v100
	v_exp_f32_e32 v84, v84
	s_nop 0
	v_add_f32_e32 v84, 1.0, v84
	v_div_scale_f32 v71, s[74:75], v84, v84, v100
	v_rcp_f32_e32 v82, v71
	s_nop 0
	v_fma_f32 v92, -v71, v82, 1.0
	v_fmac_f32_e32 v82, v92, v82
	v_div_scale_f32 v88, vcc, v100, v84, v100
	v_mul_f32_e32 v90, v88, v82
	v_fma_f32 v92, -v71, v90, v88
	v_fmac_f32_e32 v90, v92, v82
	v_fma_f32 v71, -v71, v90, v88
	v_div_fmas_f32 v71, v71, v82, v90
	v_div_fixup_f32 v100, v71, v84, v100
	v_mul_f32_e32 v70, v70, v100
	v_cvt_pk_bf16_f32 v70, v70, s0
	global_store_short v26, v70, s[18:19]
	v_add_u32_e32 v26, 0x80000, v26
	v_lshlrev_b32_e32 v102, 16, v102
	v_lshlrev_b32_e32 v103, 16, v103
	v_lshlrev_b32_e32 v101, 16, v101
	v_mul_f32_e32 v101, v16, v101
	v_fmac_f32_e32 v101, v14, v102
	v_fmac_f32_e32 v101, v17, v103
	v_add_f32_e32 v101, v12, v101
	v_fma_f32 v27, v36, v8, v74
	v_mul_f32_e32 v70, v27, v101
	v_lshlrev_b32_e32 v107, 16, v107
	v_mul_f32_e32 v84, 0xbfb8aa3b, v107
	v_exp_f32_e32 v84, v84
	s_nop 0
	v_add_f32_e32 v84, 1.0, v84
	v_div_scale_f32 v71, s[74:75], v84, v84, v107
	v_rcp_f32_e32 v82, v71
	s_nop 0
	v_fma_f32 v92, -v71, v82, 1.0
	v_fmac_f32_e32 v82, v92, v82
	v_div_scale_f32 v88, vcc, v107, v84, v107
	v_mul_f32_e32 v90, v88, v82
	v_fma_f32 v92, -v71, v90, v88
	v_fmac_f32_e32 v90, v92, v82
	v_fma_f32 v71, -v71, v90, v88
	v_div_fmas_f32 v71, v71, v82, v90
	v_div_fixup_f32 v107, v71, v84, v107
	v_mul_f32_e32 v70, v70, v107
	v_cvt_pk_bf16_f32 v70, v70, s0
	global_store_short v26, v70, s[70:71]
	v_lshlrev_b32_e32 v105, 16, v105
	v_lshlrev_b32_e32 v106, 16, v106
	v_lshlrev_b32_e32 v104, 16, v104
	v_mul_f32_e32 v104, v16, v104
	v_fmac_f32_e32 v104, v14, v105
	v_fmac_f32_e32 v104, v17, v106
	v_add_f32_e32 v104, v12, v104
	v_fma_f32 v27, v30, v8, v75
	v_mul_f32_e32 v70, v27, v104
	v_lshlrev_b32_e32 v108, 16, v108
	v_mul_f32_e32 v84, 0xbfb8aa3b, v108
	v_exp_f32_e32 v84, v84
	s_nop 0
	v_add_f32_e32 v84, 1.0, v84
	v_div_scale_f32 v71, s[74:75], v84, v84, v108
	v_rcp_f32_e32 v82, v71
	s_nop 0
	v_fma_f32 v92, -v71, v82, 1.0
	v_fmac_f32_e32 v82, v92, v82
	v_div_scale_f32 v88, vcc, v108, v84, v108
	v_mul_f32_e32 v90, v88, v82
	v_fma_f32 v92, -v71, v90, v88
	v_fmac_f32_e32 v90, v92, v82
	v_fma_f32 v71, -v71, v90, v88
	v_div_fmas_f32 v71, v71, v82, v90
	v_div_fixup_f32 v108, v71, v84, v108
	v_mul_f32_e32 v70, v70, v108
	v_cvt_pk_bf16_f32 v70, v70, s0
	global_store_short v26, v70, s[18:19]
	v_add_u32_e32 v109, 0x1000, v109
	global_load_ushort v9, v109, s[36:37] offset:-2
	global_load_ushort v11, v109, s[36:37]
	global_load_ushort v13, v109, s[36:37] offset:2
	global_load_ushort v15, v109, s[72:73] offset:-2
	global_load_ushort v81, v109, s[72:73]
	global_load_ushort v83, v109, s[72:73] offset:2
	global_load_ushort v85, v109, s[0:1]
	global_load_ushort v87, v109, s[4:5]
	global_load_ushort v89, v109, s[36:37] offset:1022
	global_load_ushort v91, v109, s[36:37] offset:1024
	global_load_ushort v93, v109, s[36:37] offset:1026
	global_load_ushort v94, v109, s[72:73] offset:1022
	global_load_ushort v95, v109, s[72:73] offset:1024
	global_load_ushort v96, v109, s[72:73] offset:1026
	global_load_ushort v97, v109, s[0:1] offset:1024
	global_load_ushort v98, v109, s[4:5] offset:1024
	global_load_ushort v99, v109, s[36:37] offset:2046
	global_load_ushort v100, v109, s[36:37] offset:2048
	global_load_ushort v101, v109, s[36:37] offset:2050
	global_load_ushort v102, v109, s[72:73] offset:2046
	global_load_ushort v103, v109, s[72:73] offset:2048
	global_load_ushort v104, v109, s[72:73] offset:2050
	global_load_ushort v105, v109, s[0:1] offset:2048
	global_load_ushort v106, v109, s[4:5] offset:2048
	global_load_ushort v107, v109, s[36:37] offset:3070
	global_load_ushort v108, v109, s[36:37] offset:3072
	global_load_ushort v32, v109, s[36:37] offset:3074
	global_load_ushort v78, v109, s[72:73] offset:3070
	global_load_ushort v34, v109, s[72:73] offset:3072
	global_load_ushort v79, v109, s[72:73] offset:3074
	global_load_ushort v33, v109, s[0:1] offset:3072
	global_load_ushort v76, v109, s[4:5] offset:3072
	s_waitcnt vmcnt(0)
	v_add_u32_e32 v26, 0x80000, v26
	v_lshlrev_b32_e32 v11, 16, v11
	v_lshlrev_b32_e32 v13, 16, v13
	v_lshlrev_b32_e32 v9, 16, v9
	v_mul_f32_e32 v9, v16, v9
	v_fmac_f32_e32 v9, v14, v11
	v_fmac_f32_e32 v9, v17, v13
	v_add_f32_e32 v9, v12, v9
	v_fma_f32 v27, v39, v8, v66
	v_mul_f32_e32 v70, v27, v9
	v_lshlrev_b32_e32 v85, 16, v85
	v_mul_f32_e32 v84, 0xbfb8aa3b, v85
	v_exp_f32_e32 v84, v84
	s_nop 0
	v_add_f32_e32 v84, 1.0, v84
	v_div_scale_f32 v71, s[74:75], v84, v84, v85
	v_rcp_f32_e32 v82, v71
	s_nop 0
	v_fma_f32 v92, -v71, v82, 1.0
	v_fmac_f32_e32 v82, v92, v82
	v_div_scale_f32 v88, vcc, v85, v84, v85
	v_mul_f32_e32 v90, v88, v82
	v_fma_f32 v92, -v71, v90, v88
	v_fmac_f32_e32 v90, v92, v82
	v_fma_f32 v71, -v71, v90, v88
	v_div_fmas_f32 v71, v71, v82, v90
	v_div_fixup_f32 v85, v71, v84, v85
	v_mul_f32_e32 v70, v70, v85
	v_cvt_pk_bf16_f32 v70, v70, s0
	global_store_short v26, v70, s[70:71]
	v_lshlrev_b32_e32 v81, 16, v81
	v_lshlrev_b32_e32 v83, 16, v83
	v_lshlrev_b32_e32 v15, 16, v15
	v_mul_f32_e32 v15, v16, v15
	v_fmac_f32_e32 v15, v14, v81
	v_fmac_f32_e32 v15, v17, v83
	v_add_f32_e32 v15, v12, v15
	v_fma_f32 v27, v41, v8, v67
	v_mul_f32_e32 v70, v27, v15
	v_lshlrev_b32_e32 v87, 16, v87
	v_mul_f32_e32 v84, 0xbfb8aa3b, v87
	v_exp_f32_e32 v84, v84
	s_nop 0
	v_add_f32_e32 v84, 1.0, v84
	v_div_scale_f32 v71, s[74:75], v84, v84, v87
	v_rcp_f32_e32 v82, v71
	s_nop 0
	v_fma_f32 v92, -v71, v82, 1.0
	v_fmac_f32_e32 v82, v92, v82
	v_div_scale_f32 v88, vcc, v87, v84, v87
	v_mul_f32_e32 v90, v88, v82
	v_fma_f32 v92, -v71, v90, v88
	v_fmac_f32_e32 v90, v92, v82
	v_fma_f32 v71, -v71, v90, v88
	v_div_fmas_f32 v71, v71, v82, v90
	v_div_fixup_f32 v87, v71, v84, v87
	v_mul_f32_e32 v70, v70, v87
	v_cvt_pk_bf16_f32 v70, v70, s0
	global_store_short v26, v70, s[18:19]
	v_add_u32_e32 v26, 0x80000, v26
	v_lshlrev_b32_e32 v91, 16, v91
	v_lshlrev_b32_e32 v93, 16, v93
	v_lshlrev_b32_e32 v89, 16, v89
	v_mul_f32_e32 v89, v16, v89
	v_fmac_f32_e32 v89, v14, v91
	v_fmac_f32_e32 v89, v17, v93
	v_add_f32_e32 v89, v12, v89
	v_fma_f32 v27, v38, v8, v68
	v_mul_f32_e32 v70, v27, v89
	v_lshlrev_b32_e32 v97, 16, v97
	v_mul_f32_e32 v84, 0xbfb8aa3b, v97
	v_exp_f32_e32 v84, v84
	s_nop 0
	v_add_f32_e32 v84, 1.0, v84
	v_div_scale_f32 v71, s[74:75], v84, v84, v97
	v_rcp_f32_e32 v82, v71
	s_nop 0
	v_fma_f32 v92, -v71, v82, 1.0
	v_fmac_f32_e32 v82, v92, v82
	v_div_scale_f32 v88, vcc, v97, v84, v97
	v_mul_f32_e32 v90, v88, v82
	v_fma_f32 v92, -v71, v90, v88
	v_fmac_f32_e32 v90, v92, v82
	v_fma_f32 v71, -v71, v90, v88
	v_div_fmas_f32 v71, v71, v82, v90
	v_div_fixup_f32 v97, v71, v84, v97
	v_mul_f32_e32 v70, v70, v97
	v_cvt_pk_bf16_f32 v70, v70, s0
	global_store_short v26, v70, s[70:71]
	v_lshlrev_b32_e32 v95, 16, v95
	v_lshlrev_b32_e32 v96, 16, v96
	v_lshlrev_b32_e32 v94, 16, v94
	v_mul_f32_e32 v94, v16, v94
	v_fmac_f32_e32 v94, v14, v95
	v_fmac_f32_e32 v94, v17, v96
	v_add_f32_e32 v94, v12, v94
	v_fma_f32 v27, v40, v8, v69
	v_mul_f32_e32 v70, v27, v94
	v_lshlrev_b32_e32 v98, 16, v98
	v_mul_f32_e32 v84, 0xbfb8aa3b, v98
	v_exp_f32_e32 v84, v84
	s_nop 0
	v_add_f32_e32 v84, 1.0, v84
	v_div_scale_f32 v71, s[74:75], v84, v84, v98
	v_rcp_f32_e32 v82, v71
	s_nop 0
	v_fma_f32 v92, -v71, v82, 1.0
	v_fmac_f32_e32 v82, v92, v82
	v_div_scale_f32 v88, vcc, v98, v84, v98
	v_mul_f32_e32 v90, v88, v82
	v_fma_f32 v92, -v71, v90, v88
	v_fmac_f32_e32 v90, v92, v82
	v_fma_f32 v71, -v71, v90, v88
	v_div_fmas_f32 v71, v71, v82, v90
	v_div_fixup_f32 v98, v71, v84, v98
	v_mul_f32_e32 v70, v70, v98
	v_cvt_pk_bf16_f32 v70, v70, s0
	global_store_short v26, v70, s[18:19]
	v_add_u32_e32 v26, 0x80000, v26
	v_lshlrev_b32_e32 v100, 16, v100
	v_lshlrev_b32_e32 v101, 16, v101
	v_lshlrev_b32_e32 v99, 16, v99
	v_mul_f32_e32 v99, v16, v99
	v_fmac_f32_e32 v99, v14, v100
	v_fmac_f32_e32 v99, v17, v101
	v_add_f32_e32 v99, v12, v99
	v_fma_f32 v27, v43, v8, v62
	v_mul_f32_e32 v70, v27, v99
	v_lshlrev_b32_e32 v105, 16, v105
	v_mul_f32_e32 v84, 0xbfb8aa3b, v105
	v_exp_f32_e32 v84, v84
	s_nop 0
	v_add_f32_e32 v84, 1.0, v84
	v_div_scale_f32 v71, s[74:75], v84, v84, v105
	v_rcp_f32_e32 v82, v71
	s_nop 0
	v_fma_f32 v92, -v71, v82, 1.0
	v_fmac_f32_e32 v82, v92, v82
	v_div_scale_f32 v88, vcc, v105, v84, v105
	v_mul_f32_e32 v90, v88, v82
	v_fma_f32 v92, -v71, v90, v88
	v_fmac_f32_e32 v90, v92, v82
	v_fma_f32 v71, -v71, v90, v88
	v_div_fmas_f32 v71, v71, v82, v90
	v_div_fixup_f32 v105, v71, v84, v105
	v_mul_f32_e32 v70, v70, v105
	v_cvt_pk_bf16_f32 v70, v70, s0
	global_store_short v26, v70, s[70:71]
	v_lshlrev_b32_e32 v103, 16, v103
	v_lshlrev_b32_e32 v104, 16, v104
	v_lshlrev_b32_e32 v102, 16, v102
	v_mul_f32_e32 v102, v16, v102
	v_fmac_f32_e32 v102, v14, v103
	v_fmac_f32_e32 v102, v17, v104
	v_add_f32_e32 v102, v12, v102
	v_fma_f32 v27, v45, v8, v63
	v_mul_f32_e32 v70, v27, v102
	v_lshlrev_b32_e32 v106, 16, v106
	v_mul_f32_e32 v84, 0xbfb8aa3b, v106
	v_exp_f32_e32 v84, v84
	s_nop 0
	v_add_f32_e32 v84, 1.0, v84
	v_div_scale_f32 v71, s[74:75], v84, v84, v106
	v_rcp_f32_e32 v82, v71
	s_nop 0
	v_fma_f32 v92, -v71, v82, 1.0
	v_fmac_f32_e32 v82, v92, v82
	v_div_scale_f32 v88, vcc, v106, v84, v106
	v_mul_f32_e32 v90, v88, v82
	v_fma_f32 v92, -v71, v90, v88
	v_fmac_f32_e32 v90, v92, v82
	v_fma_f32 v71, -v71, v90, v88
	v_div_fmas_f32 v71, v71, v82, v90
	v_div_fixup_f32 v106, v71, v84, v106
	v_mul_f32_e32 v70, v70, v106
	v_cvt_pk_bf16_f32 v70, v70, s0
	global_store_short v26, v70, s[18:19]
	v_add_u32_e32 v26, 0x80000, v26
	v_lshlrev_b32_e32 v108, 16, v108
	v_lshlrev_b32_e32 v32, 16, v32
	v_lshlrev_b32_e32 v107, 16, v107
	v_mul_f32_e32 v107, v16, v107
	v_fmac_f32_e32 v107, v14, v108
	v_fmac_f32_e32 v107, v17, v32
	v_add_f32_e32 v107, v12, v107
	v_fma_f32 v27, v42, v8, v64
	v_mul_f32_e32 v70, v27, v107
	v_lshlrev_b32_e32 v33, 16, v33
	v_mul_f32_e32 v84, 0xbfb8aa3b, v33
	v_exp_f32_e32 v84, v84
	s_nop 0
	v_add_f32_e32 v84, 1.0, v84
	v_div_scale_f32 v71, s[74:75], v84, v84, v33
	v_rcp_f32_e32 v82, v71
	s_nop 0
	v_fma_f32 v92, -v71, v82, 1.0
	v_fmac_f32_e32 v82, v92, v82
	v_div_scale_f32 v88, vcc, v33, v84, v33
	v_mul_f32_e32 v90, v88, v82
	v_fma_f32 v92, -v71, v90, v88
	v_fmac_f32_e32 v90, v92, v82
	v_fma_f32 v71, -v71, v90, v88
	v_div_fmas_f32 v71, v71, v82, v90
	v_div_fixup_f32 v33, v71, v84, v33
	v_mul_f32_e32 v70, v70, v33
	v_cvt_pk_bf16_f32 v70, v70, s0
	global_store_short v26, v70, s[70:71]
	v_lshlrev_b32_e32 v34, 16, v34
	v_lshlrev_b32_e32 v79, 16, v79
	v_lshlrev_b32_e32 v78, 16, v78
	v_mul_f32_e32 v78, v16, v78
	v_fmac_f32_e32 v78, v14, v34
	v_fmac_f32_e32 v78, v17, v79
	v_add_f32_e32 v78, v12, v78
	v_fma_f32 v27, v44, v8, v65
	v_mul_f32_e32 v70, v27, v78
	v_lshlrev_b32_e32 v76, 16, v76
	v_mul_f32_e32 v84, 0xbfb8aa3b, v76
	v_exp_f32_e32 v84, v84
	s_nop 0
	v_add_f32_e32 v84, 1.0, v84
	v_div_scale_f32 v71, s[74:75], v84, v84, v76
	v_rcp_f32_e32 v82, v71
	s_nop 0
	v_fma_f32 v92, -v71, v82, 1.0
	v_fmac_f32_e32 v82, v92, v82
	v_div_scale_f32 v88, vcc, v76, v84, v76
	v_mul_f32_e32 v90, v88, v82
	v_fma_f32 v92, -v71, v90, v88
	v_fmac_f32_e32 v90, v92, v82
	v_fma_f32 v71, -v71, v90, v88
	v_div_fmas_f32 v71, v71, v82, v90
	v_div_fixup_f32 v76, v71, v84, v76
	v_mul_f32_e32 v70, v70, v76
	v_cvt_pk_bf16_f32 v70, v70, s0
	global_store_short v26, v70, s[18:19]
	v_add_u32_e32 v109, 0x1000, v109
	global_load_ushort v9, v109, s[36:37] offset:-2
	global_load_ushort v11, v109, s[36:37]
	global_load_ushort v13, v109, s[36:37] offset:2
	global_load_ushort v15, v109, s[72:73] offset:-2
	global_load_ushort v81, v109, s[72:73]
	global_load_ushort v83, v109, s[72:73] offset:2
	global_load_ushort v85, v109, s[0:1]
	global_load_ushort v87, v109, s[4:5]
	global_load_ushort v89, v109, s[36:37] offset:1022
	global_load_ushort v91, v109, s[36:37] offset:1024
	global_load_ushort v93, v109, s[36:37] offset:1026
	global_load_ushort v94, v109, s[72:73] offset:1022
	global_load_ushort v95, v109, s[72:73] offset:1024
	global_load_ushort v96, v109, s[72:73] offset:1026
	global_load_ushort v97, v109, s[0:1] offset:1024
	global_load_ushort v98, v109, s[4:5] offset:1024
	global_load_ushort v99, v109, s[36:37] offset:2046
	global_load_ushort v100, v109, s[36:37] offset:2048
	global_load_ushort v101, v109, s[36:37] offset:2050
	global_load_ushort v102, v109, s[72:73] offset:2046
	global_load_ushort v103, v109, s[72:73] offset:2048
	global_load_ushort v104, v109, s[72:73] offset:2050
	global_load_ushort v105, v109, s[0:1] offset:2048
	global_load_ushort v106, v109, s[4:5] offset:2048
	global_load_ushort v107, v109, s[36:37] offset:3070
	global_load_ushort v108, v109, s[36:37] offset:3072
	global_load_ushort v32, v109, s[36:37] offset:3074
	global_load_ushort v78, v109, s[72:73] offset:3070
	global_load_ushort v34, v109, s[72:73] offset:3072
	global_load_ushort v79, v109, s[72:73] offset:3074
	global_load_ushort v33, v109, s[0:1] offset:3072
	global_load_ushort v76, v109, s[4:5] offset:3072
	s_waitcnt vmcnt(0)
	v_add_u32_e32 v26, 0x80000, v26
	v_lshlrev_b32_e32 v11, 16, v11
	v_lshlrev_b32_e32 v13, 16, v13
	v_lshlrev_b32_e32 v9, 16, v9
	v_mul_f32_e32 v9, v16, v9
	v_fmac_f32_e32 v9, v14, v11
	v_fmac_f32_e32 v9, v17, v13
	v_add_f32_e32 v9, v12, v9
	v_fma_f32 v27, v47, v8, v22
	v_mul_f32_e32 v70, v27, v9
	v_lshlrev_b32_e32 v85, 16, v85
	v_mul_f32_e32 v84, 0xbfb8aa3b, v85
	v_exp_f32_e32 v84, v84
	s_nop 0
	v_add_f32_e32 v84, 1.0, v84
	v_div_scale_f32 v71, s[74:75], v84, v84, v85
	v_rcp_f32_e32 v82, v71
	s_nop 0
	v_fma_f32 v92, -v71, v82, 1.0
	v_fmac_f32_e32 v82, v92, v82
	v_div_scale_f32 v88, vcc, v85, v84, v85
	v_mul_f32_e32 v90, v88, v82
	v_fma_f32 v92, -v71, v90, v88
	v_fmac_f32_e32 v90, v92, v82
	v_fma_f32 v71, -v71, v90, v88
	v_div_fmas_f32 v71, v71, v82, v90
	v_div_fixup_f32 v85, v71, v84, v85
	v_mul_f32_e32 v70, v70, v85
	v_cvt_pk_bf16_f32 v70, v70, s0
	global_store_short v26, v70, s[70:71]
	v_lshlrev_b32_e32 v81, 16, v81
	v_lshlrev_b32_e32 v83, 16, v83
	v_lshlrev_b32_e32 v15, 16, v15
	v_mul_f32_e32 v15, v16, v15
	v_fmac_f32_e32 v15, v14, v81
	v_fmac_f32_e32 v15, v17, v83
	v_add_f32_e32 v15, v12, v15
	v_fma_f32 v27, v49, v8, v23
	v_mul_f32_e32 v70, v27, v15
	v_lshlrev_b32_e32 v87, 16, v87
	v_mul_f32_e32 v84, 0xbfb8aa3b, v87
	v_exp_f32_e32 v84, v84
	s_nop 0
	v_add_f32_e32 v84, 1.0, v84
	v_div_scale_f32 v71, s[74:75], v84, v84, v87
	v_rcp_f32_e32 v82, v71
	s_nop 0
	v_fma_f32 v92, -v71, v82, 1.0
	v_fmac_f32_e32 v82, v92, v82
	v_div_scale_f32 v88, vcc, v87, v84, v87
	v_mul_f32_e32 v90, v88, v82
	v_fma_f32 v92, -v71, v90, v88
	v_fmac_f32_e32 v90, v92, v82
	v_fma_f32 v71, -v71, v90, v88
	v_div_fmas_f32 v71, v71, v82, v90
	v_div_fixup_f32 v87, v71, v84, v87
	v_mul_f32_e32 v70, v70, v87
	v_cvt_pk_bf16_f32 v70, v70, s0
	global_store_short v26, v70, s[18:19]
	v_add_u32_e32 v26, 0x80000, v26
	v_lshlrev_b32_e32 v91, 16, v91
	v_lshlrev_b32_e32 v93, 16, v93
	v_lshlrev_b32_e32 v89, 16, v89
	v_mul_f32_e32 v89, v16, v89
	v_fmac_f32_e32 v89, v14, v91
	v_fmac_f32_e32 v89, v17, v93
	v_add_f32_e32 v89, v12, v89
	v_fma_f32 v27, v46, v8, v24
	v_mul_f32_e32 v70, v27, v89
	v_lshlrev_b32_e32 v97, 16, v97
	v_mul_f32_e32 v84, 0xbfb8aa3b, v97
	v_exp_f32_e32 v84, v84
	s_nop 0
	v_add_f32_e32 v84, 1.0, v84
	v_div_scale_f32 v71, s[74:75], v84, v84, v97
	v_rcp_f32_e32 v82, v71
	s_nop 0
	v_fma_f32 v92, -v71, v82, 1.0
	v_fmac_f32_e32 v82, v92, v82
	v_div_scale_f32 v88, vcc, v97, v84, v97
	v_mul_f32_e32 v90, v88, v82
	v_fma_f32 v92, -v71, v90, v88
	v_fmac_f32_e32 v90, v92, v82
	v_fma_f32 v71, -v71, v90, v88
	v_div_fmas_f32 v71, v71, v82, v90
	v_div_fixup_f32 v97, v71, v84, v97
	v_mul_f32_e32 v70, v70, v97
	v_cvt_pk_bf16_f32 v70, v70, s0
	global_store_short v26, v70, s[70:71]
	v_lshlrev_b32_e32 v95, 16, v95
	v_lshlrev_b32_e32 v96, 16, v96
	v_lshlrev_b32_e32 v94, 16, v94
	v_mul_f32_e32 v94, v16, v94
	v_fmac_f32_e32 v94, v14, v95
	v_fmac_f32_e32 v94, v17, v96
	v_add_f32_e32 v94, v12, v94
	v_fma_f32 v27, v48, v8, v25
	v_mul_f32_e32 v70, v27, v94
	v_lshlrev_b32_e32 v98, 16, v98
	v_mul_f32_e32 v84, 0xbfb8aa3b, v98
	v_exp_f32_e32 v84, v84
	s_nop 0
	v_add_f32_e32 v84, 1.0, v84
	v_div_scale_f32 v71, s[74:75], v84, v84, v98
	v_rcp_f32_e32 v82, v71
	s_nop 0
	v_fma_f32 v92, -v71, v82, 1.0
	v_fmac_f32_e32 v82, v92, v82
	v_div_scale_f32 v88, vcc, v98, v84, v98
	v_mul_f32_e32 v90, v88, v82
	v_fma_f32 v92, -v71, v90, v88
	v_fmac_f32_e32 v90, v92, v82
	v_fma_f32 v71, -v71, v90, v88
	v_div_fmas_f32 v71, v71, v82, v90
	v_div_fixup_f32 v98, v71, v84, v98
	v_mul_f32_e32 v70, v70, v98
	v_cvt_pk_bf16_f32 v70, v70, s0
	global_store_short v26, v70, s[18:19]
	v_add_u32_e32 v26, 0x80000, v26
	v_lshlrev_b32_e32 v100, 16, v100
	v_lshlrev_b32_e32 v101, 16, v101
	v_lshlrev_b32_e32 v99, 16, v99
	v_mul_f32_e32 v99, v16, v99
	v_fmac_f32_e32 v99, v14, v100
	v_fmac_f32_e32 v99, v17, v101
	v_add_f32_e32 v99, v12, v99
	v_fma_f32 v27, v51, v8, v18
	v_mul_f32_e32 v70, v27, v99
	v_lshlrev_b32_e32 v105, 16, v105
	v_mul_f32_e32 v84, 0xbfb8aa3b, v105
	v_exp_f32_e32 v84, v84
	s_nop 0
	v_add_f32_e32 v84, 1.0, v84
	v_div_scale_f32 v71, s[74:75], v84, v84, v105
	v_rcp_f32_e32 v82, v71
	s_nop 0
	v_fma_f32 v92, -v71, v82, 1.0
	v_fmac_f32_e32 v82, v92, v82
	v_div_scale_f32 v88, vcc, v105, v84, v105
	v_mul_f32_e32 v90, v88, v82
	v_fma_f32 v92, -v71, v90, v88
	v_fmac_f32_e32 v90, v92, v82
	v_fma_f32 v71, -v71, v90, v88
	v_div_fmas_f32 v71, v71, v82, v90
	v_div_fixup_f32 v105, v71, v84, v105
	v_mul_f32_e32 v70, v70, v105
	v_cvt_pk_bf16_f32 v70, v70, s0
	global_store_short v26, v70, s[70:71]
	v_lshlrev_b32_e32 v103, 16, v103
	v_lshlrev_b32_e32 v104, 16, v104
	v_lshlrev_b32_e32 v102, 16, v102
	v_mul_f32_e32 v102, v16, v102
	v_fmac_f32_e32 v102, v14, v103
	v_fmac_f32_e32 v102, v17, v104
	v_add_f32_e32 v102, v12, v102
	v_fma_f32 v27, v53, v8, v19
	v_mul_f32_e32 v70, v27, v102
	v_lshlrev_b32_e32 v106, 16, v106
	v_mul_f32_e32 v84, 0xbfb8aa3b, v106
	v_exp_f32_e32 v84, v84
	s_nop 0
	v_add_f32_e32 v84, 1.0, v84
	v_div_scale_f32 v71, s[74:75], v84, v84, v106
	v_rcp_f32_e32 v82, v71
	s_nop 0
	v_fma_f32 v92, -v71, v82, 1.0
	v_fmac_f32_e32 v82, v92, v82
	v_div_scale_f32 v88, vcc, v106, v84, v106
	v_mul_f32_e32 v90, v88, v82
	v_fma_f32 v92, -v71, v90, v88
	v_fmac_f32_e32 v90, v92, v82
	v_fma_f32 v71, -v71, v90, v88
	v_div_fmas_f32 v71, v71, v82, v90
	v_div_fixup_f32 v106, v71, v84, v106
	v_mul_f32_e32 v70, v70, v106
	v_cvt_pk_bf16_f32 v70, v70, s0
	global_store_short v26, v70, s[18:19]
	v_add_u32_e32 v26, 0x80000, v26
	v_lshlrev_b32_e32 v108, 16, v108
	v_lshlrev_b32_e32 v32, 16, v32
	v_lshlrev_b32_e32 v107, 16, v107
	v_mul_f32_e32 v107, v16, v107
	v_fmac_f32_e32 v107, v14, v108
	v_fmac_f32_e32 v107, v17, v32
	v_add_f32_e32 v107, v12, v107
	v_fma_f32 v27, v50, v8, v20
	v_mul_f32_e32 v70, v27, v107
	v_lshlrev_b32_e32 v33, 16, v33
	v_mul_f32_e32 v84, 0xbfb8aa3b, v33
	v_exp_f32_e32 v84, v84
	s_nop 0
	v_add_f32_e32 v84, 1.0, v84
	v_div_scale_f32 v71, s[74:75], v84, v84, v33
	v_rcp_f32_e32 v82, v71
	s_nop 0
	v_fma_f32 v92, -v71, v82, 1.0
	v_fmac_f32_e32 v82, v92, v82
	v_div_scale_f32 v88, vcc, v33, v84, v33
	v_mul_f32_e32 v90, v88, v82
	v_fma_f32 v92, -v71, v90, v88
	v_fmac_f32_e32 v90, v92, v82
	v_fma_f32 v71, -v71, v90, v88
	v_div_fmas_f32 v71, v71, v82, v90
	v_div_fixup_f32 v33, v71, v84, v33
	v_mul_f32_e32 v70, v70, v33
	v_cvt_pk_bf16_f32 v70, v70, s0
	global_store_short v26, v70, s[70:71]
	v_lshlrev_b32_e32 v34, 16, v34
	v_lshlrev_b32_e32 v79, 16, v79
	v_lshlrev_b32_e32 v78, 16, v78
	v_mul_f32_e32 v78, v16, v78
	v_fmac_f32_e32 v78, v14, v34
	v_fmac_f32_e32 v78, v17, v79
	v_add_f32_e32 v78, v12, v78
	v_fma_f32 v27, v52, v8, v21
	v_mul_f32_e32 v70, v27, v78
	v_lshlrev_b32_e32 v76, 16, v76
	v_mul_f32_e32 v84, 0xbfb8aa3b, v76
	v_exp_f32_e32 v84, v84
	s_nop 0
	v_add_f32_e32 v84, 1.0, v84
	v_div_scale_f32 v71, s[74:75], v84, v84, v76
	v_rcp_f32_e32 v82, v71
	s_nop 0
	v_fma_f32 v92, -v71, v82, 1.0
	v_fmac_f32_e32 v82, v92, v82
	v_div_scale_f32 v88, vcc, v76, v84, v76
	v_mul_f32_e32 v90, v88, v82
	v_fma_f32 v92, -v71, v90, v88
	v_fmac_f32_e32 v90, v92, v82
	v_fma_f32 v71, -v71, v90, v88
	v_div_fmas_f32 v71, v71, v82, v90
	v_div_fixup_f32 v76, v71, v84, v76
	v_mul_f32_e32 v70, v70, v76
	v_cvt_pk_bf16_f32 v70, v70, s0
	global_store_short v26, v70, s[18:19]
	v_add_u32_e32 v52, 0x1e00, v10
	v_cmp_gt_i32_e32 vcc, 0x1fff, v52
	v_min_i32_e32 v52, 0x1ffe, v52
	v_lshlrev_b32_e32 v52, 1, v52
	s_nop 0
	v_cndmask_b32_e64 v21, 0, 1.0, vcc
	v_add_u32_e32 v109, 0x1000, v109
	global_load_ushort v9, v109, s[36:37] offset:-2
	global_load_ushort v11, v109, s[36:37]
	global_load_ushort v13, v109, s[36:37] offset:2
	global_load_ushort v15, v109, s[72:73] offset:-2
	global_load_ushort v81, v109, s[72:73]
	global_load_ushort v83, v109, s[72:73] offset:2
	global_load_ushort v85, v109, s[0:1]
	global_load_ushort v87, v109, s[4:5]
	global_load_ushort v89, v109, s[36:37] offset:1022
	global_load_ushort v91, v109, s[36:37] offset:1024
	global_load_ushort v93, v109, s[36:37] offset:1026
	global_load_ushort v94, v109, s[72:73] offset:1022
	global_load_ushort v95, v109, s[72:73] offset:1024
	global_load_ushort v96, v109, s[72:73] offset:1026
	global_load_ushort v97, v109, s[0:1] offset:1024
	global_load_ushort v98, v109, s[4:5] offset:1024
	global_load_ushort v99, v109, s[36:37] offset:2046
	global_load_ushort v100, v109, s[36:37] offset:2048
	global_load_ushort v101, v109, s[36:37] offset:2050
	global_load_ushort v102, v109, s[72:73] offset:2046
	global_load_ushort v103, v109, s[72:73] offset:2048
	global_load_ushort v104, v109, s[72:73] offset:2050
	global_load_ushort v105, v109, s[0:1] offset:2048
	global_load_ushort v106, v109, s[4:5] offset:2048
	global_load_ushort v107, v109, s[36:37] offset:3070
	global_load_ushort v108, v109, s[36:37] offset:3072
	global_load_ushort v32, v52, s[36:37] offset:2
	global_load_ushort v78, v109, s[72:73] offset:3070
	global_load_ushort v34, v109, s[72:73] offset:3072
	global_load_ushort v79, v52, s[72:73] offset:2
	global_load_ushort v33, v109, s[0:1] offset:3072
	global_load_ushort v76, v109, s[4:5] offset:3072
	s_waitcnt vmcnt(0)
	v_add_u32_e32 v26, 0x80000, v26
	v_lshlrev_b32_e32 v11, 16, v11
	v_lshlrev_b32_e32 v13, 16, v13
	v_lshlrev_b32_e32 v9, 16, v9
	v_mul_f32_e32 v9, v16, v9
	v_fmac_f32_e32 v9, v14, v11
	v_fmac_f32_e32 v9, v17, v13
	v_add_f32_e32 v9, v12, v9
	v_fma_f32 v27, v55, v8, v4
	v_mul_f32_e32 v70, v27, v9
	v_lshlrev_b32_e32 v85, 16, v85
	v_mul_f32_e32 v84, 0xbfb8aa3b, v85
	v_exp_f32_e32 v84, v84
	s_nop 0
	v_add_f32_e32 v84, 1.0, v84
	v_div_scale_f32 v71, s[74:75], v84, v84, v85
	v_rcp_f32_e32 v82, v71
	s_nop 0
	v_fma_f32 v92, -v71, v82, 1.0
	v_fmac_f32_e32 v82, v92, v82
	v_div_scale_f32 v88, vcc, v85, v84, v85
	v_mul_f32_e32 v90, v88, v82
	v_fma_f32 v92, -v71, v90, v88
	v_fmac_f32_e32 v90, v92, v82
	v_fma_f32 v71, -v71, v90, v88
	v_div_fmas_f32 v71, v71, v82, v90
	v_div_fixup_f32 v85, v71, v84, v85
	v_mul_f32_e32 v70, v70, v85
	v_cvt_pk_bf16_f32 v70, v70, s0
	global_store_short v26, v70, s[70:71]
	v_lshlrev_b32_e32 v81, 16, v81
	v_lshlrev_b32_e32 v83, 16, v83
	v_lshlrev_b32_e32 v15, 16, v15
	v_mul_f32_e32 v15, v16, v15
	v_fmac_f32_e32 v15, v14, v81
	v_fmac_f32_e32 v15, v17, v83
	v_add_f32_e32 v15, v12, v15
	v_fma_f32 v27, v57, v8, v5
	v_mul_f32_e32 v70, v27, v15
	v_lshlrev_b32_e32 v87, 16, v87
	v_mul_f32_e32 v84, 0xbfb8aa3b, v87
	v_exp_f32_e32 v84, v84
	s_nop 0
	v_add_f32_e32 v84, 1.0, v84
	v_div_scale_f32 v71, s[74:75], v84, v84, v87
	v_rcp_f32_e32 v82, v71
	s_nop 0
	v_fma_f32 v92, -v71, v82, 1.0
	v_fmac_f32_e32 v82, v92, v82
	v_div_scale_f32 v88, vcc, v87, v84, v87
	v_mul_f32_e32 v90, v88, v82
	v_fma_f32 v92, -v71, v90, v88
	v_fmac_f32_e32 v90, v92, v82
	v_fma_f32 v71, -v71, v90, v88
	v_div_fmas_f32 v71, v71, v82, v90
	v_div_fixup_f32 v87, v71, v84, v87
	v_mul_f32_e32 v70, v70, v87
	v_cvt_pk_bf16_f32 v70, v70, s0
	global_store_short v26, v70, s[18:19]
	v_add_u32_e32 v26, 0x80000, v26
	v_lshlrev_b32_e32 v91, 16, v91
	v_lshlrev_b32_e32 v93, 16, v93
	v_lshlrev_b32_e32 v89, 16, v89
	v_mul_f32_e32 v89, v16, v89
	v_fmac_f32_e32 v89, v14, v91
	v_fmac_f32_e32 v89, v17, v93
	v_add_f32_e32 v89, v12, v89
	v_fma_f32 v27, v54, v8, v6
	v_mul_f32_e32 v70, v27, v89
	v_lshlrev_b32_e32 v97, 16, v97
	v_mul_f32_e32 v84, 0xbfb8aa3b, v97
	v_exp_f32_e32 v84, v84
	s_nop 0
	v_add_f32_e32 v84, 1.0, v84
	v_div_scale_f32 v71, s[74:75], v84, v84, v97
	v_rcp_f32_e32 v82, v71
	s_nop 0
	v_fma_f32 v92, -v71, v82, 1.0
	v_fmac_f32_e32 v82, v92, v82
	v_div_scale_f32 v88, vcc, v97, v84, v97
	v_mul_f32_e32 v90, v88, v82
	v_fma_f32 v92, -v71, v90, v88
	v_fmac_f32_e32 v90, v92, v82
	v_fma_f32 v71, -v71, v90, v88
	v_div_fmas_f32 v71, v71, v82, v90
	v_div_fixup_f32 v97, v71, v84, v97
	v_mul_f32_e32 v70, v70, v97
	v_cvt_pk_bf16_f32 v70, v70, s0
	global_store_short v26, v70, s[70:71]
	v_lshlrev_b32_e32 v95, 16, v95
	v_lshlrev_b32_e32 v96, 16, v96
	v_lshlrev_b32_e32 v94, 16, v94
	v_mul_f32_e32 v94, v16, v94
	v_fmac_f32_e32 v94, v14, v95
	v_fmac_f32_e32 v94, v17, v96
	v_add_f32_e32 v94, v12, v94
	v_fma_f32 v27, v56, v8, v7
	v_mul_f32_e32 v70, v27, v94
	v_lshlrev_b32_e32 v98, 16, v98
	v_mul_f32_e32 v84, 0xbfb8aa3b, v98
	v_exp_f32_e32 v84, v84
	s_nop 0
	v_add_f32_e32 v84, 1.0, v84
	v_div_scale_f32 v71, s[74:75], v84, v84, v98
	v_rcp_f32_e32 v82, v71
	s_nop 0
	v_fma_f32 v92, -v71, v82, 1.0
	v_fmac_f32_e32 v82, v92, v82
	v_div_scale_f32 v88, vcc, v98, v84, v98
	v_mul_f32_e32 v90, v88, v82
	v_fma_f32 v92, -v71, v90, v88
	v_fmac_f32_e32 v90, v92, v82
	v_fma_f32 v71, -v71, v90, v88
	v_div_fmas_f32 v71, v71, v82, v90
	v_div_fixup_f32 v98, v71, v84, v98
	v_mul_f32_e32 v70, v70, v98
	v_cvt_pk_bf16_f32 v70, v70, s0
	global_store_short v26, v70, s[18:19]
	v_add_u32_e32 v26, 0x80000, v26
	v_lshlrev_b32_e32 v100, 16, v100
	v_lshlrev_b32_e32 v101, 16, v101
	v_lshlrev_b32_e32 v99, 16, v99
	v_mul_f32_e32 v99, v16, v99
	v_fmac_f32_e32 v99, v14, v100
	v_fmac_f32_e32 v99, v17, v101
	v_add_f32_e32 v99, v12, v99
	v_fma_f32 v27, v59, v8, v0
	v_mul_f32_e32 v70, v27, v99
	v_lshlrev_b32_e32 v105, 16, v105
	v_mul_f32_e32 v84, 0xbfb8aa3b, v105
	v_exp_f32_e32 v84, v84
	s_nop 0
	v_add_f32_e32 v84, 1.0, v84
	v_div_scale_f32 v71, s[74:75], v84, v84, v105
	v_rcp_f32_e32 v82, v71
	s_nop 0
	v_fma_f32 v92, -v71, v82, 1.0
	v_fmac_f32_e32 v82, v92, v82
	v_div_scale_f32 v88, vcc, v105, v84, v105
	v_mul_f32_e32 v90, v88, v82
	v_fma_f32 v92, -v71, v90, v88
	v_fmac_f32_e32 v90, v92, v82
	v_fma_f32 v71, -v71, v90, v88
	v_div_fmas_f32 v71, v71, v82, v90
	v_div_fixup_f32 v105, v71, v84, v105
	v_mul_f32_e32 v70, v70, v105
	v_cvt_pk_bf16_f32 v70, v70, s0
	global_store_short v26, v70, s[70:71]
	v_lshlrev_b32_e32 v103, 16, v103
	v_lshlrev_b32_e32 v104, 16, v104
	v_lshlrev_b32_e32 v102, 16, v102
	v_mul_f32_e32 v102, v16, v102
	v_fmac_f32_e32 v102, v14, v103
	v_fmac_f32_e32 v102, v17, v104
	v_add_f32_e32 v102, v12, v102
	v_fma_f32 v27, v61, v8, v1
	v_mul_f32_e32 v70, v27, v102
	v_lshlrev_b32_e32 v106, 16, v106
	v_mul_f32_e32 v84, 0xbfb8aa3b, v106
	v_exp_f32_e32 v84, v84
	s_nop 0
	v_add_f32_e32 v84, 1.0, v84
	v_div_scale_f32 v71, s[74:75], v84, v84, v106
	v_rcp_f32_e32 v82, v71
	s_nop 0
	v_fma_f32 v92, -v71, v82, 1.0
	v_fmac_f32_e32 v82, v92, v82
	v_div_scale_f32 v88, vcc, v106, v84, v106
	v_mul_f32_e32 v90, v88, v82
	v_fma_f32 v92, -v71, v90, v88
	v_fmac_f32_e32 v90, v92, v82
	v_fma_f32 v71, -v71, v90, v88
	v_div_fmas_f32 v71, v71, v82, v90
	v_div_fixup_f32 v106, v71, v84, v106
	v_mul_f32_e32 v70, v70, v106
	v_cvt_pk_bf16_f32 v70, v70, s0
	global_store_short v26, v70, s[18:19]
	v_add_u32_e32 v26, 0x80000, v26
	v_lshlrev_b32_e32 v108, 16, v108
	v_lshlrev_b32_e32 v32, 16, v32
	v_lshlrev_b32_e32 v107, 16, v107
	v_mul_f32_e32 v107, v16, v107
	v_mul_f32_e32 v32, v21, v32
	v_fmac_f32_e32 v107, v14, v108
	v_fmac_f32_e32 v107, v17, v32
	v_add_f32_e32 v107, v12, v107
	v_fma_f32 v27, v58, v8, v2
	v_mul_f32_e32 v70, v27, v107
	v_lshlrev_b32_e32 v33, 16, v33
	v_mul_f32_e32 v84, 0xbfb8aa3b, v33
	v_exp_f32_e32 v84, v84
	s_nop 0
	v_add_f32_e32 v84, 1.0, v84
	v_div_scale_f32 v71, s[74:75], v84, v84, v33
	v_rcp_f32_e32 v82, v71
	s_nop 0
	v_fma_f32 v92, -v71, v82, 1.0
	v_fmac_f32_e32 v82, v92, v82
	v_div_scale_f32 v88, vcc, v33, v84, v33
	v_mul_f32_e32 v90, v88, v82
	v_fma_f32 v92, -v71, v90, v88
	v_fmac_f32_e32 v90, v92, v82
	v_fma_f32 v71, -v71, v90, v88
	v_div_fmas_f32 v71, v71, v82, v90
	v_div_fixup_f32 v33, v71, v84, v33
	v_mul_f32_e32 v70, v70, v33
	v_cvt_pk_bf16_f32 v70, v70, s0
	global_store_short v26, v70, s[70:71]
	v_lshlrev_b32_e32 v34, 16, v34
	v_lshlrev_b32_e32 v79, 16, v79
	v_lshlrev_b32_e32 v78, 16, v78
	v_mul_f32_e32 v78, v16, v78
	v_mul_f32_e32 v79, v21, v79
	v_fmac_f32_e32 v78, v14, v34
	v_fmac_f32_e32 v78, v17, v79
	v_add_f32_e32 v78, v12, v78
	v_fma_f32 v27, v60, v8, v3
	v_mul_f32_e32 v70, v27, v78
	v_lshlrev_b32_e32 v76, 16, v76
	v_mul_f32_e32 v84, 0xbfb8aa3b, v76
	v_exp_f32_e32 v84, v84
	s_nop 0
	v_add_f32_e32 v84, 1.0, v84
	v_div_scale_f32 v71, s[74:75], v84, v84, v76
	v_rcp_f32_e32 v82, v71
	s_nop 0
	v_fma_f32 v92, -v71, v82, 1.0
	v_fmac_f32_e32 v82, v92, v82
	v_div_scale_f32 v88, vcc, v76, v84, v76
	v_mul_f32_e32 v90, v88, v82
	v_fma_f32 v92, -v71, v90, v88
	v_fmac_f32_e32 v90, v92, v82
	v_fma_f32 v71, -v71, v90, v88
	v_div_fmas_f32 v71, v71, v82, v90
	v_div_fixup_f32 v76, v71, v84, v76
	v_mul_f32_e32 v70, v70, v76
	v_cvt_pk_bf16_f32 v70, v70, s0
	global_store_short v26, v70, s[18:19]
	s_mov_b64 s[74:75], 0
